# hand-off: closing barrier 2 MFMAs early, finishing wave at prio 2 for its last pair, partner at prio 1 from the start
# baseline (speedup 1.0000x reference)
.LBB0_183:
	s_ashr_i32 s13, s12, 31
	s_lshl_b64 s[24:25], s[12:13], 19
	s_add_u32 s24, s80, s24
	s_addc_u32 s25, s81, s25
	s_and_b64 s[30:31], s[4:5], exec
	s_cselect_b32 s13, s25, s45
	s_cselect_b32 s66, s24, s44
	s_ashr_i32 s11, s10, 31
	s_lshl_b64 s[30:31], s[10:11], 19
	s_add_u32 s30, s52, s30
	s_addc_u32 s31, s53, s31
	s_and_b64 s[48:49], s[4:5], exec
	s_cselect_b32 s11, s31, s47
	s_cselect_b32 s67, s30, s46
	s_add_u32 s44, s44, 0x40080
	s_addc_u32 s45, s45, 0
	s_add_u32 s68, s46, 0x100
	s_addc_u32 s69, s47, 0
	s_mov_b32 s70, -2
	ds_read_b128 v[140:143], v147
	ds_read_b128 v[150:153], v147 offset:1024
	ds_read_b128 v[154:157], v147 offset:2048
	ds_read_b128 v[158:161], v147 offset:3072
	ds_read_b128 v[162:165], v148
	ds_read_b128 v[166:169], v148 offset:1024
	ds_read_b128 v[170:173], v148 offset:2048
	ds_read_b128 v[174:177], v148 offset:3072
	s_add_u32 s18, s44, 0xfffc0080
	s_addc_u32 s19, s45, -1
	s_cmp_eq_u32 s70, 12
	s_cselect_b32 s49, s13, s19
	s_cselect_b32 s48, s66, s18
	s_cselect_b32 s47, s11, s69
	s_cselect_b32 s46, s67, s68
	v_lshl_add_u64 v[178:179], s[44:45], 0, v[132:133]
	s_add_i32 m0, s37, 0xc000
	ds_read_b128 v[184:187], v149
	ds_read_b128 v[188:191], v149 offset:1024
	ds_read_b128 v[192:195], v149 offset:2048
	ds_read_b128 v[196:199], v149 offset:3072
	ds_read_b128 v[200:203], v149 offset:4096
	ds_read_b128 v[204:207], v149 offset:5120
	ds_read_b128 v[208:211], v149 offset:6144
	ds_read_b128 v[212:215], v149 offset:7168
	global_load_lds_dwordx4 v[178:179], off
	v_lshl_add_u64 v[178:179], s[44:45], 0, v[134:135]
	s_add_i32 m0, s37, 0xe000
	s_nop 0
	global_load_lds_dwordx4 v[178:179], off
	s_waitcnt vmcnt(8)
	s_waitcnt lgkmcnt(0)
	s_barrier
	s_setprio 1
	s_waitcnt lgkmcnt(0)
	v_mfma_f32_16x16x32_bf16 v[124:127], v[140:143], v[184:187], 0
	v_mfma_f32_16x16x32_bf16 v[124:127], v[150:153], v[188:191], v[124:127]
	v_mfma_f32_16x16x32_bf16 v[120:123], v[154:157], v[184:187], 0
	v_mfma_f32_16x16x32_bf16 v[120:123], v[158:161], v[188:191], v[120:123]
	v_mfma_f32_16x16x32_bf16 v[108:111], v[140:143], v[192:195], 0
	v_mfma_f32_16x16x32_bf16 v[108:111], v[150:153], v[196:199], v[108:111]
	v_mfma_f32_16x16x32_bf16 v[104:107], v[154:157], v[192:195], 0
	v_mfma_f32_16x16x32_bf16 v[104:107], v[158:161], v[196:199], v[104:107]
	v_mfma_f32_16x16x32_bf16 v[92:95], v[140:143], v[200:203], 0
	v_mfma_f32_16x16x32_bf16 v[92:95], v[150:153], v[204:207], v[92:95]
	v_mfma_f32_16x16x32_bf16 v[88:91], v[154:157], v[200:203], 0
	v_mfma_f32_16x16x32_bf16 v[88:91], v[158:161], v[204:207], v[88:91]
	v_mfma_f32_16x16x32_bf16 v[76:79], v[140:143], v[208:211], 0
	v_mfma_f32_16x16x32_bf16 v[76:79], v[150:153], v[212:215], v[76:79]
	v_mfma_f32_16x16x32_bf16 v[72:75], v[154:157], v[208:211], 0
	v_mfma_f32_16x16x32_bf16 v[72:75], v[158:161], v[212:215], v[72:75]
	v_mfma_f32_16x16x32_bf16 v[116:119], v[162:165], v[184:187], 0
	v_mfma_f32_16x16x32_bf16 v[116:119], v[166:169], v[188:191], v[116:119]
	v_mfma_f32_16x16x32_bf16 v[112:115], v[170:173], v[184:187], 0
	v_mfma_f32_16x16x32_bf16 v[112:115], v[174:177], v[188:191], v[112:115]
	v_mfma_f32_16x16x32_bf16 v[100:103], v[162:165], v[192:195], 0
	v_mfma_f32_16x16x32_bf16 v[100:103], v[166:169], v[196:199], v[100:103]
	v_mfma_f32_16x16x32_bf16 v[96:99], v[170:173], v[192:195], 0
	v_mfma_f32_16x16x32_bf16 v[96:99], v[174:177], v[196:199], v[96:99]
	v_mfma_f32_16x16x32_bf16 v[84:87], v[162:165], v[200:203], 0
	v_mfma_f32_16x16x32_bf16 v[84:87], v[166:169], v[204:207], v[84:87]
	v_mfma_f32_16x16x32_bf16 v[80:83], v[170:173], v[200:203], 0
	v_mfma_f32_16x16x32_bf16 v[80:83], v[174:177], v[204:207], v[80:83]
	v_mfma_f32_16x16x32_bf16 v[68:71], v[162:165], v[208:211], 0
	v_mfma_f32_16x16x32_bf16 v[68:71], v[166:169], v[212:215], v[68:71]
	s_setprio 2
	s_barrier
	v_mfma_f32_16x16x32_bf16 v[64:67], v[170:173], v[208:211], 0
	v_mfma_f32_16x16x32_bf16 v[64:67], v[174:177], v[212:215], v[64:67]
	s_setprio 0
	s_add_i32 s18, s62, s54
	v_lshl_add_u64 v[178:179], s[46:47], 0, v[130:131]
	s_mov_b32 m0, s18
	ds_read_b128 v[184:187], v149 offset:16384
	ds_read_b128 v[188:191], v149 offset:17408
	ds_read_b128 v[192:195], v149 offset:18432
	ds_read_b128 v[196:199], v149 offset:19456
	ds_read_b128 v[200:203], v149 offset:20480
	ds_read_b128 v[204:207], v149 offset:21504
	ds_read_b128 v[208:211], v149 offset:22528
	ds_read_b128 v[212:215], v149 offset:23552
	global_load_lds_dwordx4 v[178:179], off
	s_add_i32 m0, s18, 0x2000
	s_add_u32 s72, s46, 0x40000
	v_lshl_add_u64 v[216:217], s[46:47], 0, v[128:129]
	s_addc_u32 s73, s47, 0
	s_add_i32 s18, s63, s54
	global_load_lds_dwordx4 v[216:217], off
	v_lshl_add_u64 v[218:219], s[72:73], 0, v[130:131]
	s_mov_b32 m0, s18
	v_lshl_add_u64 v[220:221], s[48:49], 0, v[128:129]
	global_load_lds_dwordx4 v[218:219], off
	v_lshl_add_u64 v[218:219], s[72:73], 0, v[128:129]
	s_add_i32 m0, s18, 0x2000
	s_nop 0
	global_load_lds_dwordx4 v[218:219], off
	v_lshl_add_u64 v[218:219], s[48:49], 0, v[130:131]
	s_mov_b32 m0, s37
	s_nop 0
	global_load_lds_dwordx4 v[218:219], off
	s_mov_b32 m0, s56
	s_nop 0
	global_load_lds_dwordx4 v[220:221], off
	s_waitcnt vmcnt(8)
	s_waitcnt lgkmcnt(0)
	s_barrier
	s_setprio 1
	s_waitcnt lgkmcnt(0)
	v_mfma_f32_16x16x32_bf16 v[60:63], v[140:143], v[184:187], 0
	v_mfma_f32_16x16x32_bf16 v[60:63], v[150:153], v[188:191], v[60:63]
	v_mfma_f32_16x16x32_bf16 v[56:59], v[154:157], v[184:187], 0
	v_mfma_f32_16x16x32_bf16 v[56:59], v[158:161], v[188:191], v[56:59]
	v_mfma_f32_16x16x32_bf16 v[44:47], v[140:143], v[192:195], 0
	v_mfma_f32_16x16x32_bf16 v[44:47], v[150:153], v[196:199], v[44:47]
	v_mfma_f32_16x16x32_bf16 v[40:43], v[154:157], v[192:195], 0
	v_mfma_f32_16x16x32_bf16 v[40:43], v[158:161], v[196:199], v[40:43]
	v_mfma_f32_16x16x32_bf16 v[28:31], v[140:143], v[200:203], 0
	v_mfma_f32_16x16x32_bf16 v[28:31], v[150:153], v[204:207], v[28:31]
	v_mfma_f32_16x16x32_bf16 v[24:27], v[154:157], v[200:203], 0
	v_mfma_f32_16x16x32_bf16 v[24:27], v[158:161], v[204:207], v[24:27]
	v_mfma_f32_16x16x32_bf16 v[12:15], v[140:143], v[208:211], 0
	v_mfma_f32_16x16x32_bf16 v[12:15], v[150:153], v[212:215], v[12:15]
	v_mfma_f32_16x16x32_bf16 v[8:11], v[154:157], v[208:211], 0
	v_mfma_f32_16x16x32_bf16 v[8:11], v[158:161], v[212:215], v[8:11]
	v_mfma_f32_16x16x32_bf16 v[52:55], v[162:165], v[184:187], 0
	v_mfma_f32_16x16x32_bf16 v[52:55], v[166:169], v[188:191], v[52:55]
	v_mfma_f32_16x16x32_bf16 v[48:51], v[170:173], v[184:187], 0
	v_mfma_f32_16x16x32_bf16 v[48:51], v[174:177], v[188:191], v[48:51]
	v_mfma_f32_16x16x32_bf16 v[36:39], v[162:165], v[192:195], 0
	v_mfma_f32_16x16x32_bf16 v[36:39], v[166:169], v[196:199], v[36:39]
	v_mfma_f32_16x16x32_bf16 v[32:35], v[170:173], v[192:195], 0
	v_mfma_f32_16x16x32_bf16 v[32:35], v[174:177], v[196:199], v[32:35]
	v_mfma_f32_16x16x32_bf16 v[20:23], v[162:165], v[200:203], 0
	v_mfma_f32_16x16x32_bf16 v[20:23], v[166:169], v[204:207], v[20:23]
	v_mfma_f32_16x16x32_bf16 v[16:19], v[170:173], v[200:203], 0
	v_mfma_f32_16x16x32_bf16 v[16:19], v[174:177], v[204:207], v[16:19]
	v_mfma_f32_16x16x32_bf16 v[4:7], v[162:165], v[208:211], 0
	v_mfma_f32_16x16x32_bf16 v[4:7], v[166:169], v[212:215], v[4:7]
	s_setprio 2
	s_barrier
	v_mfma_f32_16x16x32_bf16 v[0:3], v[170:173], v[208:211], 0
	v_mfma_f32_16x16x32_bf16 v[0:3], v[174:177], v[212:215], v[0:3]
	s_setprio 0
	s_branch .Lmid_gemm0
.LBB0_184:
	ds_read_b128 v[140:143], v147
	ds_read_b128 v[150:153], v147 offset:1024
	ds_read_b128 v[154:157], v147 offset:2048
	ds_read_b128 v[158:161], v147 offset:3072
	ds_read_b128 v[162:165], v148
	ds_read_b128 v[166:169], v148 offset:1024
	ds_read_b128 v[170:173], v148 offset:2048
	ds_read_b128 v[174:177], v148 offset:3072
	s_add_u32 s18, s44, 0xfffc0080
	s_addc_u32 s19, s45, -1
	s_cmp_eq_u32 s70, 12
	s_cselect_b32 s49, s13, s19
	s_cselect_b32 s48, s66, s18
	s_cselect_b32 s47, s11, s69
	s_cselect_b32 s46, s67, s68
	v_lshl_add_u64 v[178:179], s[44:45], 0, v[132:133]
	s_add_i32 m0, s37, 0xc000
	ds_read_b128 v[184:187], v149
	ds_read_b128 v[188:191], v149 offset:1024
	ds_read_b128 v[192:195], v149 offset:2048
	ds_read_b128 v[196:199], v149 offset:3072
	ds_read_b128 v[200:203], v149 offset:4096
	ds_read_b128 v[204:207], v149 offset:5120
	ds_read_b128 v[208:211], v149 offset:6144
	ds_read_b128 v[212:215], v149 offset:7168
	global_load_lds_dwordx4 v[178:179], off
	v_lshl_add_u64 v[178:179], s[44:45], 0, v[134:135]
	s_add_i32 m0, s37, 0xe000
	s_nop 0
	global_load_lds_dwordx4 v[178:179], off
	s_waitcnt vmcnt(8)
	s_waitcnt lgkmcnt(0)
	s_barrier
	s_setprio 1
	s_waitcnt lgkmcnt(0)
	v_mfma_f32_16x16x32_bf16 v[124:127], v[140:143], v[184:187], v[124:127]
	v_mfma_f32_16x16x32_bf16 v[124:127], v[150:153], v[188:191], v[124:127]
	v_mfma_f32_16x16x32_bf16 v[120:123], v[154:157], v[184:187], v[120:123]
	v_mfma_f32_16x16x32_bf16 v[120:123], v[158:161], v[188:191], v[120:123]
	v_mfma_f32_16x16x32_bf16 v[108:111], v[140:143], v[192:195], v[108:111]
	v_mfma_f32_16x16x32_bf16 v[108:111], v[150:153], v[196:199], v[108:111]
	v_mfma_f32_16x16x32_bf16 v[104:107], v[154:157], v[192:195], v[104:107]
	v_mfma_f32_16x16x32_bf16 v[104:107], v[158:161], v[196:199], v[104:107]
	v_mfma_f32_16x16x32_bf16 v[92:95], v[140:143], v[200:203], v[92:95]
	v_mfma_f32_16x16x32_bf16 v[92:95], v[150:153], v[204:207], v[92:95]
	v_mfma_f32_16x16x32_bf16 v[88:91], v[154:157], v[200:203], v[88:91]
	v_mfma_f32_16x16x32_bf16 v[88:91], v[158:161], v[204:207], v[88:91]
	v_mfma_f32_16x16x32_bf16 v[76:79], v[140:143], v[208:211], v[76:79]
	v_mfma_f32_16x16x32_bf16 v[76:79], v[150:153], v[212:215], v[76:79]
	v_mfma_f32_16x16x32_bf16 v[72:75], v[154:157], v[208:211], v[72:75]
	v_mfma_f32_16x16x32_bf16 v[72:75], v[158:161], v[212:215], v[72:75]
	v_mfma_f32_16x16x32_bf16 v[116:119], v[162:165], v[184:187], v[116:119]
	v_mfma_f32_16x16x32_bf16 v[116:119], v[166:169], v[188:191], v[116:119]
	v_mfma_f32_16x16x32_bf16 v[112:115], v[170:173], v[184:187], v[112:115]
	v_mfma_f32_16x16x32_bf16 v[112:115], v[174:177], v[188:191], v[112:115]
	v_mfma_f32_16x16x32_bf16 v[100:103], v[162:165], v[192:195], v[100:103]
	v_mfma_f32_16x16x32_bf16 v[100:103], v[166:169], v[196:199], v[100:103]
	v_mfma_f32_16x16x32_bf16 v[96:99], v[170:173], v[192:195], v[96:99]
	v_mfma_f32_16x16x32_bf16 v[96:99], v[174:177], v[196:199], v[96:99]
	v_mfma_f32_16x16x32_bf16 v[84:87], v[162:165], v[200:203], v[84:87]
	v_mfma_f32_16x16x32_bf16 v[84:87], v[166:169], v[204:207], v[84:87]
	v_mfma_f32_16x16x32_bf16 v[80:83], v[170:173], v[200:203], v[80:83]
	v_mfma_f32_16x16x32_bf16 v[80:83], v[174:177], v[204:207], v[80:83]
	v_mfma_f32_16x16x32_bf16 v[68:71], v[162:165], v[208:211], v[68:71]
	v_mfma_f32_16x16x32_bf16 v[68:71], v[166:169], v[212:215], v[68:71]
	s_setprio 2
	s_barrier
	v_mfma_f32_16x16x32_bf16 v[64:67], v[170:173], v[208:211], v[64:67]
	v_mfma_f32_16x16x32_bf16 v[64:67], v[174:177], v[212:215], v[64:67]
	s_setprio 0
	s_add_i32 s18, s62, s54
	v_lshl_add_u64 v[178:179], s[46:47], 0, v[130:131]
	s_mov_b32 m0, s18
	ds_read_b128 v[184:187], v149 offset:16384
	ds_read_b128 v[188:191], v149 offset:17408
	ds_read_b128 v[192:195], v149 offset:18432
	ds_read_b128 v[196:199], v149 offset:19456
	ds_read_b128 v[200:203], v149 offset:20480
	ds_read_b128 v[204:207], v149 offset:21504
	ds_read_b128 v[208:211], v149 offset:22528
	ds_read_b128 v[212:215], v149 offset:23552
	global_load_lds_dwordx4 v[178:179], off
	s_add_i32 m0, s18, 0x2000
	s_add_u32 s72, s46, 0x40000
	v_lshl_add_u64 v[216:217], s[46:47], 0, v[128:129]
	s_addc_u32 s73, s47, 0
	s_add_i32 s18, s63, s54
	global_load_lds_dwordx4 v[216:217], off
	v_lshl_add_u64 v[218:219], s[72:73], 0, v[130:131]
	s_mov_b32 m0, s18
	v_lshl_add_u64 v[220:221], s[48:49], 0, v[128:129]
	global_load_lds_dwordx4 v[218:219], off
	v_lshl_add_u64 v[218:219], s[72:73], 0, v[128:129]
	s_add_i32 m0, s18, 0x2000
	s_nop 0
	global_load_lds_dwordx4 v[218:219], off
	v_lshl_add_u64 v[218:219], s[48:49], 0, v[130:131]
	s_mov_b32 m0, s37
	s_nop 0
	global_load_lds_dwordx4 v[218:219], off
	s_mov_b32 m0, s56
	s_nop 0
	global_load_lds_dwordx4 v[220:221], off
	s_waitcnt vmcnt(8)
	s_waitcnt lgkmcnt(0)
	s_barrier
	s_setprio 1
	s_waitcnt lgkmcnt(0)
	v_mfma_f32_16x16x32_bf16 v[60:63], v[140:143], v[184:187], v[60:63]
	v_mfma_f32_16x16x32_bf16 v[60:63], v[150:153], v[188:191], v[60:63]
	v_mfma_f32_16x16x32_bf16 v[56:59], v[154:157], v[184:187], v[56:59]
	v_mfma_f32_16x16x32_bf16 v[56:59], v[158:161], v[188:191], v[56:59]
	v_mfma_f32_16x16x32_bf16 v[44:47], v[140:143], v[192:195], v[44:47]
	v_mfma_f32_16x16x32_bf16 v[44:47], v[150:153], v[196:199], v[44:47]
	v_mfma_f32_16x16x32_bf16 v[40:43], v[154:157], v[192:195], v[40:43]
	v_mfma_f32_16x16x32_bf16 v[40:43], v[158:161], v[196:199], v[40:43]
	v_mfma_f32_16x16x32_bf16 v[28:31], v[140:143], v[200:203], v[28:31]
	v_mfma_f32_16x16x32_bf16 v[28:31], v[150:153], v[204:207], v[28:31]
	v_mfma_f32_16x16x32_bf16 v[24:27], v[154:157], v[200:203], v[24:27]
	v_mfma_f32_16x16x32_bf16 v[24:27], v[158:161], v[204:207], v[24:27]
	v_mfma_f32_16x16x32_bf16 v[12:15], v[140:143], v[208:211], v[12:15]
	v_mfma_f32_16x16x32_bf16 v[12:15], v[150:153], v[212:215], v[12:15]
	v_mfma_f32_16x16x32_bf16 v[8:11], v[154:157], v[208:211], v[8:11]
	v_mfma_f32_16x16x32_bf16 v[8:11], v[158:161], v[212:215], v[8:11]
	v_mfma_f32_16x16x32_bf16 v[52:55], v[162:165], v[184:187], v[52:55]
	v_mfma_f32_16x16x32_bf16 v[52:55], v[166:169], v[188:191], v[52:55]
	v_mfma_f32_16x16x32_bf16 v[48:51], v[170:173], v[184:187], v[48:51]
	v_mfma_f32_16x16x32_bf16 v[48:51], v[174:177], v[188:191], v[48:51]
	v_mfma_f32_16x16x32_bf16 v[36:39], v[162:165], v[192:195], v[36:39]
	v_mfma_f32_16x16x32_bf16 v[36:39], v[166:169], v[196:199], v[36:39]
	v_mfma_f32_16x16x32_bf16 v[32:35], v[170:173], v[192:195], v[32:35]
	v_mfma_f32_16x16x32_bf16 v[32:35], v[174:177], v[196:199], v[32:35]
	v_mfma_f32_16x16x32_bf16 v[20:23], v[162:165], v[200:203], v[20:23]
	v_mfma_f32_16x16x32_bf16 v[20:23], v[166:169], v[204:207], v[20:23]
	v_mfma_f32_16x16x32_bf16 v[16:19], v[170:173], v[200:203], v[16:19]
	v_mfma_f32_16x16x32_bf16 v[16:19], v[174:177], v[204:207], v[16:19]
	v_mfma_f32_16x16x32_bf16 v[4:7], v[162:165], v[208:211], v[4:7]
	v_mfma_f32_16x16x32_bf16 v[4:7], v[166:169], v[212:215], v[4:7]
	s_setprio 2
	s_barrier
	v_mfma_f32_16x16x32_bf16 v[0:3], v[170:173], v[208:211], v[0:3]
	v_mfma_f32_16x16x32_bf16 v[0:3], v[174:177], v[212:215], v[0:3]
	s_setprio 0
.Lmid_gemm0:
	s_add_i32 s18, 0, 0x18000
	s_add_i32 s19, 0, 0x1c000
	v_add_u32_e32 v158, s18, v145
	v_add_u32_e32 v174, s19, v145
	ds_read_b128 v[140:143], v158
	ds_read_b128 v[150:153], v158 offset:1024
	ds_read_b128 v[154:157], v158 offset:2048
	ds_read_b128 v[158:161], v158 offset:3072
	ds_read_b128 v[162:165], v174
	ds_read_b128 v[166:169], v174 offset:1024
	ds_read_b128 v[170:173], v174 offset:2048
	ds_read_b128 v[174:177], v174 offset:3072
	s_add_u32 s48, s48, 0x40000
	s_addc_u32 s49, s49, 0
	s_mov_b32 m0, s57
	v_lshl_add_u64 v[222:223], s[48:49], 0, v[130:131]
	ds_read_b128 v[184:187], v149 offset:32768
	ds_read_b128 v[188:191], v149 offset:33792
	ds_read_b128 v[192:195], v149 offset:34816
	ds_read_b128 v[196:199], v149 offset:35840
	ds_read_b128 v[200:203], v149 offset:36864
	ds_read_b128 v[204:207], v149 offset:37888
	ds_read_b128 v[208:211], v149 offset:38912
	ds_read_b128 v[212:215], v149 offset:39936
	global_load_lds_dwordx4 v[222:223], off
	v_lshl_add_u64 v[222:223], s[48:49], 0, v[128:129]
	s_mov_b32 m0, s58
	s_nop 0
	global_load_lds_dwordx4 v[222:223], off
	s_waitcnt vmcnt(8)
	s_waitcnt lgkmcnt(0)
	s_barrier
	s_setprio 1
	s_waitcnt lgkmcnt(0)
	v_mfma_f32_16x16x32_bf16 v[124:127], v[140:143], v[184:187], v[124:127]
	v_mfma_f32_16x16x32_bf16 v[124:127], v[150:153], v[188:191], v[124:127]
	v_mfma_f32_16x16x32_bf16 v[120:123], v[154:157], v[184:187], v[120:123]
	v_mfma_f32_16x16x32_bf16 v[120:123], v[158:161], v[188:191], v[120:123]
	v_mfma_f32_16x16x32_bf16 v[108:111], v[140:143], v[192:195], v[108:111]
	v_mfma_f32_16x16x32_bf16 v[108:111], v[150:153], v[196:199], v[108:111]
	v_mfma_f32_16x16x32_bf16 v[104:107], v[154:157], v[192:195], v[104:107]
	v_mfma_f32_16x16x32_bf16 v[104:107], v[158:161], v[196:199], v[104:107]
	v_mfma_f32_16x16x32_bf16 v[92:95], v[140:143], v[200:203], v[92:95]
	v_mfma_f32_16x16x32_bf16 v[92:95], v[150:153], v[204:207], v[92:95]
	v_mfma_f32_16x16x32_bf16 v[88:91], v[154:157], v[200:203], v[88:91]
	v_mfma_f32_16x16x32_bf16 v[88:91], v[158:161], v[204:207], v[88:91]
	v_mfma_f32_16x16x32_bf16 v[76:79], v[140:143], v[208:211], v[76:79]
	v_mfma_f32_16x16x32_bf16 v[76:79], v[150:153], v[212:215], v[76:79]
	v_mfma_f32_16x16x32_bf16 v[72:75], v[154:157], v[208:211], v[72:75]
	v_mfma_f32_16x16x32_bf16 v[72:75], v[158:161], v[212:215], v[72:75]
	v_mfma_f32_16x16x32_bf16 v[116:119], v[162:165], v[184:187], v[116:119]
	v_mfma_f32_16x16x32_bf16 v[116:119], v[166:169], v[188:191], v[116:119]
	v_mfma_f32_16x16x32_bf16 v[112:115], v[170:173], v[184:187], v[112:115]
	v_mfma_f32_16x16x32_bf16 v[112:115], v[174:177], v[188:191], v[112:115]
	v_mfma_f32_16x16x32_bf16 v[100:103], v[162:165], v[192:195], v[100:103]
	v_mfma_f32_16x16x32_bf16 v[100:103], v[166:169], v[196:199], v[100:103]
	v_mfma_f32_16x16x32_bf16 v[96:99], v[170:173], v[192:195], v[96:99]
	v_mfma_f32_16x16x32_bf16 v[96:99], v[174:177], v[196:199], v[96:99]
	v_mfma_f32_16x16x32_bf16 v[84:87], v[162:165], v[200:203], v[84:87]
	v_mfma_f32_16x16x32_bf16 v[84:87], v[166:169], v[204:207], v[84:87]
	v_mfma_f32_16x16x32_bf16 v[80:83], v[170:173], v[200:203], v[80:83]
	v_mfma_f32_16x16x32_bf16 v[80:83], v[174:177], v[204:207], v[80:83]
	v_mfma_f32_16x16x32_bf16 v[68:71], v[162:165], v[208:211], v[68:71]
	v_mfma_f32_16x16x32_bf16 v[68:71], v[166:169], v[212:215], v[68:71]
	s_setprio 2
	s_barrier
	v_mfma_f32_16x16x32_bf16 v[64:67], v[170:173], v[208:211], v[64:67]
	v_mfma_f32_16x16x32_bf16 v[64:67], v[174:177], v[212:215], v[64:67]
	s_setprio 0
	s_add_i32 s18, s18, s54
	v_lshl_add_u64 v[178:179], v[178:179], 0, s[6:7]
	s_mov_b32 m0, s18
	ds_read_b128 v[184:187], v149 offset:49152
	ds_read_b128 v[188:191], v149 offset:50176
	ds_read_b128 v[192:195], v149 offset:51200
	ds_read_b128 v[196:199], v149 offset:52224
	ds_read_b128 v[200:203], v149 offset:53248
	ds_read_b128 v[204:207], v149 offset:54272
	ds_read_b128 v[208:211], v149 offset:55296
	ds_read_b128 v[212:215], v149 offset:56320
	global_load_lds_dwordx4 v[178:179], off
	s_add_i32 m0, s18, 0x2000
	s_add_u32 s46, s46, 0x40080
	v_lshl_add_u64 v[178:179], v[216:217], 0, s[6:7]
	s_addc_u32 s47, s47, 0
	s_add_i32 s18, s19, s54
	global_load_lds_dwordx4 v[178:179], off
	v_lshl_add_u64 v[178:179], s[46:47], 0, v[130:131]
	s_mov_b32 m0, s18
	s_nop 0
	global_load_lds_dwordx4 v[178:179], off
	v_lshl_add_u64 v[178:179], s[46:47], 0, v[128:129]
	s_add_i32 m0, s18, 0x2000
	s_nop 0
	global_load_lds_dwordx4 v[178:179], off
	v_lshl_add_u64 v[178:179], v[218:219], 0, s[6:7]
	s_mov_b32 m0, s60
	s_nop 0
	global_load_lds_dwordx4 v[178:179], off
	v_lshl_add_u64 v[178:179], v[220:221], 0, s[6:7]
	s_mov_b32 m0, s61
	s_nop 0
	global_load_lds_dwordx4 v[178:179], off
	s_waitcnt vmcnt(8)
	s_waitcnt lgkmcnt(0)
	s_barrier
	s_setprio 1
	s_waitcnt lgkmcnt(0)
	v_mfma_f32_16x16x32_bf16 v[60:63], v[140:143], v[184:187], v[60:63]
	v_mfma_f32_16x16x32_bf16 v[60:63], v[150:153], v[188:191], v[60:63]
	v_mfma_f32_16x16x32_bf16 v[56:59], v[154:157], v[184:187], v[56:59]
	v_mfma_f32_16x16x32_bf16 v[56:59], v[158:161], v[188:191], v[56:59]
	v_mfma_f32_16x16x32_bf16 v[44:47], v[140:143], v[192:195], v[44:47]
	v_mfma_f32_16x16x32_bf16 v[44:47], v[150:153], v[196:199], v[44:47]
	v_mfma_f32_16x16x32_bf16 v[40:43], v[154:157], v[192:195], v[40:43]
	v_mfma_f32_16x16x32_bf16 v[40:43], v[158:161], v[196:199], v[40:43]
	v_mfma_f32_16x16x32_bf16 v[28:31], v[140:143], v[200:203], v[28:31]
	v_mfma_f32_16x16x32_bf16 v[28:31], v[150:153], v[204:207], v[28:31]
	v_mfma_f32_16x16x32_bf16 v[24:27], v[154:157], v[200:203], v[24:27]
	v_mfma_f32_16x16x32_bf16 v[24:27], v[158:161], v[204:207], v[24:27]
	v_mfma_f32_16x16x32_bf16 v[12:15], v[140:143], v[208:211], v[12:15]
	v_mfma_f32_16x16x32_bf16 v[12:15], v[150:153], v[212:215], v[12:15]
	v_mfma_f32_16x16x32_bf16 v[8:11], v[154:157], v[208:211], v[8:11]
	v_mfma_f32_16x16x32_bf16 v[8:11], v[158:161], v[212:215], v[8:11]
	v_mfma_f32_16x16x32_bf16 v[52:55], v[162:165], v[184:187], v[52:55]
	v_mfma_f32_16x16x32_bf16 v[52:55], v[166:169], v[188:191], v[52:55]
	v_mfma_f32_16x16x32_bf16 v[48:51], v[170:173], v[184:187], v[48:51]
	v_mfma_f32_16x16x32_bf16 v[48:51], v[174:177], v[188:191], v[48:51]
	v_mfma_f32_16x16x32_bf16 v[36:39], v[162:165], v[192:195], v[36:39]
	v_mfma_f32_16x16x32_bf16 v[36:39], v[166:169], v[196:199], v[36:39]
	v_mfma_f32_16x16x32_bf16 v[32:35], v[170:173], v[192:195], v[32:35]
	v_mfma_f32_16x16x32_bf16 v[32:35], v[174:177], v[196:199], v[32:35]
	v_mfma_f32_16x16x32_bf16 v[20:23], v[162:165], v[200:203], v[20:23]
	v_mfma_f32_16x16x32_bf16 v[20:23], v[166:169], v[204:207], v[20:23]
	v_mfma_f32_16x16x32_bf16 v[16:19], v[170:173], v[200:203], v[16:19]
	v_mfma_f32_16x16x32_bf16 v[16:19], v[174:177], v[204:207], v[16:19]
	v_mfma_f32_16x16x32_bf16 v[4:7], v[162:165], v[208:211], v[4:7]
	v_mfma_f32_16x16x32_bf16 v[4:7], v[166:169], v[212:215], v[4:7]
	s_setprio 2
	s_barrier
	v_mfma_f32_16x16x32_bf16 v[0:3], v[170:173], v[208:211], v[0:3]
	v_mfma_f32_16x16x32_bf16 v[0:3], v[174:177], v[212:215], v[0:3]
	s_setprio 0
	s_add_i32 s70, s70, 2
	s_add_u32 s44, s44, 0x100
	s_addc_u32 s45, s45, 0
	s_add_u32 s68, s68, 0x100
	s_addc_u32 s69, s69, 0
	s_cmp_gt_u32 s70, 13
	s_cbranch_scc0 .LBB0_184
	s_and_b64 vcc, exec, s[8:9]
	s_cbranch_vccz .LBB0_187
	s_barrier

.LBB0_263:
	s_add_u32 s84, s54, 0x100
	s_addc_u32 s85, s55, 0
	s_mov_b32 s86, -2
	ds_read_b128 v[152:155], v149
	ds_read_b128 v[156:159], v149 offset:1024
	ds_read_b128 v[160:163], v149 offset:2048
	ds_read_b128 v[164:167], v149 offset:3072
	ds_read_b128 v[168:171], v150
	ds_read_b128 v[172:175], v150 offset:1024
	ds_read_b128 v[176:179], v150 offset:2048
	ds_read_b128 v[184:187], v150 offset:3072
	s_add_u32 s54, s52, 0x100
	s_addc_u32 s55, s53, 0
	s_cmp_eq_u32 s86, 40
	s_cselect_b32 s59, s7, s55
	s_cselect_b32 s58, s6, s54
	s_cselect_b32 s57, s49, s85
	s_cselect_b32 s56, s48, s84
	v_lshl_add_u64 v[144:145], s[52:53], 0, v[136:137]
	s_add_i32 m0, s63, 0xc000
	ds_read_b128 v[188:191], v151
	ds_read_b128 v[192:195], v151 offset:1024
	ds_read_b128 v[196:199], v151 offset:2048
	ds_read_b128 v[200:203], v151 offset:3072
	ds_read_b128 v[204:207], v151 offset:4096
	ds_read_b128 v[208:211], v151 offset:5120
	ds_read_b128 v[212:215], v151 offset:6144
	ds_read_b128 v[216:219], v151 offset:7168
	global_load_lds_dwordx4 v[144:145], off
	v_lshl_add_u64 v[144:145], s[52:53], 0, v[138:139]
	s_add_i32 m0, s63, 0xe000
	s_nop 0
	global_load_lds_dwordx4 v[144:145], off
	s_waitcnt vmcnt(8)
	s_waitcnt lgkmcnt(0)
	s_barrier
	s_setprio 1
	s_waitcnt lgkmcnt(0)
	v_mfma_f32_16x16x32_bf16 v[124:127], v[152:155], v[188:191], 0
	v_mfma_f32_16x16x32_bf16 v[124:127], v[156:159], v[192:195], v[124:127]
	v_mfma_f32_16x16x32_bf16 v[120:123], v[160:163], v[188:191], 0
	v_mfma_f32_16x16x32_bf16 v[120:123], v[164:167], v[192:195], v[120:123]
	v_mfma_f32_16x16x32_bf16 v[116:119], v[152:155], v[196:199], 0
	v_mfma_f32_16x16x32_bf16 v[116:119], v[156:159], v[200:203], v[116:119]
	v_mfma_f32_16x16x32_bf16 v[108:111], v[160:163], v[196:199], 0
	v_mfma_f32_16x16x32_bf16 v[108:111], v[164:167], v[200:203], v[108:111]
	v_mfma_f32_16x16x32_bf16 v[100:103], v[152:155], v[204:207], 0
	v_mfma_f32_16x16x32_bf16 v[100:103], v[156:159], v[208:211], v[100:103]
	v_mfma_f32_16x16x32_bf16 v[92:95], v[160:163], v[204:207], 0
	v_mfma_f32_16x16x32_bf16 v[92:95], v[164:167], v[208:211], v[92:95]
	v_mfma_f32_16x16x32_bf16 v[84:87], v[152:155], v[212:215], 0
	v_mfma_f32_16x16x32_bf16 v[84:87], v[156:159], v[216:219], v[84:87]
	v_mfma_f32_16x16x32_bf16 v[76:79], v[160:163], v[212:215], 0
	v_mfma_f32_16x16x32_bf16 v[76:79], v[164:167], v[216:219], v[76:79]
	v_mfma_f32_16x16x32_bf16 v[112:115], v[168:171], v[188:191], 0
	v_mfma_f32_16x16x32_bf16 v[112:115], v[172:175], v[192:195], v[112:115]
	v_mfma_f32_16x16x32_bf16 v[104:107], v[176:179], v[188:191], 0
	v_mfma_f32_16x16x32_bf16 v[104:107], v[184:187], v[192:195], v[104:107]
	v_mfma_f32_16x16x32_bf16 v[96:99], v[168:171], v[196:199], 0
	v_mfma_f32_16x16x32_bf16 v[96:99], v[172:175], v[200:203], v[96:99]
	v_mfma_f32_16x16x32_bf16 v[88:91], v[176:179], v[196:199], 0
	v_mfma_f32_16x16x32_bf16 v[88:91], v[184:187], v[200:203], v[88:91]
	v_mfma_f32_16x16x32_bf16 v[80:83], v[168:171], v[204:207], 0
	v_mfma_f32_16x16x32_bf16 v[80:83], v[172:175], v[208:211], v[80:83]
	v_mfma_f32_16x16x32_bf16 v[72:75], v[176:179], v[204:207], 0
	v_mfma_f32_16x16x32_bf16 v[72:75], v[184:187], v[208:211], v[72:75]
	v_mfma_f32_16x16x32_bf16 v[68:71], v[168:171], v[212:215], 0
	v_mfma_f32_16x16x32_bf16 v[68:71], v[172:175], v[216:219], v[68:71]
	s_setprio 2
	s_barrier
	v_mfma_f32_16x16x32_bf16 v[64:67], v[176:179], v[212:215], 0
	v_mfma_f32_16x16x32_bf16 v[64:67], v[184:187], v[216:219], v[64:67]
	s_setprio 0
	s_add_i32 s18, s70, s62
	v_lshl_add_u64 v[144:145], s[56:57], 0, v[130:131]
	s_mov_b32 m0, s18
	ds_read_b128 v[188:191], v151 offset:16384
	ds_read_b128 v[192:195], v151 offset:17408
	ds_read_b128 v[196:199], v151 offset:18432
	ds_read_b128 v[200:203], v151 offset:19456
	ds_read_b128 v[204:207], v151 offset:20480
	ds_read_b128 v[208:211], v151 offset:21504
	ds_read_b128 v[212:215], v151 offset:22528
	ds_read_b128 v[216:219], v151 offset:23552
	global_load_lds_dwordx4 v[144:145], off
	s_add_i32 m0, s18, 0x2000
	s_add_u32 s52, s56, 0xb0000
	v_lshl_add_u64 v[220:221], s[56:57], 0, v[134:135]
	s_addc_u32 s53, s57, 0
	s_add_i32 s18, s71, s62
	global_load_lds_dwordx4 v[220:221], off
	v_lshl_add_u64 v[222:223], s[52:53], 0, v[130:131]
	s_mov_b32 m0, s18
	v_lshl_add_u64 v[224:225], s[58:59], 0, v[132:133]
	global_load_lds_dwordx4 v[222:223], off
	v_lshl_add_u64 v[222:223], s[52:53], 0, v[134:135]
	s_add_i32 m0, s18, 0x2000
	s_nop 0
	global_load_lds_dwordx4 v[222:223], off
	v_lshl_add_u64 v[222:223], s[58:59], 0, v[128:129]
	s_mov_b32 m0, s63
	s_nop 0
	global_load_lds_dwordx4 v[222:223], off
	s_mov_b32 m0, s64
	s_nop 0
	global_load_lds_dwordx4 v[224:225], off
	s_waitcnt vmcnt(8)
	s_waitcnt lgkmcnt(0)
	s_barrier
	s_setprio 1
	s_waitcnt lgkmcnt(0)
	v_mfma_f32_16x16x32_bf16 v[60:63], v[152:155], v[188:191], 0
	v_mfma_f32_16x16x32_bf16 v[60:63], v[156:159], v[192:195], v[60:63]
	v_mfma_f32_16x16x32_bf16 v[56:59], v[160:163], v[188:191], 0
	v_mfma_f32_16x16x32_bf16 v[56:59], v[164:167], v[192:195], v[56:59]
	v_mfma_f32_16x16x32_bf16 v[52:55], v[152:155], v[196:199], 0
	v_mfma_f32_16x16x32_bf16 v[52:55], v[156:159], v[200:203], v[52:55]
	v_mfma_f32_16x16x32_bf16 v[44:47], v[160:163], v[196:199], 0
	v_mfma_f32_16x16x32_bf16 v[44:47], v[164:167], v[200:203], v[44:47]
	v_mfma_f32_16x16x32_bf16 v[36:39], v[152:155], v[204:207], 0
	v_mfma_f32_16x16x32_bf16 v[36:39], v[156:159], v[208:211], v[36:39]
	v_mfma_f32_16x16x32_bf16 v[28:31], v[160:163], v[204:207], 0
	v_mfma_f32_16x16x32_bf16 v[28:31], v[164:167], v[208:211], v[28:31]
	v_mfma_f32_16x16x32_bf16 v[20:23], v[152:155], v[212:215], 0
	v_mfma_f32_16x16x32_bf16 v[20:23], v[156:159], v[216:219], v[20:23]
	v_mfma_f32_16x16x32_bf16 v[12:15], v[160:163], v[212:215], 0
	v_mfma_f32_16x16x32_bf16 v[12:15], v[164:167], v[216:219], v[12:15]
	v_mfma_f32_16x16x32_bf16 v[48:51], v[168:171], v[188:191], 0
	v_mfma_f32_16x16x32_bf16 v[48:51], v[172:175], v[192:195], v[48:51]
	v_mfma_f32_16x16x32_bf16 v[40:43], v[176:179], v[188:191], 0
	v_mfma_f32_16x16x32_bf16 v[40:43], v[184:187], v[192:195], v[40:43]
	v_mfma_f32_16x16x32_bf16 v[32:35], v[168:171], v[196:199], 0
	v_mfma_f32_16x16x32_bf16 v[32:35], v[172:175], v[200:203], v[32:35]
	v_mfma_f32_16x16x32_bf16 v[24:27], v[176:179], v[196:199], 0
	v_mfma_f32_16x16x32_bf16 v[24:27], v[184:187], v[200:203], v[24:27]
	v_mfma_f32_16x16x32_bf16 v[16:19], v[168:171], v[204:207], 0
	v_mfma_f32_16x16x32_bf16 v[16:19], v[172:175], v[208:211], v[16:19]
	v_mfma_f32_16x16x32_bf16 v[8:11], v[176:179], v[204:207], 0
	v_mfma_f32_16x16x32_bf16 v[8:11], v[184:187], v[208:211], v[8:11]
	v_mfma_f32_16x16x32_bf16 v[4:7], v[168:171], v[212:215], 0
	v_mfma_f32_16x16x32_bf16 v[4:7], v[172:175], v[216:219], v[4:7]
	s_setprio 2
	s_barrier
	v_mfma_f32_16x16x32_bf16 v[0:3], v[176:179], v[212:215], 0
	v_mfma_f32_16x16x32_bf16 v[0:3], v[184:187], v[216:219], v[0:3]
	s_setprio 0
	s_branch .Lmid_gemm1
.LBB0_264:
	ds_read_b128 v[152:155], v149
	ds_read_b128 v[156:159], v149 offset:1024
	ds_read_b128 v[160:163], v149 offset:2048
	ds_read_b128 v[164:167], v149 offset:3072
	ds_read_b128 v[168:171], v150
	ds_read_b128 v[172:175], v150 offset:1024
	ds_read_b128 v[176:179], v150 offset:2048
	ds_read_b128 v[184:187], v150 offset:3072
	s_add_u32 s54, s52, 0x100
	s_addc_u32 s55, s53, 0
	s_cmp_eq_u32 s86, 40
	s_cselect_b32 s59, s7, s55
	s_cselect_b32 s58, s6, s54
	s_cselect_b32 s57, s49, s85
	s_cselect_b32 s56, s48, s84
	v_lshl_add_u64 v[144:145], s[52:53], 0, v[136:137]
	s_add_i32 m0, s63, 0xc000
	ds_read_b128 v[188:191], v151
	ds_read_b128 v[192:195], v151 offset:1024
	ds_read_b128 v[196:199], v151 offset:2048
	ds_read_b128 v[200:203], v151 offset:3072
	ds_read_b128 v[204:207], v151 offset:4096
	ds_read_b128 v[208:211], v151 offset:5120
	ds_read_b128 v[212:215], v151 offset:6144
	ds_read_b128 v[216:219], v151 offset:7168
	global_load_lds_dwordx4 v[144:145], off
	v_lshl_add_u64 v[144:145], s[52:53], 0, v[138:139]
	s_add_i32 m0, s63, 0xe000
	s_nop 0
	global_load_lds_dwordx4 v[144:145], off
	s_waitcnt vmcnt(8)
	s_waitcnt lgkmcnt(0)
	s_barrier
	s_setprio 1
	s_waitcnt lgkmcnt(0)
	v_mfma_f32_16x16x32_bf16 v[124:127], v[152:155], v[188:191], v[124:127]
	v_mfma_f32_16x16x32_bf16 v[124:127], v[156:159], v[192:195], v[124:127]
	v_mfma_f32_16x16x32_bf16 v[120:123], v[160:163], v[188:191], v[120:123]
	v_mfma_f32_16x16x32_bf16 v[120:123], v[164:167], v[192:195], v[120:123]
	v_mfma_f32_16x16x32_bf16 v[116:119], v[152:155], v[196:199], v[116:119]
	v_mfma_f32_16x16x32_bf16 v[116:119], v[156:159], v[200:203], v[116:119]
	v_mfma_f32_16x16x32_bf16 v[108:111], v[160:163], v[196:199], v[108:111]
	v_mfma_f32_16x16x32_bf16 v[108:111], v[164:167], v[200:203], v[108:111]
	v_mfma_f32_16x16x32_bf16 v[100:103], v[152:155], v[204:207], v[100:103]
	v_mfma_f32_16x16x32_bf16 v[100:103], v[156:159], v[208:211], v[100:103]
	v_mfma_f32_16x16x32_bf16 v[92:95], v[160:163], v[204:207], v[92:95]
	v_mfma_f32_16x16x32_bf16 v[92:95], v[164:167], v[208:211], v[92:95]
	v_mfma_f32_16x16x32_bf16 v[84:87], v[152:155], v[212:215], v[84:87]
	v_mfma_f32_16x16x32_bf16 v[84:87], v[156:159], v[216:219], v[84:87]
	v_mfma_f32_16x16x32_bf16 v[76:79], v[160:163], v[212:215], v[76:79]
	v_mfma_f32_16x16x32_bf16 v[76:79], v[164:167], v[216:219], v[76:79]
	v_mfma_f32_16x16x32_bf16 v[112:115], v[168:171], v[188:191], v[112:115]
	v_mfma_f32_16x16x32_bf16 v[112:115], v[172:175], v[192:195], v[112:115]
	v_mfma_f32_16x16x32_bf16 v[104:107], v[176:179], v[188:191], v[104:107]
	v_mfma_f32_16x16x32_bf16 v[104:107], v[184:187], v[192:195], v[104:107]
	v_mfma_f32_16x16x32_bf16 v[96:99], v[168:171], v[196:199], v[96:99]
	v_mfma_f32_16x16x32_bf16 v[96:99], v[172:175], v[200:203], v[96:99]
	v_mfma_f32_16x16x32_bf16 v[88:91], v[176:179], v[196:199], v[88:91]
	v_mfma_f32_16x16x32_bf16 v[88:91], v[184:187], v[200:203], v[88:91]
	v_mfma_f32_16x16x32_bf16 v[80:83], v[168:171], v[204:207], v[80:83]
	v_mfma_f32_16x16x32_bf16 v[80:83], v[172:175], v[208:211], v[80:83]
	v_mfma_f32_16x16x32_bf16 v[72:75], v[176:179], v[204:207], v[72:75]
	v_mfma_f32_16x16x32_bf16 v[72:75], v[184:187], v[208:211], v[72:75]
	v_mfma_f32_16x16x32_bf16 v[68:71], v[168:171], v[212:215], v[68:71]
	v_mfma_f32_16x16x32_bf16 v[68:71], v[172:175], v[216:219], v[68:71]
	s_setprio 2
	s_barrier
	v_mfma_f32_16x16x32_bf16 v[64:67], v[176:179], v[212:215], v[64:67]
	v_mfma_f32_16x16x32_bf16 v[64:67], v[184:187], v[216:219], v[64:67]
	s_setprio 0
	s_add_i32 s18, s70, s62
	v_lshl_add_u64 v[144:145], s[56:57], 0, v[130:131]
	s_mov_b32 m0, s18
	ds_read_b128 v[188:191], v151 offset:16384
	ds_read_b128 v[192:195], v151 offset:17408
	ds_read_b128 v[196:199], v151 offset:18432
	ds_read_b128 v[200:203], v151 offset:19456
	ds_read_b128 v[204:207], v151 offset:20480
	ds_read_b128 v[208:211], v151 offset:21504
	ds_read_b128 v[212:215], v151 offset:22528
	ds_read_b128 v[216:219], v151 offset:23552
	global_load_lds_dwordx4 v[144:145], off
	s_add_i32 m0, s18, 0x2000
	s_add_u32 s52, s56, 0xb0000
	v_lshl_add_u64 v[220:221], s[56:57], 0, v[134:135]
	s_addc_u32 s53, s57, 0
	s_add_i32 s18, s71, s62
	global_load_lds_dwordx4 v[220:221], off
	v_lshl_add_u64 v[222:223], s[52:53], 0, v[130:131]
	s_mov_b32 m0, s18
	v_lshl_add_u64 v[224:225], s[58:59], 0, v[132:133]
	global_load_lds_dwordx4 v[222:223], off
	v_lshl_add_u64 v[222:223], s[52:53], 0, v[134:135]
	s_add_i32 m0, s18, 0x2000
	s_nop 0
	global_load_lds_dwordx4 v[222:223], off
	v_lshl_add_u64 v[222:223], s[58:59], 0, v[128:129]
	s_mov_b32 m0, s63
	s_nop 0
	global_load_lds_dwordx4 v[222:223], off
	s_mov_b32 m0, s64
	s_nop 0
	global_load_lds_dwordx4 v[224:225], off
	s_waitcnt vmcnt(8)
	s_waitcnt lgkmcnt(0)
	s_barrier
	s_setprio 1
	s_waitcnt lgkmcnt(0)
	v_mfma_f32_16x16x32_bf16 v[60:63], v[152:155], v[188:191], v[60:63]
	v_mfma_f32_16x16x32_bf16 v[60:63], v[156:159], v[192:195], v[60:63]
	v_mfma_f32_16x16x32_bf16 v[56:59], v[160:163], v[188:191], v[56:59]
	v_mfma_f32_16x16x32_bf16 v[56:59], v[164:167], v[192:195], v[56:59]
	v_mfma_f32_16x16x32_bf16 v[52:55], v[152:155], v[196:199], v[52:55]
	v_mfma_f32_16x16x32_bf16 v[52:55], v[156:159], v[200:203], v[52:55]
	v_mfma_f32_16x16x32_bf16 v[44:47], v[160:163], v[196:199], v[44:47]
	v_mfma_f32_16x16x32_bf16 v[44:47], v[164:167], v[200:203], v[44:47]
	v_mfma_f32_16x16x32_bf16 v[36:39], v[152:155], v[204:207], v[36:39]
	v_mfma_f32_16x16x32_bf16 v[36:39], v[156:159], v[208:211], v[36:39]
	v_mfma_f32_16x16x32_bf16 v[28:31], v[160:163], v[204:207], v[28:31]
	v_mfma_f32_16x16x32_bf16 v[28:31], v[164:167], v[208:211], v[28:31]
	v_mfma_f32_16x16x32_bf16 v[20:23], v[152:155], v[212:215], v[20:23]
	v_mfma_f32_16x16x32_bf16 v[20:23], v[156:159], v[216:219], v[20:23]
	v_mfma_f32_16x16x32_bf16 v[12:15], v[160:163], v[212:215], v[12:15]
	v_mfma_f32_16x16x32_bf16 v[12:15], v[164:167], v[216:219], v[12:15]
	v_mfma_f32_16x16x32_bf16 v[48:51], v[168:171], v[188:191], v[48:51]
	v_mfma_f32_16x16x32_bf16 v[48:51], v[172:175], v[192:195], v[48:51]
	v_mfma_f32_16x16x32_bf16 v[40:43], v[176:179], v[188:191], v[40:43]
	v_mfma_f32_16x16x32_bf16 v[40:43], v[184:187], v[192:195], v[40:43]
	v_mfma_f32_16x16x32_bf16 v[32:35], v[168:171], v[196:199], v[32:35]
	v_mfma_f32_16x16x32_bf16 v[32:35], v[172:175], v[200:203], v[32:35]
	v_mfma_f32_16x16x32_bf16 v[24:27], v[176:179], v[196:199], v[24:27]
	v_mfma_f32_16x16x32_bf16 v[24:27], v[184:187], v[200:203], v[24:27]
	v_mfma_f32_16x16x32_bf16 v[16:19], v[168:171], v[204:207], v[16:19]
	v_mfma_f32_16x16x32_bf16 v[16:19], v[172:175], v[208:211], v[16:19]
	v_mfma_f32_16x16x32_bf16 v[8:11], v[176:179], v[204:207], v[8:11]
	v_mfma_f32_16x16x32_bf16 v[8:11], v[184:187], v[208:211], v[8:11]
	v_mfma_f32_16x16x32_bf16 v[4:7], v[168:171], v[212:215], v[4:7]
	v_mfma_f32_16x16x32_bf16 v[4:7], v[172:175], v[216:219], v[4:7]
	s_setprio 2
	s_barrier
	v_mfma_f32_16x16x32_bf16 v[0:3], v[176:179], v[212:215], v[0:3]
	v_mfma_f32_16x16x32_bf16 v[0:3], v[184:187], v[216:219], v[0:3]
	s_setprio 0
.Lmid_gemm1:
	s_add_i32 s18, 0, 0x18000
	s_add_i32 s19, 0, 0x1c000
	v_add_u32_e32 v164, s18, v147
	v_add_u32_e32 v181, s19, v147
	ds_read_b128 v[152:155], v164
	ds_read_b128 v[156:159], v164 offset:1024
	ds_read_b128 v[160:163], v164 offset:2048
	ds_read_b128 v[164:167], v164 offset:3072
	ds_read_b128 v[168:171], v181
	ds_read_b128 v[172:175], v181 offset:1024
	ds_read_b128 v[176:179], v181 offset:2048
	ds_read_b128 v[184:187], v181 offset:3072
	s_add_u32 s52, s58, 0xb0000
	s_addc_u32 s53, s59, 0
	s_mov_b32 m0, s65
	v_lshl_add_u64 v[226:227], s[52:53], 0, v[128:129]
	ds_read_b128 v[188:191], v151 offset:32768
	ds_read_b128 v[192:195], v151 offset:33792
	ds_read_b128 v[196:199], v151 offset:34816
	ds_read_b128 v[200:203], v151 offset:35840
	ds_read_b128 v[204:207], v151 offset:36864
	ds_read_b128 v[208:211], v151 offset:37888
	ds_read_b128 v[212:215], v151 offset:38912
	ds_read_b128 v[216:219], v151 offset:39936
	global_load_lds_dwordx4 v[226:227], off
	v_lshl_add_u64 v[226:227], s[52:53], 0, v[132:133]
	s_mov_b32 m0, s66
	s_nop 0
	global_load_lds_dwordx4 v[226:227], off
	s_waitcnt vmcnt(8)
	s_waitcnt lgkmcnt(0)
	s_barrier
	s_setprio 1
	s_waitcnt lgkmcnt(0)
	v_mfma_f32_16x16x32_bf16 v[124:127], v[152:155], v[188:191], v[124:127]
	v_mfma_f32_16x16x32_bf16 v[124:127], v[156:159], v[192:195], v[124:127]
	v_mfma_f32_16x16x32_bf16 v[120:123], v[160:163], v[188:191], v[120:123]
	v_mfma_f32_16x16x32_bf16 v[120:123], v[164:167], v[192:195], v[120:123]
	v_mfma_f32_16x16x32_bf16 v[116:119], v[152:155], v[196:199], v[116:119]
	v_mfma_f32_16x16x32_bf16 v[116:119], v[156:159], v[200:203], v[116:119]
	v_mfma_f32_16x16x32_bf16 v[108:111], v[160:163], v[196:199], v[108:111]
	v_mfma_f32_16x16x32_bf16 v[108:111], v[164:167], v[200:203], v[108:111]
	v_mfma_f32_16x16x32_bf16 v[100:103], v[152:155], v[204:207], v[100:103]
	v_mfma_f32_16x16x32_bf16 v[100:103], v[156:159], v[208:211], v[100:103]
	v_mfma_f32_16x16x32_bf16 v[92:95], v[160:163], v[204:207], v[92:95]
	v_mfma_f32_16x16x32_bf16 v[92:95], v[164:167], v[208:211], v[92:95]
	v_mfma_f32_16x16x32_bf16 v[84:87], v[152:155], v[212:215], v[84:87]
	v_mfma_f32_16x16x32_bf16 v[84:87], v[156:159], v[216:219], v[84:87]
	v_mfma_f32_16x16x32_bf16 v[76:79], v[160:163], v[212:215], v[76:79]
	v_mfma_f32_16x16x32_bf16 v[76:79], v[164:167], v[216:219], v[76:79]
	v_mfma_f32_16x16x32_bf16 v[112:115], v[168:171], v[188:191], v[112:115]
	v_mfma_f32_16x16x32_bf16 v[112:115], v[172:175], v[192:195], v[112:115]
	v_mfma_f32_16x16x32_bf16 v[104:107], v[176:179], v[188:191], v[104:107]
	v_mfma_f32_16x16x32_bf16 v[104:107], v[184:187], v[192:195], v[104:107]
	v_mfma_f32_16x16x32_bf16 v[96:99], v[168:171], v[196:199], v[96:99]
	v_mfma_f32_16x16x32_bf16 v[96:99], v[172:175], v[200:203], v[96:99]
	v_mfma_f32_16x16x32_bf16 v[88:91], v[176:179], v[196:199], v[88:91]
	v_mfma_f32_16x16x32_bf16 v[88:91], v[184:187], v[200:203], v[88:91]
	v_mfma_f32_16x16x32_bf16 v[80:83], v[168:171], v[204:207], v[80:83]
	v_mfma_f32_16x16x32_bf16 v[80:83], v[172:175], v[208:211], v[80:83]
	v_mfma_f32_16x16x32_bf16 v[72:75], v[176:179], v[204:207], v[72:75]
	v_mfma_f32_16x16x32_bf16 v[72:75], v[184:187], v[208:211], v[72:75]
	v_mfma_f32_16x16x32_bf16 v[68:71], v[168:171], v[212:215], v[68:71]
	v_mfma_f32_16x16x32_bf16 v[68:71], v[172:175], v[216:219], v[68:71]
	s_setprio 2
	s_barrier
	v_mfma_f32_16x16x32_bf16 v[64:67], v[176:179], v[212:215], v[64:67]
	v_mfma_f32_16x16x32_bf16 v[64:67], v[184:187], v[216:219], v[64:67]
	s_setprio 0
	s_add_i32 s18, s18, s62
	v_lshl_add_u64 v[144:145], v[144:145], 0, s[8:9]
	s_mov_b32 m0, s18
	ds_read_b128 v[188:191], v151 offset:49152
	ds_read_b128 v[192:195], v151 offset:50176
	ds_read_b128 v[196:199], v151 offset:51200
	ds_read_b128 v[200:203], v151 offset:52224
	ds_read_b128 v[204:207], v151 offset:53248
	ds_read_b128 v[208:211], v151 offset:54272
	ds_read_b128 v[212:215], v151 offset:55296
	ds_read_b128 v[216:219], v151 offset:56320
	global_load_lds_dwordx4 v[144:145], off
	s_add_i32 m0, s18, 0x2000
	s_add_u32 s52, s56, 0xb0080
	v_lshl_add_u64 v[144:145], v[220:221], 0, s[8:9]
	s_addc_u32 s53, s57, 0
	s_add_i32 s18, s19, s62
	global_load_lds_dwordx4 v[144:145], off
	v_lshl_add_u64 v[144:145], s[52:53], 0, v[130:131]
	s_mov_b32 m0, s18
	s_nop 0
	global_load_lds_dwordx4 v[144:145], off
	v_lshl_add_u64 v[144:145], s[52:53], 0, v[134:135]
	s_add_i32 m0, s18, 0x2000
	s_nop 0
	global_load_lds_dwordx4 v[144:145], off
	v_lshl_add_u64 v[144:145], v[222:223], 0, s[8:9]
	s_mov_b32 m0, s68
	s_nop 0
	global_load_lds_dwordx4 v[144:145], off
	v_lshl_add_u64 v[144:145], v[224:225], 0, s[8:9]
	s_mov_b32 m0, s69
	s_nop 0
	global_load_lds_dwordx4 v[144:145], off
	s_waitcnt vmcnt(8)
	s_waitcnt lgkmcnt(0)
	s_barrier
	s_setprio 1
	s_waitcnt lgkmcnt(0)
	v_mfma_f32_16x16x32_bf16 v[60:63], v[152:155], v[188:191], v[60:63]
	v_mfma_f32_16x16x32_bf16 v[60:63], v[156:159], v[192:195], v[60:63]
	v_mfma_f32_16x16x32_bf16 v[56:59], v[160:163], v[188:191], v[56:59]
	v_mfma_f32_16x16x32_bf16 v[56:59], v[164:167], v[192:195], v[56:59]
	v_mfma_f32_16x16x32_bf16 v[52:55], v[152:155], v[196:199], v[52:55]
	v_mfma_f32_16x16x32_bf16 v[52:55], v[156:159], v[200:203], v[52:55]
	v_mfma_f32_16x16x32_bf16 v[44:47], v[160:163], v[196:199], v[44:47]
	v_mfma_f32_16x16x32_bf16 v[44:47], v[164:167], v[200:203], v[44:47]
	v_mfma_f32_16x16x32_bf16 v[36:39], v[152:155], v[204:207], v[36:39]
	v_mfma_f32_16x16x32_bf16 v[36:39], v[156:159], v[208:211], v[36:39]
	v_mfma_f32_16x16x32_bf16 v[28:31], v[160:163], v[204:207], v[28:31]
	v_mfma_f32_16x16x32_bf16 v[28:31], v[164:167], v[208:211], v[28:31]
	v_mfma_f32_16x16x32_bf16 v[20:23], v[152:155], v[212:215], v[20:23]
	v_mfma_f32_16x16x32_bf16 v[20:23], v[156:159], v[216:219], v[20:23]
	v_mfma_f32_16x16x32_bf16 v[12:15], v[160:163], v[212:215], v[12:15]
	v_mfma_f32_16x16x32_bf16 v[12:15], v[164:167], v[216:219], v[12:15]
	v_mfma_f32_16x16x32_bf16 v[48:51], v[168:171], v[188:191], v[48:51]
	v_mfma_f32_16x16x32_bf16 v[48:51], v[172:175], v[192:195], v[48:51]
	v_mfma_f32_16x16x32_bf16 v[40:43], v[176:179], v[188:191], v[40:43]
	v_mfma_f32_16x16x32_bf16 v[40:43], v[184:187], v[192:195], v[40:43]
	v_mfma_f32_16x16x32_bf16 v[32:35], v[168:171], v[196:199], v[32:35]
	v_mfma_f32_16x16x32_bf16 v[32:35], v[172:175], v[200:203], v[32:35]
	v_mfma_f32_16x16x32_bf16 v[24:27], v[176:179], v[196:199], v[24:27]
	v_mfma_f32_16x16x32_bf16 v[24:27], v[184:187], v[200:203], v[24:27]
	v_mfma_f32_16x16x32_bf16 v[16:19], v[168:171], v[204:207], v[16:19]
	v_mfma_f32_16x16x32_bf16 v[16:19], v[172:175], v[208:211], v[16:19]
	v_mfma_f32_16x16x32_bf16 v[8:11], v[176:179], v[204:207], v[8:11]
	v_mfma_f32_16x16x32_bf16 v[8:11], v[184:187], v[208:211], v[8:11]
	v_mfma_f32_16x16x32_bf16 v[4:7], v[168:171], v[212:215], v[4:7]
	v_mfma_f32_16x16x32_bf16 v[4:7], v[172:175], v[216:219], v[4:7]
	s_setprio 2
	s_barrier
	v_mfma_f32_16x16x32_bf16 v[0:3], v[176:179], v[212:215], v[0:3]
	v_mfma_f32_16x16x32_bf16 v[0:3], v[184:187], v[216:219], v[0:3]
	s_setprio 0
	s_add_i32 s86, s86, 2
	s_add_u32 s84, s84, 0x100
	s_addc_u32 s85, s85, 0
	s_cmp_gt_u32 s86, 41
	s_mov_b64 s[52:53], s[54:55]
	s_cbranch_scc0 .LBB0_264
	s_and_b64 vcc, exec, s[10:11]
	s_cbranch_vccz .LBB0_267
	s_barrier

.LBB0_386:
	s_ashr_i32 s49, s48, 31
	s_lshl_b64 s[52:53], s[48:49], 19
	s_add_u32 s52, s80, s52
	s_addc_u32 s53, s81, s53
	s_and_b64 s[54:55], s[4:5], exec
	s_cselect_b32 s49, s53, s59
	s_cselect_b32 s82, s52, s58
	s_ashr_i32 s47, s46, 31
	s_lshl_b64 s[54:55], s[46:47], 19
	s_add_u32 s54, s64, s54
	s_addc_u32 s55, s65, s55
	s_and_b64 s[62:63], s[4:5], exec
	s_cselect_b32 s47, s55, s61
	s_cselect_b32 s83, s54, s60
	s_add_u32 s58, s58, 0x40080
	s_addc_u32 s59, s59, 0
	s_add_u32 s84, s60, 0x100
	s_addc_u32 s85, s61, 0
	s_mov_b32 s86, -2
	ds_read_b128 v[152:155], v148
	ds_read_b128 v[156:159], v148 offset:1024
	ds_read_b128 v[160:163], v148 offset:2048
	ds_read_b128 v[164:167], v148 offset:3072
	ds_read_b128 v[168:171], v149
	ds_read_b128 v[172:175], v149 offset:1024
	ds_read_b128 v[176:179], v149 offset:2048
	ds_read_b128 v[184:187], v149 offset:3072
	s_add_u32 s18, s58, 0xfffc0080
	s_addc_u32 s19, s59, -1
	s_cmp_eq_u32 s86, 12
	s_cselect_b32 s63, s49, s19
	s_cselect_b32 s62, s82, s18
	s_cselect_b32 s61, s47, s85
	s_cselect_b32 s60, s83, s84
	v_lshl_add_u64 v[220:221], s[58:59], 0, v[138:139]
	s_add_i32 m0, s68, 0xc000
	ds_read_b128 v[188:191], v150
	ds_read_b128 v[192:195], v150 offset:1024
	ds_read_b128 v[196:199], v150 offset:2048
	ds_read_b128 v[200:203], v150 offset:3072
	ds_read_b128 v[204:207], v150 offset:4096
	ds_read_b128 v[208:211], v150 offset:5120
	ds_read_b128 v[212:215], v150 offset:6144
	ds_read_b128 v[216:219], v150 offset:7168
	global_load_lds_dwordx4 v[220:221], off
	v_lshl_add_u64 v[220:221], s[58:59], 0, v[140:141]
	s_add_i32 m0, s68, 0xe000
	s_nop 0
	global_load_lds_dwordx4 v[220:221], off
	s_waitcnt vmcnt(8)
	s_waitcnt lgkmcnt(0)
	s_barrier
	s_setprio 1
	s_waitcnt lgkmcnt(0)
	v_mfma_f32_16x16x32_bf16 v[124:127], v[152:155], v[188:191], 0
	v_mfma_f32_16x16x32_bf16 v[124:127], v[156:159], v[192:195], v[124:127]
	v_mfma_f32_16x16x32_bf16 v[120:123], v[160:163], v[188:191], 0
	v_mfma_f32_16x16x32_bf16 v[120:123], v[164:167], v[192:195], v[120:123]
	v_mfma_f32_16x16x32_bf16 v[116:119], v[152:155], v[196:199], 0
	v_mfma_f32_16x16x32_bf16 v[116:119], v[156:159], v[200:203], v[116:119]
	v_mfma_f32_16x16x32_bf16 v[112:115], v[160:163], v[196:199], 0
	v_mfma_f32_16x16x32_bf16 v[112:115], v[164:167], v[200:203], v[112:115]
	v_mfma_f32_16x16x32_bf16 v[108:111], v[152:155], v[204:207], 0
	v_mfma_f32_16x16x32_bf16 v[108:111], v[156:159], v[208:211], v[108:111]
	v_mfma_f32_16x16x32_bf16 v[104:107], v[160:163], v[204:207], 0
	v_mfma_f32_16x16x32_bf16 v[104:107], v[164:167], v[208:211], v[104:107]
	v_mfma_f32_16x16x32_bf16 v[100:103], v[152:155], v[212:215], 0
	v_mfma_f32_16x16x32_bf16 v[100:103], v[156:159], v[216:219], v[100:103]
	v_mfma_f32_16x16x32_bf16 v[96:99], v[160:163], v[212:215], 0
	v_mfma_f32_16x16x32_bf16 v[96:99], v[164:167], v[216:219], v[96:99]
	v_mfma_f32_16x16x32_bf16 v[68:71], v[168:171], v[188:191], 0
	v_mfma_f32_16x16x32_bf16 v[68:71], v[172:175], v[192:195], v[68:71]
	v_mfma_f32_16x16x32_bf16 v[64:67], v[176:179], v[188:191], 0
	v_mfma_f32_16x16x32_bf16 v[64:67], v[184:187], v[192:195], v[64:67]
	v_mfma_f32_16x16x32_bf16 v[52:55], v[168:171], v[196:199], 0
	v_mfma_f32_16x16x32_bf16 v[52:55], v[172:175], v[200:203], v[52:55]
	v_mfma_f32_16x16x32_bf16 v[48:51], v[176:179], v[196:199], 0
	v_mfma_f32_16x16x32_bf16 v[48:51], v[184:187], v[200:203], v[48:51]
	v_mfma_f32_16x16x32_bf16 v[44:47], v[168:171], v[204:207], 0
	v_mfma_f32_16x16x32_bf16 v[44:47], v[172:175], v[208:211], v[44:47]
	v_mfma_f32_16x16x32_bf16 v[40:43], v[176:179], v[204:207], 0
	v_mfma_f32_16x16x32_bf16 v[40:43], v[184:187], v[208:211], v[40:43]
	v_mfma_f32_16x16x32_bf16 v[36:39], v[168:171], v[212:215], 0
	v_mfma_f32_16x16x32_bf16 v[36:39], v[172:175], v[216:219], v[36:39]
	s_setprio 2
	s_barrier
	v_mfma_f32_16x16x32_bf16 v[32:35], v[176:179], v[212:215], 0
	v_mfma_f32_16x16x32_bf16 v[32:35], v[184:187], v[216:219], v[32:35]
	s_setprio 0
	s_add_i32 s18, s76, s66
	v_lshl_add_u64 v[220:221], s[60:61], 0, v[132:133]
	s_mov_b32 m0, s18
	ds_read_b128 v[188:191], v150 offset:16384
	ds_read_b128 v[192:195], v150 offset:17408
	ds_read_b128 v[196:199], v150 offset:18432
	ds_read_b128 v[200:203], v150 offset:19456
	ds_read_b128 v[204:207], v150 offset:20480
	ds_read_b128 v[208:211], v150 offset:21504
	ds_read_b128 v[212:215], v150 offset:22528
	ds_read_b128 v[216:219], v150 offset:23552
	global_load_lds_dwordx4 v[220:221], off
	s_add_i32 m0, s18, 0x2000
	s_add_u32 s88, s60, 0x40000
	v_lshl_add_u64 v[222:223], s[60:61], 0, v[128:129]
	s_addc_u32 s89, s61, 0
	s_add_i32 s18, s77, s66
	global_load_lds_dwordx4 v[222:223], off
	v_lshl_add_u64 v[224:225], s[88:89], 0, v[132:133]
	s_mov_b32 m0, s18
	v_lshl_add_u64 v[226:227], s[62:63], 0, v[130:131]
	global_load_lds_dwordx4 v[224:225], off
	v_lshl_add_u64 v[224:225], s[88:89], 0, v[128:129]
	s_add_i32 m0, s18, 0x2000
	s_nop 0
	global_load_lds_dwordx4 v[224:225], off
	v_lshl_add_u64 v[224:225], s[62:63], 0, v[134:135]
	s_mov_b32 m0, s68
	s_nop 0
	global_load_lds_dwordx4 v[224:225], off
	s_mov_b32 m0, s69
	s_nop 0
	global_load_lds_dwordx4 v[226:227], off
	s_waitcnt vmcnt(8)
	s_waitcnt lgkmcnt(0)
	s_barrier
	s_setprio 1
	s_waitcnt lgkmcnt(0)
	v_mfma_f32_16x16x32_bf16 v[92:95], v[152:155], v[188:191], 0
	v_mfma_f32_16x16x32_bf16 v[92:95], v[156:159], v[192:195], v[92:95]
	v_mfma_f32_16x16x32_bf16 v[88:91], v[160:163], v[188:191], 0
	v_mfma_f32_16x16x32_bf16 v[88:91], v[164:167], v[192:195], v[88:91]
	v_mfma_f32_16x16x32_bf16 v[84:87], v[152:155], v[196:199], 0
	v_mfma_f32_16x16x32_bf16 v[84:87], v[156:159], v[200:203], v[84:87]
	v_mfma_f32_16x16x32_bf16 v[80:83], v[160:163], v[196:199], 0
	v_mfma_f32_16x16x32_bf16 v[80:83], v[164:167], v[200:203], v[80:83]
	v_mfma_f32_16x16x32_bf16 v[76:79], v[152:155], v[204:207], 0
	v_mfma_f32_16x16x32_bf16 v[76:79], v[156:159], v[208:211], v[76:79]
	v_mfma_f32_16x16x32_bf16 v[72:75], v[160:163], v[204:207], 0
	v_mfma_f32_16x16x32_bf16 v[72:75], v[164:167], v[208:211], v[72:75]
	v_mfma_f32_16x16x32_bf16 v[60:63], v[152:155], v[212:215], 0
	v_mfma_f32_16x16x32_bf16 v[60:63], v[156:159], v[216:219], v[60:63]
	v_mfma_f32_16x16x32_bf16 v[56:59], v[160:163], v[212:215], 0
	v_mfma_f32_16x16x32_bf16 v[56:59], v[164:167], v[216:219], v[56:59]
	v_mfma_f32_16x16x32_bf16 v[28:31], v[168:171], v[188:191], 0
	v_mfma_f32_16x16x32_bf16 v[28:31], v[172:175], v[192:195], v[28:31]
	v_mfma_f32_16x16x32_bf16 v[24:27], v[176:179], v[188:191], 0
	v_mfma_f32_16x16x32_bf16 v[24:27], v[184:187], v[192:195], v[24:27]
	v_mfma_f32_16x16x32_bf16 v[20:23], v[168:171], v[196:199], 0
	v_mfma_f32_16x16x32_bf16 v[20:23], v[172:175], v[200:203], v[20:23]
	v_mfma_f32_16x16x32_bf16 v[16:19], v[176:179], v[196:199], 0
	v_mfma_f32_16x16x32_bf16 v[16:19], v[184:187], v[200:203], v[16:19]
	v_mfma_f32_16x16x32_bf16 v[12:15], v[168:171], v[204:207], 0
	v_mfma_f32_16x16x32_bf16 v[12:15], v[172:175], v[208:211], v[12:15]
	v_mfma_f32_16x16x32_bf16 v[8:11], v[176:179], v[204:207], 0
	v_mfma_f32_16x16x32_bf16 v[8:11], v[184:187], v[208:211], v[8:11]
	v_mfma_f32_16x16x32_bf16 v[4:7], v[168:171], v[212:215], 0
	v_mfma_f32_16x16x32_bf16 v[4:7], v[172:175], v[216:219], v[4:7]
	s_setprio 2
	s_barrier
	v_mfma_f32_16x16x32_bf16 v[0:3], v[176:179], v[212:215], 0
	v_mfma_f32_16x16x32_bf16 v[0:3], v[184:187], v[216:219], v[0:3]
	s_setprio 0
	s_branch .Lmid_gemm2
.LBB0_387:
	ds_read_b128 v[152:155], v148
	ds_read_b128 v[156:159], v148 offset:1024
	ds_read_b128 v[160:163], v148 offset:2048
	ds_read_b128 v[164:167], v148 offset:3072
	ds_read_b128 v[168:171], v149
	ds_read_b128 v[172:175], v149 offset:1024
	ds_read_b128 v[176:179], v149 offset:2048
	ds_read_b128 v[184:187], v149 offset:3072
	s_add_u32 s18, s58, 0xfffc0080
	s_addc_u32 s19, s59, -1
	s_cmp_eq_u32 s86, 12
	s_cselect_b32 s63, s49, s19
	s_cselect_b32 s62, s82, s18
	s_cselect_b32 s61, s47, s85
	s_cselect_b32 s60, s83, s84
	v_lshl_add_u64 v[220:221], s[58:59], 0, v[138:139]
	s_add_i32 m0, s68, 0xc000
	ds_read_b128 v[188:191], v150
	ds_read_b128 v[192:195], v150 offset:1024
	ds_read_b128 v[196:199], v150 offset:2048
	ds_read_b128 v[200:203], v150 offset:3072
	ds_read_b128 v[204:207], v150 offset:4096
	ds_read_b128 v[208:211], v150 offset:5120
	ds_read_b128 v[212:215], v150 offset:6144
	ds_read_b128 v[216:219], v150 offset:7168
	global_load_lds_dwordx4 v[220:221], off
	v_lshl_add_u64 v[220:221], s[58:59], 0, v[140:141]
	s_add_i32 m0, s68, 0xe000
	s_nop 0
	global_load_lds_dwordx4 v[220:221], off
	s_waitcnt vmcnt(8)
	s_waitcnt lgkmcnt(0)
	s_barrier
	s_setprio 1
	s_waitcnt lgkmcnt(0)
	v_mfma_f32_16x16x32_bf16 v[124:127], v[152:155], v[188:191], v[124:127]
	v_mfma_f32_16x16x32_bf16 v[124:127], v[156:159], v[192:195], v[124:127]
	v_mfma_f32_16x16x32_bf16 v[120:123], v[160:163], v[188:191], v[120:123]
	v_mfma_f32_16x16x32_bf16 v[120:123], v[164:167], v[192:195], v[120:123]
	v_mfma_f32_16x16x32_bf16 v[116:119], v[152:155], v[196:199], v[116:119]
	v_mfma_f32_16x16x32_bf16 v[116:119], v[156:159], v[200:203], v[116:119]
	v_mfma_f32_16x16x32_bf16 v[112:115], v[160:163], v[196:199], v[112:115]
	v_mfma_f32_16x16x32_bf16 v[112:115], v[164:167], v[200:203], v[112:115]
	v_mfma_f32_16x16x32_bf16 v[108:111], v[152:155], v[204:207], v[108:111]
	v_mfma_f32_16x16x32_bf16 v[108:111], v[156:159], v[208:211], v[108:111]
	v_mfma_f32_16x16x32_bf16 v[104:107], v[160:163], v[204:207], v[104:107]
	v_mfma_f32_16x16x32_bf16 v[104:107], v[164:167], v[208:211], v[104:107]
	v_mfma_f32_16x16x32_bf16 v[100:103], v[152:155], v[212:215], v[100:103]
	v_mfma_f32_16x16x32_bf16 v[100:103], v[156:159], v[216:219], v[100:103]
	v_mfma_f32_16x16x32_bf16 v[96:99], v[160:163], v[212:215], v[96:99]
	v_mfma_f32_16x16x32_bf16 v[96:99], v[164:167], v[216:219], v[96:99]
	v_mfma_f32_16x16x32_bf16 v[68:71], v[168:171], v[188:191], v[68:71]
	v_mfma_f32_16x16x32_bf16 v[68:71], v[172:175], v[192:195], v[68:71]
	v_mfma_f32_16x16x32_bf16 v[64:67], v[176:179], v[188:191], v[64:67]
	v_mfma_f32_16x16x32_bf16 v[64:67], v[184:187], v[192:195], v[64:67]
	v_mfma_f32_16x16x32_bf16 v[52:55], v[168:171], v[196:199], v[52:55]
	v_mfma_f32_16x16x32_bf16 v[52:55], v[172:175], v[200:203], v[52:55]
	v_mfma_f32_16x16x32_bf16 v[48:51], v[176:179], v[196:199], v[48:51]
	v_mfma_f32_16x16x32_bf16 v[48:51], v[184:187], v[200:203], v[48:51]
	v_mfma_f32_16x16x32_bf16 v[44:47], v[168:171], v[204:207], v[44:47]
	v_mfma_f32_16x16x32_bf16 v[44:47], v[172:175], v[208:211], v[44:47]
	v_mfma_f32_16x16x32_bf16 v[40:43], v[176:179], v[204:207], v[40:43]
	v_mfma_f32_16x16x32_bf16 v[40:43], v[184:187], v[208:211], v[40:43]
	v_mfma_f32_16x16x32_bf16 v[36:39], v[168:171], v[212:215], v[36:39]
	v_mfma_f32_16x16x32_bf16 v[36:39], v[172:175], v[216:219], v[36:39]
	s_setprio 2
	s_barrier
	v_mfma_f32_16x16x32_bf16 v[32:35], v[176:179], v[212:215], v[32:35]
	v_mfma_f32_16x16x32_bf16 v[32:35], v[184:187], v[216:219], v[32:35]
	s_setprio 0
	s_add_i32 s18, s76, s66
	v_lshl_add_u64 v[220:221], s[60:61], 0, v[132:133]
	s_mov_b32 m0, s18
	ds_read_b128 v[188:191], v150 offset:16384
	ds_read_b128 v[192:195], v150 offset:17408
	ds_read_b128 v[196:199], v150 offset:18432
	ds_read_b128 v[200:203], v150 offset:19456
	ds_read_b128 v[204:207], v150 offset:20480
	ds_read_b128 v[208:211], v150 offset:21504
	ds_read_b128 v[212:215], v150 offset:22528
	ds_read_b128 v[216:219], v150 offset:23552
	global_load_lds_dwordx4 v[220:221], off
	s_add_i32 m0, s18, 0x2000
	s_add_u32 s88, s60, 0x40000
	v_lshl_add_u64 v[222:223], s[60:61], 0, v[128:129]
	s_addc_u32 s89, s61, 0
	s_add_i32 s18, s77, s66
	global_load_lds_dwordx4 v[222:223], off
	v_lshl_add_u64 v[224:225], s[88:89], 0, v[132:133]
	s_mov_b32 m0, s18
	v_lshl_add_u64 v[226:227], s[62:63], 0, v[130:131]
	global_load_lds_dwordx4 v[224:225], off
	v_lshl_add_u64 v[224:225], s[88:89], 0, v[128:129]
	s_add_i32 m0, s18, 0x2000
	s_nop 0
	global_load_lds_dwordx4 v[224:225], off
	v_lshl_add_u64 v[224:225], s[62:63], 0, v[134:135]
	s_mov_b32 m0, s68
	s_nop 0
	global_load_lds_dwordx4 v[224:225], off
	s_mov_b32 m0, s69
	s_nop 0
	global_load_lds_dwordx4 v[226:227], off
	s_waitcnt vmcnt(8)
	s_waitcnt lgkmcnt(0)
	s_barrier
	s_setprio 1
	s_waitcnt lgkmcnt(0)
	v_mfma_f32_16x16x32_bf16 v[92:95], v[152:155], v[188:191], v[92:95]
	v_mfma_f32_16x16x32_bf16 v[92:95], v[156:159], v[192:195], v[92:95]
	v_mfma_f32_16x16x32_bf16 v[88:91], v[160:163], v[188:191], v[88:91]
	v_mfma_f32_16x16x32_bf16 v[88:91], v[164:167], v[192:195], v[88:91]
	v_mfma_f32_16x16x32_bf16 v[84:87], v[152:155], v[196:199], v[84:87]
	v_mfma_f32_16x16x32_bf16 v[84:87], v[156:159], v[200:203], v[84:87]
	v_mfma_f32_16x16x32_bf16 v[80:83], v[160:163], v[196:199], v[80:83]
	v_mfma_f32_16x16x32_bf16 v[80:83], v[164:167], v[200:203], v[80:83]
	v_mfma_f32_16x16x32_bf16 v[76:79], v[152:155], v[204:207], v[76:79]
	v_mfma_f32_16x16x32_bf16 v[76:79], v[156:159], v[208:211], v[76:79]
	v_mfma_f32_16x16x32_bf16 v[72:75], v[160:163], v[204:207], v[72:75]
	v_mfma_f32_16x16x32_bf16 v[72:75], v[164:167], v[208:211], v[72:75]
	v_mfma_f32_16x16x32_bf16 v[60:63], v[152:155], v[212:215], v[60:63]
	v_mfma_f32_16x16x32_bf16 v[60:63], v[156:159], v[216:219], v[60:63]
	v_mfma_f32_16x16x32_bf16 v[56:59], v[160:163], v[212:215], v[56:59]
	v_mfma_f32_16x16x32_bf16 v[56:59], v[164:167], v[216:219], v[56:59]
	v_mfma_f32_16x16x32_bf16 v[28:31], v[168:171], v[188:191], v[28:31]
	v_mfma_f32_16x16x32_bf16 v[28:31], v[172:175], v[192:195], v[28:31]
	v_mfma_f32_16x16x32_bf16 v[24:27], v[176:179], v[188:191], v[24:27]
	v_mfma_f32_16x16x32_bf16 v[24:27], v[184:187], v[192:195], v[24:27]
	v_mfma_f32_16x16x32_bf16 v[20:23], v[168:171], v[196:199], v[20:23]
	v_mfma_f32_16x16x32_bf16 v[20:23], v[172:175], v[200:203], v[20:23]
	v_mfma_f32_16x16x32_bf16 v[16:19], v[176:179], v[196:199], v[16:19]
	v_mfma_f32_16x16x32_bf16 v[16:19], v[184:187], v[200:203], v[16:19]
	v_mfma_f32_16x16x32_bf16 v[12:15], v[168:171], v[204:207], v[12:15]
	v_mfma_f32_16x16x32_bf16 v[12:15], v[172:175], v[208:211], v[12:15]
	v_mfma_f32_16x16x32_bf16 v[8:11], v[176:179], v[204:207], v[8:11]
	v_mfma_f32_16x16x32_bf16 v[8:11], v[184:187], v[208:211], v[8:11]
	v_mfma_f32_16x16x32_bf16 v[4:7], v[168:171], v[212:215], v[4:7]
	v_mfma_f32_16x16x32_bf16 v[4:7], v[172:175], v[216:219], v[4:7]
	s_setprio 2
	s_barrier
	v_mfma_f32_16x16x32_bf16 v[0:3], v[176:179], v[212:215], v[0:3]
	v_mfma_f32_16x16x32_bf16 v[0:3], v[184:187], v[216:219], v[0:3]
	s_setprio 0
.Lmid_gemm2:
	s_add_i32 s18, 0, 0x18000
	s_add_i32 s19, 0, 0x1c000
	v_add_u32_e32 v164, s18, v147
	v_add_u32_e32 v181, s19, v147
	ds_read_b128 v[152:155], v164
	ds_read_b128 v[156:159], v164 offset:1024
	ds_read_b128 v[160:163], v164 offset:2048
	ds_read_b128 v[164:167], v164 offset:3072
	ds_read_b128 v[168:171], v181
	ds_read_b128 v[172:175], v181 offset:1024
	ds_read_b128 v[176:179], v181 offset:2048
	ds_read_b128 v[184:187], v181 offset:3072
	s_add_u32 s62, s62, 0x40000
	s_addc_u32 s63, s63, 0
	s_mov_b32 m0, s70
	v_lshl_add_u64 v[228:229], s[62:63], 0, v[134:135]
	ds_read_b128 v[188:191], v150 offset:32768
	ds_read_b128 v[192:195], v150 offset:33792
	ds_read_b128 v[196:199], v150 offset:34816
	ds_read_b128 v[200:203], v150 offset:35840
	ds_read_b128 v[204:207], v150 offset:36864
	ds_read_b128 v[208:211], v150 offset:37888
	ds_read_b128 v[212:215], v150 offset:38912
	ds_read_b128 v[216:219], v150 offset:39936
	global_load_lds_dwordx4 v[228:229], off
	v_lshl_add_u64 v[228:229], s[62:63], 0, v[130:131]
	s_mov_b32 m0, s71
	s_nop 0
	global_load_lds_dwordx4 v[228:229], off
	s_waitcnt vmcnt(8)
	s_waitcnt lgkmcnt(0)
	s_barrier
	s_setprio 1
	s_waitcnt lgkmcnt(0)
	v_mfma_f32_16x16x32_bf16 v[124:127], v[152:155], v[188:191], v[124:127]
	v_mfma_f32_16x16x32_bf16 v[124:127], v[156:159], v[192:195], v[124:127]
	v_mfma_f32_16x16x32_bf16 v[120:123], v[160:163], v[188:191], v[120:123]
	v_mfma_f32_16x16x32_bf16 v[120:123], v[164:167], v[192:195], v[120:123]
	v_mfma_f32_16x16x32_bf16 v[116:119], v[152:155], v[196:199], v[116:119]
	v_mfma_f32_16x16x32_bf16 v[116:119], v[156:159], v[200:203], v[116:119]
	v_mfma_f32_16x16x32_bf16 v[112:115], v[160:163], v[196:199], v[112:115]
	v_mfma_f32_16x16x32_bf16 v[112:115], v[164:167], v[200:203], v[112:115]
	v_mfma_f32_16x16x32_bf16 v[108:111], v[152:155], v[204:207], v[108:111]
	v_mfma_f32_16x16x32_bf16 v[108:111], v[156:159], v[208:211], v[108:111]
	v_mfma_f32_16x16x32_bf16 v[104:107], v[160:163], v[204:207], v[104:107]
	v_mfma_f32_16x16x32_bf16 v[104:107], v[164:167], v[208:211], v[104:107]
	v_mfma_f32_16x16x32_bf16 v[100:103], v[152:155], v[212:215], v[100:103]
	v_mfma_f32_16x16x32_bf16 v[100:103], v[156:159], v[216:219], v[100:103]
	v_mfma_f32_16x16x32_bf16 v[96:99], v[160:163], v[212:215], v[96:99]
	v_mfma_f32_16x16x32_bf16 v[96:99], v[164:167], v[216:219], v[96:99]
	v_mfma_f32_16x16x32_bf16 v[68:71], v[168:171], v[188:191], v[68:71]
	v_mfma_f32_16x16x32_bf16 v[68:71], v[172:175], v[192:195], v[68:71]
	v_mfma_f32_16x16x32_bf16 v[64:67], v[176:179], v[188:191], v[64:67]
	v_mfma_f32_16x16x32_bf16 v[64:67], v[184:187], v[192:195], v[64:67]
	v_mfma_f32_16x16x32_bf16 v[52:55], v[168:171], v[196:199], v[52:55]
	v_mfma_f32_16x16x32_bf16 v[52:55], v[172:175], v[200:203], v[52:55]
	v_mfma_f32_16x16x32_bf16 v[48:51], v[176:179], v[196:199], v[48:51]
	v_mfma_f32_16x16x32_bf16 v[48:51], v[184:187], v[200:203], v[48:51]
	v_mfma_f32_16x16x32_bf16 v[44:47], v[168:171], v[204:207], v[44:47]
	v_mfma_f32_16x16x32_bf16 v[44:47], v[172:175], v[208:211], v[44:47]
	v_mfma_f32_16x16x32_bf16 v[40:43], v[176:179], v[204:207], v[40:43]
	v_mfma_f32_16x16x32_bf16 v[40:43], v[184:187], v[208:211], v[40:43]
	v_mfma_f32_16x16x32_bf16 v[36:39], v[168:171], v[212:215], v[36:39]
	v_mfma_f32_16x16x32_bf16 v[36:39], v[172:175], v[216:219], v[36:39]
	s_setprio 2
	s_barrier
	v_mfma_f32_16x16x32_bf16 v[32:35], v[176:179], v[212:215], v[32:35]
	v_mfma_f32_16x16x32_bf16 v[32:35], v[184:187], v[216:219], v[32:35]
	s_setprio 0
	s_add_i32 s18, s18, s66
	v_lshl_add_u64 v[220:221], v[220:221], 0, s[6:7]
	s_mov_b32 m0, s18
	ds_read_b128 v[188:191], v150 offset:49152
	ds_read_b128 v[192:195], v150 offset:50176
	ds_read_b128 v[196:199], v150 offset:51200
	ds_read_b128 v[200:203], v150 offset:52224
	ds_read_b128 v[204:207], v150 offset:53248
	ds_read_b128 v[208:211], v150 offset:54272
	ds_read_b128 v[212:215], v150 offset:55296
	ds_read_b128 v[216:219], v150 offset:56320
	global_load_lds_dwordx4 v[220:221], off
	s_add_i32 m0, s18, 0x2000
	s_add_u32 s60, s60, 0x40080
	v_lshl_add_u64 v[220:221], v[222:223], 0, s[6:7]
	s_addc_u32 s61, s61, 0
	s_add_i32 s18, s19, s66
	global_load_lds_dwordx4 v[220:221], off
	v_lshl_add_u64 v[220:221], s[60:61], 0, v[132:133]
	s_mov_b32 m0, s18
	s_nop 0
	global_load_lds_dwordx4 v[220:221], off
	v_lshl_add_u64 v[220:221], s[60:61], 0, v[128:129]
	s_add_i32 m0, s18, 0x2000
	s_nop 0
	global_load_lds_dwordx4 v[220:221], off
	v_lshl_add_u64 v[220:221], v[224:225], 0, s[6:7]
	s_mov_b32 m0, s74
	s_nop 0
	global_load_lds_dwordx4 v[220:221], off
	v_lshl_add_u64 v[220:221], v[226:227], 0, s[6:7]
	s_mov_b32 m0, s75
	s_nop 0
	global_load_lds_dwordx4 v[220:221], off
	s_waitcnt vmcnt(8)
	s_waitcnt lgkmcnt(0)
	s_barrier
	s_setprio 1
	s_waitcnt lgkmcnt(0)
	v_mfma_f32_16x16x32_bf16 v[92:95], v[152:155], v[188:191], v[92:95]
	v_mfma_f32_16x16x32_bf16 v[92:95], v[156:159], v[192:195], v[92:95]
	v_mfma_f32_16x16x32_bf16 v[88:91], v[160:163], v[188:191], v[88:91]
	v_mfma_f32_16x16x32_bf16 v[88:91], v[164:167], v[192:195], v[88:91]
	v_mfma_f32_16x16x32_bf16 v[84:87], v[152:155], v[196:199], v[84:87]
	v_mfma_f32_16x16x32_bf16 v[84:87], v[156:159], v[200:203], v[84:87]
	v_mfma_f32_16x16x32_bf16 v[80:83], v[160:163], v[196:199], v[80:83]
	v_mfma_f32_16x16x32_bf16 v[80:83], v[164:167], v[200:203], v[80:83]
	v_mfma_f32_16x16x32_bf16 v[76:79], v[152:155], v[204:207], v[76:79]
	v_mfma_f32_16x16x32_bf16 v[76:79], v[156:159], v[208:211], v[76:79]
	v_mfma_f32_16x16x32_bf16 v[72:75], v[160:163], v[204:207], v[72:75]
	v_mfma_f32_16x16x32_bf16 v[72:75], v[164:167], v[208:211], v[72:75]
	v_mfma_f32_16x16x32_bf16 v[60:63], v[152:155], v[212:215], v[60:63]
	v_mfma_f32_16x16x32_bf16 v[60:63], v[156:159], v[216:219], v[60:63]
	v_mfma_f32_16x16x32_bf16 v[56:59], v[160:163], v[212:215], v[56:59]
	v_mfma_f32_16x16x32_bf16 v[56:59], v[164:167], v[216:219], v[56:59]
	v_mfma_f32_16x16x32_bf16 v[28:31], v[168:171], v[188:191], v[28:31]
	v_mfma_f32_16x16x32_bf16 v[28:31], v[172:175], v[192:195], v[28:31]
	v_mfma_f32_16x16x32_bf16 v[24:27], v[176:179], v[188:191], v[24:27]
	v_mfma_f32_16x16x32_bf16 v[24:27], v[184:187], v[192:195], v[24:27]
	v_mfma_f32_16x16x32_bf16 v[20:23], v[168:171], v[196:199], v[20:23]
	v_mfma_f32_16x16x32_bf16 v[20:23], v[172:175], v[200:203], v[20:23]
	v_mfma_f32_16x16x32_bf16 v[16:19], v[176:179], v[196:199], v[16:19]
	v_mfma_f32_16x16x32_bf16 v[16:19], v[184:187], v[200:203], v[16:19]
	v_mfma_f32_16x16x32_bf16 v[12:15], v[168:171], v[204:207], v[12:15]
	v_mfma_f32_16x16x32_bf16 v[12:15], v[172:175], v[208:211], v[12:15]
	v_mfma_f32_16x16x32_bf16 v[8:11], v[176:179], v[204:207], v[8:11]
	v_mfma_f32_16x16x32_bf16 v[8:11], v[184:187], v[208:211], v[8:11]
	v_mfma_f32_16x16x32_bf16 v[4:7], v[168:171], v[212:215], v[4:7]
	v_mfma_f32_16x16x32_bf16 v[4:7], v[172:175], v[216:219], v[4:7]
	s_setprio 2
	s_barrier
	v_mfma_f32_16x16x32_bf16 v[0:3], v[176:179], v[212:215], v[0:3]
	v_mfma_f32_16x16x32_bf16 v[0:3], v[184:187], v[216:219], v[0:3]
	s_setprio 0
	s_add_i32 s86, s86, 2
	s_add_u32 s58, s58, 0x100
	s_addc_u32 s59, s59, 0
	s_add_u32 s84, s84, 0x100
	s_addc_u32 s85, s85, 0
	s_cmp_gt_u32 s86, 13
	s_cbranch_scc0 .LBB0_387
	s_and_b64 vcc, exec, s[8:9]
	s_cbranch_vccz .LBB0_390
	s_barrier

.LBB0_600:
	s_ashr_i32 s49, s48, 31
	s_lshl_b64 s[18:19], s[48:49], 19
	s_add_u32 s52, s38, s18
	s_addc_u32 s53, s39, s19
	s_and_b64 s[18:19], s[4:5], exec
	s_cselect_b32 s49, s53, s59
	s_cselect_b32 s84, s52, s58
	s_ashr_i32 s47, s46, 31
	s_lshl_b64 s[18:19], s[46:47], 19
	s_add_u32 s54, s64, s18
	s_addc_u32 s55, s65, s19
	s_and_b64 s[18:19], s[4:5], exec
	s_cselect_b32 s47, s55, s61
	s_cselect_b32 s85, s54, s60
	s_add_u32 s58, s58, 0x40080
	s_addc_u32 s59, s59, 0
	s_add_u32 s86, s60, 0x100
	s_addc_u32 s87, s61, 0
	s_mov_b32 s88, -2
	ds_read_b128 v[152:155], v149
	ds_read_b128 v[156:159], v149 offset:1024
	ds_read_b128 v[160:163], v149 offset:2048
	ds_read_b128 v[164:167], v149 offset:3072
	ds_read_b128 v[168:171], v150
	ds_read_b128 v[172:175], v150 offset:1024
	ds_read_b128 v[176:179], v150 offset:2048
	ds_read_b128 v[184:187], v150 offset:3072
	s_add_u32 s18, s58, 0xfffc0080
	s_addc_u32 s19, s59, -1
	s_cmp_eq_u32 s88, 12
	s_cselect_b32 s63, s49, s19
	s_cselect_b32 s62, s84, s18
	s_cselect_b32 s61, s47, s87
	s_cselect_b32 s60, s85, s86
	v_lshl_add_u64 v[144:145], s[58:59], 0, v[136:137]
	s_add_i32 m0, s57, 0xc000
	ds_read_b128 v[188:191], v151
	ds_read_b128 v[192:195], v151 offset:1024
	ds_read_b128 v[196:199], v151 offset:2048
	ds_read_b128 v[200:203], v151 offset:3072
	ds_read_b128 v[204:207], v151 offset:4096
	ds_read_b128 v[208:211], v151 offset:5120
	ds_read_b128 v[212:215], v151 offset:6144
	ds_read_b128 v[216:219], v151 offset:7168
	global_load_lds_dwordx4 v[144:145], off
	v_lshl_add_u64 v[144:145], s[58:59], 0, v[138:139]
	s_add_i32 m0, s57, 0xe000
	s_nop 0
	global_load_lds_dwordx4 v[144:145], off
	s_waitcnt vmcnt(8)
	s_waitcnt lgkmcnt(0)
	s_barrier
	s_setprio 1
	s_waitcnt lgkmcnt(0)
	v_mfma_f32_16x16x32_bf16 v[124:127], v[152:155], v[188:191], 0
	v_mfma_f32_16x16x32_bf16 v[124:127], v[156:159], v[192:195], v[124:127]
	v_mfma_f32_16x16x32_bf16 v[120:123], v[160:163], v[188:191], 0
	v_mfma_f32_16x16x32_bf16 v[120:123], v[164:167], v[192:195], v[120:123]
	v_mfma_f32_16x16x32_bf16 v[116:119], v[152:155], v[196:199], 0
	v_mfma_f32_16x16x32_bf16 v[116:119], v[156:159], v[200:203], v[116:119]
	v_mfma_f32_16x16x32_bf16 v[108:111], v[160:163], v[196:199], 0
	v_mfma_f32_16x16x32_bf16 v[108:111], v[164:167], v[200:203], v[108:111]
	v_mfma_f32_16x16x32_bf16 v[100:103], v[152:155], v[204:207], 0
	v_mfma_f32_16x16x32_bf16 v[100:103], v[156:159], v[208:211], v[100:103]
	v_mfma_f32_16x16x32_bf16 v[92:95], v[160:163], v[204:207], 0
	v_mfma_f32_16x16x32_bf16 v[92:95], v[164:167], v[208:211], v[92:95]
	v_mfma_f32_16x16x32_bf16 v[84:87], v[152:155], v[212:215], 0
	v_mfma_f32_16x16x32_bf16 v[84:87], v[156:159], v[216:219], v[84:87]
	v_mfma_f32_16x16x32_bf16 v[76:79], v[160:163], v[212:215], 0
	v_mfma_f32_16x16x32_bf16 v[76:79], v[164:167], v[216:219], v[76:79]
	v_mfma_f32_16x16x32_bf16 v[112:115], v[168:171], v[188:191], 0
	v_mfma_f32_16x16x32_bf16 v[112:115], v[172:175], v[192:195], v[112:115]
	v_mfma_f32_16x16x32_bf16 v[104:107], v[176:179], v[188:191], 0
	v_mfma_f32_16x16x32_bf16 v[104:107], v[184:187], v[192:195], v[104:107]
	v_mfma_f32_16x16x32_bf16 v[96:99], v[168:171], v[196:199], 0
	v_mfma_f32_16x16x32_bf16 v[96:99], v[172:175], v[200:203], v[96:99]
	v_mfma_f32_16x16x32_bf16 v[88:91], v[176:179], v[196:199], 0
	v_mfma_f32_16x16x32_bf16 v[88:91], v[184:187], v[200:203], v[88:91]
	v_mfma_f32_16x16x32_bf16 v[80:83], v[168:171], v[204:207], 0
	v_mfma_f32_16x16x32_bf16 v[80:83], v[172:175], v[208:211], v[80:83]
	v_mfma_f32_16x16x32_bf16 v[72:75], v[176:179], v[204:207], 0
	v_mfma_f32_16x16x32_bf16 v[72:75], v[184:187], v[208:211], v[72:75]
	v_mfma_f32_16x16x32_bf16 v[68:71], v[168:171], v[212:215], 0
	v_mfma_f32_16x16x32_bf16 v[68:71], v[172:175], v[216:219], v[68:71]
	s_setprio 2
	s_barrier
	v_mfma_f32_16x16x32_bf16 v[64:67], v[176:179], v[212:215], 0
	v_mfma_f32_16x16x32_bf16 v[64:67], v[184:187], v[216:219], v[64:67]
	s_setprio 0
	s_add_i32 s18, s73, s66
	v_lshl_add_u64 v[144:145], s[60:61], 0, v[130:131]
	s_mov_b32 m0, s18
	ds_read_b128 v[188:191], v151 offset:16384
	ds_read_b128 v[192:195], v151 offset:17408
	ds_read_b128 v[196:199], v151 offset:18432
	ds_read_b128 v[200:203], v151 offset:19456
	ds_read_b128 v[204:207], v151 offset:20480
	ds_read_b128 v[208:211], v151 offset:21504
	ds_read_b128 v[212:215], v151 offset:22528
	ds_read_b128 v[216:219], v151 offset:23552
	global_load_lds_dwordx4 v[144:145], off
	s_add_i32 m0, s18, 0x2000
	s_add_u32 s18, s60, 0x40000
	v_lshl_add_u64 v[220:221], s[60:61], 0, v[134:135]
	s_addc_u32 s19, s61, 0
	s_add_i32 s79, s74, s66
	global_load_lds_dwordx4 v[220:221], off
	v_lshl_add_u64 v[222:223], s[18:19], 0, v[130:131]
	s_mov_b32 m0, s79
	v_lshl_add_u64 v[224:225], s[62:63], 0, v[132:133]
	global_load_lds_dwordx4 v[222:223], off
	v_lshl_add_u64 v[222:223], s[18:19], 0, v[134:135]
	s_add_i32 m0, s79, 0x2000
	s_nop 0
	global_load_lds_dwordx4 v[222:223], off
	v_lshl_add_u64 v[222:223], s[62:63], 0, v[128:129]
	s_mov_b32 m0, s57
	s_nop 0
	global_load_lds_dwordx4 v[222:223], off
	s_mov_b32 m0, s67
	s_nop 0
	global_load_lds_dwordx4 v[224:225], off
	s_waitcnt vmcnt(8)
	s_waitcnt lgkmcnt(0)
	s_barrier
	s_setprio 1
	s_waitcnt lgkmcnt(0)
	v_mfma_f32_16x16x32_bf16 v[60:63], v[152:155], v[188:191], 0
	v_mfma_f32_16x16x32_bf16 v[60:63], v[156:159], v[192:195], v[60:63]
	v_mfma_f32_16x16x32_bf16 v[56:59], v[160:163], v[188:191], 0
	v_mfma_f32_16x16x32_bf16 v[56:59], v[164:167], v[192:195], v[56:59]
	v_mfma_f32_16x16x32_bf16 v[52:55], v[152:155], v[196:199], 0
	v_mfma_f32_16x16x32_bf16 v[52:55], v[156:159], v[200:203], v[52:55]
	v_mfma_f32_16x16x32_bf16 v[44:47], v[160:163], v[196:199], 0
	v_mfma_f32_16x16x32_bf16 v[44:47], v[164:167], v[200:203], v[44:47]
	v_mfma_f32_16x16x32_bf16 v[36:39], v[152:155], v[204:207], 0
	v_mfma_f32_16x16x32_bf16 v[36:39], v[156:159], v[208:211], v[36:39]
	v_mfma_f32_16x16x32_bf16 v[28:31], v[160:163], v[204:207], 0
	v_mfma_f32_16x16x32_bf16 v[28:31], v[164:167], v[208:211], v[28:31]
	v_mfma_f32_16x16x32_bf16 v[20:23], v[152:155], v[212:215], 0
	v_mfma_f32_16x16x32_bf16 v[20:23], v[156:159], v[216:219], v[20:23]
	v_mfma_f32_16x16x32_bf16 v[12:15], v[160:163], v[212:215], 0
	v_mfma_f32_16x16x32_bf16 v[12:15], v[164:167], v[216:219], v[12:15]
	v_mfma_f32_16x16x32_bf16 v[48:51], v[168:171], v[188:191], 0
	v_mfma_f32_16x16x32_bf16 v[48:51], v[172:175], v[192:195], v[48:51]
	v_mfma_f32_16x16x32_bf16 v[40:43], v[176:179], v[188:191], 0
	v_mfma_f32_16x16x32_bf16 v[40:43], v[184:187], v[192:195], v[40:43]
	v_mfma_f32_16x16x32_bf16 v[32:35], v[168:171], v[196:199], 0
	v_mfma_f32_16x16x32_bf16 v[32:35], v[172:175], v[200:203], v[32:35]
	v_mfma_f32_16x16x32_bf16 v[24:27], v[176:179], v[196:199], 0
	v_mfma_f32_16x16x32_bf16 v[24:27], v[184:187], v[200:203], v[24:27]
	v_mfma_f32_16x16x32_bf16 v[16:19], v[168:171], v[204:207], 0
	v_mfma_f32_16x16x32_bf16 v[16:19], v[172:175], v[208:211], v[16:19]
	v_mfma_f32_16x16x32_bf16 v[8:11], v[176:179], v[204:207], 0
	v_mfma_f32_16x16x32_bf16 v[8:11], v[184:187], v[208:211], v[8:11]
	v_mfma_f32_16x16x32_bf16 v[4:7], v[168:171], v[212:215], 0
	v_mfma_f32_16x16x32_bf16 v[4:7], v[172:175], v[216:219], v[4:7]
	s_setprio 2
	s_barrier
	v_mfma_f32_16x16x32_bf16 v[0:3], v[176:179], v[212:215], 0
	v_mfma_f32_16x16x32_bf16 v[0:3], v[184:187], v[216:219], v[0:3]
	s_setprio 0
	s_branch .Lmid_gemm3
.LBB0_601:
	ds_read_b128 v[152:155], v149
	ds_read_b128 v[156:159], v149 offset:1024
	ds_read_b128 v[160:163], v149 offset:2048
	ds_read_b128 v[164:167], v149 offset:3072
	ds_read_b128 v[168:171], v150
	ds_read_b128 v[172:175], v150 offset:1024
	ds_read_b128 v[176:179], v150 offset:2048
	ds_read_b128 v[184:187], v150 offset:3072
	s_add_u32 s18, s58, 0xfffc0080
	s_addc_u32 s19, s59, -1
	s_cmp_eq_u32 s88, 12
	s_cselect_b32 s63, s49, s19
	s_cselect_b32 s62, s84, s18
	s_cselect_b32 s61, s47, s87
	s_cselect_b32 s60, s85, s86
	v_lshl_add_u64 v[144:145], s[58:59], 0, v[136:137]
	s_add_i32 m0, s57, 0xc000
	ds_read_b128 v[188:191], v151
	ds_read_b128 v[192:195], v151 offset:1024
	ds_read_b128 v[196:199], v151 offset:2048
	ds_read_b128 v[200:203], v151 offset:3072
	ds_read_b128 v[204:207], v151 offset:4096
	ds_read_b128 v[208:211], v151 offset:5120
	ds_read_b128 v[212:215], v151 offset:6144
	ds_read_b128 v[216:219], v151 offset:7168
	global_load_lds_dwordx4 v[144:145], off
	v_lshl_add_u64 v[144:145], s[58:59], 0, v[138:139]
	s_add_i32 m0, s57, 0xe000
	s_nop 0
	global_load_lds_dwordx4 v[144:145], off
	s_waitcnt vmcnt(8)
	s_waitcnt lgkmcnt(0)
	s_barrier
	s_setprio 1
	s_waitcnt lgkmcnt(0)
	v_mfma_f32_16x16x32_bf16 v[124:127], v[152:155], v[188:191], v[124:127]
	v_mfma_f32_16x16x32_bf16 v[124:127], v[156:159], v[192:195], v[124:127]
	v_mfma_f32_16x16x32_bf16 v[120:123], v[160:163], v[188:191], v[120:123]
	v_mfma_f32_16x16x32_bf16 v[120:123], v[164:167], v[192:195], v[120:123]
	v_mfma_f32_16x16x32_bf16 v[116:119], v[152:155], v[196:199], v[116:119]
	v_mfma_f32_16x16x32_bf16 v[116:119], v[156:159], v[200:203], v[116:119]
	v_mfma_f32_16x16x32_bf16 v[108:111], v[160:163], v[196:199], v[108:111]
	v_mfma_f32_16x16x32_bf16 v[108:111], v[164:167], v[200:203], v[108:111]
	v_mfma_f32_16x16x32_bf16 v[100:103], v[152:155], v[204:207], v[100:103]
	v_mfma_f32_16x16x32_bf16 v[100:103], v[156:159], v[208:211], v[100:103]
	v_mfma_f32_16x16x32_bf16 v[92:95], v[160:163], v[204:207], v[92:95]
	v_mfma_f32_16x16x32_bf16 v[92:95], v[164:167], v[208:211], v[92:95]
	v_mfma_f32_16x16x32_bf16 v[84:87], v[152:155], v[212:215], v[84:87]
	v_mfma_f32_16x16x32_bf16 v[84:87], v[156:159], v[216:219], v[84:87]
	v_mfma_f32_16x16x32_bf16 v[76:79], v[160:163], v[212:215], v[76:79]
	v_mfma_f32_16x16x32_bf16 v[76:79], v[164:167], v[216:219], v[76:79]
	v_mfma_f32_16x16x32_bf16 v[112:115], v[168:171], v[188:191], v[112:115]
	v_mfma_f32_16x16x32_bf16 v[112:115], v[172:175], v[192:195], v[112:115]
	v_mfma_f32_16x16x32_bf16 v[104:107], v[176:179], v[188:191], v[104:107]
	v_mfma_f32_16x16x32_bf16 v[104:107], v[184:187], v[192:195], v[104:107]
	v_mfma_f32_16x16x32_bf16 v[96:99], v[168:171], v[196:199], v[96:99]
	v_mfma_f32_16x16x32_bf16 v[96:99], v[172:175], v[200:203], v[96:99]
	v_mfma_f32_16x16x32_bf16 v[88:91], v[176:179], v[196:199], v[88:91]
	v_mfma_f32_16x16x32_bf16 v[88:91], v[184:187], v[200:203], v[88:91]
	v_mfma_f32_16x16x32_bf16 v[80:83], v[168:171], v[204:207], v[80:83]
	v_mfma_f32_16x16x32_bf16 v[80:83], v[172:175], v[208:211], v[80:83]
	v_mfma_f32_16x16x32_bf16 v[72:75], v[176:179], v[204:207], v[72:75]
	v_mfma_f32_16x16x32_bf16 v[72:75], v[184:187], v[208:211], v[72:75]
	v_mfma_f32_16x16x32_bf16 v[68:71], v[168:171], v[212:215], v[68:71]
	v_mfma_f32_16x16x32_bf16 v[68:71], v[172:175], v[216:219], v[68:71]
	s_setprio 2
	s_barrier
	v_mfma_f32_16x16x32_bf16 v[64:67], v[176:179], v[212:215], v[64:67]
	v_mfma_f32_16x16x32_bf16 v[64:67], v[184:187], v[216:219], v[64:67]
	s_setprio 0
	s_add_i32 s18, s73, s66
	v_lshl_add_u64 v[144:145], s[60:61], 0, v[130:131]
	s_mov_b32 m0, s18
	ds_read_b128 v[188:191], v151 offset:16384
	ds_read_b128 v[192:195], v151 offset:17408
	ds_read_b128 v[196:199], v151 offset:18432
	ds_read_b128 v[200:203], v151 offset:19456
	ds_read_b128 v[204:207], v151 offset:20480
	ds_read_b128 v[208:211], v151 offset:21504
	ds_read_b128 v[212:215], v151 offset:22528
	ds_read_b128 v[216:219], v151 offset:23552
	global_load_lds_dwordx4 v[144:145], off
	s_add_i32 m0, s18, 0x2000
	s_add_u32 s18, s60, 0x40000
	v_lshl_add_u64 v[220:221], s[60:61], 0, v[134:135]
	s_addc_u32 s19, s61, 0
	s_add_i32 s79, s74, s66
	global_load_lds_dwordx4 v[220:221], off
	v_lshl_add_u64 v[222:223], s[18:19], 0, v[130:131]
	s_mov_b32 m0, s79
	v_lshl_add_u64 v[224:225], s[62:63], 0, v[132:133]
	global_load_lds_dwordx4 v[222:223], off
	v_lshl_add_u64 v[222:223], s[18:19], 0, v[134:135]
	s_add_i32 m0, s79, 0x2000
	s_nop 0
	global_load_lds_dwordx4 v[222:223], off
	v_lshl_add_u64 v[222:223], s[62:63], 0, v[128:129]
	s_mov_b32 m0, s57
	s_nop 0
	global_load_lds_dwordx4 v[222:223], off
	s_mov_b32 m0, s67
	s_nop 0
	global_load_lds_dwordx4 v[224:225], off
	s_waitcnt vmcnt(8)
	s_waitcnt lgkmcnt(0)
	s_barrier
	s_setprio 1
	s_waitcnt lgkmcnt(0)
	v_mfma_f32_16x16x32_bf16 v[60:63], v[152:155], v[188:191], v[60:63]
	v_mfma_f32_16x16x32_bf16 v[60:63], v[156:159], v[192:195], v[60:63]
	v_mfma_f32_16x16x32_bf16 v[56:59], v[160:163], v[188:191], v[56:59]
	v_mfma_f32_16x16x32_bf16 v[56:59], v[164:167], v[192:195], v[56:59]
	v_mfma_f32_16x16x32_bf16 v[52:55], v[152:155], v[196:199], v[52:55]
	v_mfma_f32_16x16x32_bf16 v[52:55], v[156:159], v[200:203], v[52:55]
	v_mfma_f32_16x16x32_bf16 v[44:47], v[160:163], v[196:199], v[44:47]
	v_mfma_f32_16x16x32_bf16 v[44:47], v[164:167], v[200:203], v[44:47]
	v_mfma_f32_16x16x32_bf16 v[36:39], v[152:155], v[204:207], v[36:39]
	v_mfma_f32_16x16x32_bf16 v[36:39], v[156:159], v[208:211], v[36:39]
	v_mfma_f32_16x16x32_bf16 v[28:31], v[160:163], v[204:207], v[28:31]
	v_mfma_f32_16x16x32_bf16 v[28:31], v[164:167], v[208:211], v[28:31]
	v_mfma_f32_16x16x32_bf16 v[20:23], v[152:155], v[212:215], v[20:23]
	v_mfma_f32_16x16x32_bf16 v[20:23], v[156:159], v[216:219], v[20:23]
	v_mfma_f32_16x16x32_bf16 v[12:15], v[160:163], v[212:215], v[12:15]
	v_mfma_f32_16x16x32_bf16 v[12:15], v[164:167], v[216:219], v[12:15]
	v_mfma_f32_16x16x32_bf16 v[48:51], v[168:171], v[188:191], v[48:51]
	v_mfma_f32_16x16x32_bf16 v[48:51], v[172:175], v[192:195], v[48:51]
	v_mfma_f32_16x16x32_bf16 v[40:43], v[176:179], v[188:191], v[40:43]
	v_mfma_f32_16x16x32_bf16 v[40:43], v[184:187], v[192:195], v[40:43]
	v_mfma_f32_16x16x32_bf16 v[32:35], v[168:171], v[196:199], v[32:35]
	v_mfma_f32_16x16x32_bf16 v[32:35], v[172:175], v[200:203], v[32:35]
	v_mfma_f32_16x16x32_bf16 v[24:27], v[176:179], v[196:199], v[24:27]
	v_mfma_f32_16x16x32_bf16 v[24:27], v[184:187], v[200:203], v[24:27]
	v_mfma_f32_16x16x32_bf16 v[16:19], v[168:171], v[204:207], v[16:19]
	v_mfma_f32_16x16x32_bf16 v[16:19], v[172:175], v[208:211], v[16:19]
	v_mfma_f32_16x16x32_bf16 v[8:11], v[176:179], v[204:207], v[8:11]
	v_mfma_f32_16x16x32_bf16 v[8:11], v[184:187], v[208:211], v[8:11]
	v_mfma_f32_16x16x32_bf16 v[4:7], v[168:171], v[212:215], v[4:7]
	v_mfma_f32_16x16x32_bf16 v[4:7], v[172:175], v[216:219], v[4:7]
	s_setprio 2
	s_barrier
	v_mfma_f32_16x16x32_bf16 v[0:3], v[176:179], v[212:215], v[0:3]
	v_mfma_f32_16x16x32_bf16 v[0:3], v[184:187], v[216:219], v[0:3]
	s_setprio 0
.Lmid_gemm3:
	s_add_i32 s79, 0, 0x18000
	s_add_i32 s89, 0, 0x1c000
	v_add_u32_e32 v164, s79, v147
	v_add_u32_e32 v181, s89, v147
	ds_read_b128 v[152:155], v164
	ds_read_b128 v[156:159], v164 offset:1024
	ds_read_b128 v[160:163], v164 offset:2048
	ds_read_b128 v[164:167], v164 offset:3072
	ds_read_b128 v[168:171], v181
	ds_read_b128 v[172:175], v181 offset:1024
	ds_read_b128 v[176:179], v181 offset:2048
	ds_read_b128 v[184:187], v181 offset:3072
	s_add_u32 s18, s62, 0x40000
	s_addc_u32 s19, s63, 0
	s_mov_b32 m0, s68
	v_lshl_add_u64 v[226:227], s[18:19], 0, v[128:129]
	ds_read_b128 v[188:191], v151 offset:32768
	ds_read_b128 v[192:195], v151 offset:33792
	ds_read_b128 v[196:199], v151 offset:34816
	ds_read_b128 v[200:203], v151 offset:35840
	ds_read_b128 v[204:207], v151 offset:36864
	ds_read_b128 v[208:211], v151 offset:37888
	ds_read_b128 v[212:215], v151 offset:38912
	ds_read_b128 v[216:219], v151 offset:39936
	global_load_lds_dwordx4 v[226:227], off
	v_lshl_add_u64 v[226:227], s[18:19], 0, v[132:133]
	s_mov_b32 m0, s69
	s_nop 0
	global_load_lds_dwordx4 v[226:227], off
	s_waitcnt vmcnt(8)
	s_waitcnt lgkmcnt(0)
	s_barrier
	s_setprio 1
	s_waitcnt lgkmcnt(0)
	v_mfma_f32_16x16x32_bf16 v[124:127], v[152:155], v[188:191], v[124:127]
	v_mfma_f32_16x16x32_bf16 v[124:127], v[156:159], v[192:195], v[124:127]
	v_mfma_f32_16x16x32_bf16 v[120:123], v[160:163], v[188:191], v[120:123]
	v_mfma_f32_16x16x32_bf16 v[120:123], v[164:167], v[192:195], v[120:123]
	v_mfma_f32_16x16x32_bf16 v[116:119], v[152:155], v[196:199], v[116:119]
	v_mfma_f32_16x16x32_bf16 v[116:119], v[156:159], v[200:203], v[116:119]
	v_mfma_f32_16x16x32_bf16 v[108:111], v[160:163], v[196:199], v[108:111]
	v_mfma_f32_16x16x32_bf16 v[108:111], v[164:167], v[200:203], v[108:111]
	v_mfma_f32_16x16x32_bf16 v[100:103], v[152:155], v[204:207], v[100:103]
	v_mfma_f32_16x16x32_bf16 v[100:103], v[156:159], v[208:211], v[100:103]
	v_mfma_f32_16x16x32_bf16 v[92:95], v[160:163], v[204:207], v[92:95]
	v_mfma_f32_16x16x32_bf16 v[92:95], v[164:167], v[208:211], v[92:95]
	v_mfma_f32_16x16x32_bf16 v[84:87], v[152:155], v[212:215], v[84:87]
	v_mfma_f32_16x16x32_bf16 v[84:87], v[156:159], v[216:219], v[84:87]
	v_mfma_f32_16x16x32_bf16 v[76:79], v[160:163], v[212:215], v[76:79]
	v_mfma_f32_16x16x32_bf16 v[76:79], v[164:167], v[216:219], v[76:79]
	v_mfma_f32_16x16x32_bf16 v[112:115], v[168:171], v[188:191], v[112:115]
	v_mfma_f32_16x16x32_bf16 v[112:115], v[172:175], v[192:195], v[112:115]
	v_mfma_f32_16x16x32_bf16 v[104:107], v[176:179], v[188:191], v[104:107]
	v_mfma_f32_16x16x32_bf16 v[104:107], v[184:187], v[192:195], v[104:107]
	v_mfma_f32_16x16x32_bf16 v[96:99], v[168:171], v[196:199], v[96:99]
	v_mfma_f32_16x16x32_bf16 v[96:99], v[172:175], v[200:203], v[96:99]
	v_mfma_f32_16x16x32_bf16 v[88:91], v[176:179], v[196:199], v[88:91]
	v_mfma_f32_16x16x32_bf16 v[88:91], v[184:187], v[200:203], v[88:91]
	v_mfma_f32_16x16x32_bf16 v[80:83], v[168:171], v[204:207], v[80:83]
	v_mfma_f32_16x16x32_bf16 v[80:83], v[172:175], v[208:211], v[80:83]
	v_mfma_f32_16x16x32_bf16 v[72:75], v[176:179], v[204:207], v[72:75]
	v_mfma_f32_16x16x32_bf16 v[72:75], v[184:187], v[208:211], v[72:75]
	v_mfma_f32_16x16x32_bf16 v[68:71], v[168:171], v[212:215], v[68:71]
	v_mfma_f32_16x16x32_bf16 v[68:71], v[172:175], v[216:219], v[68:71]
	s_setprio 2
	s_barrier
	v_mfma_f32_16x16x32_bf16 v[64:67], v[176:179], v[212:215], v[64:67]
	v_mfma_f32_16x16x32_bf16 v[64:67], v[184:187], v[216:219], v[64:67]
	s_setprio 0
	s_add_i32 s18, s79, s66
	v_lshl_add_u64 v[144:145], v[144:145], 0, s[10:11]
	s_mov_b32 m0, s18
	ds_read_b128 v[188:191], v151 offset:49152
	ds_read_b128 v[192:195], v151 offset:50176
	ds_read_b128 v[196:199], v151 offset:51200
	ds_read_b128 v[200:203], v151 offset:52224
	ds_read_b128 v[204:207], v151 offset:53248
	ds_read_b128 v[208:211], v151 offset:54272
	ds_read_b128 v[212:215], v151 offset:55296
	ds_read_b128 v[216:219], v151 offset:56320
	global_load_lds_dwordx4 v[144:145], off
	s_add_i32 m0, s18, 0x2000
	s_add_u32 s18, s60, 0x40080
	v_lshl_add_u64 v[144:145], v[220:221], 0, s[10:11]
	s_addc_u32 s19, s61, 0
	s_add_i32 s60, s89, s66
	global_load_lds_dwordx4 v[144:145], off
	v_lshl_add_u64 v[144:145], s[18:19], 0, v[130:131]
	s_mov_b32 m0, s60
	s_nop 0
	global_load_lds_dwordx4 v[144:145], off
	v_lshl_add_u64 v[144:145], s[18:19], 0, v[134:135]
	s_add_i32 m0, s60, 0x2000
	s_nop 0
	global_load_lds_dwordx4 v[144:145], off
	v_lshl_add_u64 v[144:145], v[222:223], 0, s[10:11]
	s_mov_b32 m0, s71
	s_nop 0
	global_load_lds_dwordx4 v[144:145], off
	v_lshl_add_u64 v[144:145], v[224:225], 0, s[10:11]
	s_mov_b32 m0, s72
	s_nop 0
	global_load_lds_dwordx4 v[144:145], off
	s_waitcnt vmcnt(8)
	s_waitcnt lgkmcnt(0)
	s_barrier
	s_setprio 1
	s_waitcnt lgkmcnt(0)
	v_mfma_f32_16x16x32_bf16 v[60:63], v[152:155], v[188:191], v[60:63]
	v_mfma_f32_16x16x32_bf16 v[60:63], v[156:159], v[192:195], v[60:63]
	v_mfma_f32_16x16x32_bf16 v[56:59], v[160:163], v[188:191], v[56:59]
	v_mfma_f32_16x16x32_bf16 v[56:59], v[164:167], v[192:195], v[56:59]
	v_mfma_f32_16x16x32_bf16 v[52:55], v[152:155], v[196:199], v[52:55]
	v_mfma_f32_16x16x32_bf16 v[52:55], v[156:159], v[200:203], v[52:55]
	v_mfma_f32_16x16x32_bf16 v[44:47], v[160:163], v[196:199], v[44:47]
	v_mfma_f32_16x16x32_bf16 v[44:47], v[164:167], v[200:203], v[44:47]
	v_mfma_f32_16x16x32_bf16 v[36:39], v[152:155], v[204:207], v[36:39]
	v_mfma_f32_16x16x32_bf16 v[36:39], v[156:159], v[208:211], v[36:39]
	v_mfma_f32_16x16x32_bf16 v[28:31], v[160:163], v[204:207], v[28:31]
	v_mfma_f32_16x16x32_bf16 v[28:31], v[164:167], v[208:211], v[28:31]
	v_mfma_f32_16x16x32_bf16 v[20:23], v[152:155], v[212:215], v[20:23]
	v_mfma_f32_16x16x32_bf16 v[20:23], v[156:159], v[216:219], v[20:23]
	v_mfma_f32_16x16x32_bf16 v[12:15], v[160:163], v[212:215], v[12:15]
	v_mfma_f32_16x16x32_bf16 v[12:15], v[164:167], v[216:219], v[12:15]
	v_mfma_f32_16x16x32_bf16 v[48:51], v[168:171], v[188:191], v[48:51]
	v_mfma_f32_16x16x32_bf16 v[48:51], v[172:175], v[192:195], v[48:51]
	v_mfma_f32_16x16x32_bf16 v[40:43], v[176:179], v[188:191], v[40:43]
	v_mfma_f32_16x16x32_bf16 v[40:43], v[184:187], v[192:195], v[40:43]
	v_mfma_f32_16x16x32_bf16 v[32:35], v[168:171], v[196:199], v[32:35]
	v_mfma_f32_16x16x32_bf16 v[32:35], v[172:175], v[200:203], v[32:35]
	v_mfma_f32_16x16x32_bf16 v[24:27], v[176:179], v[196:199], v[24:27]
	v_mfma_f32_16x16x32_bf16 v[24:27], v[184:187], v[200:203], v[24:27]
	v_mfma_f32_16x16x32_bf16 v[16:19], v[168:171], v[204:207], v[16:19]
	v_mfma_f32_16x16x32_bf16 v[16:19], v[172:175], v[208:211], v[16:19]
	v_mfma_f32_16x16x32_bf16 v[8:11], v[176:179], v[204:207], v[8:11]
	v_mfma_f32_16x16x32_bf16 v[8:11], v[184:187], v[208:211], v[8:11]
	v_mfma_f32_16x16x32_bf16 v[4:7], v[168:171], v[212:215], v[4:7]
	v_mfma_f32_16x16x32_bf16 v[4:7], v[172:175], v[216:219], v[4:7]
	s_setprio 2
	s_barrier
	v_mfma_f32_16x16x32_bf16 v[0:3], v[176:179], v[212:215], v[0:3]
	v_mfma_f32_16x16x32_bf16 v[0:3], v[184:187], v[216:219], v[0:3]
	s_setprio 0
	s_add_i32 s88, s88, 2
	s_add_u32 s58, s58, 0x100
	s_addc_u32 s59, s59, 0
	s_add_u32 s86, s86, 0x100
	s_addc_u32 s87, s87, 0
	s_cmp_gt_u32 s88, 13
	s_cbranch_scc0 .LBB0_601
	s_and_b64 vcc, exec, s[12:13]
	s_cbranch_vccz .LBB0_604
	s_barrier

.LBB0_723:
	s_ashr_i32 s31, s30, 31
	s_lshl_b64 s[36:37], s[30:31], 19
	s_add_u32 s36, s80, s36
	s_addc_u32 s37, s81, s37
	s_and_b64 s[44:45], s[10:11], exec
	s_cselect_b32 s31, s37, s49
	s_cselect_b32 s70, s36, s48
	s_ashr_i32 s19, s18, 31
	s_lshl_b64 s[44:45], s[18:19], 19
	s_add_u32 s44, s56, s44
	s_addc_u32 s45, s57, s45
	s_and_b64 s[54:55], s[10:11], exec
	s_cselect_b32 s19, s45, s53
	s_cselect_b32 s71, s44, s52
	s_add_u32 s48, s48, 0x40080
	s_addc_u32 s49, s49, 0
	s_add_u32 s72, s52, 0x100
	s_addc_u32 s73, s53, 0
	s_mov_b32 s74, -2
	ds_read_b128 v[140:143], v147
	ds_read_b128 v[150:153], v147 offset:1024
	ds_read_b128 v[154:157], v147 offset:2048
	ds_read_b128 v[158:161], v147 offset:3072
	ds_read_b128 v[162:165], v148
	ds_read_b128 v[166:169], v148 offset:1024
	ds_read_b128 v[170:173], v148 offset:2048
	ds_read_b128 v[174:177], v148 offset:3072
	s_add_u32 s52, s48, 0xfffc0080
	s_addc_u32 s53, s49, -1
	s_cmp_eq_u32 s74, 12
	s_cselect_b32 s55, s31, s53
	s_cselect_b32 s54, s70, s52
	s_cselect_b32 s53, s19, s73
	s_cselect_b32 s52, s71, s72
	v_lshl_add_u64 v[178:179], s[48:49], 0, v[132:133]
	s_add_i32 m0, s47, 0xc000
	ds_read_b128 v[184:187], v149
	ds_read_b128 v[188:191], v149 offset:1024
	ds_read_b128 v[192:195], v149 offset:2048
	ds_read_b128 v[196:199], v149 offset:3072
	ds_read_b128 v[200:203], v149 offset:4096
	ds_read_b128 v[204:207], v149 offset:5120
	ds_read_b128 v[208:211], v149 offset:6144
	ds_read_b128 v[212:215], v149 offset:7168
	global_load_lds_dwordx4 v[178:179], off
	v_lshl_add_u64 v[178:179], s[48:49], 0, v[134:135]
	s_add_i32 m0, s47, 0xe000
	s_nop 0
	global_load_lds_dwordx4 v[178:179], off
	s_waitcnt vmcnt(8)
	s_waitcnt lgkmcnt(0)
	s_barrier
	s_setprio 1
	s_waitcnt lgkmcnt(0)
	v_mfma_f32_16x16x32_bf16 v[124:127], v[140:143], v[184:187], 0
	v_mfma_f32_16x16x32_bf16 v[124:127], v[150:153], v[188:191], v[124:127]
	v_mfma_f32_16x16x32_bf16 v[120:123], v[154:157], v[184:187], 0
	v_mfma_f32_16x16x32_bf16 v[120:123], v[158:161], v[188:191], v[120:123]
	v_mfma_f32_16x16x32_bf16 v[108:111], v[140:143], v[192:195], 0
	v_mfma_f32_16x16x32_bf16 v[108:111], v[150:153], v[196:199], v[108:111]
	v_mfma_f32_16x16x32_bf16 v[104:107], v[154:157], v[192:195], 0
	v_mfma_f32_16x16x32_bf16 v[104:107], v[158:161], v[196:199], v[104:107]
	v_mfma_f32_16x16x32_bf16 v[92:95], v[140:143], v[200:203], 0
	v_mfma_f32_16x16x32_bf16 v[92:95], v[150:153], v[204:207], v[92:95]
	v_mfma_f32_16x16x32_bf16 v[88:91], v[154:157], v[200:203], 0
	v_mfma_f32_16x16x32_bf16 v[88:91], v[158:161], v[204:207], v[88:91]
	v_mfma_f32_16x16x32_bf16 v[76:79], v[140:143], v[208:211], 0
	v_mfma_f32_16x16x32_bf16 v[76:79], v[150:153], v[212:215], v[76:79]
	v_mfma_f32_16x16x32_bf16 v[72:75], v[154:157], v[208:211], 0
	v_mfma_f32_16x16x32_bf16 v[72:75], v[158:161], v[212:215], v[72:75]
	v_mfma_f32_16x16x32_bf16 v[116:119], v[162:165], v[184:187], 0
	v_mfma_f32_16x16x32_bf16 v[116:119], v[166:169], v[188:191], v[116:119]
	v_mfma_f32_16x16x32_bf16 v[112:115], v[170:173], v[184:187], 0
	v_mfma_f32_16x16x32_bf16 v[112:115], v[174:177], v[188:191], v[112:115]
	v_mfma_f32_16x16x32_bf16 v[100:103], v[162:165], v[192:195], 0
	v_mfma_f32_16x16x32_bf16 v[100:103], v[166:169], v[196:199], v[100:103]
	v_mfma_f32_16x16x32_bf16 v[96:99], v[170:173], v[192:195], 0
	v_mfma_f32_16x16x32_bf16 v[96:99], v[174:177], v[196:199], v[96:99]
	v_mfma_f32_16x16x32_bf16 v[84:87], v[162:165], v[200:203], 0
	v_mfma_f32_16x16x32_bf16 v[84:87], v[166:169], v[204:207], v[84:87]
	v_mfma_f32_16x16x32_bf16 v[80:83], v[170:173], v[200:203], 0
	v_mfma_f32_16x16x32_bf16 v[80:83], v[174:177], v[204:207], v[80:83]
	v_mfma_f32_16x16x32_bf16 v[68:71], v[162:165], v[208:211], 0
	v_mfma_f32_16x16x32_bf16 v[68:71], v[166:169], v[212:215], v[68:71]
	s_setprio 2
	s_barrier
	v_mfma_f32_16x16x32_bf16 v[64:67], v[170:173], v[208:211], 0
	v_mfma_f32_16x16x32_bf16 v[64:67], v[174:177], v[212:215], v[64:67]
	s_setprio 0
	s_add_i32 s75, s66, s58
	v_lshl_add_u64 v[178:179], s[52:53], 0, v[130:131]
	s_mov_b32 m0, s75
	ds_read_b128 v[184:187], v149 offset:16384
	ds_read_b128 v[188:191], v149 offset:17408
	ds_read_b128 v[192:195], v149 offset:18432
	ds_read_b128 v[196:199], v149 offset:19456
	ds_read_b128 v[200:203], v149 offset:20480
	ds_read_b128 v[204:207], v149 offset:21504
	ds_read_b128 v[208:211], v149 offset:22528
	ds_read_b128 v[212:215], v149 offset:23552
	global_load_lds_dwordx4 v[178:179], off
	s_add_i32 m0, s75, 0x2000
	s_add_u32 s76, s52, 0x40000
	v_lshl_add_u64 v[216:217], s[52:53], 0, v[128:129]
	s_addc_u32 s77, s53, 0
	s_add_i32 s75, s67, s58
	global_load_lds_dwordx4 v[216:217], off
	v_lshl_add_u64 v[218:219], s[76:77], 0, v[130:131]
	s_mov_b32 m0, s75
	v_lshl_add_u64 v[220:221], s[54:55], 0, v[128:129]
	global_load_lds_dwordx4 v[218:219], off
	v_lshl_add_u64 v[218:219], s[76:77], 0, v[128:129]
	s_add_i32 m0, s75, 0x2000
	s_nop 0
	global_load_lds_dwordx4 v[218:219], off
	v_lshl_add_u64 v[218:219], s[54:55], 0, v[130:131]
	s_mov_b32 m0, s47
	s_nop 0
	global_load_lds_dwordx4 v[218:219], off
	s_mov_b32 m0, s60
	s_nop 0
	global_load_lds_dwordx4 v[220:221], off
	s_waitcnt vmcnt(8)
	s_waitcnt lgkmcnt(0)
	s_barrier
	s_setprio 1
	s_waitcnt lgkmcnt(0)
	v_mfma_f32_16x16x32_bf16 v[60:63], v[140:143], v[184:187], 0
	v_mfma_f32_16x16x32_bf16 v[60:63], v[150:153], v[188:191], v[60:63]
	v_mfma_f32_16x16x32_bf16 v[56:59], v[154:157], v[184:187], 0
	v_mfma_f32_16x16x32_bf16 v[56:59], v[158:161], v[188:191], v[56:59]
	v_mfma_f32_16x16x32_bf16 v[44:47], v[140:143], v[192:195], 0
	v_mfma_f32_16x16x32_bf16 v[44:47], v[150:153], v[196:199], v[44:47]
	v_mfma_f32_16x16x32_bf16 v[40:43], v[154:157], v[192:195], 0
	v_mfma_f32_16x16x32_bf16 v[40:43], v[158:161], v[196:199], v[40:43]
	v_mfma_f32_16x16x32_bf16 v[28:31], v[140:143], v[200:203], 0
	v_mfma_f32_16x16x32_bf16 v[28:31], v[150:153], v[204:207], v[28:31]
	v_mfma_f32_16x16x32_bf16 v[24:27], v[154:157], v[200:203], 0
	v_mfma_f32_16x16x32_bf16 v[24:27], v[158:161], v[204:207], v[24:27]
	v_mfma_f32_16x16x32_bf16 v[12:15], v[140:143], v[208:211], 0
	v_mfma_f32_16x16x32_bf16 v[12:15], v[150:153], v[212:215], v[12:15]
	v_mfma_f32_16x16x32_bf16 v[8:11], v[154:157], v[208:211], 0
	v_mfma_f32_16x16x32_bf16 v[8:11], v[158:161], v[212:215], v[8:11]
	v_mfma_f32_16x16x32_bf16 v[52:55], v[162:165], v[184:187], 0
	v_mfma_f32_16x16x32_bf16 v[52:55], v[166:169], v[188:191], v[52:55]
	v_mfma_f32_16x16x32_bf16 v[48:51], v[170:173], v[184:187], 0
	v_mfma_f32_16x16x32_bf16 v[48:51], v[174:177], v[188:191], v[48:51]
	v_mfma_f32_16x16x32_bf16 v[36:39], v[162:165], v[192:195], 0
	v_mfma_f32_16x16x32_bf16 v[36:39], v[166:169], v[196:199], v[36:39]
	v_mfma_f32_16x16x32_bf16 v[32:35], v[170:173], v[192:195], 0
	v_mfma_f32_16x16x32_bf16 v[32:35], v[174:177], v[196:199], v[32:35]
	v_mfma_f32_16x16x32_bf16 v[20:23], v[162:165], v[200:203], 0
	v_mfma_f32_16x16x32_bf16 v[20:23], v[166:169], v[204:207], v[20:23]
	v_mfma_f32_16x16x32_bf16 v[16:19], v[170:173], v[200:203], 0
	v_mfma_f32_16x16x32_bf16 v[16:19], v[174:177], v[204:207], v[16:19]
	v_mfma_f32_16x16x32_bf16 v[4:7], v[162:165], v[208:211], 0
	v_mfma_f32_16x16x32_bf16 v[4:7], v[166:169], v[212:215], v[4:7]
	s_setprio 2
	s_barrier
	v_mfma_f32_16x16x32_bf16 v[0:3], v[170:173], v[208:211], 0
	v_mfma_f32_16x16x32_bf16 v[0:3], v[174:177], v[212:215], v[0:3]
	s_setprio 0
	s_branch .Lmid_gemm4
.LBB0_724:
	ds_read_b128 v[140:143], v147
	ds_read_b128 v[150:153], v147 offset:1024
	ds_read_b128 v[154:157], v147 offset:2048
	ds_read_b128 v[158:161], v147 offset:3072
	ds_read_b128 v[162:165], v148
	ds_read_b128 v[166:169], v148 offset:1024
	ds_read_b128 v[170:173], v148 offset:2048
	ds_read_b128 v[174:177], v148 offset:3072
	s_add_u32 s52, s48, 0xfffc0080
	s_addc_u32 s53, s49, -1
	s_cmp_eq_u32 s74, 12
	s_cselect_b32 s55, s31, s53
	s_cselect_b32 s54, s70, s52
	s_cselect_b32 s53, s19, s73
	s_cselect_b32 s52, s71, s72
	v_lshl_add_u64 v[178:179], s[48:49], 0, v[132:133]
	s_add_i32 m0, s47, 0xc000
	ds_read_b128 v[184:187], v149
	ds_read_b128 v[188:191], v149 offset:1024
	ds_read_b128 v[192:195], v149 offset:2048
	ds_read_b128 v[196:199], v149 offset:3072
	ds_read_b128 v[200:203], v149 offset:4096
	ds_read_b128 v[204:207], v149 offset:5120
	ds_read_b128 v[208:211], v149 offset:6144
	ds_read_b128 v[212:215], v149 offset:7168
	global_load_lds_dwordx4 v[178:179], off
	v_lshl_add_u64 v[178:179], s[48:49], 0, v[134:135]
	s_add_i32 m0, s47, 0xe000
	s_nop 0
	global_load_lds_dwordx4 v[178:179], off
	s_waitcnt vmcnt(8)
	s_waitcnt lgkmcnt(0)
	s_barrier
	s_setprio 1
	s_waitcnt lgkmcnt(0)
	v_mfma_f32_16x16x32_bf16 v[124:127], v[140:143], v[184:187], v[124:127]
	v_mfma_f32_16x16x32_bf16 v[124:127], v[150:153], v[188:191], v[124:127]
	v_mfma_f32_16x16x32_bf16 v[120:123], v[154:157], v[184:187], v[120:123]
	v_mfma_f32_16x16x32_bf16 v[120:123], v[158:161], v[188:191], v[120:123]
	v_mfma_f32_16x16x32_bf16 v[108:111], v[140:143], v[192:195], v[108:111]
	v_mfma_f32_16x16x32_bf16 v[108:111], v[150:153], v[196:199], v[108:111]
	v_mfma_f32_16x16x32_bf16 v[104:107], v[154:157], v[192:195], v[104:107]
	v_mfma_f32_16x16x32_bf16 v[104:107], v[158:161], v[196:199], v[104:107]
	v_mfma_f32_16x16x32_bf16 v[92:95], v[140:143], v[200:203], v[92:95]
	v_mfma_f32_16x16x32_bf16 v[92:95], v[150:153], v[204:207], v[92:95]
	v_mfma_f32_16x16x32_bf16 v[88:91], v[154:157], v[200:203], v[88:91]
	v_mfma_f32_16x16x32_bf16 v[88:91], v[158:161], v[204:207], v[88:91]
	v_mfma_f32_16x16x32_bf16 v[76:79], v[140:143], v[208:211], v[76:79]
	v_mfma_f32_16x16x32_bf16 v[76:79], v[150:153], v[212:215], v[76:79]
	v_mfma_f32_16x16x32_bf16 v[72:75], v[154:157], v[208:211], v[72:75]
	v_mfma_f32_16x16x32_bf16 v[72:75], v[158:161], v[212:215], v[72:75]
	v_mfma_f32_16x16x32_bf16 v[116:119], v[162:165], v[184:187], v[116:119]
	v_mfma_f32_16x16x32_bf16 v[116:119], v[166:169], v[188:191], v[116:119]
	v_mfma_f32_16x16x32_bf16 v[112:115], v[170:173], v[184:187], v[112:115]
	v_mfma_f32_16x16x32_bf16 v[112:115], v[174:177], v[188:191], v[112:115]
	v_mfma_f32_16x16x32_bf16 v[100:103], v[162:165], v[192:195], v[100:103]
	v_mfma_f32_16x16x32_bf16 v[100:103], v[166:169], v[196:199], v[100:103]
	v_mfma_f32_16x16x32_bf16 v[96:99], v[170:173], v[192:195], v[96:99]
	v_mfma_f32_16x16x32_bf16 v[96:99], v[174:177], v[196:199], v[96:99]
	v_mfma_f32_16x16x32_bf16 v[84:87], v[162:165], v[200:203], v[84:87]
	v_mfma_f32_16x16x32_bf16 v[84:87], v[166:169], v[204:207], v[84:87]
	v_mfma_f32_16x16x32_bf16 v[80:83], v[170:173], v[200:203], v[80:83]
	v_mfma_f32_16x16x32_bf16 v[80:83], v[174:177], v[204:207], v[80:83]
	v_mfma_f32_16x16x32_bf16 v[68:71], v[162:165], v[208:211], v[68:71]
	v_mfma_f32_16x16x32_bf16 v[68:71], v[166:169], v[212:215], v[68:71]
	s_setprio 2
	s_barrier
	v_mfma_f32_16x16x32_bf16 v[64:67], v[170:173], v[208:211], v[64:67]
	v_mfma_f32_16x16x32_bf16 v[64:67], v[174:177], v[212:215], v[64:67]
	s_setprio 0
	s_add_i32 s75, s66, s58
	v_lshl_add_u64 v[178:179], s[52:53], 0, v[130:131]
	s_mov_b32 m0, s75
	ds_read_b128 v[184:187], v149 offset:16384
	ds_read_b128 v[188:191], v149 offset:17408
	ds_read_b128 v[192:195], v149 offset:18432
	ds_read_b128 v[196:199], v149 offset:19456
	ds_read_b128 v[200:203], v149 offset:20480
	ds_read_b128 v[204:207], v149 offset:21504
	ds_read_b128 v[208:211], v149 offset:22528
	ds_read_b128 v[212:215], v149 offset:23552
	global_load_lds_dwordx4 v[178:179], off
	s_add_i32 m0, s75, 0x2000
	s_add_u32 s76, s52, 0x40000
	v_lshl_add_u64 v[216:217], s[52:53], 0, v[128:129]
	s_addc_u32 s77, s53, 0
	s_add_i32 s75, s67, s58
	global_load_lds_dwordx4 v[216:217], off
	v_lshl_add_u64 v[218:219], s[76:77], 0, v[130:131]
	s_mov_b32 m0, s75
	v_lshl_add_u64 v[220:221], s[54:55], 0, v[128:129]
	global_load_lds_dwordx4 v[218:219], off
	v_lshl_add_u64 v[218:219], s[76:77], 0, v[128:129]
	s_add_i32 m0, s75, 0x2000
	s_nop 0
	global_load_lds_dwordx4 v[218:219], off
	v_lshl_add_u64 v[218:219], s[54:55], 0, v[130:131]
	s_mov_b32 m0, s47
	s_nop 0
	global_load_lds_dwordx4 v[218:219], off
	s_mov_b32 m0, s60
	s_nop 0
	global_load_lds_dwordx4 v[220:221], off
	s_waitcnt vmcnt(8)
	s_waitcnt lgkmcnt(0)
	s_barrier
	s_setprio 1
	s_waitcnt lgkmcnt(0)
	v_mfma_f32_16x16x32_bf16 v[60:63], v[140:143], v[184:187], v[60:63]
	v_mfma_f32_16x16x32_bf16 v[60:63], v[150:153], v[188:191], v[60:63]
	v_mfma_f32_16x16x32_bf16 v[56:59], v[154:157], v[184:187], v[56:59]
	v_mfma_f32_16x16x32_bf16 v[56:59], v[158:161], v[188:191], v[56:59]
	v_mfma_f32_16x16x32_bf16 v[44:47], v[140:143], v[192:195], v[44:47]
	v_mfma_f32_16x16x32_bf16 v[44:47], v[150:153], v[196:199], v[44:47]
	v_mfma_f32_16x16x32_bf16 v[40:43], v[154:157], v[192:195], v[40:43]
	v_mfma_f32_16x16x32_bf16 v[40:43], v[158:161], v[196:199], v[40:43]
	v_mfma_f32_16x16x32_bf16 v[28:31], v[140:143], v[200:203], v[28:31]
	v_mfma_f32_16x16x32_bf16 v[28:31], v[150:153], v[204:207], v[28:31]
	v_mfma_f32_16x16x32_bf16 v[24:27], v[154:157], v[200:203], v[24:27]
	v_mfma_f32_16x16x32_bf16 v[24:27], v[158:161], v[204:207], v[24:27]
	v_mfma_f32_16x16x32_bf16 v[12:15], v[140:143], v[208:211], v[12:15]
	v_mfma_f32_16x16x32_bf16 v[12:15], v[150:153], v[212:215], v[12:15]
	v_mfma_f32_16x16x32_bf16 v[8:11], v[154:157], v[208:211], v[8:11]
	v_mfma_f32_16x16x32_bf16 v[8:11], v[158:161], v[212:215], v[8:11]
	v_mfma_f32_16x16x32_bf16 v[52:55], v[162:165], v[184:187], v[52:55]
	v_mfma_f32_16x16x32_bf16 v[52:55], v[166:169], v[188:191], v[52:55]
	v_mfma_f32_16x16x32_bf16 v[48:51], v[170:173], v[184:187], v[48:51]
	v_mfma_f32_16x16x32_bf16 v[48:51], v[174:177], v[188:191], v[48:51]
	v_mfma_f32_16x16x32_bf16 v[36:39], v[162:165], v[192:195], v[36:39]
	v_mfma_f32_16x16x32_bf16 v[36:39], v[166:169], v[196:199], v[36:39]
	v_mfma_f32_16x16x32_bf16 v[32:35], v[170:173], v[192:195], v[32:35]
	v_mfma_f32_16x16x32_bf16 v[32:35], v[174:177], v[196:199], v[32:35]
	v_mfma_f32_16x16x32_bf16 v[20:23], v[162:165], v[200:203], v[20:23]
	v_mfma_f32_16x16x32_bf16 v[20:23], v[166:169], v[204:207], v[20:23]
	v_mfma_f32_16x16x32_bf16 v[16:19], v[170:173], v[200:203], v[16:19]
	v_mfma_f32_16x16x32_bf16 v[16:19], v[174:177], v[204:207], v[16:19]
	v_mfma_f32_16x16x32_bf16 v[4:7], v[162:165], v[208:211], v[4:7]
	v_mfma_f32_16x16x32_bf16 v[4:7], v[166:169], v[212:215], v[4:7]
	s_setprio 2
	s_barrier
	v_mfma_f32_16x16x32_bf16 v[0:3], v[170:173], v[208:211], v[0:3]
	v_mfma_f32_16x16x32_bf16 v[0:3], v[174:177], v[212:215], v[0:3]
	s_setprio 0
.Lmid_gemm4:
	s_add_i32 s75, 0, 0x18000
	s_add_i32 s76, 0, 0x1c000
	v_add_u32_e32 v158, s75, v145
	v_add_u32_e32 v174, s76, v145
	ds_read_b128 v[140:143], v158
	ds_read_b128 v[150:153], v158 offset:1024
	ds_read_b128 v[154:157], v158 offset:2048
	ds_read_b128 v[158:161], v158 offset:3072
	ds_read_b128 v[162:165], v174
	ds_read_b128 v[166:169], v174 offset:1024
	ds_read_b128 v[170:173], v174 offset:2048
	ds_read_b128 v[174:177], v174 offset:3072
	s_add_u32 s54, s54, 0x40000
	s_addc_u32 s55, s55, 0
	s_mov_b32 m0, s61
	v_lshl_add_u64 v[222:223], s[54:55], 0, v[130:131]
	ds_read_b128 v[184:187], v149 offset:32768
	ds_read_b128 v[188:191], v149 offset:33792
	ds_read_b128 v[192:195], v149 offset:34816
	ds_read_b128 v[196:199], v149 offset:35840
	ds_read_b128 v[200:203], v149 offset:36864
	ds_read_b128 v[204:207], v149 offset:37888
	ds_read_b128 v[208:211], v149 offset:38912
	ds_read_b128 v[212:215], v149 offset:39936
	global_load_lds_dwordx4 v[222:223], off
	v_lshl_add_u64 v[222:223], s[54:55], 0, v[128:129]
	s_mov_b32 m0, s62
	s_nop 0
	global_load_lds_dwordx4 v[222:223], off
	s_waitcnt vmcnt(8)
	s_waitcnt lgkmcnt(0)
	s_barrier
	s_setprio 1
	s_waitcnt lgkmcnt(0)
	v_mfma_f32_16x16x32_bf16 v[124:127], v[140:143], v[184:187], v[124:127]
	v_mfma_f32_16x16x32_bf16 v[124:127], v[150:153], v[188:191], v[124:127]
	v_mfma_f32_16x16x32_bf16 v[120:123], v[154:157], v[184:187], v[120:123]
	v_mfma_f32_16x16x32_bf16 v[120:123], v[158:161], v[188:191], v[120:123]
	v_mfma_f32_16x16x32_bf16 v[108:111], v[140:143], v[192:195], v[108:111]
	v_mfma_f32_16x16x32_bf16 v[108:111], v[150:153], v[196:199], v[108:111]
	v_mfma_f32_16x16x32_bf16 v[104:107], v[154:157], v[192:195], v[104:107]
	v_mfma_f32_16x16x32_bf16 v[104:107], v[158:161], v[196:199], v[104:107]
	v_mfma_f32_16x16x32_bf16 v[92:95], v[140:143], v[200:203], v[92:95]
	v_mfma_f32_16x16x32_bf16 v[92:95], v[150:153], v[204:207], v[92:95]
	v_mfma_f32_16x16x32_bf16 v[88:91], v[154:157], v[200:203], v[88:91]
	v_mfma_f32_16x16x32_bf16 v[88:91], v[158:161], v[204:207], v[88:91]
	v_mfma_f32_16x16x32_bf16 v[76:79], v[140:143], v[208:211], v[76:79]
	v_mfma_f32_16x16x32_bf16 v[76:79], v[150:153], v[212:215], v[76:79]
	v_mfma_f32_16x16x32_bf16 v[72:75], v[154:157], v[208:211], v[72:75]
	v_mfma_f32_16x16x32_bf16 v[72:75], v[158:161], v[212:215], v[72:75]
	v_mfma_f32_16x16x32_bf16 v[116:119], v[162:165], v[184:187], v[116:119]
	v_mfma_f32_16x16x32_bf16 v[116:119], v[166:169], v[188:191], v[116:119]
	v_mfma_f32_16x16x32_bf16 v[112:115], v[170:173], v[184:187], v[112:115]
	v_mfma_f32_16x16x32_bf16 v[112:115], v[174:177], v[188:191], v[112:115]
	v_mfma_f32_16x16x32_bf16 v[100:103], v[162:165], v[192:195], v[100:103]
	v_mfma_f32_16x16x32_bf16 v[100:103], v[166:169], v[196:199], v[100:103]
	v_mfma_f32_16x16x32_bf16 v[96:99], v[170:173], v[192:195], v[96:99]
	v_mfma_f32_16x16x32_bf16 v[96:99], v[174:177], v[196:199], v[96:99]
	v_mfma_f32_16x16x32_bf16 v[84:87], v[162:165], v[200:203], v[84:87]
	v_mfma_f32_16x16x32_bf16 v[84:87], v[166:169], v[204:207], v[84:87]
	v_mfma_f32_16x16x32_bf16 v[80:83], v[170:173], v[200:203], v[80:83]
	v_mfma_f32_16x16x32_bf16 v[80:83], v[174:177], v[204:207], v[80:83]
	v_mfma_f32_16x16x32_bf16 v[68:71], v[162:165], v[208:211], v[68:71]
	v_mfma_f32_16x16x32_bf16 v[68:71], v[166:169], v[212:215], v[68:71]
	s_setprio 2
	s_barrier
	v_mfma_f32_16x16x32_bf16 v[64:67], v[170:173], v[208:211], v[64:67]
	v_mfma_f32_16x16x32_bf16 v[64:67], v[174:177], v[212:215], v[64:67]
	s_setprio 0
	s_add_i32 s54, s75, s58
	v_lshl_add_u64 v[178:179], v[178:179], 0, s[12:13]
	s_mov_b32 m0, s54
	ds_read_b128 v[184:187], v149 offset:49152
	ds_read_b128 v[188:191], v149 offset:50176
	ds_read_b128 v[192:195], v149 offset:51200
	ds_read_b128 v[196:199], v149 offset:52224
	ds_read_b128 v[200:203], v149 offset:53248
	ds_read_b128 v[204:207], v149 offset:54272
	ds_read_b128 v[208:211], v149 offset:55296
	ds_read_b128 v[212:215], v149 offset:56320
	global_load_lds_dwordx4 v[178:179], off
	s_add_i32 m0, s54, 0x2000
	s_add_u32 s52, s52, 0x40080
	v_lshl_add_u64 v[178:179], v[216:217], 0, s[12:13]
	s_addc_u32 s53, s53, 0
	s_add_i32 s54, s76, s58
	global_load_lds_dwordx4 v[178:179], off
	v_lshl_add_u64 v[178:179], s[52:53], 0, v[130:131]
	s_mov_b32 m0, s54
	s_nop 0
	global_load_lds_dwordx4 v[178:179], off
	v_lshl_add_u64 v[178:179], s[52:53], 0, v[128:129]
	s_add_i32 m0, s54, 0x2000
	s_nop 0
	global_load_lds_dwordx4 v[178:179], off
	v_lshl_add_u64 v[178:179], v[218:219], 0, s[12:13]
	s_mov_b32 m0, s64
	s_nop 0
	global_load_lds_dwordx4 v[178:179], off
	v_lshl_add_u64 v[178:179], v[220:221], 0, s[12:13]
	s_mov_b32 m0, s65
	s_nop 0
	global_load_lds_dwordx4 v[178:179], off
	s_waitcnt vmcnt(8)
	s_waitcnt lgkmcnt(0)
	s_barrier
	s_setprio 1
	s_waitcnt lgkmcnt(0)
	v_mfma_f32_16x16x32_bf16 v[60:63], v[140:143], v[184:187], v[60:63]
	v_mfma_f32_16x16x32_bf16 v[60:63], v[150:153], v[188:191], v[60:63]
	v_mfma_f32_16x16x32_bf16 v[56:59], v[154:157], v[184:187], v[56:59]
	v_mfma_f32_16x16x32_bf16 v[56:59], v[158:161], v[188:191], v[56:59]
	v_mfma_f32_16x16x32_bf16 v[44:47], v[140:143], v[192:195], v[44:47]
	v_mfma_f32_16x16x32_bf16 v[44:47], v[150:153], v[196:199], v[44:47]
	v_mfma_f32_16x16x32_bf16 v[40:43], v[154:157], v[192:195], v[40:43]
	v_mfma_f32_16x16x32_bf16 v[40:43], v[158:161], v[196:199], v[40:43]
	v_mfma_f32_16x16x32_bf16 v[28:31], v[140:143], v[200:203], v[28:31]
	v_mfma_f32_16x16x32_bf16 v[28:31], v[150:153], v[204:207], v[28:31]
	v_mfma_f32_16x16x32_bf16 v[24:27], v[154:157], v[200:203], v[24:27]
	v_mfma_f32_16x16x32_bf16 v[24:27], v[158:161], v[204:207], v[24:27]
	v_mfma_f32_16x16x32_bf16 v[12:15], v[140:143], v[208:211], v[12:15]
	v_mfma_f32_16x16x32_bf16 v[12:15], v[150:153], v[212:215], v[12:15]
	v_mfma_f32_16x16x32_bf16 v[8:11], v[154:157], v[208:211], v[8:11]
	v_mfma_f32_16x16x32_bf16 v[8:11], v[158:161], v[212:215], v[8:11]
	v_mfma_f32_16x16x32_bf16 v[52:55], v[162:165], v[184:187], v[52:55]
	v_mfma_f32_16x16x32_bf16 v[52:55], v[166:169], v[188:191], v[52:55]
	v_mfma_f32_16x16x32_bf16 v[48:51], v[170:173], v[184:187], v[48:51]
	v_mfma_f32_16x16x32_bf16 v[48:51], v[174:177], v[188:191], v[48:51]
	v_mfma_f32_16x16x32_bf16 v[36:39], v[162:165], v[192:195], v[36:39]
	v_mfma_f32_16x16x32_bf16 v[36:39], v[166:169], v[196:199], v[36:39]
	v_mfma_f32_16x16x32_bf16 v[32:35], v[170:173], v[192:195], v[32:35]
	v_mfma_f32_16x16x32_bf16 v[32:35], v[174:177], v[196:199], v[32:35]
	v_mfma_f32_16x16x32_bf16 v[20:23], v[162:165], v[200:203], v[20:23]
	v_mfma_f32_16x16x32_bf16 v[20:23], v[166:169], v[204:207], v[20:23]
	v_mfma_f32_16x16x32_bf16 v[16:19], v[170:173], v[200:203], v[16:19]
	v_mfma_f32_16x16x32_bf16 v[16:19], v[174:177], v[204:207], v[16:19]
	v_mfma_f32_16x16x32_bf16 v[4:7], v[162:165], v[208:211], v[4:7]
	v_mfma_f32_16x16x32_bf16 v[4:7], v[166:169], v[212:215], v[4:7]
	s_setprio 2
	s_barrier
	v_mfma_f32_16x16x32_bf16 v[0:3], v[170:173], v[208:211], v[0:3]
	v_mfma_f32_16x16x32_bf16 v[0:3], v[174:177], v[212:215], v[0:3]
	s_setprio 0
	s_add_i32 s74, s74, 2
	s_add_u32 s48, s48, 0x100
	s_addc_u32 s49, s49, 0
	s_add_u32 s72, s72, 0x100
	s_addc_u32 s73, s73, 0
	s_cmp_gt_u32 s74, 13
	s_cbranch_scc0 .LBB0_724
	s_and_b64 vcc, exec, s[16:17]
	s_cbranch_vccz .LBB0_727
	s_barrier

.LBB0_803:
	s_add_u32 s84, s54, 0x100
	s_addc_u32 s85, s55, 0
	s_mov_b32 s86, -2
	ds_read_b128 v[152:155], v149
	ds_read_b128 v[156:159], v149 offset:1024
	ds_read_b128 v[160:163], v149 offset:2048
	ds_read_b128 v[164:167], v149 offset:3072
	ds_read_b128 v[168:171], v150
	ds_read_b128 v[172:175], v150 offset:1024
	ds_read_b128 v[176:179], v150 offset:2048
	ds_read_b128 v[184:187], v150 offset:3072
	s_add_u32 s54, s52, 0x100
	s_addc_u32 s55, s53, 0
	s_cmp_eq_u32 s86, 40
	s_cselect_b32 s59, s13, s55
	s_cselect_b32 s58, s12, s54
	s_cselect_b32 s57, s49, s85
	s_cselect_b32 s56, s48, s84
	v_lshl_add_u64 v[144:145], s[52:53], 0, v[136:137]
	s_add_i32 m0, s63, 0xc000
	ds_read_b128 v[188:191], v151
	ds_read_b128 v[192:195], v151 offset:1024
	ds_read_b128 v[196:199], v151 offset:2048
	ds_read_b128 v[200:203], v151 offset:3072
	ds_read_b128 v[204:207], v151 offset:4096
	ds_read_b128 v[208:211], v151 offset:5120
	ds_read_b128 v[212:215], v151 offset:6144
	ds_read_b128 v[216:219], v151 offset:7168
	global_load_lds_dwordx4 v[144:145], off
	v_lshl_add_u64 v[144:145], s[52:53], 0, v[138:139]
	s_add_i32 m0, s63, 0xe000
	s_nop 0
	global_load_lds_dwordx4 v[144:145], off
	s_waitcnt vmcnt(8)
	s_waitcnt lgkmcnt(0)
	s_barrier
	s_setprio 1
	s_waitcnt lgkmcnt(0)
	v_mfma_f32_16x16x32_bf16 v[124:127], v[152:155], v[188:191], 0
	v_mfma_f32_16x16x32_bf16 v[124:127], v[156:159], v[192:195], v[124:127]
	v_mfma_f32_16x16x32_bf16 v[120:123], v[160:163], v[188:191], 0
	v_mfma_f32_16x16x32_bf16 v[120:123], v[164:167], v[192:195], v[120:123]
	v_mfma_f32_16x16x32_bf16 v[116:119], v[152:155], v[196:199], 0
	v_mfma_f32_16x16x32_bf16 v[116:119], v[156:159], v[200:203], v[116:119]
	v_mfma_f32_16x16x32_bf16 v[108:111], v[160:163], v[196:199], 0
	v_mfma_f32_16x16x32_bf16 v[108:111], v[164:167], v[200:203], v[108:111]
	v_mfma_f32_16x16x32_bf16 v[100:103], v[152:155], v[204:207], 0
	v_mfma_f32_16x16x32_bf16 v[100:103], v[156:159], v[208:211], v[100:103]
	v_mfma_f32_16x16x32_bf16 v[92:95], v[160:163], v[204:207], 0
	v_mfma_f32_16x16x32_bf16 v[92:95], v[164:167], v[208:211], v[92:95]
	v_mfma_f32_16x16x32_bf16 v[84:87], v[152:155], v[212:215], 0
	v_mfma_f32_16x16x32_bf16 v[84:87], v[156:159], v[216:219], v[84:87]
	v_mfma_f32_16x16x32_bf16 v[76:79], v[160:163], v[212:215], 0
	v_mfma_f32_16x16x32_bf16 v[76:79], v[164:167], v[216:219], v[76:79]
	v_mfma_f32_16x16x32_bf16 v[112:115], v[168:171], v[188:191], 0
	v_mfma_f32_16x16x32_bf16 v[112:115], v[172:175], v[192:195], v[112:115]
	v_mfma_f32_16x16x32_bf16 v[104:107], v[176:179], v[188:191], 0
	v_mfma_f32_16x16x32_bf16 v[104:107], v[184:187], v[192:195], v[104:107]
	v_mfma_f32_16x16x32_bf16 v[96:99], v[168:171], v[196:199], 0
	v_mfma_f32_16x16x32_bf16 v[96:99], v[172:175], v[200:203], v[96:99]
	v_mfma_f32_16x16x32_bf16 v[88:91], v[176:179], v[196:199], 0
	v_mfma_f32_16x16x32_bf16 v[88:91], v[184:187], v[200:203], v[88:91]
	v_mfma_f32_16x16x32_bf16 v[80:83], v[168:171], v[204:207], 0
	v_mfma_f32_16x16x32_bf16 v[80:83], v[172:175], v[208:211], v[80:83]
	v_mfma_f32_16x16x32_bf16 v[72:75], v[176:179], v[204:207], 0
	v_mfma_f32_16x16x32_bf16 v[72:75], v[184:187], v[208:211], v[72:75]
	v_mfma_f32_16x16x32_bf16 v[68:71], v[168:171], v[212:215], 0
	v_mfma_f32_16x16x32_bf16 v[68:71], v[172:175], v[216:219], v[68:71]
	s_setprio 2
	s_barrier
	v_mfma_f32_16x16x32_bf16 v[64:67], v[176:179], v[212:215], 0
	v_mfma_f32_16x16x32_bf16 v[64:67], v[184:187], v[216:219], v[64:67]
	s_setprio 0
	s_add_i32 s52, s70, s62
	v_lshl_add_u64 v[144:145], s[56:57], 0, v[130:131]
	s_mov_b32 m0, s52
	ds_read_b128 v[188:191], v151 offset:16384
	ds_read_b128 v[192:195], v151 offset:17408
	ds_read_b128 v[196:199], v151 offset:18432
	ds_read_b128 v[200:203], v151 offset:19456
	ds_read_b128 v[204:207], v151 offset:20480
	ds_read_b128 v[208:211], v151 offset:21504
	ds_read_b128 v[212:215], v151 offset:22528
	ds_read_b128 v[216:219], v151 offset:23552
	global_load_lds_dwordx4 v[144:145], off
	s_add_i32 m0, s52, 0x2000
	s_add_u32 s52, s56, 0xb0000
	v_lshl_add_u64 v[220:221], s[56:57], 0, v[134:135]
	s_addc_u32 s53, s57, 0
	s_add_i32 s79, s71, s62
	global_load_lds_dwordx4 v[220:221], off
	v_lshl_add_u64 v[222:223], s[52:53], 0, v[130:131]
	s_mov_b32 m0, s79
	v_lshl_add_u64 v[224:225], s[58:59], 0, v[132:133]
	global_load_lds_dwordx4 v[222:223], off
	v_lshl_add_u64 v[222:223], s[52:53], 0, v[134:135]
	s_add_i32 m0, s79, 0x2000
	s_nop 0
	global_load_lds_dwordx4 v[222:223], off
	v_lshl_add_u64 v[222:223], s[58:59], 0, v[128:129]
	s_mov_b32 m0, s63
	s_nop 0
	global_load_lds_dwordx4 v[222:223], off
	s_mov_b32 m0, s64
	s_nop 0
	global_load_lds_dwordx4 v[224:225], off
	s_waitcnt vmcnt(8)
	s_waitcnt lgkmcnt(0)
	s_barrier
	s_setprio 1
	s_waitcnt lgkmcnt(0)
	v_mfma_f32_16x16x32_bf16 v[60:63], v[152:155], v[188:191], 0
	v_mfma_f32_16x16x32_bf16 v[60:63], v[156:159], v[192:195], v[60:63]
	v_mfma_f32_16x16x32_bf16 v[56:59], v[160:163], v[188:191], 0
	v_mfma_f32_16x16x32_bf16 v[56:59], v[164:167], v[192:195], v[56:59]
	v_mfma_f32_16x16x32_bf16 v[52:55], v[152:155], v[196:199], 0
	v_mfma_f32_16x16x32_bf16 v[52:55], v[156:159], v[200:203], v[52:55]
	v_mfma_f32_16x16x32_bf16 v[44:47], v[160:163], v[196:199], 0
	v_mfma_f32_16x16x32_bf16 v[44:47], v[164:167], v[200:203], v[44:47]
	v_mfma_f32_16x16x32_bf16 v[36:39], v[152:155], v[204:207], 0
	v_mfma_f32_16x16x32_bf16 v[36:39], v[156:159], v[208:211], v[36:39]
	v_mfma_f32_16x16x32_bf16 v[28:31], v[160:163], v[204:207], 0
	v_mfma_f32_16x16x32_bf16 v[28:31], v[164:167], v[208:211], v[28:31]
	v_mfma_f32_16x16x32_bf16 v[20:23], v[152:155], v[212:215], 0
	v_mfma_f32_16x16x32_bf16 v[20:23], v[156:159], v[216:219], v[20:23]
	v_mfma_f32_16x16x32_bf16 v[12:15], v[160:163], v[212:215], 0
	v_mfma_f32_16x16x32_bf16 v[12:15], v[164:167], v[216:219], v[12:15]
	v_mfma_f32_16x16x32_bf16 v[48:51], v[168:171], v[188:191], 0
	v_mfma_f32_16x16x32_bf16 v[48:51], v[172:175], v[192:195], v[48:51]
	v_mfma_f32_16x16x32_bf16 v[40:43], v[176:179], v[188:191], 0
	v_mfma_f32_16x16x32_bf16 v[40:43], v[184:187], v[192:195], v[40:43]
	v_mfma_f32_16x16x32_bf16 v[32:35], v[168:171], v[196:199], 0
	v_mfma_f32_16x16x32_bf16 v[32:35], v[172:175], v[200:203], v[32:35]
	v_mfma_f32_16x16x32_bf16 v[24:27], v[176:179], v[196:199], 0
	v_mfma_f32_16x16x32_bf16 v[24:27], v[184:187], v[200:203], v[24:27]
	v_mfma_f32_16x16x32_bf16 v[16:19], v[168:171], v[204:207], 0
	v_mfma_f32_16x16x32_bf16 v[16:19], v[172:175], v[208:211], v[16:19]
	v_mfma_f32_16x16x32_bf16 v[8:11], v[176:179], v[204:207], 0
	v_mfma_f32_16x16x32_bf16 v[8:11], v[184:187], v[208:211], v[8:11]
	v_mfma_f32_16x16x32_bf16 v[4:7], v[168:171], v[212:215], 0
	v_mfma_f32_16x16x32_bf16 v[4:7], v[172:175], v[216:219], v[4:7]
	s_setprio 2
	s_barrier
	v_mfma_f32_16x16x32_bf16 v[0:3], v[176:179], v[212:215], 0
	v_mfma_f32_16x16x32_bf16 v[0:3], v[184:187], v[216:219], v[0:3]
	s_setprio 0
	s_branch .Lmid_gemm5
.LBB0_804:
	ds_read_b128 v[152:155], v149
	ds_read_b128 v[156:159], v149 offset:1024
	ds_read_b128 v[160:163], v149 offset:2048
	ds_read_b128 v[164:167], v149 offset:3072
	ds_read_b128 v[168:171], v150
	ds_read_b128 v[172:175], v150 offset:1024
	ds_read_b128 v[176:179], v150 offset:2048
	ds_read_b128 v[184:187], v150 offset:3072
	s_add_u32 s54, s52, 0x100
	s_addc_u32 s55, s53, 0
	s_cmp_eq_u32 s86, 40
	s_cselect_b32 s59, s13, s55
	s_cselect_b32 s58, s12, s54
	s_cselect_b32 s57, s49, s85
	s_cselect_b32 s56, s48, s84
	v_lshl_add_u64 v[144:145], s[52:53], 0, v[136:137]
	s_add_i32 m0, s63, 0xc000
	ds_read_b128 v[188:191], v151
	ds_read_b128 v[192:195], v151 offset:1024
	ds_read_b128 v[196:199], v151 offset:2048
	ds_read_b128 v[200:203], v151 offset:3072
	ds_read_b128 v[204:207], v151 offset:4096
	ds_read_b128 v[208:211], v151 offset:5120
	ds_read_b128 v[212:215], v151 offset:6144
	ds_read_b128 v[216:219], v151 offset:7168
	global_load_lds_dwordx4 v[144:145], off
	v_lshl_add_u64 v[144:145], s[52:53], 0, v[138:139]
	s_add_i32 m0, s63, 0xe000
	s_nop 0
	global_load_lds_dwordx4 v[144:145], off
	s_waitcnt vmcnt(8)
	s_waitcnt lgkmcnt(0)
	s_barrier
	s_setprio 1
	s_waitcnt lgkmcnt(0)
	v_mfma_f32_16x16x32_bf16 v[124:127], v[152:155], v[188:191], v[124:127]
	v_mfma_f32_16x16x32_bf16 v[124:127], v[156:159], v[192:195], v[124:127]
	v_mfma_f32_16x16x32_bf16 v[120:123], v[160:163], v[188:191], v[120:123]
	v_mfma_f32_16x16x32_bf16 v[120:123], v[164:167], v[192:195], v[120:123]
	v_mfma_f32_16x16x32_bf16 v[116:119], v[152:155], v[196:199], v[116:119]
	v_mfma_f32_16x16x32_bf16 v[116:119], v[156:159], v[200:203], v[116:119]
	v_mfma_f32_16x16x32_bf16 v[108:111], v[160:163], v[196:199], v[108:111]
	v_mfma_f32_16x16x32_bf16 v[108:111], v[164:167], v[200:203], v[108:111]
	v_mfma_f32_16x16x32_bf16 v[100:103], v[152:155], v[204:207], v[100:103]
	v_mfma_f32_16x16x32_bf16 v[100:103], v[156:159], v[208:211], v[100:103]
	v_mfma_f32_16x16x32_bf16 v[92:95], v[160:163], v[204:207], v[92:95]
	v_mfma_f32_16x16x32_bf16 v[92:95], v[164:167], v[208:211], v[92:95]
	v_mfma_f32_16x16x32_bf16 v[84:87], v[152:155], v[212:215], v[84:87]
	v_mfma_f32_16x16x32_bf16 v[84:87], v[156:159], v[216:219], v[84:87]
	v_mfma_f32_16x16x32_bf16 v[76:79], v[160:163], v[212:215], v[76:79]
	v_mfma_f32_16x16x32_bf16 v[76:79], v[164:167], v[216:219], v[76:79]
	v_mfma_f32_16x16x32_bf16 v[112:115], v[168:171], v[188:191], v[112:115]
	v_mfma_f32_16x16x32_bf16 v[112:115], v[172:175], v[192:195], v[112:115]
	v_mfma_f32_16x16x32_bf16 v[104:107], v[176:179], v[188:191], v[104:107]
	v_mfma_f32_16x16x32_bf16 v[104:107], v[184:187], v[192:195], v[104:107]
	v_mfma_f32_16x16x32_bf16 v[96:99], v[168:171], v[196:199], v[96:99]
	v_mfma_f32_16x16x32_bf16 v[96:99], v[172:175], v[200:203], v[96:99]
	v_mfma_f32_16x16x32_bf16 v[88:91], v[176:179], v[196:199], v[88:91]
	v_mfma_f32_16x16x32_bf16 v[88:91], v[184:187], v[200:203], v[88:91]
	v_mfma_f32_16x16x32_bf16 v[80:83], v[168:171], v[204:207], v[80:83]
	v_mfma_f32_16x16x32_bf16 v[80:83], v[172:175], v[208:211], v[80:83]
	v_mfma_f32_16x16x32_bf16 v[72:75], v[176:179], v[204:207], v[72:75]
	v_mfma_f32_16x16x32_bf16 v[72:75], v[184:187], v[208:211], v[72:75]
	v_mfma_f32_16x16x32_bf16 v[68:71], v[168:171], v[212:215], v[68:71]
	v_mfma_f32_16x16x32_bf16 v[68:71], v[172:175], v[216:219], v[68:71]
	s_setprio 2
	s_barrier
	v_mfma_f32_16x16x32_bf16 v[64:67], v[176:179], v[212:215], v[64:67]
	v_mfma_f32_16x16x32_bf16 v[64:67], v[184:187], v[216:219], v[64:67]
	s_setprio 0
	s_add_i32 s52, s70, s62
	v_lshl_add_u64 v[144:145], s[56:57], 0, v[130:131]
	s_mov_b32 m0, s52
	ds_read_b128 v[188:191], v151 offset:16384
	ds_read_b128 v[192:195], v151 offset:17408
	ds_read_b128 v[196:199], v151 offset:18432
	ds_read_b128 v[200:203], v151 offset:19456
	ds_read_b128 v[204:207], v151 offset:20480
	ds_read_b128 v[208:211], v151 offset:21504
	ds_read_b128 v[212:215], v151 offset:22528
	ds_read_b128 v[216:219], v151 offset:23552
	global_load_lds_dwordx4 v[144:145], off
	s_add_i32 m0, s52, 0x2000
	s_add_u32 s52, s56, 0xb0000
	v_lshl_add_u64 v[220:221], s[56:57], 0, v[134:135]
	s_addc_u32 s53, s57, 0
	s_add_i32 s79, s71, s62
	global_load_lds_dwordx4 v[220:221], off
	v_lshl_add_u64 v[222:223], s[52:53], 0, v[130:131]
	s_mov_b32 m0, s79
	v_lshl_add_u64 v[224:225], s[58:59], 0, v[132:133]
	global_load_lds_dwordx4 v[222:223], off
	v_lshl_add_u64 v[222:223], s[52:53], 0, v[134:135]
	s_add_i32 m0, s79, 0x2000
	s_nop 0
	global_load_lds_dwordx4 v[222:223], off
	v_lshl_add_u64 v[222:223], s[58:59], 0, v[128:129]
	s_mov_b32 m0, s63
	s_nop 0
	global_load_lds_dwordx4 v[222:223], off
	s_mov_b32 m0, s64
	s_nop 0
	global_load_lds_dwordx4 v[224:225], off
	s_waitcnt vmcnt(8)
	s_waitcnt lgkmcnt(0)
	s_barrier
	s_setprio 1
	s_waitcnt lgkmcnt(0)
	v_mfma_f32_16x16x32_bf16 v[60:63], v[152:155], v[188:191], v[60:63]
	v_mfma_f32_16x16x32_bf16 v[60:63], v[156:159], v[192:195], v[60:63]
	v_mfma_f32_16x16x32_bf16 v[56:59], v[160:163], v[188:191], v[56:59]
	v_mfma_f32_16x16x32_bf16 v[56:59], v[164:167], v[192:195], v[56:59]
	v_mfma_f32_16x16x32_bf16 v[52:55], v[152:155], v[196:199], v[52:55]
	v_mfma_f32_16x16x32_bf16 v[52:55], v[156:159], v[200:203], v[52:55]
	v_mfma_f32_16x16x32_bf16 v[44:47], v[160:163], v[196:199], v[44:47]
	v_mfma_f32_16x16x32_bf16 v[44:47], v[164:167], v[200:203], v[44:47]
	v_mfma_f32_16x16x32_bf16 v[36:39], v[152:155], v[204:207], v[36:39]
	v_mfma_f32_16x16x32_bf16 v[36:39], v[156:159], v[208:211], v[36:39]
	v_mfma_f32_16x16x32_bf16 v[28:31], v[160:163], v[204:207], v[28:31]
	v_mfma_f32_16x16x32_bf16 v[28:31], v[164:167], v[208:211], v[28:31]
	v_mfma_f32_16x16x32_bf16 v[20:23], v[152:155], v[212:215], v[20:23]
	v_mfma_f32_16x16x32_bf16 v[20:23], v[156:159], v[216:219], v[20:23]
	v_mfma_f32_16x16x32_bf16 v[12:15], v[160:163], v[212:215], v[12:15]
	v_mfma_f32_16x16x32_bf16 v[12:15], v[164:167], v[216:219], v[12:15]
	v_mfma_f32_16x16x32_bf16 v[48:51], v[168:171], v[188:191], v[48:51]
	v_mfma_f32_16x16x32_bf16 v[48:51], v[172:175], v[192:195], v[48:51]
	v_mfma_f32_16x16x32_bf16 v[40:43], v[176:179], v[188:191], v[40:43]
	v_mfma_f32_16x16x32_bf16 v[40:43], v[184:187], v[192:195], v[40:43]
	v_mfma_f32_16x16x32_bf16 v[32:35], v[168:171], v[196:199], v[32:35]
	v_mfma_f32_16x16x32_bf16 v[32:35], v[172:175], v[200:203], v[32:35]
	v_mfma_f32_16x16x32_bf16 v[24:27], v[176:179], v[196:199], v[24:27]
	v_mfma_f32_16x16x32_bf16 v[24:27], v[184:187], v[200:203], v[24:27]
	v_mfma_f32_16x16x32_bf16 v[16:19], v[168:171], v[204:207], v[16:19]
	v_mfma_f32_16x16x32_bf16 v[16:19], v[172:175], v[208:211], v[16:19]
	v_mfma_f32_16x16x32_bf16 v[8:11], v[176:179], v[204:207], v[8:11]
	v_mfma_f32_16x16x32_bf16 v[8:11], v[184:187], v[208:211], v[8:11]
	v_mfma_f32_16x16x32_bf16 v[4:7], v[168:171], v[212:215], v[4:7]
	v_mfma_f32_16x16x32_bf16 v[4:7], v[172:175], v[216:219], v[4:7]
	s_setprio 2
	s_barrier
	v_mfma_f32_16x16x32_bf16 v[0:3], v[176:179], v[212:215], v[0:3]
	v_mfma_f32_16x16x32_bf16 v[0:3], v[184:187], v[216:219], v[0:3]
	s_setprio 0
.Lmid_gemm5:
	s_add_i32 s79, 0, 0x18000
	s_add_i32 s87, 0, 0x1c000
	v_add_u32_e32 v164, s79, v147
	v_add_u32_e32 v181, s87, v147
	ds_read_b128 v[152:155], v164
	ds_read_b128 v[156:159], v164 offset:1024
	ds_read_b128 v[160:163], v164 offset:2048
	ds_read_b128 v[164:167], v164 offset:3072
	ds_read_b128 v[168:171], v181
	ds_read_b128 v[172:175], v181 offset:1024
	ds_read_b128 v[176:179], v181 offset:2048
	ds_read_b128 v[184:187], v181 offset:3072
	s_add_u32 s52, s58, 0xb0000
	s_addc_u32 s53, s59, 0
	s_mov_b32 m0, s65
	v_lshl_add_u64 v[226:227], s[52:53], 0, v[128:129]
	ds_read_b128 v[188:191], v151 offset:32768
	ds_read_b128 v[192:195], v151 offset:33792
	ds_read_b128 v[196:199], v151 offset:34816
	ds_read_b128 v[200:203], v151 offset:35840
	ds_read_b128 v[204:207], v151 offset:36864
	ds_read_b128 v[208:211], v151 offset:37888
	ds_read_b128 v[212:215], v151 offset:38912
	ds_read_b128 v[216:219], v151 offset:39936
	global_load_lds_dwordx4 v[226:227], off
	v_lshl_add_u64 v[226:227], s[52:53], 0, v[132:133]
	s_mov_b32 m0, s66
	s_nop 0
	global_load_lds_dwordx4 v[226:227], off
	s_waitcnt vmcnt(8)
	s_waitcnt lgkmcnt(0)
	s_barrier
	s_setprio 1
	s_waitcnt lgkmcnt(0)
	v_mfma_f32_16x16x32_bf16 v[124:127], v[152:155], v[188:191], v[124:127]
	v_mfma_f32_16x16x32_bf16 v[124:127], v[156:159], v[192:195], v[124:127]
	v_mfma_f32_16x16x32_bf16 v[120:123], v[160:163], v[188:191], v[120:123]
	v_mfma_f32_16x16x32_bf16 v[120:123], v[164:167], v[192:195], v[120:123]
	v_mfma_f32_16x16x32_bf16 v[116:119], v[152:155], v[196:199], v[116:119]
	v_mfma_f32_16x16x32_bf16 v[116:119], v[156:159], v[200:203], v[116:119]
	v_mfma_f32_16x16x32_bf16 v[108:111], v[160:163], v[196:199], v[108:111]
	v_mfma_f32_16x16x32_bf16 v[108:111], v[164:167], v[200:203], v[108:111]
	v_mfma_f32_16x16x32_bf16 v[100:103], v[152:155], v[204:207], v[100:103]
	v_mfma_f32_16x16x32_bf16 v[100:103], v[156:159], v[208:211], v[100:103]
	v_mfma_f32_16x16x32_bf16 v[92:95], v[160:163], v[204:207], v[92:95]
	v_mfma_f32_16x16x32_bf16 v[92:95], v[164:167], v[208:211], v[92:95]
	v_mfma_f32_16x16x32_bf16 v[84:87], v[152:155], v[212:215], v[84:87]
	v_mfma_f32_16x16x32_bf16 v[84:87], v[156:159], v[216:219], v[84:87]
	v_mfma_f32_16x16x32_bf16 v[76:79], v[160:163], v[212:215], v[76:79]
	v_mfma_f32_16x16x32_bf16 v[76:79], v[164:167], v[216:219], v[76:79]
	v_mfma_f32_16x16x32_bf16 v[112:115], v[168:171], v[188:191], v[112:115]
	v_mfma_f32_16x16x32_bf16 v[112:115], v[172:175], v[192:195], v[112:115]
	v_mfma_f32_16x16x32_bf16 v[104:107], v[176:179], v[188:191], v[104:107]
	v_mfma_f32_16x16x32_bf16 v[104:107], v[184:187], v[192:195], v[104:107]
	v_mfma_f32_16x16x32_bf16 v[96:99], v[168:171], v[196:199], v[96:99]
	v_mfma_f32_16x16x32_bf16 v[96:99], v[172:175], v[200:203], v[96:99]
	v_mfma_f32_16x16x32_bf16 v[88:91], v[176:179], v[196:199], v[88:91]
	v_mfma_f32_16x16x32_bf16 v[88:91], v[184:187], v[200:203], v[88:91]
	v_mfma_f32_16x16x32_bf16 v[80:83], v[168:171], v[204:207], v[80:83]
	v_mfma_f32_16x16x32_bf16 v[80:83], v[172:175], v[208:211], v[80:83]
	v_mfma_f32_16x16x32_bf16 v[72:75], v[176:179], v[204:207], v[72:75]
	v_mfma_f32_16x16x32_bf16 v[72:75], v[184:187], v[208:211], v[72:75]
	v_mfma_f32_16x16x32_bf16 v[68:71], v[168:171], v[212:215], v[68:71]
	v_mfma_f32_16x16x32_bf16 v[68:71], v[172:175], v[216:219], v[68:71]
	s_setprio 2
	s_barrier
	v_mfma_f32_16x16x32_bf16 v[64:67], v[176:179], v[212:215], v[64:67]
	v_mfma_f32_16x16x32_bf16 v[64:67], v[184:187], v[216:219], v[64:67]
	s_setprio 0
	s_add_i32 s52, s79, s62
	v_lshl_add_u64 v[144:145], v[144:145], 0, s[16:17]
	s_mov_b32 m0, s52
	ds_read_b128 v[188:191], v151 offset:49152
	ds_read_b128 v[192:195], v151 offset:50176
	ds_read_b128 v[196:199], v151 offset:51200
	ds_read_b128 v[200:203], v151 offset:52224
	ds_read_b128 v[204:207], v151 offset:53248
	ds_read_b128 v[208:211], v151 offset:54272
	ds_read_b128 v[212:215], v151 offset:55296
	ds_read_b128 v[216:219], v151 offset:56320
	global_load_lds_dwordx4 v[144:145], off
	s_add_i32 m0, s52, 0x2000
	s_add_u32 s52, s56, 0xb0080
	v_lshl_add_u64 v[144:145], v[220:221], 0, s[16:17]
	s_addc_u32 s53, s57, 0
	s_add_i32 s56, s87, s62
	global_load_lds_dwordx4 v[144:145], off
	v_lshl_add_u64 v[144:145], s[52:53], 0, v[130:131]
	s_mov_b32 m0, s56
	s_nop 0
	global_load_lds_dwordx4 v[144:145], off
	v_lshl_add_u64 v[144:145], s[52:53], 0, v[134:135]
	s_add_i32 m0, s56, 0x2000
	s_nop 0
	global_load_lds_dwordx4 v[144:145], off
	v_lshl_add_u64 v[144:145], v[222:223], 0, s[16:17]
	s_mov_b32 m0, s68
	s_nop 0
	global_load_lds_dwordx4 v[144:145], off
	v_lshl_add_u64 v[144:145], v[224:225], 0, s[16:17]
	s_mov_b32 m0, s69
	s_nop 0
	global_load_lds_dwordx4 v[144:145], off
	s_waitcnt vmcnt(8)
	s_waitcnt lgkmcnt(0)
	s_barrier
	s_setprio 1
	s_waitcnt lgkmcnt(0)
	v_mfma_f32_16x16x32_bf16 v[60:63], v[152:155], v[188:191], v[60:63]
	v_mfma_f32_16x16x32_bf16 v[60:63], v[156:159], v[192:195], v[60:63]
	v_mfma_f32_16x16x32_bf16 v[56:59], v[160:163], v[188:191], v[56:59]
	v_mfma_f32_16x16x32_bf16 v[56:59], v[164:167], v[192:195], v[56:59]
	v_mfma_f32_16x16x32_bf16 v[52:55], v[152:155], v[196:199], v[52:55]
	v_mfma_f32_16x16x32_bf16 v[52:55], v[156:159], v[200:203], v[52:55]
	v_mfma_f32_16x16x32_bf16 v[44:47], v[160:163], v[196:199], v[44:47]
	v_mfma_f32_16x16x32_bf16 v[44:47], v[164:167], v[200:203], v[44:47]
	v_mfma_f32_16x16x32_bf16 v[36:39], v[152:155], v[204:207], v[36:39]
	v_mfma_f32_16x16x32_bf16 v[36:39], v[156:159], v[208:211], v[36:39]
	v_mfma_f32_16x16x32_bf16 v[28:31], v[160:163], v[204:207], v[28:31]
	v_mfma_f32_16x16x32_bf16 v[28:31], v[164:167], v[208:211], v[28:31]
	v_mfma_f32_16x16x32_bf16 v[20:23], v[152:155], v[212:215], v[20:23]
	v_mfma_f32_16x16x32_bf16 v[20:23], v[156:159], v[216:219], v[20:23]
	v_mfma_f32_16x16x32_bf16 v[12:15], v[160:163], v[212:215], v[12:15]
	v_mfma_f32_16x16x32_bf16 v[12:15], v[164:167], v[216:219], v[12:15]
	v_mfma_f32_16x16x32_bf16 v[48:51], v[168:171], v[188:191], v[48:51]
	v_mfma_f32_16x16x32_bf16 v[48:51], v[172:175], v[192:195], v[48:51]
	v_mfma_f32_16x16x32_bf16 v[40:43], v[176:179], v[188:191], v[40:43]
	v_mfma_f32_16x16x32_bf16 v[40:43], v[184:187], v[192:195], v[40:43]
	v_mfma_f32_16x16x32_bf16 v[32:35], v[168:171], v[196:199], v[32:35]
	v_mfma_f32_16x16x32_bf16 v[32:35], v[172:175], v[200:203], v[32:35]
	v_mfma_f32_16x16x32_bf16 v[24:27], v[176:179], v[196:199], v[24:27]
	v_mfma_f32_16x16x32_bf16 v[24:27], v[184:187], v[200:203], v[24:27]
	v_mfma_f32_16x16x32_bf16 v[16:19], v[168:171], v[204:207], v[16:19]
	v_mfma_f32_16x16x32_bf16 v[16:19], v[172:175], v[208:211], v[16:19]
	v_mfma_f32_16x16x32_bf16 v[8:11], v[176:179], v[204:207], v[8:11]
	v_mfma_f32_16x16x32_bf16 v[8:11], v[184:187], v[208:211], v[8:11]
	v_mfma_f32_16x16x32_bf16 v[4:7], v[168:171], v[212:215], v[4:7]
	v_mfma_f32_16x16x32_bf16 v[4:7], v[172:175], v[216:219], v[4:7]
	s_setprio 2
	s_barrier
	v_mfma_f32_16x16x32_bf16 v[0:3], v[176:179], v[212:215], v[0:3]
	v_mfma_f32_16x16x32_bf16 v[0:3], v[184:187], v[216:219], v[0:3]
	s_setprio 0
	s_add_i32 s86, s86, 2
	s_add_u32 s84, s84, 0x100
	s_addc_u32 s85, s85, 0
	s_cmp_gt_u32 s86, 41
	s_mov_b64 s[52:53], s[54:55]
	s_cbranch_scc0 .LBB0_804
	s_and_b64 vcc, exec, s[18:19]
	s_cbranch_vccz .LBB0_807
	s_barrier

.LBB0_934:
	s_ashr_i32 s53, s52, 31
	s_lshl_b64 s[54:55], s[52:53], 19
	s_add_u32 s54, s80, s54
	s_addc_u32 s55, s81, s55
	s_and_b64 s[56:57], s[10:11], exec
	s_cselect_b32 s53, s55, s61
	s_cselect_b32 s83, s54, s60
	s_ashr_i32 s49, s48, 31
	s_lshl_b64 s[56:57], s[48:49], 19
	s_add_u32 s56, s66, s56
	s_addc_u32 s57, s67, s57
	s_and_b64 s[64:65], s[10:11], exec
	s_cselect_b32 s49, s57, s63
	s_cselect_b32 s84, s56, s62
	s_add_u32 s60, s60, 0x40080
	s_addc_u32 s61, s61, 0
	s_add_u32 s85, s62, 0x100
	s_addc_u32 s86, s63, 0
	s_mov_b32 s87, -2
	ds_read_b128 v[152:155], v148
	ds_read_b128 v[156:159], v148 offset:1024
	ds_read_b128 v[160:163], v148 offset:2048
	ds_read_b128 v[164:167], v148 offset:3072
	ds_read_b128 v[168:171], v149
	ds_read_b128 v[172:175], v149 offset:1024
	ds_read_b128 v[176:179], v149 offset:2048
	ds_read_b128 v[184:187], v149 offset:3072
	s_add_u32 s62, s60, 0xfffc0080
	s_addc_u32 s63, s61, -1
	s_cmp_eq_u32 s87, 12
	s_cselect_b32 s65, s53, s63
	s_cselect_b32 s64, s83, s62
	s_cselect_b32 s63, s49, s86
	s_cselect_b32 s62, s84, s85
	v_lshl_add_u64 v[220:221], s[60:61], 0, v[138:139]
	s_add_i32 m0, s69, 0xc000
	ds_read_b128 v[188:191], v150
	ds_read_b128 v[192:195], v150 offset:1024
	ds_read_b128 v[196:199], v150 offset:2048
	ds_read_b128 v[200:203], v150 offset:3072
	ds_read_b128 v[204:207], v150 offset:4096
	ds_read_b128 v[208:211], v150 offset:5120
	ds_read_b128 v[212:215], v150 offset:6144
	ds_read_b128 v[216:219], v150 offset:7168
	global_load_lds_dwordx4 v[220:221], off
	v_lshl_add_u64 v[220:221], s[60:61], 0, v[140:141]
	s_add_i32 m0, s69, 0xe000
	s_nop 0
	global_load_lds_dwordx4 v[220:221], off
	s_waitcnt vmcnt(8)
	s_waitcnt lgkmcnt(0)
	s_barrier
	s_setprio 1
	s_waitcnt lgkmcnt(0)
	v_mfma_f32_16x16x32_bf16 v[124:127], v[152:155], v[188:191], 0
	v_mfma_f32_16x16x32_bf16 v[124:127], v[156:159], v[192:195], v[124:127]
	v_mfma_f32_16x16x32_bf16 v[120:123], v[160:163], v[188:191], 0
	v_mfma_f32_16x16x32_bf16 v[120:123], v[164:167], v[192:195], v[120:123]
	v_mfma_f32_16x16x32_bf16 v[116:119], v[152:155], v[196:199], 0
	v_mfma_f32_16x16x32_bf16 v[116:119], v[156:159], v[200:203], v[116:119]
	v_mfma_f32_16x16x32_bf16 v[112:115], v[160:163], v[196:199], 0
	v_mfma_f32_16x16x32_bf16 v[112:115], v[164:167], v[200:203], v[112:115]
	v_mfma_f32_16x16x32_bf16 v[108:111], v[152:155], v[204:207], 0
	v_mfma_f32_16x16x32_bf16 v[108:111], v[156:159], v[208:211], v[108:111]
	v_mfma_f32_16x16x32_bf16 v[104:107], v[160:163], v[204:207], 0
	v_mfma_f32_16x16x32_bf16 v[104:107], v[164:167], v[208:211], v[104:107]
	v_mfma_f32_16x16x32_bf16 v[100:103], v[152:155], v[212:215], 0
	v_mfma_f32_16x16x32_bf16 v[100:103], v[156:159], v[216:219], v[100:103]
	v_mfma_f32_16x16x32_bf16 v[96:99], v[160:163], v[212:215], 0
	v_mfma_f32_16x16x32_bf16 v[96:99], v[164:167], v[216:219], v[96:99]
	v_mfma_f32_16x16x32_bf16 v[76:79], v[168:171], v[188:191], 0
	v_mfma_f32_16x16x32_bf16 v[76:79], v[172:175], v[192:195], v[76:79]
	v_mfma_f32_16x16x32_bf16 v[68:71], v[176:179], v[188:191], 0
	v_mfma_f32_16x16x32_bf16 v[68:71], v[184:187], v[192:195], v[68:71]
	v_mfma_f32_16x16x32_bf16 v[60:63], v[168:171], v[196:199], 0
	v_mfma_f32_16x16x32_bf16 v[60:63], v[172:175], v[200:203], v[60:63]
	v_mfma_f32_16x16x32_bf16 v[52:55], v[176:179], v[196:199], 0
	v_mfma_f32_16x16x32_bf16 v[52:55], v[184:187], v[200:203], v[52:55]
	v_mfma_f32_16x16x32_bf16 v[44:47], v[168:171], v[204:207], 0
	v_mfma_f32_16x16x32_bf16 v[44:47], v[172:175], v[208:211], v[44:47]
	v_mfma_f32_16x16x32_bf16 v[40:43], v[176:179], v[204:207], 0
	v_mfma_f32_16x16x32_bf16 v[40:43], v[184:187], v[208:211], v[40:43]
	v_mfma_f32_16x16x32_bf16 v[36:39], v[168:171], v[212:215], 0
	v_mfma_f32_16x16x32_bf16 v[36:39], v[172:175], v[216:219], v[36:39]
	s_setprio 2
	s_barrier
	v_mfma_f32_16x16x32_bf16 v[32:35], v[176:179], v[212:215], 0
	v_mfma_f32_16x16x32_bf16 v[32:35], v[184:187], v[216:219], v[32:35]
	s_setprio 0
	s_add_i32 s79, s77, s68
	v_lshl_add_u64 v[220:221], s[62:63], 0, v[130:131]
	s_mov_b32 m0, s79
	ds_read_b128 v[188:191], v150 offset:16384
	ds_read_b128 v[192:195], v150 offset:17408
	ds_read_b128 v[196:199], v150 offset:18432
	ds_read_b128 v[200:203], v150 offset:19456
	ds_read_b128 v[204:207], v150 offset:20480
	ds_read_b128 v[208:211], v150 offset:21504
	ds_read_b128 v[212:215], v150 offset:22528
	ds_read_b128 v[216:219], v150 offset:23552
	global_load_lds_dwordx4 v[220:221], off
	s_add_i32 m0, s79, 0x2000
	s_add_u32 s88, s62, 0x40000
	v_lshl_add_u64 v[222:223], s[62:63], 0, v[134:135]
	s_addc_u32 s89, s63, 0
	s_add_i32 s79, s82, s68
	global_load_lds_dwordx4 v[222:223], off
	v_lshl_add_u64 v[224:225], s[88:89], 0, v[130:131]
	s_mov_b32 m0, s79
	v_lshl_add_u64 v[226:227], s[64:65], 0, v[132:133]
	global_load_lds_dwordx4 v[224:225], off
	v_lshl_add_u64 v[224:225], s[88:89], 0, v[134:135]
	s_add_i32 m0, s79, 0x2000
	s_nop 0
	global_load_lds_dwordx4 v[224:225], off
	v_lshl_add_u64 v[224:225], s[64:65], 0, v[128:129]
	s_mov_b32 m0, s69
	s_nop 0
	global_load_lds_dwordx4 v[224:225], off
	s_mov_b32 m0, s70
	s_nop 0
	global_load_lds_dwordx4 v[226:227], off
	s_waitcnt vmcnt(8)
	s_waitcnt lgkmcnt(0)
	s_barrier
	s_setprio 1
	s_waitcnt lgkmcnt(0)
	v_mfma_f32_16x16x32_bf16 v[92:95], v[152:155], v[188:191], 0
	v_mfma_f32_16x16x32_bf16 v[92:95], v[156:159], v[192:195], v[92:95]
	v_mfma_f32_16x16x32_bf16 v[88:91], v[160:163], v[188:191], 0
	v_mfma_f32_16x16x32_bf16 v[88:91], v[164:167], v[192:195], v[88:91]
	v_mfma_f32_16x16x32_bf16 v[84:87], v[152:155], v[196:199], 0
	v_mfma_f32_16x16x32_bf16 v[84:87], v[156:159], v[200:203], v[84:87]
	v_mfma_f32_16x16x32_bf16 v[80:83], v[160:163], v[196:199], 0
	v_mfma_f32_16x16x32_bf16 v[80:83], v[164:167], v[200:203], v[80:83]
	v_mfma_f32_16x16x32_bf16 v[72:75], v[152:155], v[204:207], 0
	v_mfma_f32_16x16x32_bf16 v[72:75], v[156:159], v[208:211], v[72:75]
	v_mfma_f32_16x16x32_bf16 v[64:67], v[160:163], v[204:207], 0
	v_mfma_f32_16x16x32_bf16 v[64:67], v[164:167], v[208:211], v[64:67]
	v_mfma_f32_16x16x32_bf16 v[56:59], v[152:155], v[212:215], 0
	v_mfma_f32_16x16x32_bf16 v[56:59], v[156:159], v[216:219], v[56:59]
	v_mfma_f32_16x16x32_bf16 v[48:51], v[160:163], v[212:215], 0
	v_mfma_f32_16x16x32_bf16 v[48:51], v[164:167], v[216:219], v[48:51]
	v_mfma_f32_16x16x32_bf16 v[28:31], v[168:171], v[188:191], 0
	v_mfma_f32_16x16x32_bf16 v[28:31], v[172:175], v[192:195], v[28:31]
	v_mfma_f32_16x16x32_bf16 v[24:27], v[176:179], v[188:191], 0
	v_mfma_f32_16x16x32_bf16 v[24:27], v[184:187], v[192:195], v[24:27]
	v_mfma_f32_16x16x32_bf16 v[20:23], v[168:171], v[196:199], 0
	v_mfma_f32_16x16x32_bf16 v[20:23], v[172:175], v[200:203], v[20:23]
	v_mfma_f32_16x16x32_bf16 v[16:19], v[176:179], v[196:199], 0
	v_mfma_f32_16x16x32_bf16 v[16:19], v[184:187], v[200:203], v[16:19]
	v_mfma_f32_16x16x32_bf16 v[12:15], v[168:171], v[204:207], 0
	v_mfma_f32_16x16x32_bf16 v[12:15], v[172:175], v[208:211], v[12:15]
	v_mfma_f32_16x16x32_bf16 v[8:11], v[176:179], v[204:207], 0
	v_mfma_f32_16x16x32_bf16 v[8:11], v[184:187], v[208:211], v[8:11]
	v_mfma_f32_16x16x32_bf16 v[4:7], v[168:171], v[212:215], 0
	v_mfma_f32_16x16x32_bf16 v[4:7], v[172:175], v[216:219], v[4:7]
	s_setprio 2
	s_barrier
	v_mfma_f32_16x16x32_bf16 v[0:3], v[176:179], v[212:215], 0
	v_mfma_f32_16x16x32_bf16 v[0:3], v[184:187], v[216:219], v[0:3]
	s_setprio 0
	s_branch .Lmid_gemm6
.LBB0_935:
	ds_read_b128 v[152:155], v148
	ds_read_b128 v[156:159], v148 offset:1024
	ds_read_b128 v[160:163], v148 offset:2048
	ds_read_b128 v[164:167], v148 offset:3072
	ds_read_b128 v[168:171], v149
	ds_read_b128 v[172:175], v149 offset:1024
	ds_read_b128 v[176:179], v149 offset:2048
	ds_read_b128 v[184:187], v149 offset:3072
	s_add_u32 s62, s60, 0xfffc0080
	s_addc_u32 s63, s61, -1
	s_cmp_eq_u32 s87, 12
	s_cselect_b32 s65, s53, s63
	s_cselect_b32 s64, s83, s62
	s_cselect_b32 s63, s49, s86
	s_cselect_b32 s62, s84, s85
	v_lshl_add_u64 v[220:221], s[60:61], 0, v[138:139]
	s_add_i32 m0, s69, 0xc000
	ds_read_b128 v[188:191], v150
	ds_read_b128 v[192:195], v150 offset:1024
	ds_read_b128 v[196:199], v150 offset:2048
	ds_read_b128 v[200:203], v150 offset:3072
	ds_read_b128 v[204:207], v150 offset:4096
	ds_read_b128 v[208:211], v150 offset:5120
	ds_read_b128 v[212:215], v150 offset:6144
	ds_read_b128 v[216:219], v150 offset:7168
	global_load_lds_dwordx4 v[220:221], off
	v_lshl_add_u64 v[220:221], s[60:61], 0, v[140:141]
	s_add_i32 m0, s69, 0xe000
	s_nop 0
	global_load_lds_dwordx4 v[220:221], off
	s_waitcnt vmcnt(8)
	s_waitcnt lgkmcnt(0)
	s_barrier
	s_setprio 1
	s_waitcnt lgkmcnt(0)
	v_mfma_f32_16x16x32_bf16 v[124:127], v[152:155], v[188:191], v[124:127]
	v_mfma_f32_16x16x32_bf16 v[124:127], v[156:159], v[192:195], v[124:127]
	v_mfma_f32_16x16x32_bf16 v[120:123], v[160:163], v[188:191], v[120:123]
	v_mfma_f32_16x16x32_bf16 v[120:123], v[164:167], v[192:195], v[120:123]
	v_mfma_f32_16x16x32_bf16 v[116:119], v[152:155], v[196:199], v[116:119]
	v_mfma_f32_16x16x32_bf16 v[116:119], v[156:159], v[200:203], v[116:119]
	v_mfma_f32_16x16x32_bf16 v[112:115], v[160:163], v[196:199], v[112:115]
	v_mfma_f32_16x16x32_bf16 v[112:115], v[164:167], v[200:203], v[112:115]
	v_mfma_f32_16x16x32_bf16 v[108:111], v[152:155], v[204:207], v[108:111]
	v_mfma_f32_16x16x32_bf16 v[108:111], v[156:159], v[208:211], v[108:111]
	v_mfma_f32_16x16x32_bf16 v[104:107], v[160:163], v[204:207], v[104:107]
	v_mfma_f32_16x16x32_bf16 v[104:107], v[164:167], v[208:211], v[104:107]
	v_mfma_f32_16x16x32_bf16 v[100:103], v[152:155], v[212:215], v[100:103]
	v_mfma_f32_16x16x32_bf16 v[100:103], v[156:159], v[216:219], v[100:103]
	v_mfma_f32_16x16x32_bf16 v[96:99], v[160:163], v[212:215], v[96:99]
	v_mfma_f32_16x16x32_bf16 v[96:99], v[164:167], v[216:219], v[96:99]
	v_mfma_f32_16x16x32_bf16 v[76:79], v[168:171], v[188:191], v[76:79]
	v_mfma_f32_16x16x32_bf16 v[76:79], v[172:175], v[192:195], v[76:79]
	v_mfma_f32_16x16x32_bf16 v[68:71], v[176:179], v[188:191], v[68:71]
	v_mfma_f32_16x16x32_bf16 v[68:71], v[184:187], v[192:195], v[68:71]
	v_mfma_f32_16x16x32_bf16 v[60:63], v[168:171], v[196:199], v[60:63]
	v_mfma_f32_16x16x32_bf16 v[60:63], v[172:175], v[200:203], v[60:63]
	v_mfma_f32_16x16x32_bf16 v[52:55], v[176:179], v[196:199], v[52:55]
	v_mfma_f32_16x16x32_bf16 v[52:55], v[184:187], v[200:203], v[52:55]
	v_mfma_f32_16x16x32_bf16 v[44:47], v[168:171], v[204:207], v[44:47]
	v_mfma_f32_16x16x32_bf16 v[44:47], v[172:175], v[208:211], v[44:47]
	v_mfma_f32_16x16x32_bf16 v[40:43], v[176:179], v[204:207], v[40:43]
	v_mfma_f32_16x16x32_bf16 v[40:43], v[184:187], v[208:211], v[40:43]
	v_mfma_f32_16x16x32_bf16 v[36:39], v[168:171], v[212:215], v[36:39]
	v_mfma_f32_16x16x32_bf16 v[36:39], v[172:175], v[216:219], v[36:39]
	s_setprio 2
	s_barrier
	v_mfma_f32_16x16x32_bf16 v[32:35], v[176:179], v[212:215], v[32:35]
	v_mfma_f32_16x16x32_bf16 v[32:35], v[184:187], v[216:219], v[32:35]
	s_setprio 0
	s_add_i32 s79, s77, s68
	v_lshl_add_u64 v[220:221], s[62:63], 0, v[130:131]
	s_mov_b32 m0, s79
	ds_read_b128 v[188:191], v150 offset:16384
	ds_read_b128 v[192:195], v150 offset:17408
	ds_read_b128 v[196:199], v150 offset:18432
	ds_read_b128 v[200:203], v150 offset:19456
	ds_read_b128 v[204:207], v150 offset:20480
	ds_read_b128 v[208:211], v150 offset:21504
	ds_read_b128 v[212:215], v150 offset:22528
	ds_read_b128 v[216:219], v150 offset:23552
	global_load_lds_dwordx4 v[220:221], off
	s_add_i32 m0, s79, 0x2000
	s_add_u32 s88, s62, 0x40000
	v_lshl_add_u64 v[222:223], s[62:63], 0, v[134:135]
	s_addc_u32 s89, s63, 0
	s_add_i32 s79, s82, s68
	global_load_lds_dwordx4 v[222:223], off
	v_lshl_add_u64 v[224:225], s[88:89], 0, v[130:131]
	s_mov_b32 m0, s79
	v_lshl_add_u64 v[226:227], s[64:65], 0, v[132:133]
	global_load_lds_dwordx4 v[224:225], off
	v_lshl_add_u64 v[224:225], s[88:89], 0, v[134:135]
	s_add_i32 m0, s79, 0x2000
	s_nop 0
	global_load_lds_dwordx4 v[224:225], off
	v_lshl_add_u64 v[224:225], s[64:65], 0, v[128:129]
	s_mov_b32 m0, s69
	s_nop 0
	global_load_lds_dwordx4 v[224:225], off
	s_mov_b32 m0, s70
	s_nop 0
	global_load_lds_dwordx4 v[226:227], off
	s_waitcnt vmcnt(8)
	s_waitcnt lgkmcnt(0)
	s_barrier
	s_setprio 1
	s_waitcnt lgkmcnt(0)
	v_mfma_f32_16x16x32_bf16 v[92:95], v[152:155], v[188:191], v[92:95]
	v_mfma_f32_16x16x32_bf16 v[92:95], v[156:159], v[192:195], v[92:95]
	v_mfma_f32_16x16x32_bf16 v[88:91], v[160:163], v[188:191], v[88:91]
	v_mfma_f32_16x16x32_bf16 v[88:91], v[164:167], v[192:195], v[88:91]
	v_mfma_f32_16x16x32_bf16 v[84:87], v[152:155], v[196:199], v[84:87]
	v_mfma_f32_16x16x32_bf16 v[84:87], v[156:159], v[200:203], v[84:87]
	v_mfma_f32_16x16x32_bf16 v[80:83], v[160:163], v[196:199], v[80:83]
	v_mfma_f32_16x16x32_bf16 v[80:83], v[164:167], v[200:203], v[80:83]
	v_mfma_f32_16x16x32_bf16 v[72:75], v[152:155], v[204:207], v[72:75]
	v_mfma_f32_16x16x32_bf16 v[72:75], v[156:159], v[208:211], v[72:75]
	v_mfma_f32_16x16x32_bf16 v[64:67], v[160:163], v[204:207], v[64:67]
	v_mfma_f32_16x16x32_bf16 v[64:67], v[164:167], v[208:211], v[64:67]
	v_mfma_f32_16x16x32_bf16 v[56:59], v[152:155], v[212:215], v[56:59]
	v_mfma_f32_16x16x32_bf16 v[56:59], v[156:159], v[216:219], v[56:59]
	v_mfma_f32_16x16x32_bf16 v[48:51], v[160:163], v[212:215], v[48:51]
	v_mfma_f32_16x16x32_bf16 v[48:51], v[164:167], v[216:219], v[48:51]
	v_mfma_f32_16x16x32_bf16 v[28:31], v[168:171], v[188:191], v[28:31]
	v_mfma_f32_16x16x32_bf16 v[28:31], v[172:175], v[192:195], v[28:31]
	v_mfma_f32_16x16x32_bf16 v[24:27], v[176:179], v[188:191], v[24:27]
	v_mfma_f32_16x16x32_bf16 v[24:27], v[184:187], v[192:195], v[24:27]
	v_mfma_f32_16x16x32_bf16 v[20:23], v[168:171], v[196:199], v[20:23]
	v_mfma_f32_16x16x32_bf16 v[20:23], v[172:175], v[200:203], v[20:23]
	v_mfma_f32_16x16x32_bf16 v[16:19], v[176:179], v[196:199], v[16:19]
	v_mfma_f32_16x16x32_bf16 v[16:19], v[184:187], v[200:203], v[16:19]
	v_mfma_f32_16x16x32_bf16 v[12:15], v[168:171], v[204:207], v[12:15]
	v_mfma_f32_16x16x32_bf16 v[12:15], v[172:175], v[208:211], v[12:15]
	v_mfma_f32_16x16x32_bf16 v[8:11], v[176:179], v[204:207], v[8:11]
	v_mfma_f32_16x16x32_bf16 v[8:11], v[184:187], v[208:211], v[8:11]
	v_mfma_f32_16x16x32_bf16 v[4:7], v[168:171], v[212:215], v[4:7]
	v_mfma_f32_16x16x32_bf16 v[4:7], v[172:175], v[216:219], v[4:7]
	s_setprio 2
	s_barrier
	v_mfma_f32_16x16x32_bf16 v[0:3], v[176:179], v[212:215], v[0:3]
	v_mfma_f32_16x16x32_bf16 v[0:3], v[184:187], v[216:219], v[0:3]
	s_setprio 0
.Lmid_gemm6:
	s_add_i32 s79, 0, 0x18000
	v_add_u32_e32 v151, s79, v147
	s_add_i32 s88, 0, 0x1c000
	ds_read_b128 v[152:155], v151
	ds_read_b128 v[156:159], v151 offset:1024
	ds_read_b128 v[160:163], v151 offset:2048
	ds_read_b128 v[164:167], v151 offset:3072
	v_add_u32_e32 v151, s88, v147
	ds_read_b128 v[168:171], v151
	ds_read_b128 v[172:175], v151 offset:1024
	ds_read_b128 v[176:179], v151 offset:2048
	ds_read_b128 v[184:187], v151 offset:3072
	s_add_u32 s64, s64, 0x40000
	s_addc_u32 s65, s65, 0
	s_mov_b32 m0, s71
	v_lshl_add_u64 v[228:229], s[64:65], 0, v[128:129]
	ds_read_b128 v[188:191], v150 offset:32768
	ds_read_b128 v[192:195], v150 offset:33792
	ds_read_b128 v[196:199], v150 offset:34816
	ds_read_b128 v[200:203], v150 offset:35840
	ds_read_b128 v[204:207], v150 offset:36864
	ds_read_b128 v[208:211], v150 offset:37888
	ds_read_b128 v[212:215], v150 offset:38912
	ds_read_b128 v[216:219], v150 offset:39936
	global_load_lds_dwordx4 v[228:229], off
	v_lshl_add_u64 v[228:229], s[64:65], 0, v[132:133]
	s_mov_b32 m0, s72
	s_nop 0
	global_load_lds_dwordx4 v[228:229], off
	s_waitcnt vmcnt(8)
	s_waitcnt lgkmcnt(0)
	s_barrier
	s_setprio 1
	s_waitcnt lgkmcnt(0)
	v_mfma_f32_16x16x32_bf16 v[124:127], v[152:155], v[188:191], v[124:127]
	v_mfma_f32_16x16x32_bf16 v[124:127], v[156:159], v[192:195], v[124:127]
	v_mfma_f32_16x16x32_bf16 v[120:123], v[160:163], v[188:191], v[120:123]
	v_mfma_f32_16x16x32_bf16 v[120:123], v[164:167], v[192:195], v[120:123]
	v_mfma_f32_16x16x32_bf16 v[116:119], v[152:155], v[196:199], v[116:119]
	v_mfma_f32_16x16x32_bf16 v[116:119], v[156:159], v[200:203], v[116:119]
	v_mfma_f32_16x16x32_bf16 v[112:115], v[160:163], v[196:199], v[112:115]
	v_mfma_f32_16x16x32_bf16 v[112:115], v[164:167], v[200:203], v[112:115]
	v_mfma_f32_16x16x32_bf16 v[108:111], v[152:155], v[204:207], v[108:111]
	v_mfma_f32_16x16x32_bf16 v[108:111], v[156:159], v[208:211], v[108:111]
	v_mfma_f32_16x16x32_bf16 v[104:107], v[160:163], v[204:207], v[104:107]
	v_mfma_f32_16x16x32_bf16 v[104:107], v[164:167], v[208:211], v[104:107]
	v_mfma_f32_16x16x32_bf16 v[100:103], v[152:155], v[212:215], v[100:103]
	v_mfma_f32_16x16x32_bf16 v[100:103], v[156:159], v[216:219], v[100:103]
	v_mfma_f32_16x16x32_bf16 v[96:99], v[160:163], v[212:215], v[96:99]
	v_mfma_f32_16x16x32_bf16 v[96:99], v[164:167], v[216:219], v[96:99]
	v_mfma_f32_16x16x32_bf16 v[76:79], v[168:171], v[188:191], v[76:79]
	v_mfma_f32_16x16x32_bf16 v[76:79], v[172:175], v[192:195], v[76:79]
	v_mfma_f32_16x16x32_bf16 v[68:71], v[176:179], v[188:191], v[68:71]
	v_mfma_f32_16x16x32_bf16 v[68:71], v[184:187], v[192:195], v[68:71]
	v_mfma_f32_16x16x32_bf16 v[60:63], v[168:171], v[196:199], v[60:63]
	v_mfma_f32_16x16x32_bf16 v[60:63], v[172:175], v[200:203], v[60:63]
	v_mfma_f32_16x16x32_bf16 v[52:55], v[176:179], v[196:199], v[52:55]
	v_mfma_f32_16x16x32_bf16 v[52:55], v[184:187], v[200:203], v[52:55]
	v_mfma_f32_16x16x32_bf16 v[44:47], v[168:171], v[204:207], v[44:47]
	v_mfma_f32_16x16x32_bf16 v[44:47], v[172:175], v[208:211], v[44:47]
	v_mfma_f32_16x16x32_bf16 v[40:43], v[176:179], v[204:207], v[40:43]
	v_mfma_f32_16x16x32_bf16 v[40:43], v[184:187], v[208:211], v[40:43]
	v_mfma_f32_16x16x32_bf16 v[36:39], v[168:171], v[212:215], v[36:39]
	v_mfma_f32_16x16x32_bf16 v[36:39], v[172:175], v[216:219], v[36:39]
	s_setprio 2
	s_barrier
	v_mfma_f32_16x16x32_bf16 v[32:35], v[176:179], v[212:215], v[32:35]
	v_mfma_f32_16x16x32_bf16 v[32:35], v[184:187], v[216:219], v[32:35]
	s_setprio 0
	s_add_i32 s64, s79, s68
	v_lshl_add_u64 v[220:221], v[220:221], 0, s[12:13]
	s_mov_b32 m0, s64
	ds_read_b128 v[188:191], v150 offset:49152
	ds_read_b128 v[192:195], v150 offset:50176
	ds_read_b128 v[196:199], v150 offset:51200
	ds_read_b128 v[200:203], v150 offset:52224
	ds_read_b128 v[204:207], v150 offset:53248
	ds_read_b128 v[208:211], v150 offset:54272
	ds_read_b128 v[212:215], v150 offset:55296
	ds_read_b128 v[216:219], v150 offset:56320
	global_load_lds_dwordx4 v[220:221], off
	s_add_i32 m0, s64, 0x2000
	s_add_u32 s62, s62, 0x40080
	v_lshl_add_u64 v[220:221], v[222:223], 0, s[12:13]
	s_addc_u32 s63, s63, 0
	s_add_i32 s64, s88, s68
	global_load_lds_dwordx4 v[220:221], off
	v_lshl_add_u64 v[220:221], s[62:63], 0, v[130:131]
	s_mov_b32 m0, s64
	s_nop 0
	global_load_lds_dwordx4 v[220:221], off
	v_lshl_add_u64 v[220:221], s[62:63], 0, v[134:135]
	s_add_i32 m0, s64, 0x2000
	s_nop 0
	global_load_lds_dwordx4 v[220:221], off
	v_lshl_add_u64 v[220:221], v[224:225], 0, s[12:13]
	s_mov_b32 m0, s75
	s_nop 0
	global_load_lds_dwordx4 v[220:221], off
	v_lshl_add_u64 v[220:221], v[226:227], 0, s[12:13]
	s_mov_b32 m0, s76
	s_nop 0
	global_load_lds_dwordx4 v[220:221], off
	s_waitcnt vmcnt(8)
	s_waitcnt lgkmcnt(0)
	s_barrier
	s_setprio 1
	s_waitcnt lgkmcnt(0)
	v_mfma_f32_16x16x32_bf16 v[92:95], v[152:155], v[188:191], v[92:95]
	v_mfma_f32_16x16x32_bf16 v[92:95], v[156:159], v[192:195], v[92:95]
	v_mfma_f32_16x16x32_bf16 v[88:91], v[160:163], v[188:191], v[88:91]
	v_mfma_f32_16x16x32_bf16 v[88:91], v[164:167], v[192:195], v[88:91]
	v_mfma_f32_16x16x32_bf16 v[84:87], v[152:155], v[196:199], v[84:87]
	v_mfma_f32_16x16x32_bf16 v[84:87], v[156:159], v[200:203], v[84:87]
	v_mfma_f32_16x16x32_bf16 v[80:83], v[160:163], v[196:199], v[80:83]
	v_mfma_f32_16x16x32_bf16 v[80:83], v[164:167], v[200:203], v[80:83]
	v_mfma_f32_16x16x32_bf16 v[72:75], v[152:155], v[204:207], v[72:75]
	v_mfma_f32_16x16x32_bf16 v[72:75], v[156:159], v[208:211], v[72:75]
	v_mfma_f32_16x16x32_bf16 v[64:67], v[160:163], v[204:207], v[64:67]
	v_mfma_f32_16x16x32_bf16 v[64:67], v[164:167], v[208:211], v[64:67]
	v_mfma_f32_16x16x32_bf16 v[56:59], v[152:155], v[212:215], v[56:59]
	v_mfma_f32_16x16x32_bf16 v[56:59], v[156:159], v[216:219], v[56:59]
	v_mfma_f32_16x16x32_bf16 v[48:51], v[160:163], v[212:215], v[48:51]
	v_mfma_f32_16x16x32_bf16 v[48:51], v[164:167], v[216:219], v[48:51]
	v_mfma_f32_16x16x32_bf16 v[28:31], v[168:171], v[188:191], v[28:31]
	v_mfma_f32_16x16x32_bf16 v[28:31], v[172:175], v[192:195], v[28:31]
	v_mfma_f32_16x16x32_bf16 v[24:27], v[176:179], v[188:191], v[24:27]
	v_mfma_f32_16x16x32_bf16 v[24:27], v[184:187], v[192:195], v[24:27]
	v_mfma_f32_16x16x32_bf16 v[20:23], v[168:171], v[196:199], v[20:23]
	v_mfma_f32_16x16x32_bf16 v[20:23], v[172:175], v[200:203], v[20:23]
	v_mfma_f32_16x16x32_bf16 v[16:19], v[176:179], v[196:199], v[16:19]
	v_mfma_f32_16x16x32_bf16 v[16:19], v[184:187], v[200:203], v[16:19]
	v_mfma_f32_16x16x32_bf16 v[12:15], v[168:171], v[204:207], v[12:15]
	v_mfma_f32_16x16x32_bf16 v[12:15], v[172:175], v[208:211], v[12:15]
	v_mfma_f32_16x16x32_bf16 v[8:11], v[176:179], v[204:207], v[8:11]
	v_mfma_f32_16x16x32_bf16 v[8:11], v[184:187], v[208:211], v[8:11]
	v_mfma_f32_16x16x32_bf16 v[4:7], v[168:171], v[212:215], v[4:7]
	v_mfma_f32_16x16x32_bf16 v[4:7], v[172:175], v[216:219], v[4:7]
	s_setprio 2
	s_barrier
	v_mfma_f32_16x16x32_bf16 v[0:3], v[176:179], v[212:215], v[0:3]
	v_mfma_f32_16x16x32_bf16 v[0:3], v[184:187], v[216:219], v[0:3]
	s_setprio 0
	s_add_i32 s87, s87, 2
	s_add_u32 s60, s60, 0x100
	s_addc_u32 s61, s61, 0
	s_add_u32 s85, s85, 0x100
	s_addc_u32 s86, s86, 0
	s_cmp_gt_u32 s87, 13
	s_cbranch_scc0 .LBB0_935
	s_and_b64 vcc, exec, s[16:17]
	s_cbranch_vccz .LBB0_938
	s_barrier

.LBB0_950:
	s_ashr_i32 s37, s36, 31
	s_lshl_b64 s[44:45], s[36:37], 19
	s_add_u32 s44, s80, s44
	s_addc_u32 s45, s81, s45
	s_and_b64 s[46:47], s[10:11], exec
	s_cselect_b32 s37, s45, s53
	s_cselect_b32 s72, s44, s52
	s_ashr_i32 s19, s18, 31
	s_lshl_b64 s[46:47], s[18:19], 19
	s_add_u32 s46, s58, s46
	s_addc_u32 s47, s59, s47
	s_and_b64 s[56:57], s[10:11], exec
	s_cselect_b32 s19, s47, s55
	s_cselect_b32 s73, s46, s54
	s_add_u32 s52, s52, 0x40080
	s_addc_u32 s53, s53, 0
	s_add_u32 s74, s54, 0x100
	s_addc_u32 s75, s55, 0
	s_mov_b32 s76, -2
	ds_read_b128 v[140:143], v147
	ds_read_b128 v[150:153], v147 offset:1024
	ds_read_b128 v[154:157], v147 offset:2048
	ds_read_b128 v[158:161], v147 offset:3072
	ds_read_b128 v[162:165], v148
	ds_read_b128 v[166:169], v148 offset:1024
	ds_read_b128 v[170:173], v148 offset:2048
	ds_read_b128 v[174:177], v148 offset:3072
	s_add_u32 s54, s52, 0xfffc0080
	s_addc_u32 s55, s53, -1
	s_cmp_eq_u32 s76, 12
	s_cselect_b32 s57, s37, s55
	s_cselect_b32 s56, s72, s54
	s_cselect_b32 s55, s19, s75
	s_cselect_b32 s54, s73, s74
	v_lshl_add_u64 v[178:179], s[52:53], 0, v[132:133]
	s_add_i32 m0, s49, 0xc000
	ds_read_b128 v[184:187], v149
	ds_read_b128 v[188:191], v149 offset:1024
	ds_read_b128 v[192:195], v149 offset:2048
	ds_read_b128 v[196:199], v149 offset:3072
	ds_read_b128 v[200:203], v149 offset:4096
	ds_read_b128 v[204:207], v149 offset:5120
	ds_read_b128 v[208:211], v149 offset:6144
	ds_read_b128 v[212:215], v149 offset:7168
	global_load_lds_dwordx4 v[178:179], off
	v_lshl_add_u64 v[178:179], s[52:53], 0, v[134:135]
	s_add_i32 m0, s49, 0xe000
	s_nop 0
	global_load_lds_dwordx4 v[178:179], off
	s_waitcnt vmcnt(8)
	s_waitcnt lgkmcnt(0)
	s_barrier
	s_setprio 1
	s_waitcnt lgkmcnt(0)
	v_mfma_f32_16x16x32_bf16 v[124:127], v[140:143], v[184:187], 0
	v_mfma_f32_16x16x32_bf16 v[124:127], v[150:153], v[188:191], v[124:127]
	v_mfma_f32_16x16x32_bf16 v[120:123], v[154:157], v[184:187], 0
	v_mfma_f32_16x16x32_bf16 v[120:123], v[158:161], v[188:191], v[120:123]
	v_mfma_f32_16x16x32_bf16 v[108:111], v[140:143], v[192:195], 0
	v_mfma_f32_16x16x32_bf16 v[108:111], v[150:153], v[196:199], v[108:111]
	v_mfma_f32_16x16x32_bf16 v[104:107], v[154:157], v[192:195], 0
	v_mfma_f32_16x16x32_bf16 v[104:107], v[158:161], v[196:199], v[104:107]
	v_mfma_f32_16x16x32_bf16 v[92:95], v[140:143], v[200:203], 0
	v_mfma_f32_16x16x32_bf16 v[92:95], v[150:153], v[204:207], v[92:95]
	v_mfma_f32_16x16x32_bf16 v[88:91], v[154:157], v[200:203], 0
	v_mfma_f32_16x16x32_bf16 v[88:91], v[158:161], v[204:207], v[88:91]
	v_mfma_f32_16x16x32_bf16 v[76:79], v[140:143], v[208:211], 0
	v_mfma_f32_16x16x32_bf16 v[76:79], v[150:153], v[212:215], v[76:79]
	v_mfma_f32_16x16x32_bf16 v[72:75], v[154:157], v[208:211], 0
	v_mfma_f32_16x16x32_bf16 v[72:75], v[158:161], v[212:215], v[72:75]
	v_mfma_f32_16x16x32_bf16 v[116:119], v[162:165], v[184:187], 0
	v_mfma_f32_16x16x32_bf16 v[116:119], v[166:169], v[188:191], v[116:119]
	v_mfma_f32_16x16x32_bf16 v[112:115], v[170:173], v[184:187], 0
	v_mfma_f32_16x16x32_bf16 v[112:115], v[174:177], v[188:191], v[112:115]
	v_mfma_f32_16x16x32_bf16 v[100:103], v[162:165], v[192:195], 0
	v_mfma_f32_16x16x32_bf16 v[100:103], v[166:169], v[196:199], v[100:103]
	v_mfma_f32_16x16x32_bf16 v[96:99], v[170:173], v[192:195], 0
	v_mfma_f32_16x16x32_bf16 v[96:99], v[174:177], v[196:199], v[96:99]
	v_mfma_f32_16x16x32_bf16 v[84:87], v[162:165], v[200:203], 0
	v_mfma_f32_16x16x32_bf16 v[84:87], v[166:169], v[204:207], v[84:87]
	v_mfma_f32_16x16x32_bf16 v[80:83], v[170:173], v[200:203], 0
	v_mfma_f32_16x16x32_bf16 v[80:83], v[174:177], v[204:207], v[80:83]
	v_mfma_f32_16x16x32_bf16 v[68:71], v[162:165], v[208:211], 0
	v_mfma_f32_16x16x32_bf16 v[68:71], v[166:169], v[212:215], v[68:71]
	s_setprio 2
	s_barrier
	v_mfma_f32_16x16x32_bf16 v[64:67], v[170:173], v[208:211], 0
	v_mfma_f32_16x16x32_bf16 v[64:67], v[174:177], v[212:215], v[64:67]
	s_setprio 0
	s_add_i32 s77, s68, s60
	v_lshl_add_u64 v[178:179], s[54:55], 0, v[130:131]
	s_mov_b32 m0, s77
	ds_read_b128 v[184:187], v149 offset:16384
	ds_read_b128 v[188:191], v149 offset:17408
	ds_read_b128 v[192:195], v149 offset:18432
	ds_read_b128 v[196:199], v149 offset:19456
	ds_read_b128 v[200:203], v149 offset:20480
	ds_read_b128 v[204:207], v149 offset:21504
	ds_read_b128 v[208:211], v149 offset:22528
	ds_read_b128 v[212:215], v149 offset:23552
	global_load_lds_dwordx4 v[178:179], off
	s_add_i32 m0, s77, 0x2000
	s_add_u32 s82, s54, 0x40000
	v_lshl_add_u64 v[216:217], s[54:55], 0, v[128:129]
	s_addc_u32 s83, s55, 0
	s_add_i32 s77, s69, s60
	global_load_lds_dwordx4 v[216:217], off
	v_lshl_add_u64 v[218:219], s[82:83], 0, v[130:131]
	s_mov_b32 m0, s77
	v_lshl_add_u64 v[220:221], s[56:57], 0, v[128:129]
	global_load_lds_dwordx4 v[218:219], off
	v_lshl_add_u64 v[218:219], s[82:83], 0, v[128:129]
	s_add_i32 m0, s77, 0x2000
	s_nop 0
	global_load_lds_dwordx4 v[218:219], off
	v_lshl_add_u64 v[218:219], s[56:57], 0, v[130:131]
	s_mov_b32 m0, s49
	s_nop 0
	global_load_lds_dwordx4 v[218:219], off
	s_mov_b32 m0, s62
	s_nop 0
	global_load_lds_dwordx4 v[220:221], off
	s_waitcnt vmcnt(8)
	s_waitcnt lgkmcnt(0)
	s_barrier
	s_setprio 1
	s_waitcnt lgkmcnt(0)
	v_mfma_f32_16x16x32_bf16 v[60:63], v[140:143], v[184:187], 0
	v_mfma_f32_16x16x32_bf16 v[60:63], v[150:153], v[188:191], v[60:63]
	v_mfma_f32_16x16x32_bf16 v[56:59], v[154:157], v[184:187], 0
	v_mfma_f32_16x16x32_bf16 v[56:59], v[158:161], v[188:191], v[56:59]
	v_mfma_f32_16x16x32_bf16 v[44:47], v[140:143], v[192:195], 0
	v_mfma_f32_16x16x32_bf16 v[44:47], v[150:153], v[196:199], v[44:47]
	v_mfma_f32_16x16x32_bf16 v[40:43], v[154:157], v[192:195], 0
	v_mfma_f32_16x16x32_bf16 v[40:43], v[158:161], v[196:199], v[40:43]
	v_mfma_f32_16x16x32_bf16 v[28:31], v[140:143], v[200:203], 0
	v_mfma_f32_16x16x32_bf16 v[28:31], v[150:153], v[204:207], v[28:31]
	v_mfma_f32_16x16x32_bf16 v[24:27], v[154:157], v[200:203], 0
	v_mfma_f32_16x16x32_bf16 v[24:27], v[158:161], v[204:207], v[24:27]
	v_mfma_f32_16x16x32_bf16 v[12:15], v[140:143], v[208:211], 0
	v_mfma_f32_16x16x32_bf16 v[12:15], v[150:153], v[212:215], v[12:15]
	v_mfma_f32_16x16x32_bf16 v[8:11], v[154:157], v[208:211], 0
	v_mfma_f32_16x16x32_bf16 v[8:11], v[158:161], v[212:215], v[8:11]
	v_mfma_f32_16x16x32_bf16 v[52:55], v[162:165], v[184:187], 0
	v_mfma_f32_16x16x32_bf16 v[52:55], v[166:169], v[188:191], v[52:55]
	v_mfma_f32_16x16x32_bf16 v[48:51], v[170:173], v[184:187], 0
	v_mfma_f32_16x16x32_bf16 v[48:51], v[174:177], v[188:191], v[48:51]
	v_mfma_f32_16x16x32_bf16 v[36:39], v[162:165], v[192:195], 0
	v_mfma_f32_16x16x32_bf16 v[36:39], v[166:169], v[196:199], v[36:39]
	v_mfma_f32_16x16x32_bf16 v[32:35], v[170:173], v[192:195], 0
	v_mfma_f32_16x16x32_bf16 v[32:35], v[174:177], v[196:199], v[32:35]
	v_mfma_f32_16x16x32_bf16 v[20:23], v[162:165], v[200:203], 0
	v_mfma_f32_16x16x32_bf16 v[20:23], v[166:169], v[204:207], v[20:23]
	v_mfma_f32_16x16x32_bf16 v[16:19], v[170:173], v[200:203], 0
	v_mfma_f32_16x16x32_bf16 v[16:19], v[174:177], v[204:207], v[16:19]
	v_mfma_f32_16x16x32_bf16 v[4:7], v[162:165], v[208:211], 0
	v_mfma_f32_16x16x32_bf16 v[4:7], v[166:169], v[212:215], v[4:7]
	s_setprio 2
	s_barrier
	v_mfma_f32_16x16x32_bf16 v[0:3], v[170:173], v[208:211], 0
	v_mfma_f32_16x16x32_bf16 v[0:3], v[174:177], v[212:215], v[0:3]
	s_setprio 0
	s_branch .Lmid_gemm7
.LBB0_951:
	ds_read_b128 v[140:143], v147
	ds_read_b128 v[150:153], v147 offset:1024
	ds_read_b128 v[154:157], v147 offset:2048
	ds_read_b128 v[158:161], v147 offset:3072
	ds_read_b128 v[162:165], v148
	ds_read_b128 v[166:169], v148 offset:1024
	ds_read_b128 v[170:173], v148 offset:2048
	ds_read_b128 v[174:177], v148 offset:3072
	s_add_u32 s54, s52, 0xfffc0080
	s_addc_u32 s55, s53, -1
	s_cmp_eq_u32 s76, 12
	s_cselect_b32 s57, s37, s55
	s_cselect_b32 s56, s72, s54
	s_cselect_b32 s55, s19, s75
	s_cselect_b32 s54, s73, s74
	v_lshl_add_u64 v[178:179], s[52:53], 0, v[132:133]
	s_add_i32 m0, s49, 0xc000
	ds_read_b128 v[184:187], v149
	ds_read_b128 v[188:191], v149 offset:1024
	ds_read_b128 v[192:195], v149 offset:2048
	ds_read_b128 v[196:199], v149 offset:3072
	ds_read_b128 v[200:203], v149 offset:4096
	ds_read_b128 v[204:207], v149 offset:5120
	ds_read_b128 v[208:211], v149 offset:6144
	ds_read_b128 v[212:215], v149 offset:7168
	global_load_lds_dwordx4 v[178:179], off
	v_lshl_add_u64 v[178:179], s[52:53], 0, v[134:135]
	s_add_i32 m0, s49, 0xe000
	s_nop 0
	global_load_lds_dwordx4 v[178:179], off
	s_waitcnt vmcnt(8)
	s_waitcnt lgkmcnt(0)
	s_barrier
	s_setprio 1
	s_waitcnt lgkmcnt(0)
	v_mfma_f32_16x16x32_bf16 v[124:127], v[140:143], v[184:187], v[124:127]
	v_mfma_f32_16x16x32_bf16 v[124:127], v[150:153], v[188:191], v[124:127]
	v_mfma_f32_16x16x32_bf16 v[120:123], v[154:157], v[184:187], v[120:123]
	v_mfma_f32_16x16x32_bf16 v[120:123], v[158:161], v[188:191], v[120:123]
	v_mfma_f32_16x16x32_bf16 v[108:111], v[140:143], v[192:195], v[108:111]
	v_mfma_f32_16x16x32_bf16 v[108:111], v[150:153], v[196:199], v[108:111]
	v_mfma_f32_16x16x32_bf16 v[104:107], v[154:157], v[192:195], v[104:107]
	v_mfma_f32_16x16x32_bf16 v[104:107], v[158:161], v[196:199], v[104:107]
	v_mfma_f32_16x16x32_bf16 v[92:95], v[140:143], v[200:203], v[92:95]
	v_mfma_f32_16x16x32_bf16 v[92:95], v[150:153], v[204:207], v[92:95]
	v_mfma_f32_16x16x32_bf16 v[88:91], v[154:157], v[200:203], v[88:91]
	v_mfma_f32_16x16x32_bf16 v[88:91], v[158:161], v[204:207], v[88:91]
	v_mfma_f32_16x16x32_bf16 v[76:79], v[140:143], v[208:211], v[76:79]
	v_mfma_f32_16x16x32_bf16 v[76:79], v[150:153], v[212:215], v[76:79]
	v_mfma_f32_16x16x32_bf16 v[72:75], v[154:157], v[208:211], v[72:75]
	v_mfma_f32_16x16x32_bf16 v[72:75], v[158:161], v[212:215], v[72:75]
	v_mfma_f32_16x16x32_bf16 v[116:119], v[162:165], v[184:187], v[116:119]
	v_mfma_f32_16x16x32_bf16 v[116:119], v[166:169], v[188:191], v[116:119]
	v_mfma_f32_16x16x32_bf16 v[112:115], v[170:173], v[184:187], v[112:115]
	v_mfma_f32_16x16x32_bf16 v[112:115], v[174:177], v[188:191], v[112:115]
	v_mfma_f32_16x16x32_bf16 v[100:103], v[162:165], v[192:195], v[100:103]
	v_mfma_f32_16x16x32_bf16 v[100:103], v[166:169], v[196:199], v[100:103]
	v_mfma_f32_16x16x32_bf16 v[96:99], v[170:173], v[192:195], v[96:99]
	v_mfma_f32_16x16x32_bf16 v[96:99], v[174:177], v[196:199], v[96:99]
	v_mfma_f32_16x16x32_bf16 v[84:87], v[162:165], v[200:203], v[84:87]
	v_mfma_f32_16x16x32_bf16 v[84:87], v[166:169], v[204:207], v[84:87]
	v_mfma_f32_16x16x32_bf16 v[80:83], v[170:173], v[200:203], v[80:83]
	v_mfma_f32_16x16x32_bf16 v[80:83], v[174:177], v[204:207], v[80:83]
	v_mfma_f32_16x16x32_bf16 v[68:71], v[162:165], v[208:211], v[68:71]
	v_mfma_f32_16x16x32_bf16 v[68:71], v[166:169], v[212:215], v[68:71]
	s_setprio 2
	s_barrier
	v_mfma_f32_16x16x32_bf16 v[64:67], v[170:173], v[208:211], v[64:67]
	v_mfma_f32_16x16x32_bf16 v[64:67], v[174:177], v[212:215], v[64:67]
	s_setprio 0
	s_add_i32 s77, s68, s60
	v_lshl_add_u64 v[178:179], s[54:55], 0, v[130:131]
	s_mov_b32 m0, s77
	ds_read_b128 v[184:187], v149 offset:16384
	ds_read_b128 v[188:191], v149 offset:17408
	ds_read_b128 v[192:195], v149 offset:18432
	ds_read_b128 v[196:199], v149 offset:19456
	ds_read_b128 v[200:203], v149 offset:20480
	ds_read_b128 v[204:207], v149 offset:21504
	ds_read_b128 v[208:211], v149 offset:22528
	ds_read_b128 v[212:215], v149 offset:23552
	global_load_lds_dwordx4 v[178:179], off
	s_add_i32 m0, s77, 0x2000
	s_add_u32 s82, s54, 0x40000
	v_lshl_add_u64 v[216:217], s[54:55], 0, v[128:129]
	s_addc_u32 s83, s55, 0
	s_add_i32 s77, s69, s60
	global_load_lds_dwordx4 v[216:217], off
	v_lshl_add_u64 v[218:219], s[82:83], 0, v[130:131]
	s_mov_b32 m0, s77
	v_lshl_add_u64 v[220:221], s[56:57], 0, v[128:129]
	global_load_lds_dwordx4 v[218:219], off
	v_lshl_add_u64 v[218:219], s[82:83], 0, v[128:129]
	s_add_i32 m0, s77, 0x2000
	s_nop 0
	global_load_lds_dwordx4 v[218:219], off
	v_lshl_add_u64 v[218:219], s[56:57], 0, v[130:131]
	s_mov_b32 m0, s49
	s_nop 0
	global_load_lds_dwordx4 v[218:219], off
	s_mov_b32 m0, s62
	s_nop 0
	global_load_lds_dwordx4 v[220:221], off
	s_waitcnt vmcnt(8)
	s_waitcnt lgkmcnt(0)
	s_barrier
	s_setprio 1
	s_waitcnt lgkmcnt(0)
	v_mfma_f32_16x16x32_bf16 v[60:63], v[140:143], v[184:187], v[60:63]
	v_mfma_f32_16x16x32_bf16 v[60:63], v[150:153], v[188:191], v[60:63]
	v_mfma_f32_16x16x32_bf16 v[56:59], v[154:157], v[184:187], v[56:59]
	v_mfma_f32_16x16x32_bf16 v[56:59], v[158:161], v[188:191], v[56:59]
	v_mfma_f32_16x16x32_bf16 v[44:47], v[140:143], v[192:195], v[44:47]
	v_mfma_f32_16x16x32_bf16 v[44:47], v[150:153], v[196:199], v[44:47]
	v_mfma_f32_16x16x32_bf16 v[40:43], v[154:157], v[192:195], v[40:43]
	v_mfma_f32_16x16x32_bf16 v[40:43], v[158:161], v[196:199], v[40:43]
	v_mfma_f32_16x16x32_bf16 v[28:31], v[140:143], v[200:203], v[28:31]
	v_mfma_f32_16x16x32_bf16 v[28:31], v[150:153], v[204:207], v[28:31]
	v_mfma_f32_16x16x32_bf16 v[24:27], v[154:157], v[200:203], v[24:27]
	v_mfma_f32_16x16x32_bf16 v[24:27], v[158:161], v[204:207], v[24:27]
	v_mfma_f32_16x16x32_bf16 v[12:15], v[140:143], v[208:211], v[12:15]
	v_mfma_f32_16x16x32_bf16 v[12:15], v[150:153], v[212:215], v[12:15]
	v_mfma_f32_16x16x32_bf16 v[8:11], v[154:157], v[208:211], v[8:11]
	v_mfma_f32_16x16x32_bf16 v[8:11], v[158:161], v[212:215], v[8:11]
	v_mfma_f32_16x16x32_bf16 v[52:55], v[162:165], v[184:187], v[52:55]
	v_mfma_f32_16x16x32_bf16 v[52:55], v[166:169], v[188:191], v[52:55]
	v_mfma_f32_16x16x32_bf16 v[48:51], v[170:173], v[184:187], v[48:51]
	v_mfma_f32_16x16x32_bf16 v[48:51], v[174:177], v[188:191], v[48:51]
	v_mfma_f32_16x16x32_bf16 v[36:39], v[162:165], v[192:195], v[36:39]
	v_mfma_f32_16x16x32_bf16 v[36:39], v[166:169], v[196:199], v[36:39]
	v_mfma_f32_16x16x32_bf16 v[32:35], v[170:173], v[192:195], v[32:35]
	v_mfma_f32_16x16x32_bf16 v[32:35], v[174:177], v[196:199], v[32:35]
	v_mfma_f32_16x16x32_bf16 v[20:23], v[162:165], v[200:203], v[20:23]
	v_mfma_f32_16x16x32_bf16 v[20:23], v[166:169], v[204:207], v[20:23]
	v_mfma_f32_16x16x32_bf16 v[16:19], v[170:173], v[200:203], v[16:19]
	v_mfma_f32_16x16x32_bf16 v[16:19], v[174:177], v[204:207], v[16:19]
	v_mfma_f32_16x16x32_bf16 v[4:7], v[162:165], v[208:211], v[4:7]
	v_mfma_f32_16x16x32_bf16 v[4:7], v[166:169], v[212:215], v[4:7]
	s_setprio 2
	s_barrier
	v_mfma_f32_16x16x32_bf16 v[0:3], v[170:173], v[208:211], v[0:3]
	v_mfma_f32_16x16x32_bf16 v[0:3], v[174:177], v[212:215], v[0:3]
	s_setprio 0
.Lmid_gemm7:
	s_add_i32 s77, 0, 0x18000
	s_add_i32 s79, 0, 0x1c000
	v_add_u32_e32 v158, s77, v145
	v_add_u32_e32 v174, s79, v145
	ds_read_b128 v[140:143], v158
	ds_read_b128 v[150:153], v158 offset:1024
	ds_read_b128 v[154:157], v158 offset:2048
	ds_read_b128 v[158:161], v158 offset:3072
	ds_read_b128 v[162:165], v174
	ds_read_b128 v[166:169], v174 offset:1024
	ds_read_b128 v[170:173], v174 offset:2048
	ds_read_b128 v[174:177], v174 offset:3072
	s_add_u32 s56, s56, 0x40000
	s_addc_u32 s57, s57, 0
	s_mov_b32 m0, s63
	v_lshl_add_u64 v[222:223], s[56:57], 0, v[130:131]
	ds_read_b128 v[184:187], v149 offset:32768
	ds_read_b128 v[188:191], v149 offset:33792
	ds_read_b128 v[192:195], v149 offset:34816
	ds_read_b128 v[196:199], v149 offset:35840
	ds_read_b128 v[200:203], v149 offset:36864
	ds_read_b128 v[204:207], v149 offset:37888
	ds_read_b128 v[208:211], v149 offset:38912
	ds_read_b128 v[212:215], v149 offset:39936
	global_load_lds_dwordx4 v[222:223], off
	v_lshl_add_u64 v[222:223], s[56:57], 0, v[128:129]
	s_mov_b32 m0, s64
	s_nop 0
	global_load_lds_dwordx4 v[222:223], off
	s_waitcnt vmcnt(8)
	s_waitcnt lgkmcnt(0)
	s_barrier
	s_setprio 1
	s_waitcnt lgkmcnt(0)
	v_mfma_f32_16x16x32_bf16 v[124:127], v[140:143], v[184:187], v[124:127]
	v_mfma_f32_16x16x32_bf16 v[124:127], v[150:153], v[188:191], v[124:127]
	v_mfma_f32_16x16x32_bf16 v[120:123], v[154:157], v[184:187], v[120:123]
	v_mfma_f32_16x16x32_bf16 v[120:123], v[158:161], v[188:191], v[120:123]
	v_mfma_f32_16x16x32_bf16 v[108:111], v[140:143], v[192:195], v[108:111]
	v_mfma_f32_16x16x32_bf16 v[108:111], v[150:153], v[196:199], v[108:111]
	v_mfma_f32_16x16x32_bf16 v[104:107], v[154:157], v[192:195], v[104:107]
	v_mfma_f32_16x16x32_bf16 v[104:107], v[158:161], v[196:199], v[104:107]
	v_mfma_f32_16x16x32_bf16 v[92:95], v[140:143], v[200:203], v[92:95]
	v_mfma_f32_16x16x32_bf16 v[92:95], v[150:153], v[204:207], v[92:95]
	v_mfma_f32_16x16x32_bf16 v[88:91], v[154:157], v[200:203], v[88:91]
	v_mfma_f32_16x16x32_bf16 v[88:91], v[158:161], v[204:207], v[88:91]
	v_mfma_f32_16x16x32_bf16 v[76:79], v[140:143], v[208:211], v[76:79]
	v_mfma_f32_16x16x32_bf16 v[76:79], v[150:153], v[212:215], v[76:79]
	v_mfma_f32_16x16x32_bf16 v[72:75], v[154:157], v[208:211], v[72:75]
	v_mfma_f32_16x16x32_bf16 v[72:75], v[158:161], v[212:215], v[72:75]
	v_mfma_f32_16x16x32_bf16 v[116:119], v[162:165], v[184:187], v[116:119]
	v_mfma_f32_16x16x32_bf16 v[116:119], v[166:169], v[188:191], v[116:119]
	v_mfma_f32_16x16x32_bf16 v[112:115], v[170:173], v[184:187], v[112:115]
	v_mfma_f32_16x16x32_bf16 v[112:115], v[174:177], v[188:191], v[112:115]
	v_mfma_f32_16x16x32_bf16 v[100:103], v[162:165], v[192:195], v[100:103]
	v_mfma_f32_16x16x32_bf16 v[100:103], v[166:169], v[196:199], v[100:103]
	v_mfma_f32_16x16x32_bf16 v[96:99], v[170:173], v[192:195], v[96:99]
	v_mfma_f32_16x16x32_bf16 v[96:99], v[174:177], v[196:199], v[96:99]
	v_mfma_f32_16x16x32_bf16 v[84:87], v[162:165], v[200:203], v[84:87]
	v_mfma_f32_16x16x32_bf16 v[84:87], v[166:169], v[204:207], v[84:87]
	v_mfma_f32_16x16x32_bf16 v[80:83], v[170:173], v[200:203], v[80:83]
	v_mfma_f32_16x16x32_bf16 v[80:83], v[174:177], v[204:207], v[80:83]
	v_mfma_f32_16x16x32_bf16 v[68:71], v[162:165], v[208:211], v[68:71]
	v_mfma_f32_16x16x32_bf16 v[68:71], v[166:169], v[212:215], v[68:71]
	s_setprio 2
	s_barrier
	v_mfma_f32_16x16x32_bf16 v[64:67], v[170:173], v[208:211], v[64:67]
	v_mfma_f32_16x16x32_bf16 v[64:67], v[174:177], v[212:215], v[64:67]
	s_setprio 0
	s_add_i32 s56, s77, s60
	v_lshl_add_u64 v[178:179], v[178:179], 0, s[12:13]
	s_mov_b32 m0, s56
	ds_read_b128 v[184:187], v149 offset:49152
	ds_read_b128 v[188:191], v149 offset:50176
	ds_read_b128 v[192:195], v149 offset:51200
	ds_read_b128 v[196:199], v149 offset:52224
	ds_read_b128 v[200:203], v149 offset:53248
	ds_read_b128 v[204:207], v149 offset:54272
	ds_read_b128 v[208:211], v149 offset:55296
	ds_read_b128 v[212:215], v149 offset:56320
	global_load_lds_dwordx4 v[178:179], off
	s_add_i32 m0, s56, 0x2000
	s_add_u32 s54, s54, 0x40080
	v_lshl_add_u64 v[178:179], v[216:217], 0, s[12:13]
	s_addc_u32 s55, s55, 0
	s_add_i32 s56, s79, s60
	global_load_lds_dwordx4 v[178:179], off
	v_lshl_add_u64 v[178:179], s[54:55], 0, v[130:131]
	s_mov_b32 m0, s56
	s_nop 0
	global_load_lds_dwordx4 v[178:179], off
	v_lshl_add_u64 v[178:179], s[54:55], 0, v[128:129]
	s_add_i32 m0, s56, 0x2000
	s_nop 0
	global_load_lds_dwordx4 v[178:179], off
	v_lshl_add_u64 v[178:179], v[218:219], 0, s[12:13]
	s_mov_b32 m0, s66
	s_nop 0
	global_load_lds_dwordx4 v[178:179], off
	v_lshl_add_u64 v[178:179], v[220:221], 0, s[12:13]
	s_mov_b32 m0, s67
	s_nop 0
	global_load_lds_dwordx4 v[178:179], off
	s_waitcnt vmcnt(8)
	s_waitcnt lgkmcnt(0)
	s_barrier
	s_setprio 1
	s_waitcnt lgkmcnt(0)
	v_mfma_f32_16x16x32_bf16 v[60:63], v[140:143], v[184:187], v[60:63]
	v_mfma_f32_16x16x32_bf16 v[60:63], v[150:153], v[188:191], v[60:63]
	v_mfma_f32_16x16x32_bf16 v[56:59], v[154:157], v[184:187], v[56:59]
	v_mfma_f32_16x16x32_bf16 v[56:59], v[158:161], v[188:191], v[56:59]
	v_mfma_f32_16x16x32_bf16 v[44:47], v[140:143], v[192:195], v[44:47]
	v_mfma_f32_16x16x32_bf16 v[44:47], v[150:153], v[196:199], v[44:47]
	v_mfma_f32_16x16x32_bf16 v[40:43], v[154:157], v[192:195], v[40:43]
	v_mfma_f32_16x16x32_bf16 v[40:43], v[158:161], v[196:199], v[40:43]
	v_mfma_f32_16x16x32_bf16 v[28:31], v[140:143], v[200:203], v[28:31]
	v_mfma_f32_16x16x32_bf16 v[28:31], v[150:153], v[204:207], v[28:31]
	v_mfma_f32_16x16x32_bf16 v[24:27], v[154:157], v[200:203], v[24:27]
	v_mfma_f32_16x16x32_bf16 v[24:27], v[158:161], v[204:207], v[24:27]
	v_mfma_f32_16x16x32_bf16 v[12:15], v[140:143], v[208:211], v[12:15]
	v_mfma_f32_16x16x32_bf16 v[12:15], v[150:153], v[212:215], v[12:15]
	v_mfma_f32_16x16x32_bf16 v[8:11], v[154:157], v[208:211], v[8:11]
	v_mfma_f32_16x16x32_bf16 v[8:11], v[158:161], v[212:215], v[8:11]
	v_mfma_f32_16x16x32_bf16 v[52:55], v[162:165], v[184:187], v[52:55]
	v_mfma_f32_16x16x32_bf16 v[52:55], v[166:169], v[188:191], v[52:55]
	v_mfma_f32_16x16x32_bf16 v[48:51], v[170:173], v[184:187], v[48:51]
	v_mfma_f32_16x16x32_bf16 v[48:51], v[174:177], v[188:191], v[48:51]
	v_mfma_f32_16x16x32_bf16 v[36:39], v[162:165], v[192:195], v[36:39]
	v_mfma_f32_16x16x32_bf16 v[36:39], v[166:169], v[196:199], v[36:39]
	v_mfma_f32_16x16x32_bf16 v[32:35], v[170:173], v[192:195], v[32:35]
	v_mfma_f32_16x16x32_bf16 v[32:35], v[174:177], v[196:199], v[32:35]
	v_mfma_f32_16x16x32_bf16 v[20:23], v[162:165], v[200:203], v[20:23]
	v_mfma_f32_16x16x32_bf16 v[20:23], v[166:169], v[204:207], v[20:23]
	v_mfma_f32_16x16x32_bf16 v[16:19], v[170:173], v[200:203], v[16:19]
	v_mfma_f32_16x16x32_bf16 v[16:19], v[174:177], v[204:207], v[16:19]
	v_mfma_f32_16x16x32_bf16 v[4:7], v[162:165], v[208:211], v[4:7]
	v_mfma_f32_16x16x32_bf16 v[4:7], v[166:169], v[212:215], v[4:7]
	s_setprio 2
	s_barrier
	v_mfma_f32_16x16x32_bf16 v[0:3], v[170:173], v[208:211], v[0:3]
	v_mfma_f32_16x16x32_bf16 v[0:3], v[174:177], v[212:215], v[0:3]
	s_setprio 0
	s_add_i32 s76, s76, 2
	s_add_u32 s52, s52, 0x100
	s_addc_u32 s53, s53, 0
	s_add_u32 s74, s74, 0x100
	s_addc_u32 s75, s75, 0
	s_cmp_gt_u32 s76, 13
	s_cbranch_scc0 .LBB0_951
	s_and_b64 vcc, exec, s[16:17]
	s_cbranch_vccz .LBB0_954
	s_barrier

.LBB0_1030:
	s_add_u32 s86, s56, 0x100
	s_addc_u32 s87, s57, 0
	s_mov_b32 s88, -2
	ds_read_b128 v[152:155], v149
	ds_read_b128 v[156:159], v149 offset:1024
	ds_read_b128 v[160:163], v149 offset:2048
	ds_read_b128 v[164:167], v149 offset:3072
	ds_read_b128 v[168:171], v150
	ds_read_b128 v[172:175], v150 offset:1024
	ds_read_b128 v[176:179], v150 offset:2048
	ds_read_b128 v[184:187], v150 offset:3072
	s_add_u32 s56, s54, 0x100
	s_addc_u32 s57, s55, 0
	s_cmp_eq_u32 s88, 40
	s_cselect_b32 s61, s13, s57
	s_cselect_b32 s60, s12, s56
	s_cselect_b32 s59, s53, s87
	s_cselect_b32 s58, s52, s86
	v_lshl_add_u64 v[144:145], s[54:55], 0, v[136:137]
	s_add_i32 m0, s65, 0xc000
	ds_read_b128 v[188:191], v151
	ds_read_b128 v[192:195], v151 offset:1024
	ds_read_b128 v[196:199], v151 offset:2048
	ds_read_b128 v[200:203], v151 offset:3072
	ds_read_b128 v[204:207], v151 offset:4096
	ds_read_b128 v[208:211], v151 offset:5120
	ds_read_b128 v[212:215], v151 offset:6144
	ds_read_b128 v[216:219], v151 offset:7168
	global_load_lds_dwordx4 v[144:145], off
	v_lshl_add_u64 v[144:145], s[54:55], 0, v[138:139]
	s_add_i32 m0, s65, 0xe000
	s_nop 0
	global_load_lds_dwordx4 v[144:145], off
	s_waitcnt vmcnt(8)
	s_waitcnt lgkmcnt(0)
	s_barrier
	s_setprio 1
	s_waitcnt lgkmcnt(0)
	v_mfma_f32_16x16x32_bf16 v[124:127], v[152:155], v[188:191], 0
	v_mfma_f32_16x16x32_bf16 v[124:127], v[156:159], v[192:195], v[124:127]
	v_mfma_f32_16x16x32_bf16 v[120:123], v[160:163], v[188:191], 0
	v_mfma_f32_16x16x32_bf16 v[120:123], v[164:167], v[192:195], v[120:123]
	v_mfma_f32_16x16x32_bf16 v[116:119], v[152:155], v[196:199], 0
	v_mfma_f32_16x16x32_bf16 v[116:119], v[156:159], v[200:203], v[116:119]
	v_mfma_f32_16x16x32_bf16 v[108:111], v[160:163], v[196:199], 0
	v_mfma_f32_16x16x32_bf16 v[108:111], v[164:167], v[200:203], v[108:111]
	v_mfma_f32_16x16x32_bf16 v[100:103], v[152:155], v[204:207], 0
	v_mfma_f32_16x16x32_bf16 v[100:103], v[156:159], v[208:211], v[100:103]
	v_mfma_f32_16x16x32_bf16 v[92:95], v[160:163], v[204:207], 0
	v_mfma_f32_16x16x32_bf16 v[92:95], v[164:167], v[208:211], v[92:95]
	v_mfma_f32_16x16x32_bf16 v[84:87], v[152:155], v[212:215], 0
	v_mfma_f32_16x16x32_bf16 v[84:87], v[156:159], v[216:219], v[84:87]
	v_mfma_f32_16x16x32_bf16 v[76:79], v[160:163], v[212:215], 0
	v_mfma_f32_16x16x32_bf16 v[76:79], v[164:167], v[216:219], v[76:79]
	v_mfma_f32_16x16x32_bf16 v[112:115], v[168:171], v[188:191], 0
	v_mfma_f32_16x16x32_bf16 v[112:115], v[172:175], v[192:195], v[112:115]
	v_mfma_f32_16x16x32_bf16 v[104:107], v[176:179], v[188:191], 0
	v_mfma_f32_16x16x32_bf16 v[104:107], v[184:187], v[192:195], v[104:107]
	v_mfma_f32_16x16x32_bf16 v[96:99], v[168:171], v[196:199], 0
	v_mfma_f32_16x16x32_bf16 v[96:99], v[172:175], v[200:203], v[96:99]
	v_mfma_f32_16x16x32_bf16 v[88:91], v[176:179], v[196:199], 0
	v_mfma_f32_16x16x32_bf16 v[88:91], v[184:187], v[200:203], v[88:91]
	v_mfma_f32_16x16x32_bf16 v[80:83], v[168:171], v[204:207], 0
	v_mfma_f32_16x16x32_bf16 v[80:83], v[172:175], v[208:211], v[80:83]
	v_mfma_f32_16x16x32_bf16 v[72:75], v[176:179], v[204:207], 0
	v_mfma_f32_16x16x32_bf16 v[72:75], v[184:187], v[208:211], v[72:75]
	v_mfma_f32_16x16x32_bf16 v[68:71], v[168:171], v[212:215], 0
	v_mfma_f32_16x16x32_bf16 v[68:71], v[172:175], v[216:219], v[68:71]
	s_setprio 2
	s_barrier
	v_mfma_f32_16x16x32_bf16 v[64:67], v[176:179], v[212:215], 0
	v_mfma_f32_16x16x32_bf16 v[64:67], v[184:187], v[216:219], v[64:67]
	s_setprio 0
	s_add_i32 s54, s72, s64
	v_lshl_add_u64 v[144:145], s[58:59], 0, v[130:131]
	s_mov_b32 m0, s54
	ds_read_b128 v[188:191], v151 offset:16384
	ds_read_b128 v[192:195], v151 offset:17408
	ds_read_b128 v[196:199], v151 offset:18432
	ds_read_b128 v[200:203], v151 offset:19456
	ds_read_b128 v[204:207], v151 offset:20480
	ds_read_b128 v[208:211], v151 offset:21504
	ds_read_b128 v[212:215], v151 offset:22528
	ds_read_b128 v[216:219], v151 offset:23552
	global_load_lds_dwordx4 v[144:145], off
	s_add_i32 m0, s54, 0x2000
	s_add_u32 s54, s58, 0xb0000
	v_lshl_add_u64 v[220:221], s[58:59], 0, v[134:135]
	s_addc_u32 s55, s59, 0
	s_add_i32 s79, s73, s64
	global_load_lds_dwordx4 v[220:221], off
	v_lshl_add_u64 v[222:223], s[54:55], 0, v[130:131]
	s_mov_b32 m0, s79
	v_lshl_add_u64 v[224:225], s[60:61], 0, v[132:133]
	global_load_lds_dwordx4 v[222:223], off
	v_lshl_add_u64 v[222:223], s[54:55], 0, v[134:135]
	s_add_i32 m0, s79, 0x2000
	s_nop 0
	global_load_lds_dwordx4 v[222:223], off
	v_lshl_add_u64 v[222:223], s[60:61], 0, v[128:129]
	s_mov_b32 m0, s65
	s_nop 0
	global_load_lds_dwordx4 v[222:223], off
	s_mov_b32 m0, s66
	s_nop 0
	global_load_lds_dwordx4 v[224:225], off
	s_waitcnt vmcnt(8)
	s_waitcnt lgkmcnt(0)
	s_barrier
	s_setprio 1
	s_waitcnt lgkmcnt(0)
	v_mfma_f32_16x16x32_bf16 v[60:63], v[152:155], v[188:191], 0
	v_mfma_f32_16x16x32_bf16 v[60:63], v[156:159], v[192:195], v[60:63]
	v_mfma_f32_16x16x32_bf16 v[56:59], v[160:163], v[188:191], 0
	v_mfma_f32_16x16x32_bf16 v[56:59], v[164:167], v[192:195], v[56:59]
	v_mfma_f32_16x16x32_bf16 v[52:55], v[152:155], v[196:199], 0
	v_mfma_f32_16x16x32_bf16 v[52:55], v[156:159], v[200:203], v[52:55]
	v_mfma_f32_16x16x32_bf16 v[44:47], v[160:163], v[196:199], 0
	v_mfma_f32_16x16x32_bf16 v[44:47], v[164:167], v[200:203], v[44:47]
	v_mfma_f32_16x16x32_bf16 v[36:39], v[152:155], v[204:207], 0
	v_mfma_f32_16x16x32_bf16 v[36:39], v[156:159], v[208:211], v[36:39]
	v_mfma_f32_16x16x32_bf16 v[28:31], v[160:163], v[204:207], 0
	v_mfma_f32_16x16x32_bf16 v[28:31], v[164:167], v[208:211], v[28:31]
	v_mfma_f32_16x16x32_bf16 v[20:23], v[152:155], v[212:215], 0
	v_mfma_f32_16x16x32_bf16 v[20:23], v[156:159], v[216:219], v[20:23]
	v_mfma_f32_16x16x32_bf16 v[12:15], v[160:163], v[212:215], 0
	v_mfma_f32_16x16x32_bf16 v[12:15], v[164:167], v[216:219], v[12:15]
	v_mfma_f32_16x16x32_bf16 v[48:51], v[168:171], v[188:191], 0
	v_mfma_f32_16x16x32_bf16 v[48:51], v[172:175], v[192:195], v[48:51]
	v_mfma_f32_16x16x32_bf16 v[40:43], v[176:179], v[188:191], 0
	v_mfma_f32_16x16x32_bf16 v[40:43], v[184:187], v[192:195], v[40:43]
	v_mfma_f32_16x16x32_bf16 v[32:35], v[168:171], v[196:199], 0
	v_mfma_f32_16x16x32_bf16 v[32:35], v[172:175], v[200:203], v[32:35]
	v_mfma_f32_16x16x32_bf16 v[24:27], v[176:179], v[196:199], 0
	v_mfma_f32_16x16x32_bf16 v[24:27], v[184:187], v[200:203], v[24:27]
	v_mfma_f32_16x16x32_bf16 v[16:19], v[168:171], v[204:207], 0
	v_mfma_f32_16x16x32_bf16 v[16:19], v[172:175], v[208:211], v[16:19]
	v_mfma_f32_16x16x32_bf16 v[8:11], v[176:179], v[204:207], 0
	v_mfma_f32_16x16x32_bf16 v[8:11], v[184:187], v[208:211], v[8:11]
	v_mfma_f32_16x16x32_bf16 v[4:7], v[168:171], v[212:215], 0
	v_mfma_f32_16x16x32_bf16 v[4:7], v[172:175], v[216:219], v[4:7]
	s_setprio 2
	s_barrier
	v_mfma_f32_16x16x32_bf16 v[0:3], v[176:179], v[212:215], 0
	v_mfma_f32_16x16x32_bf16 v[0:3], v[184:187], v[216:219], v[0:3]
	s_setprio 0
	s_branch .Lmid_gemm8
.LBB0_1031:
	ds_read_b128 v[152:155], v149
	ds_read_b128 v[156:159], v149 offset:1024
	ds_read_b128 v[160:163], v149 offset:2048
	ds_read_b128 v[164:167], v149 offset:3072
	ds_read_b128 v[168:171], v150
	ds_read_b128 v[172:175], v150 offset:1024
	ds_read_b128 v[176:179], v150 offset:2048
	ds_read_b128 v[184:187], v150 offset:3072
	s_add_u32 s56, s54, 0x100
	s_addc_u32 s57, s55, 0
	s_cmp_eq_u32 s88, 40
	s_cselect_b32 s61, s13, s57
	s_cselect_b32 s60, s12, s56
	s_cselect_b32 s59, s53, s87
	s_cselect_b32 s58, s52, s86
	v_lshl_add_u64 v[144:145], s[54:55], 0, v[136:137]
	s_add_i32 m0, s65, 0xc000
	ds_read_b128 v[188:191], v151
	ds_read_b128 v[192:195], v151 offset:1024
	ds_read_b128 v[196:199], v151 offset:2048
	ds_read_b128 v[200:203], v151 offset:3072
	ds_read_b128 v[204:207], v151 offset:4096
	ds_read_b128 v[208:211], v151 offset:5120
	ds_read_b128 v[212:215], v151 offset:6144
	ds_read_b128 v[216:219], v151 offset:7168
	global_load_lds_dwordx4 v[144:145], off
	v_lshl_add_u64 v[144:145], s[54:55], 0, v[138:139]
	s_add_i32 m0, s65, 0xe000
	s_nop 0
	global_load_lds_dwordx4 v[144:145], off
	s_waitcnt vmcnt(8)
	s_waitcnt lgkmcnt(0)
	s_barrier
	s_setprio 1
	s_waitcnt lgkmcnt(0)
	v_mfma_f32_16x16x32_bf16 v[124:127], v[152:155], v[188:191], v[124:127]
	v_mfma_f32_16x16x32_bf16 v[124:127], v[156:159], v[192:195], v[124:127]
	v_mfma_f32_16x16x32_bf16 v[120:123], v[160:163], v[188:191], v[120:123]
	v_mfma_f32_16x16x32_bf16 v[120:123], v[164:167], v[192:195], v[120:123]
	v_mfma_f32_16x16x32_bf16 v[116:119], v[152:155], v[196:199], v[116:119]
	v_mfma_f32_16x16x32_bf16 v[116:119], v[156:159], v[200:203], v[116:119]
	v_mfma_f32_16x16x32_bf16 v[108:111], v[160:163], v[196:199], v[108:111]
	v_mfma_f32_16x16x32_bf16 v[108:111], v[164:167], v[200:203], v[108:111]
	v_mfma_f32_16x16x32_bf16 v[100:103], v[152:155], v[204:207], v[100:103]
	v_mfma_f32_16x16x32_bf16 v[100:103], v[156:159], v[208:211], v[100:103]
	v_mfma_f32_16x16x32_bf16 v[92:95], v[160:163], v[204:207], v[92:95]
	v_mfma_f32_16x16x32_bf16 v[92:95], v[164:167], v[208:211], v[92:95]
	v_mfma_f32_16x16x32_bf16 v[84:87], v[152:155], v[212:215], v[84:87]
	v_mfma_f32_16x16x32_bf16 v[84:87], v[156:159], v[216:219], v[84:87]
	v_mfma_f32_16x16x32_bf16 v[76:79], v[160:163], v[212:215], v[76:79]
	v_mfma_f32_16x16x32_bf16 v[76:79], v[164:167], v[216:219], v[76:79]
	v_mfma_f32_16x16x32_bf16 v[112:115], v[168:171], v[188:191], v[112:115]
	v_mfma_f32_16x16x32_bf16 v[112:115], v[172:175], v[192:195], v[112:115]
	v_mfma_f32_16x16x32_bf16 v[104:107], v[176:179], v[188:191], v[104:107]
	v_mfma_f32_16x16x32_bf16 v[104:107], v[184:187], v[192:195], v[104:107]
	v_mfma_f32_16x16x32_bf16 v[96:99], v[168:171], v[196:199], v[96:99]
	v_mfma_f32_16x16x32_bf16 v[96:99], v[172:175], v[200:203], v[96:99]
	v_mfma_f32_16x16x32_bf16 v[88:91], v[176:179], v[196:199], v[88:91]
	v_mfma_f32_16x16x32_bf16 v[88:91], v[184:187], v[200:203], v[88:91]
	v_mfma_f32_16x16x32_bf16 v[80:83], v[168:171], v[204:207], v[80:83]
	v_mfma_f32_16x16x32_bf16 v[80:83], v[172:175], v[208:211], v[80:83]
	v_mfma_f32_16x16x32_bf16 v[72:75], v[176:179], v[204:207], v[72:75]
	v_mfma_f32_16x16x32_bf16 v[72:75], v[184:187], v[208:211], v[72:75]
	v_mfma_f32_16x16x32_bf16 v[68:71], v[168:171], v[212:215], v[68:71]
	v_mfma_f32_16x16x32_bf16 v[68:71], v[172:175], v[216:219], v[68:71]
	s_setprio 2
	s_barrier
	v_mfma_f32_16x16x32_bf16 v[64:67], v[176:179], v[212:215], v[64:67]
	v_mfma_f32_16x16x32_bf16 v[64:67], v[184:187], v[216:219], v[64:67]
	s_setprio 0
	s_add_i32 s54, s72, s64
	v_lshl_add_u64 v[144:145], s[58:59], 0, v[130:131]
	s_mov_b32 m0, s54
	ds_read_b128 v[188:191], v151 offset:16384
	ds_read_b128 v[192:195], v151 offset:17408
	ds_read_b128 v[196:199], v151 offset:18432
	ds_read_b128 v[200:203], v151 offset:19456
	ds_read_b128 v[204:207], v151 offset:20480
	ds_read_b128 v[208:211], v151 offset:21504
	ds_read_b128 v[212:215], v151 offset:22528
	ds_read_b128 v[216:219], v151 offset:23552
	global_load_lds_dwordx4 v[144:145], off
	s_add_i32 m0, s54, 0x2000
	s_add_u32 s54, s58, 0xb0000
	v_lshl_add_u64 v[220:221], s[58:59], 0, v[134:135]
	s_addc_u32 s55, s59, 0
	s_add_i32 s79, s73, s64
	global_load_lds_dwordx4 v[220:221], off
	v_lshl_add_u64 v[222:223], s[54:55], 0, v[130:131]
	s_mov_b32 m0, s79
	v_lshl_add_u64 v[224:225], s[60:61], 0, v[132:133]
	global_load_lds_dwordx4 v[222:223], off
	v_lshl_add_u64 v[222:223], s[54:55], 0, v[134:135]
	s_add_i32 m0, s79, 0x2000
	s_nop 0
	global_load_lds_dwordx4 v[222:223], off
	v_lshl_add_u64 v[222:223], s[60:61], 0, v[128:129]
	s_mov_b32 m0, s65
	s_nop 0
	global_load_lds_dwordx4 v[222:223], off
	s_mov_b32 m0, s66
	s_nop 0
	global_load_lds_dwordx4 v[224:225], off
	s_waitcnt vmcnt(8)
	s_waitcnt lgkmcnt(0)
	s_barrier
	s_setprio 1
	s_waitcnt lgkmcnt(0)
	v_mfma_f32_16x16x32_bf16 v[60:63], v[152:155], v[188:191], v[60:63]
	v_mfma_f32_16x16x32_bf16 v[60:63], v[156:159], v[192:195], v[60:63]
	v_mfma_f32_16x16x32_bf16 v[56:59], v[160:163], v[188:191], v[56:59]
	v_mfma_f32_16x16x32_bf16 v[56:59], v[164:167], v[192:195], v[56:59]
	v_mfma_f32_16x16x32_bf16 v[52:55], v[152:155], v[196:199], v[52:55]
	v_mfma_f32_16x16x32_bf16 v[52:55], v[156:159], v[200:203], v[52:55]
	v_mfma_f32_16x16x32_bf16 v[44:47], v[160:163], v[196:199], v[44:47]
	v_mfma_f32_16x16x32_bf16 v[44:47], v[164:167], v[200:203], v[44:47]
	v_mfma_f32_16x16x32_bf16 v[36:39], v[152:155], v[204:207], v[36:39]
	v_mfma_f32_16x16x32_bf16 v[36:39], v[156:159], v[208:211], v[36:39]
	v_mfma_f32_16x16x32_bf16 v[28:31], v[160:163], v[204:207], v[28:31]
	v_mfma_f32_16x16x32_bf16 v[28:31], v[164:167], v[208:211], v[28:31]
	v_mfma_f32_16x16x32_bf16 v[20:23], v[152:155], v[212:215], v[20:23]
	v_mfma_f32_16x16x32_bf16 v[20:23], v[156:159], v[216:219], v[20:23]
	v_mfma_f32_16x16x32_bf16 v[12:15], v[160:163], v[212:215], v[12:15]
	v_mfma_f32_16x16x32_bf16 v[12:15], v[164:167], v[216:219], v[12:15]
	v_mfma_f32_16x16x32_bf16 v[48:51], v[168:171], v[188:191], v[48:51]
	v_mfma_f32_16x16x32_bf16 v[48:51], v[172:175], v[192:195], v[48:51]
	v_mfma_f32_16x16x32_bf16 v[40:43], v[176:179], v[188:191], v[40:43]
	v_mfma_f32_16x16x32_bf16 v[40:43], v[184:187], v[192:195], v[40:43]
	v_mfma_f32_16x16x32_bf16 v[32:35], v[168:171], v[196:199], v[32:35]
	v_mfma_f32_16x16x32_bf16 v[32:35], v[172:175], v[200:203], v[32:35]
	v_mfma_f32_16x16x32_bf16 v[24:27], v[176:179], v[196:199], v[24:27]
	v_mfma_f32_16x16x32_bf16 v[24:27], v[184:187], v[200:203], v[24:27]
	v_mfma_f32_16x16x32_bf16 v[16:19], v[168:171], v[204:207], v[16:19]
	v_mfma_f32_16x16x32_bf16 v[16:19], v[172:175], v[208:211], v[16:19]
	v_mfma_f32_16x16x32_bf16 v[8:11], v[176:179], v[204:207], v[8:11]
	v_mfma_f32_16x16x32_bf16 v[8:11], v[184:187], v[208:211], v[8:11]
	v_mfma_f32_16x16x32_bf16 v[4:7], v[168:171], v[212:215], v[4:7]
	v_mfma_f32_16x16x32_bf16 v[4:7], v[172:175], v[216:219], v[4:7]
	s_setprio 2
	s_barrier
	v_mfma_f32_16x16x32_bf16 v[0:3], v[176:179], v[212:215], v[0:3]
	v_mfma_f32_16x16x32_bf16 v[0:3], v[184:187], v[216:219], v[0:3]
	s_setprio 0
.Lmid_gemm8:
	s_add_i32 s79, 0, 0x18000
	s_add_i32 s89, 0, 0x1c000
	v_add_u32_e32 v164, s79, v147
	v_add_u32_e32 v181, s89, v147
	ds_read_b128 v[152:155], v164
	ds_read_b128 v[156:159], v164 offset:1024
	ds_read_b128 v[160:163], v164 offset:2048
	ds_read_b128 v[164:167], v164 offset:3072
	ds_read_b128 v[168:171], v181
	ds_read_b128 v[172:175], v181 offset:1024
	ds_read_b128 v[176:179], v181 offset:2048
	ds_read_b128 v[184:187], v181 offset:3072
	s_add_u32 s54, s60, 0xb0000
	s_addc_u32 s55, s61, 0
	s_mov_b32 m0, s67
	v_lshl_add_u64 v[226:227], s[54:55], 0, v[128:129]
	ds_read_b128 v[188:191], v151 offset:32768
	ds_read_b128 v[192:195], v151 offset:33792
	ds_read_b128 v[196:199], v151 offset:34816
	ds_read_b128 v[200:203], v151 offset:35840
	ds_read_b128 v[204:207], v151 offset:36864
	ds_read_b128 v[208:211], v151 offset:37888
	ds_read_b128 v[212:215], v151 offset:38912
	ds_read_b128 v[216:219], v151 offset:39936
	global_load_lds_dwordx4 v[226:227], off
	v_lshl_add_u64 v[226:227], s[54:55], 0, v[132:133]
	s_mov_b32 m0, s68
	s_nop 0
	global_load_lds_dwordx4 v[226:227], off
	s_waitcnt vmcnt(8)
	s_waitcnt lgkmcnt(0)
	s_barrier
	s_setprio 1
	s_waitcnt lgkmcnt(0)
	v_mfma_f32_16x16x32_bf16 v[124:127], v[152:155], v[188:191], v[124:127]
	v_mfma_f32_16x16x32_bf16 v[124:127], v[156:159], v[192:195], v[124:127]
	v_mfma_f32_16x16x32_bf16 v[120:123], v[160:163], v[188:191], v[120:123]
	v_mfma_f32_16x16x32_bf16 v[120:123], v[164:167], v[192:195], v[120:123]
	v_mfma_f32_16x16x32_bf16 v[116:119], v[152:155], v[196:199], v[116:119]
	v_mfma_f32_16x16x32_bf16 v[116:119], v[156:159], v[200:203], v[116:119]
	v_mfma_f32_16x16x32_bf16 v[108:111], v[160:163], v[196:199], v[108:111]
	v_mfma_f32_16x16x32_bf16 v[108:111], v[164:167], v[200:203], v[108:111]
	v_mfma_f32_16x16x32_bf16 v[100:103], v[152:155], v[204:207], v[100:103]
	v_mfma_f32_16x16x32_bf16 v[100:103], v[156:159], v[208:211], v[100:103]
	v_mfma_f32_16x16x32_bf16 v[92:95], v[160:163], v[204:207], v[92:95]
	v_mfma_f32_16x16x32_bf16 v[92:95], v[164:167], v[208:211], v[92:95]
	v_mfma_f32_16x16x32_bf16 v[84:87], v[152:155], v[212:215], v[84:87]
	v_mfma_f32_16x16x32_bf16 v[84:87], v[156:159], v[216:219], v[84:87]
	v_mfma_f32_16x16x32_bf16 v[76:79], v[160:163], v[212:215], v[76:79]
	v_mfma_f32_16x16x32_bf16 v[76:79], v[164:167], v[216:219], v[76:79]
	v_mfma_f32_16x16x32_bf16 v[112:115], v[168:171], v[188:191], v[112:115]
	v_mfma_f32_16x16x32_bf16 v[112:115], v[172:175], v[192:195], v[112:115]
	v_mfma_f32_16x16x32_bf16 v[104:107], v[176:179], v[188:191], v[104:107]
	v_mfma_f32_16x16x32_bf16 v[104:107], v[184:187], v[192:195], v[104:107]
	v_mfma_f32_16x16x32_bf16 v[96:99], v[168:171], v[196:199], v[96:99]
	v_mfma_f32_16x16x32_bf16 v[96:99], v[172:175], v[200:203], v[96:99]
	v_mfma_f32_16x16x32_bf16 v[88:91], v[176:179], v[196:199], v[88:91]
	v_mfma_f32_16x16x32_bf16 v[88:91], v[184:187], v[200:203], v[88:91]
	v_mfma_f32_16x16x32_bf16 v[80:83], v[168:171], v[204:207], v[80:83]
	v_mfma_f32_16x16x32_bf16 v[80:83], v[172:175], v[208:211], v[80:83]
	v_mfma_f32_16x16x32_bf16 v[72:75], v[176:179], v[204:207], v[72:75]
	v_mfma_f32_16x16x32_bf16 v[72:75], v[184:187], v[208:211], v[72:75]
	v_mfma_f32_16x16x32_bf16 v[68:71], v[168:171], v[212:215], v[68:71]
	v_mfma_f32_16x16x32_bf16 v[68:71], v[172:175], v[216:219], v[68:71]
	s_setprio 2
	s_barrier
	v_mfma_f32_16x16x32_bf16 v[64:67], v[176:179], v[212:215], v[64:67]
	v_mfma_f32_16x16x32_bf16 v[64:67], v[184:187], v[216:219], v[64:67]
	s_setprio 0
	s_add_i32 s54, s79, s64
	v_lshl_add_u64 v[144:145], v[144:145], 0, s[16:17]
	s_mov_b32 m0, s54
	ds_read_b128 v[188:191], v151 offset:49152
	ds_read_b128 v[192:195], v151 offset:50176
	ds_read_b128 v[196:199], v151 offset:51200
	ds_read_b128 v[200:203], v151 offset:52224
	ds_read_b128 v[204:207], v151 offset:53248
	ds_read_b128 v[208:211], v151 offset:54272
	ds_read_b128 v[212:215], v151 offset:55296
	ds_read_b128 v[216:219], v151 offset:56320
	global_load_lds_dwordx4 v[144:145], off
	s_add_i32 m0, s54, 0x2000
	s_add_u32 s54, s58, 0xb0080
	v_lshl_add_u64 v[144:145], v[220:221], 0, s[16:17]
	s_addc_u32 s55, s59, 0
	s_add_i32 s58, s89, s64
	global_load_lds_dwordx4 v[144:145], off
	v_lshl_add_u64 v[144:145], s[54:55], 0, v[130:131]
	s_mov_b32 m0, s58
	s_nop 0
	global_load_lds_dwordx4 v[144:145], off
	v_lshl_add_u64 v[144:145], s[54:55], 0, v[134:135]
	s_add_i32 m0, s58, 0x2000
	s_nop 0
	global_load_lds_dwordx4 v[144:145], off
	v_lshl_add_u64 v[144:145], v[222:223], 0, s[16:17]
	s_mov_b32 m0, s70
	s_nop 0
	global_load_lds_dwordx4 v[144:145], off
	v_lshl_add_u64 v[144:145], v[224:225], 0, s[16:17]
	s_mov_b32 m0, s71
	s_nop 0
	global_load_lds_dwordx4 v[144:145], off
	s_waitcnt vmcnt(8)
	s_waitcnt lgkmcnt(0)
	s_barrier
	s_setprio 1
	s_waitcnt lgkmcnt(0)
	v_mfma_f32_16x16x32_bf16 v[60:63], v[152:155], v[188:191], v[60:63]
	v_mfma_f32_16x16x32_bf16 v[60:63], v[156:159], v[192:195], v[60:63]
	v_mfma_f32_16x16x32_bf16 v[56:59], v[160:163], v[188:191], v[56:59]
	v_mfma_f32_16x16x32_bf16 v[56:59], v[164:167], v[192:195], v[56:59]
	v_mfma_f32_16x16x32_bf16 v[52:55], v[152:155], v[196:199], v[52:55]
	v_mfma_f32_16x16x32_bf16 v[52:55], v[156:159], v[200:203], v[52:55]
	v_mfma_f32_16x16x32_bf16 v[44:47], v[160:163], v[196:199], v[44:47]
	v_mfma_f32_16x16x32_bf16 v[44:47], v[164:167], v[200:203], v[44:47]
	v_mfma_f32_16x16x32_bf16 v[36:39], v[152:155], v[204:207], v[36:39]
	v_mfma_f32_16x16x32_bf16 v[36:39], v[156:159], v[208:211], v[36:39]
	v_mfma_f32_16x16x32_bf16 v[28:31], v[160:163], v[204:207], v[28:31]
	v_mfma_f32_16x16x32_bf16 v[28:31], v[164:167], v[208:211], v[28:31]
	v_mfma_f32_16x16x32_bf16 v[20:23], v[152:155], v[212:215], v[20:23]
	v_mfma_f32_16x16x32_bf16 v[20:23], v[156:159], v[216:219], v[20:23]
	v_mfma_f32_16x16x32_bf16 v[12:15], v[160:163], v[212:215], v[12:15]
	v_mfma_f32_16x16x32_bf16 v[12:15], v[164:167], v[216:219], v[12:15]
	v_mfma_f32_16x16x32_bf16 v[48:51], v[168:171], v[188:191], v[48:51]
	v_mfma_f32_16x16x32_bf16 v[48:51], v[172:175], v[192:195], v[48:51]
	v_mfma_f32_16x16x32_bf16 v[40:43], v[176:179], v[188:191], v[40:43]
	v_mfma_f32_16x16x32_bf16 v[40:43], v[184:187], v[192:195], v[40:43]
	v_mfma_f32_16x16x32_bf16 v[32:35], v[168:171], v[196:199], v[32:35]
	v_mfma_f32_16x16x32_bf16 v[32:35], v[172:175], v[200:203], v[32:35]
	v_mfma_f32_16x16x32_bf16 v[24:27], v[176:179], v[196:199], v[24:27]
	v_mfma_f32_16x16x32_bf16 v[24:27], v[184:187], v[200:203], v[24:27]
	v_mfma_f32_16x16x32_bf16 v[16:19], v[168:171], v[204:207], v[16:19]
	v_mfma_f32_16x16x32_bf16 v[16:19], v[172:175], v[208:211], v[16:19]
	v_mfma_f32_16x16x32_bf16 v[8:11], v[176:179], v[204:207], v[8:11]
	v_mfma_f32_16x16x32_bf16 v[8:11], v[184:187], v[208:211], v[8:11]
	v_mfma_f32_16x16x32_bf16 v[4:7], v[168:171], v[212:215], v[4:7]
	v_mfma_f32_16x16x32_bf16 v[4:7], v[172:175], v[216:219], v[4:7]
	s_setprio 2
	s_barrier
	v_mfma_f32_16x16x32_bf16 v[0:3], v[176:179], v[212:215], v[0:3]
	v_mfma_f32_16x16x32_bf16 v[0:3], v[184:187], v[216:219], v[0:3]
	s_setprio 0
	s_add_i32 s88, s88, 2
	s_add_u32 s86, s86, 0x100
	s_addc_u32 s87, s87, 0
	s_cmp_gt_u32 s88, 41
	s_mov_b64 s[54:55], s[56:57]
	s_cbranch_scc0 .LBB0_1031
	s_and_b64 vcc, exec, s[18:19]
	s_cbranch_vccz .LBB0_1034
	s_barrier

.LBB0_1161:
	s_ashr_i32 s53, s52, 31
	s_lshl_b64 s[54:55], s[52:53], 19
	s_add_u32 s54, s80, s54
	s_addc_u32 s55, s81, s55
	s_and_b64 s[56:57], s[10:11], exec
	s_cselect_b32 s53, s55, s61
	s_cselect_b32 s83, s54, s60
	s_ashr_i32 s49, s48, 31
	s_lshl_b64 s[56:57], s[48:49], 19
	s_add_u32 s56, s66, s56
	s_addc_u32 s57, s67, s57
	s_and_b64 s[64:65], s[10:11], exec
	s_cselect_b32 s49, s57, s63
	s_cselect_b32 s84, s56, s62
	s_add_u32 s60, s60, 0x40080
	s_addc_u32 s61, s61, 0
	s_add_u32 s85, s62, 0x100
	s_addc_u32 s86, s63, 0
	s_mov_b32 s87, -2
	ds_read_b128 v[152:155], v148
	ds_read_b128 v[156:159], v148 offset:1024
	ds_read_b128 v[160:163], v148 offset:2048
	ds_read_b128 v[164:167], v148 offset:3072
	ds_read_b128 v[168:171], v149
	ds_read_b128 v[172:175], v149 offset:1024
	ds_read_b128 v[176:179], v149 offset:2048
	ds_read_b128 v[184:187], v149 offset:3072
	s_add_u32 s62, s60, 0xfffc0080
	s_addc_u32 s63, s61, -1
	s_cmp_eq_u32 s87, 12
	s_cselect_b32 s65, s53, s63
	s_cselect_b32 s64, s83, s62
	s_cselect_b32 s63, s49, s86
	s_cselect_b32 s62, s84, s85
	v_lshl_add_u64 v[220:221], s[60:61], 0, v[138:139]
	s_add_i32 m0, s69, 0xc000
	ds_read_b128 v[188:191], v150
	ds_read_b128 v[192:195], v150 offset:1024
	ds_read_b128 v[196:199], v150 offset:2048
	ds_read_b128 v[200:203], v150 offset:3072
	ds_read_b128 v[204:207], v150 offset:4096
	ds_read_b128 v[208:211], v150 offset:5120
	ds_read_b128 v[212:215], v150 offset:6144
	ds_read_b128 v[216:219], v150 offset:7168
	global_load_lds_dwordx4 v[220:221], off
	v_lshl_add_u64 v[220:221], s[60:61], 0, v[140:141]
	s_add_i32 m0, s69, 0xe000
	s_nop 0
	global_load_lds_dwordx4 v[220:221], off
	s_waitcnt vmcnt(8)
	s_waitcnt lgkmcnt(0)
	s_barrier
	s_setprio 1
	s_waitcnt lgkmcnt(0)
	v_mfma_f32_16x16x32_bf16 v[124:127], v[152:155], v[188:191], 0
	v_mfma_f32_16x16x32_bf16 v[124:127], v[156:159], v[192:195], v[124:127]
	v_mfma_f32_16x16x32_bf16 v[120:123], v[160:163], v[188:191], 0
	v_mfma_f32_16x16x32_bf16 v[120:123], v[164:167], v[192:195], v[120:123]
	v_mfma_f32_16x16x32_bf16 v[116:119], v[152:155], v[196:199], 0
	v_mfma_f32_16x16x32_bf16 v[116:119], v[156:159], v[200:203], v[116:119]
	v_mfma_f32_16x16x32_bf16 v[112:115], v[160:163], v[196:199], 0
	v_mfma_f32_16x16x32_bf16 v[112:115], v[164:167], v[200:203], v[112:115]
	v_mfma_f32_16x16x32_bf16 v[108:111], v[152:155], v[204:207], 0
	v_mfma_f32_16x16x32_bf16 v[108:111], v[156:159], v[208:211], v[108:111]
	v_mfma_f32_16x16x32_bf16 v[104:107], v[160:163], v[204:207], 0
	v_mfma_f32_16x16x32_bf16 v[104:107], v[164:167], v[208:211], v[104:107]
	v_mfma_f32_16x16x32_bf16 v[100:103], v[152:155], v[212:215], 0
	v_mfma_f32_16x16x32_bf16 v[100:103], v[156:159], v[216:219], v[100:103]
	v_mfma_f32_16x16x32_bf16 v[96:99], v[160:163], v[212:215], 0
	v_mfma_f32_16x16x32_bf16 v[96:99], v[164:167], v[216:219], v[96:99]
	v_mfma_f32_16x16x32_bf16 v[68:71], v[168:171], v[188:191], 0
	v_mfma_f32_16x16x32_bf16 v[68:71], v[172:175], v[192:195], v[68:71]
	v_mfma_f32_16x16x32_bf16 v[64:67], v[176:179], v[188:191], 0
	v_mfma_f32_16x16x32_bf16 v[64:67], v[184:187], v[192:195], v[64:67]
	v_mfma_f32_16x16x32_bf16 v[52:55], v[168:171], v[196:199], 0
	v_mfma_f32_16x16x32_bf16 v[52:55], v[172:175], v[200:203], v[52:55]
	v_mfma_f32_16x16x32_bf16 v[48:51], v[176:179], v[196:199], 0
	v_mfma_f32_16x16x32_bf16 v[48:51], v[184:187], v[200:203], v[48:51]
	v_mfma_f32_16x16x32_bf16 v[44:47], v[168:171], v[204:207], 0
	v_mfma_f32_16x16x32_bf16 v[44:47], v[172:175], v[208:211], v[44:47]
	v_mfma_f32_16x16x32_bf16 v[40:43], v[176:179], v[204:207], 0
	v_mfma_f32_16x16x32_bf16 v[40:43], v[184:187], v[208:211], v[40:43]
	v_mfma_f32_16x16x32_bf16 v[36:39], v[168:171], v[212:215], 0
	v_mfma_f32_16x16x32_bf16 v[36:39], v[172:175], v[216:219], v[36:39]
	s_setprio 2
	s_barrier
	v_mfma_f32_16x16x32_bf16 v[32:35], v[176:179], v[212:215], 0
	v_mfma_f32_16x16x32_bf16 v[32:35], v[184:187], v[216:219], v[32:35]
	s_setprio 0
	s_add_i32 s79, s77, s68
	v_lshl_add_u64 v[220:221], s[62:63], 0, v[130:131]
	s_mov_b32 m0, s79
	ds_read_b128 v[188:191], v150 offset:16384
	ds_read_b128 v[192:195], v150 offset:17408
	ds_read_b128 v[196:199], v150 offset:18432
	ds_read_b128 v[200:203], v150 offset:19456
	ds_read_b128 v[204:207], v150 offset:20480
	ds_read_b128 v[208:211], v150 offset:21504
	ds_read_b128 v[212:215], v150 offset:22528
	ds_read_b128 v[216:219], v150 offset:23552
	global_load_lds_dwordx4 v[220:221], off
	s_add_i32 m0, s79, 0x2000
	s_add_u32 s88, s62, 0x40000
	v_lshl_add_u64 v[222:223], s[62:63], 0, v[134:135]
	s_addc_u32 s89, s63, 0
	s_add_i32 s79, s82, s68
	global_load_lds_dwordx4 v[222:223], off
	v_lshl_add_u64 v[224:225], s[88:89], 0, v[130:131]
	s_mov_b32 m0, s79
	v_lshl_add_u64 v[226:227], s[64:65], 0, v[132:133]
	global_load_lds_dwordx4 v[224:225], off
	v_lshl_add_u64 v[224:225], s[88:89], 0, v[134:135]
	s_add_i32 m0, s79, 0x2000
	s_nop 0
	global_load_lds_dwordx4 v[224:225], off
	v_lshl_add_u64 v[224:225], s[64:65], 0, v[128:129]
	s_mov_b32 m0, s69
	s_nop 0
	global_load_lds_dwordx4 v[224:225], off
	s_mov_b32 m0, s70
	s_nop 0
	global_load_lds_dwordx4 v[226:227], off
	s_waitcnt vmcnt(8)
	s_waitcnt lgkmcnt(0)
	s_barrier
	s_setprio 1
	s_waitcnt lgkmcnt(0)
	v_mfma_f32_16x16x32_bf16 v[92:95], v[152:155], v[188:191], 0
	v_mfma_f32_16x16x32_bf16 v[92:95], v[156:159], v[192:195], v[92:95]
	v_mfma_f32_16x16x32_bf16 v[88:91], v[160:163], v[188:191], 0
	v_mfma_f32_16x16x32_bf16 v[88:91], v[164:167], v[192:195], v[88:91]
	v_mfma_f32_16x16x32_bf16 v[84:87], v[152:155], v[196:199], 0
	v_mfma_f32_16x16x32_bf16 v[84:87], v[156:159], v[200:203], v[84:87]
	v_mfma_f32_16x16x32_bf16 v[80:83], v[160:163], v[196:199], 0
	v_mfma_f32_16x16x32_bf16 v[80:83], v[164:167], v[200:203], v[80:83]
	v_mfma_f32_16x16x32_bf16 v[76:79], v[152:155], v[204:207], 0
	v_mfma_f32_16x16x32_bf16 v[76:79], v[156:159], v[208:211], v[76:79]
	v_mfma_f32_16x16x32_bf16 v[72:75], v[160:163], v[204:207], 0
	v_mfma_f32_16x16x32_bf16 v[72:75], v[164:167], v[208:211], v[72:75]
	v_mfma_f32_16x16x32_bf16 v[60:63], v[152:155], v[212:215], 0
	v_mfma_f32_16x16x32_bf16 v[60:63], v[156:159], v[216:219], v[60:63]
	v_mfma_f32_16x16x32_bf16 v[56:59], v[160:163], v[212:215], 0
	v_mfma_f32_16x16x32_bf16 v[56:59], v[164:167], v[216:219], v[56:59]
	v_mfma_f32_16x16x32_bf16 v[28:31], v[168:171], v[188:191], 0
	v_mfma_f32_16x16x32_bf16 v[28:31], v[172:175], v[192:195], v[28:31]
	v_mfma_f32_16x16x32_bf16 v[24:27], v[176:179], v[188:191], 0
	v_mfma_f32_16x16x32_bf16 v[24:27], v[184:187], v[192:195], v[24:27]
	v_mfma_f32_16x16x32_bf16 v[20:23], v[168:171], v[196:199], 0
	v_mfma_f32_16x16x32_bf16 v[20:23], v[172:175], v[200:203], v[20:23]
	v_mfma_f32_16x16x32_bf16 v[16:19], v[176:179], v[196:199], 0
	v_mfma_f32_16x16x32_bf16 v[16:19], v[184:187], v[200:203], v[16:19]
	v_mfma_f32_16x16x32_bf16 v[12:15], v[168:171], v[204:207], 0
	v_mfma_f32_16x16x32_bf16 v[12:15], v[172:175], v[208:211], v[12:15]
	v_mfma_f32_16x16x32_bf16 v[8:11], v[176:179], v[204:207], 0
	v_mfma_f32_16x16x32_bf16 v[8:11], v[184:187], v[208:211], v[8:11]
	v_mfma_f32_16x16x32_bf16 v[4:7], v[168:171], v[212:215], 0
	v_mfma_f32_16x16x32_bf16 v[4:7], v[172:175], v[216:219], v[4:7]
	s_setprio 2
	s_barrier
	v_mfma_f32_16x16x32_bf16 v[0:3], v[176:179], v[212:215], 0
	v_mfma_f32_16x16x32_bf16 v[0:3], v[184:187], v[216:219], v[0:3]
	s_setprio 0
	s_branch .Lmid_gemm9
.LBB0_1162:
	ds_read_b128 v[152:155], v148
	ds_read_b128 v[156:159], v148 offset:1024
	ds_read_b128 v[160:163], v148 offset:2048
	ds_read_b128 v[164:167], v148 offset:3072
	ds_read_b128 v[168:171], v149
	ds_read_b128 v[172:175], v149 offset:1024
	ds_read_b128 v[176:179], v149 offset:2048
	ds_read_b128 v[184:187], v149 offset:3072
	s_add_u32 s62, s60, 0xfffc0080
	s_addc_u32 s63, s61, -1
	s_cmp_eq_u32 s87, 12
	s_cselect_b32 s65, s53, s63
	s_cselect_b32 s64, s83, s62
	s_cselect_b32 s63, s49, s86
	s_cselect_b32 s62, s84, s85
	v_lshl_add_u64 v[220:221], s[60:61], 0, v[138:139]
	s_add_i32 m0, s69, 0xc000
	ds_read_b128 v[188:191], v150
	ds_read_b128 v[192:195], v150 offset:1024
	ds_read_b128 v[196:199], v150 offset:2048
	ds_read_b128 v[200:203], v150 offset:3072
	ds_read_b128 v[204:207], v150 offset:4096
	ds_read_b128 v[208:211], v150 offset:5120
	ds_read_b128 v[212:215], v150 offset:6144
	ds_read_b128 v[216:219], v150 offset:7168
	global_load_lds_dwordx4 v[220:221], off
	v_lshl_add_u64 v[220:221], s[60:61], 0, v[140:141]
	s_add_i32 m0, s69, 0xe000
	s_nop 0
	global_load_lds_dwordx4 v[220:221], off
	s_waitcnt vmcnt(8)
	s_waitcnt lgkmcnt(0)
	s_barrier
	s_setprio 1
	s_waitcnt lgkmcnt(0)
	v_mfma_f32_16x16x32_bf16 v[124:127], v[152:155], v[188:191], v[124:127]
	v_mfma_f32_16x16x32_bf16 v[124:127], v[156:159], v[192:195], v[124:127]
	v_mfma_f32_16x16x32_bf16 v[120:123], v[160:163], v[188:191], v[120:123]
	v_mfma_f32_16x16x32_bf16 v[120:123], v[164:167], v[192:195], v[120:123]
	v_mfma_f32_16x16x32_bf16 v[116:119], v[152:155], v[196:199], v[116:119]
	v_mfma_f32_16x16x32_bf16 v[116:119], v[156:159], v[200:203], v[116:119]
	v_mfma_f32_16x16x32_bf16 v[112:115], v[160:163], v[196:199], v[112:115]
	v_mfma_f32_16x16x32_bf16 v[112:115], v[164:167], v[200:203], v[112:115]
	v_mfma_f32_16x16x32_bf16 v[108:111], v[152:155], v[204:207], v[108:111]
	v_mfma_f32_16x16x32_bf16 v[108:111], v[156:159], v[208:211], v[108:111]
	v_mfma_f32_16x16x32_bf16 v[104:107], v[160:163], v[204:207], v[104:107]
	v_mfma_f32_16x16x32_bf16 v[104:107], v[164:167], v[208:211], v[104:107]
	v_mfma_f32_16x16x32_bf16 v[100:103], v[152:155], v[212:215], v[100:103]
	v_mfma_f32_16x16x32_bf16 v[100:103], v[156:159], v[216:219], v[100:103]
	v_mfma_f32_16x16x32_bf16 v[96:99], v[160:163], v[212:215], v[96:99]
	v_mfma_f32_16x16x32_bf16 v[96:99], v[164:167], v[216:219], v[96:99]
	v_mfma_f32_16x16x32_bf16 v[68:71], v[168:171], v[188:191], v[68:71]
	v_mfma_f32_16x16x32_bf16 v[68:71], v[172:175], v[192:195], v[68:71]
	v_mfma_f32_16x16x32_bf16 v[64:67], v[176:179], v[188:191], v[64:67]
	v_mfma_f32_16x16x32_bf16 v[64:67], v[184:187], v[192:195], v[64:67]
	v_mfma_f32_16x16x32_bf16 v[52:55], v[168:171], v[196:199], v[52:55]
	v_mfma_f32_16x16x32_bf16 v[52:55], v[172:175], v[200:203], v[52:55]
	v_mfma_f32_16x16x32_bf16 v[48:51], v[176:179], v[196:199], v[48:51]
	v_mfma_f32_16x16x32_bf16 v[48:51], v[184:187], v[200:203], v[48:51]
	v_mfma_f32_16x16x32_bf16 v[44:47], v[168:171], v[204:207], v[44:47]
	v_mfma_f32_16x16x32_bf16 v[44:47], v[172:175], v[208:211], v[44:47]
	v_mfma_f32_16x16x32_bf16 v[40:43], v[176:179], v[204:207], v[40:43]
	v_mfma_f32_16x16x32_bf16 v[40:43], v[184:187], v[208:211], v[40:43]
	v_mfma_f32_16x16x32_bf16 v[36:39], v[168:171], v[212:215], v[36:39]
	v_mfma_f32_16x16x32_bf16 v[36:39], v[172:175], v[216:219], v[36:39]
	s_setprio 2
	s_barrier
	v_mfma_f32_16x16x32_bf16 v[32:35], v[176:179], v[212:215], v[32:35]
	v_mfma_f32_16x16x32_bf16 v[32:35], v[184:187], v[216:219], v[32:35]
	s_setprio 0
	s_add_i32 s79, s77, s68
	v_lshl_add_u64 v[220:221], s[62:63], 0, v[130:131]
	s_mov_b32 m0, s79
	ds_read_b128 v[188:191], v150 offset:16384
	ds_read_b128 v[192:195], v150 offset:17408
	ds_read_b128 v[196:199], v150 offset:18432
	ds_read_b128 v[200:203], v150 offset:19456
	ds_read_b128 v[204:207], v150 offset:20480
	ds_read_b128 v[208:211], v150 offset:21504
	ds_read_b128 v[212:215], v150 offset:22528
	ds_read_b128 v[216:219], v150 offset:23552
	global_load_lds_dwordx4 v[220:221], off
	s_add_i32 m0, s79, 0x2000
	s_add_u32 s88, s62, 0x40000
	v_lshl_add_u64 v[222:223], s[62:63], 0, v[134:135]
	s_addc_u32 s89, s63, 0
	s_add_i32 s79, s82, s68
	global_load_lds_dwordx4 v[222:223], off
	v_lshl_add_u64 v[224:225], s[88:89], 0, v[130:131]
	s_mov_b32 m0, s79
	v_lshl_add_u64 v[226:227], s[64:65], 0, v[132:133]
	global_load_lds_dwordx4 v[224:225], off
	v_lshl_add_u64 v[224:225], s[88:89], 0, v[134:135]
	s_add_i32 m0, s79, 0x2000
	s_nop 0
	global_load_lds_dwordx4 v[224:225], off
	v_lshl_add_u64 v[224:225], s[64:65], 0, v[128:129]
	s_mov_b32 m0, s69
	s_nop 0
	global_load_lds_dwordx4 v[224:225], off
	s_mov_b32 m0, s70
	s_nop 0
	global_load_lds_dwordx4 v[226:227], off
	s_waitcnt vmcnt(8)
	s_waitcnt lgkmcnt(0)
	s_barrier
	s_setprio 1
	s_waitcnt lgkmcnt(0)
	v_mfma_f32_16x16x32_bf16 v[92:95], v[152:155], v[188:191], v[92:95]
	v_mfma_f32_16x16x32_bf16 v[92:95], v[156:159], v[192:195], v[92:95]
	v_mfma_f32_16x16x32_bf16 v[88:91], v[160:163], v[188:191], v[88:91]
	v_mfma_f32_16x16x32_bf16 v[88:91], v[164:167], v[192:195], v[88:91]
	v_mfma_f32_16x16x32_bf16 v[84:87], v[152:155], v[196:199], v[84:87]
	v_mfma_f32_16x16x32_bf16 v[84:87], v[156:159], v[200:203], v[84:87]
	v_mfma_f32_16x16x32_bf16 v[80:83], v[160:163], v[196:199], v[80:83]
	v_mfma_f32_16x16x32_bf16 v[80:83], v[164:167], v[200:203], v[80:83]
	v_mfma_f32_16x16x32_bf16 v[76:79], v[152:155], v[204:207], v[76:79]
	v_mfma_f32_16x16x32_bf16 v[76:79], v[156:159], v[208:211], v[76:79]
	v_mfma_f32_16x16x32_bf16 v[72:75], v[160:163], v[204:207], v[72:75]
	v_mfma_f32_16x16x32_bf16 v[72:75], v[164:167], v[208:211], v[72:75]
	v_mfma_f32_16x16x32_bf16 v[60:63], v[152:155], v[212:215], v[60:63]
	v_mfma_f32_16x16x32_bf16 v[60:63], v[156:159], v[216:219], v[60:63]
	v_mfma_f32_16x16x32_bf16 v[56:59], v[160:163], v[212:215], v[56:59]
	v_mfma_f32_16x16x32_bf16 v[56:59], v[164:167], v[216:219], v[56:59]
	v_mfma_f32_16x16x32_bf16 v[28:31], v[168:171], v[188:191], v[28:31]
	v_mfma_f32_16x16x32_bf16 v[28:31], v[172:175], v[192:195], v[28:31]
	v_mfma_f32_16x16x32_bf16 v[24:27], v[176:179], v[188:191], v[24:27]
	v_mfma_f32_16x16x32_bf16 v[24:27], v[184:187], v[192:195], v[24:27]
	v_mfma_f32_16x16x32_bf16 v[20:23], v[168:171], v[196:199], v[20:23]
	v_mfma_f32_16x16x32_bf16 v[20:23], v[172:175], v[200:203], v[20:23]
	v_mfma_f32_16x16x32_bf16 v[16:19], v[176:179], v[196:199], v[16:19]
	v_mfma_f32_16x16x32_bf16 v[16:19], v[184:187], v[200:203], v[16:19]
	v_mfma_f32_16x16x32_bf16 v[12:15], v[168:171], v[204:207], v[12:15]
	v_mfma_f32_16x16x32_bf16 v[12:15], v[172:175], v[208:211], v[12:15]
	v_mfma_f32_16x16x32_bf16 v[8:11], v[176:179], v[204:207], v[8:11]
	v_mfma_f32_16x16x32_bf16 v[8:11], v[184:187], v[208:211], v[8:11]
	v_mfma_f32_16x16x32_bf16 v[4:7], v[168:171], v[212:215], v[4:7]
	v_mfma_f32_16x16x32_bf16 v[4:7], v[172:175], v[216:219], v[4:7]
	s_setprio 2
	s_barrier
	v_mfma_f32_16x16x32_bf16 v[0:3], v[176:179], v[212:215], v[0:3]
	v_mfma_f32_16x16x32_bf16 v[0:3], v[184:187], v[216:219], v[0:3]
	s_setprio 0
.Lmid_gemm9:
	s_add_i32 s79, 0, 0x18000
	s_add_i32 s88, 0, 0x1c000
	v_add_u32_e32 v164, s79, v147
	v_add_u32_e32 v181, s88, v147
	ds_read_b128 v[152:155], v164
	ds_read_b128 v[156:159], v164 offset:1024
	ds_read_b128 v[160:163], v164 offset:2048
	ds_read_b128 v[164:167], v164 offset:3072
	ds_read_b128 v[168:171], v181
	ds_read_b128 v[172:175], v181 offset:1024
	ds_read_b128 v[176:179], v181 offset:2048
	ds_read_b128 v[184:187], v181 offset:3072
	s_add_u32 s64, s64, 0x40000
	s_addc_u32 s65, s65, 0
	s_mov_b32 m0, s71
	v_lshl_add_u64 v[228:229], s[64:65], 0, v[128:129]
	ds_read_b128 v[188:191], v150 offset:32768
	ds_read_b128 v[192:195], v150 offset:33792
	ds_read_b128 v[196:199], v150 offset:34816
	ds_read_b128 v[200:203], v150 offset:35840
	ds_read_b128 v[204:207], v150 offset:36864
	ds_read_b128 v[208:211], v150 offset:37888
	ds_read_b128 v[212:215], v150 offset:38912
	ds_read_b128 v[216:219], v150 offset:39936
	global_load_lds_dwordx4 v[228:229], off
	v_lshl_add_u64 v[228:229], s[64:65], 0, v[132:133]
	s_mov_b32 m0, s72
	s_nop 0
	global_load_lds_dwordx4 v[228:229], off
	s_waitcnt vmcnt(8)
	s_waitcnt lgkmcnt(0)
	s_barrier
	s_setprio 1
	s_waitcnt lgkmcnt(0)
	v_mfma_f32_16x16x32_bf16 v[124:127], v[152:155], v[188:191], v[124:127]
	v_mfma_f32_16x16x32_bf16 v[124:127], v[156:159], v[192:195], v[124:127]
	v_mfma_f32_16x16x32_bf16 v[120:123], v[160:163], v[188:191], v[120:123]
	v_mfma_f32_16x16x32_bf16 v[120:123], v[164:167], v[192:195], v[120:123]
	v_mfma_f32_16x16x32_bf16 v[116:119], v[152:155], v[196:199], v[116:119]
	v_mfma_f32_16x16x32_bf16 v[116:119], v[156:159], v[200:203], v[116:119]
	v_mfma_f32_16x16x32_bf16 v[112:115], v[160:163], v[196:199], v[112:115]
	v_mfma_f32_16x16x32_bf16 v[112:115], v[164:167], v[200:203], v[112:115]
	v_mfma_f32_16x16x32_bf16 v[108:111], v[152:155], v[204:207], v[108:111]
	v_mfma_f32_16x16x32_bf16 v[108:111], v[156:159], v[208:211], v[108:111]
	v_mfma_f32_16x16x32_bf16 v[104:107], v[160:163], v[204:207], v[104:107]
	v_mfma_f32_16x16x32_bf16 v[104:107], v[164:167], v[208:211], v[104:107]
	v_mfma_f32_16x16x32_bf16 v[100:103], v[152:155], v[212:215], v[100:103]
	v_mfma_f32_16x16x32_bf16 v[100:103], v[156:159], v[216:219], v[100:103]
	v_mfma_f32_16x16x32_bf16 v[96:99], v[160:163], v[212:215], v[96:99]
	v_mfma_f32_16x16x32_bf16 v[96:99], v[164:167], v[216:219], v[96:99]
	v_mfma_f32_16x16x32_bf16 v[68:71], v[168:171], v[188:191], v[68:71]
	v_mfma_f32_16x16x32_bf16 v[68:71], v[172:175], v[192:195], v[68:71]
	v_mfma_f32_16x16x32_bf16 v[64:67], v[176:179], v[188:191], v[64:67]
	v_mfma_f32_16x16x32_bf16 v[64:67], v[184:187], v[192:195], v[64:67]
	v_mfma_f32_16x16x32_bf16 v[52:55], v[168:171], v[196:199], v[52:55]
	v_mfma_f32_16x16x32_bf16 v[52:55], v[172:175], v[200:203], v[52:55]
	v_mfma_f32_16x16x32_bf16 v[48:51], v[176:179], v[196:199], v[48:51]
	v_mfma_f32_16x16x32_bf16 v[48:51], v[184:187], v[200:203], v[48:51]
	v_mfma_f32_16x16x32_bf16 v[44:47], v[168:171], v[204:207], v[44:47]
	v_mfma_f32_16x16x32_bf16 v[44:47], v[172:175], v[208:211], v[44:47]
	v_mfma_f32_16x16x32_bf16 v[40:43], v[176:179], v[204:207], v[40:43]
	v_mfma_f32_16x16x32_bf16 v[40:43], v[184:187], v[208:211], v[40:43]
	v_mfma_f32_16x16x32_bf16 v[36:39], v[168:171], v[212:215], v[36:39]
	v_mfma_f32_16x16x32_bf16 v[36:39], v[172:175], v[216:219], v[36:39]
	s_setprio 2
	s_barrier
	v_mfma_f32_16x16x32_bf16 v[32:35], v[176:179], v[212:215], v[32:35]
	v_mfma_f32_16x16x32_bf16 v[32:35], v[184:187], v[216:219], v[32:35]
	s_setprio 0
	s_add_i32 s64, s79, s68
	v_lshl_add_u64 v[220:221], v[220:221], 0, s[12:13]
	s_mov_b32 m0, s64
	ds_read_b128 v[188:191], v150 offset:49152
	ds_read_b128 v[192:195], v150 offset:50176
	ds_read_b128 v[196:199], v150 offset:51200
	ds_read_b128 v[200:203], v150 offset:52224
	ds_read_b128 v[204:207], v150 offset:53248
	ds_read_b128 v[208:211], v150 offset:54272
	ds_read_b128 v[212:215], v150 offset:55296
	ds_read_b128 v[216:219], v150 offset:56320
	global_load_lds_dwordx4 v[220:221], off
	s_add_i32 m0, s64, 0x2000
	s_add_u32 s62, s62, 0x40080
	v_lshl_add_u64 v[220:221], v[222:223], 0, s[12:13]
	s_addc_u32 s63, s63, 0
	s_add_i32 s64, s88, s68
	global_load_lds_dwordx4 v[220:221], off
	v_lshl_add_u64 v[220:221], s[62:63], 0, v[130:131]
	s_mov_b32 m0, s64
	s_nop 0
	global_load_lds_dwordx4 v[220:221], off
	v_lshl_add_u64 v[220:221], s[62:63], 0, v[134:135]
	s_add_i32 m0, s64, 0x2000
	s_nop 0
	global_load_lds_dwordx4 v[220:221], off
	v_lshl_add_u64 v[220:221], v[224:225], 0, s[12:13]
	s_mov_b32 m0, s75
	s_nop 0
	global_load_lds_dwordx4 v[220:221], off
	v_lshl_add_u64 v[220:221], v[226:227], 0, s[12:13]
	s_mov_b32 m0, s76
	s_nop 0
	global_load_lds_dwordx4 v[220:221], off
	s_waitcnt vmcnt(8)
	s_waitcnt lgkmcnt(0)
	s_barrier
	s_setprio 1
	s_waitcnt lgkmcnt(0)
	v_mfma_f32_16x16x32_bf16 v[92:95], v[152:155], v[188:191], v[92:95]
	v_mfma_f32_16x16x32_bf16 v[92:95], v[156:159], v[192:195], v[92:95]
	v_mfma_f32_16x16x32_bf16 v[88:91], v[160:163], v[188:191], v[88:91]
	v_mfma_f32_16x16x32_bf16 v[88:91], v[164:167], v[192:195], v[88:91]
	v_mfma_f32_16x16x32_bf16 v[84:87], v[152:155], v[196:199], v[84:87]
	v_mfma_f32_16x16x32_bf16 v[84:87], v[156:159], v[200:203], v[84:87]
	v_mfma_f32_16x16x32_bf16 v[80:83], v[160:163], v[196:199], v[80:83]
	v_mfma_f32_16x16x32_bf16 v[80:83], v[164:167], v[200:203], v[80:83]
	v_mfma_f32_16x16x32_bf16 v[76:79], v[152:155], v[204:207], v[76:79]
	v_mfma_f32_16x16x32_bf16 v[76:79], v[156:159], v[208:211], v[76:79]
	v_mfma_f32_16x16x32_bf16 v[72:75], v[160:163], v[204:207], v[72:75]
	v_mfma_f32_16x16x32_bf16 v[72:75], v[164:167], v[208:211], v[72:75]
	v_mfma_f32_16x16x32_bf16 v[60:63], v[152:155], v[212:215], v[60:63]
	v_mfma_f32_16x16x32_bf16 v[60:63], v[156:159], v[216:219], v[60:63]
	v_mfma_f32_16x16x32_bf16 v[56:59], v[160:163], v[212:215], v[56:59]
	v_mfma_f32_16x16x32_bf16 v[56:59], v[164:167], v[216:219], v[56:59]
	v_mfma_f32_16x16x32_bf16 v[28:31], v[168:171], v[188:191], v[28:31]
	v_mfma_f32_16x16x32_bf16 v[28:31], v[172:175], v[192:195], v[28:31]
	v_mfma_f32_16x16x32_bf16 v[24:27], v[176:179], v[188:191], v[24:27]
	v_mfma_f32_16x16x32_bf16 v[24:27], v[184:187], v[192:195], v[24:27]
	v_mfma_f32_16x16x32_bf16 v[20:23], v[168:171], v[196:199], v[20:23]
	v_mfma_f32_16x16x32_bf16 v[20:23], v[172:175], v[200:203], v[20:23]
	v_mfma_f32_16x16x32_bf16 v[16:19], v[176:179], v[196:199], v[16:19]
	v_mfma_f32_16x16x32_bf16 v[16:19], v[184:187], v[200:203], v[16:19]
	v_mfma_f32_16x16x32_bf16 v[12:15], v[168:171], v[204:207], v[12:15]
	v_mfma_f32_16x16x32_bf16 v[12:15], v[172:175], v[208:211], v[12:15]
	v_mfma_f32_16x16x32_bf16 v[8:11], v[176:179], v[204:207], v[8:11]
	v_mfma_f32_16x16x32_bf16 v[8:11], v[184:187], v[208:211], v[8:11]
	v_mfma_f32_16x16x32_bf16 v[4:7], v[168:171], v[212:215], v[4:7]
	v_mfma_f32_16x16x32_bf16 v[4:7], v[172:175], v[216:219], v[4:7]
	s_setprio 2
	s_barrier
	v_mfma_f32_16x16x32_bf16 v[0:3], v[176:179], v[212:215], v[0:3]
	v_mfma_f32_16x16x32_bf16 v[0:3], v[184:187], v[216:219], v[0:3]
	s_setprio 0
	s_add_i32 s87, s87, 2
	s_add_u32 s60, s60, 0x100
	s_addc_u32 s61, s61, 0
	s_add_u32 s85, s85, 0x100
	s_addc_u32 s86, s86, 0
	s_cmp_gt_u32 s87, 13
	s_cbranch_scc0 .LBB0_1162
	s_and_b64 vcc, exec, s[16:17]
	s_cbranch_vccz .LBB0_1165
	s_barrier

.LBB0_1310:
	s_ashr_i32 s49, s48, 31
	s_lshl_b64 s[50:51], s[48:49], 19
	s_add_u32 s50, s38, s50
	s_addc_u32 s51, s39, s51
	s_and_b64 s[52:53], s[10:11], exec
	s_cselect_b32 s49, s51, s57
	s_cselect_b32 s82, s50, s56
	s_ashr_i32 s47, s46, 31
	s_lshl_b64 s[52:53], s[46:47], 19
	s_add_u32 s52, s62, s52
	s_addc_u32 s53, s63, s53
	s_and_b64 s[60:61], s[10:11], exec
	s_cselect_b32 s47, s53, s59
	s_cselect_b32 s83, s52, s58
	s_add_u32 s56, s56, 0x40080
	s_addc_u32 s57, s57, 0
	s_add_u32 s84, s58, 0x100
	s_addc_u32 s85, s59, 0
	s_mov_b32 s86, -2
	ds_read_b128 v[152:155], v149
	ds_read_b128 v[156:159], v149 offset:1024
	ds_read_b128 v[160:163], v149 offset:2048
	ds_read_b128 v[164:167], v149 offset:3072
	ds_read_b128 v[168:171], v150
	ds_read_b128 v[172:175], v150 offset:1024
	ds_read_b128 v[176:179], v150 offset:2048
	ds_read_b128 v[184:187], v150 offset:3072
	s_add_u32 s58, s56, 0xfffc0080
	s_addc_u32 s59, s57, -1
	s_cmp_eq_u32 s86, 12
	s_cselect_b32 s61, s49, s59
	s_cselect_b32 s60, s82, s58
	s_cselect_b32 s59, s47, s85
	s_cselect_b32 s58, s83, s84
	v_lshl_add_u64 v[144:145], s[56:57], 0, v[136:137]
	s_add_i32 m0, s55, 0xc000
	ds_read_b128 v[188:191], v151
	ds_read_b128 v[192:195], v151 offset:1024
	ds_read_b128 v[196:199], v151 offset:2048
	ds_read_b128 v[200:203], v151 offset:3072
	ds_read_b128 v[204:207], v151 offset:4096
	ds_read_b128 v[208:211], v151 offset:5120
	ds_read_b128 v[212:215], v151 offset:6144
	ds_read_b128 v[216:219], v151 offset:7168
	global_load_lds_dwordx4 v[144:145], off
	v_lshl_add_u64 v[144:145], s[56:57], 0, v[138:139]
	s_add_i32 m0, s55, 0xe000
	s_nop 0
	global_load_lds_dwordx4 v[144:145], off
	s_waitcnt vmcnt(8)
	s_waitcnt lgkmcnt(0)
	s_barrier
	s_setprio 1
	s_waitcnt lgkmcnt(0)
	v_mfma_f32_16x16x32_bf16 v[124:127], v[152:155], v[188:191], 0
	v_mfma_f32_16x16x32_bf16 v[124:127], v[156:159], v[192:195], v[124:127]
	v_mfma_f32_16x16x32_bf16 v[120:123], v[160:163], v[188:191], 0
	v_mfma_f32_16x16x32_bf16 v[120:123], v[164:167], v[192:195], v[120:123]
	v_mfma_f32_16x16x32_bf16 v[116:119], v[152:155], v[196:199], 0
	v_mfma_f32_16x16x32_bf16 v[116:119], v[156:159], v[200:203], v[116:119]
	v_mfma_f32_16x16x32_bf16 v[108:111], v[160:163], v[196:199], 0
	v_mfma_f32_16x16x32_bf16 v[108:111], v[164:167], v[200:203], v[108:111]
	v_mfma_f32_16x16x32_bf16 v[100:103], v[152:155], v[204:207], 0
	v_mfma_f32_16x16x32_bf16 v[100:103], v[156:159], v[208:211], v[100:103]
	v_mfma_f32_16x16x32_bf16 v[92:95], v[160:163], v[204:207], 0
	v_mfma_f32_16x16x32_bf16 v[92:95], v[164:167], v[208:211], v[92:95]
	v_mfma_f32_16x16x32_bf16 v[84:87], v[152:155], v[212:215], 0
	v_mfma_f32_16x16x32_bf16 v[84:87], v[156:159], v[216:219], v[84:87]
	v_mfma_f32_16x16x32_bf16 v[76:79], v[160:163], v[212:215], 0
	v_mfma_f32_16x16x32_bf16 v[76:79], v[164:167], v[216:219], v[76:79]
	v_mfma_f32_16x16x32_bf16 v[112:115], v[168:171], v[188:191], 0
	v_mfma_f32_16x16x32_bf16 v[112:115], v[172:175], v[192:195], v[112:115]
	v_mfma_f32_16x16x32_bf16 v[104:107], v[176:179], v[188:191], 0
	v_mfma_f32_16x16x32_bf16 v[104:107], v[184:187], v[192:195], v[104:107]
	v_mfma_f32_16x16x32_bf16 v[96:99], v[168:171], v[196:199], 0
	v_mfma_f32_16x16x32_bf16 v[96:99], v[172:175], v[200:203], v[96:99]
	v_mfma_f32_16x16x32_bf16 v[88:91], v[176:179], v[196:199], 0
	v_mfma_f32_16x16x32_bf16 v[88:91], v[184:187], v[200:203], v[88:91]
	v_mfma_f32_16x16x32_bf16 v[80:83], v[168:171], v[204:207], 0
	v_mfma_f32_16x16x32_bf16 v[80:83], v[172:175], v[208:211], v[80:83]
	v_mfma_f32_16x16x32_bf16 v[72:75], v[176:179], v[204:207], 0
	v_mfma_f32_16x16x32_bf16 v[72:75], v[184:187], v[208:211], v[72:75]
	v_mfma_f32_16x16x32_bf16 v[68:71], v[168:171], v[212:215], 0
	v_mfma_f32_16x16x32_bf16 v[68:71], v[172:175], v[216:219], v[68:71]
	s_setprio 2
	s_barrier
	v_mfma_f32_16x16x32_bf16 v[64:67], v[176:179], v[212:215], 0
	v_mfma_f32_16x16x32_bf16 v[64:67], v[184:187], v[216:219], v[64:67]
	s_setprio 0
	s_add_i32 s79, s71, s64
	v_lshl_add_u64 v[144:145], s[58:59], 0, v[130:131]
	s_mov_b32 m0, s79
	ds_read_b128 v[188:191], v151 offset:16384
	ds_read_b128 v[192:195], v151 offset:17408
	ds_read_b128 v[196:199], v151 offset:18432
	ds_read_b128 v[200:203], v151 offset:19456
	ds_read_b128 v[204:207], v151 offset:20480
	ds_read_b128 v[208:211], v151 offset:21504
	ds_read_b128 v[212:215], v151 offset:22528
	ds_read_b128 v[216:219], v151 offset:23552
	global_load_lds_dwordx4 v[144:145], off
	s_add_i32 m0, s79, 0x2000
	s_add_u32 s88, s58, 0x40000
	v_lshl_add_u64 v[220:221], s[58:59], 0, v[134:135]
	s_addc_u32 s89, s59, 0
	s_add_i32 s79, s72, s64
	global_load_lds_dwordx4 v[220:221], off
	v_lshl_add_u64 v[222:223], s[88:89], 0, v[130:131]
	s_mov_b32 m0, s79
	v_lshl_add_u64 v[224:225], s[60:61], 0, v[132:133]
	global_load_lds_dwordx4 v[222:223], off
	v_lshl_add_u64 v[222:223], s[88:89], 0, v[134:135]
	s_add_i32 m0, s79, 0x2000
	s_nop 0
	global_load_lds_dwordx4 v[222:223], off
	v_lshl_add_u64 v[222:223], s[60:61], 0, v[128:129]
	s_mov_b32 m0, s55
	s_nop 0
	global_load_lds_dwordx4 v[222:223], off
	s_mov_b32 m0, s65
	s_nop 0
	global_load_lds_dwordx4 v[224:225], off
	s_waitcnt vmcnt(8)
	s_waitcnt lgkmcnt(0)
	s_barrier
	s_setprio 1
	s_waitcnt lgkmcnt(0)
	v_mfma_f32_16x16x32_bf16 v[60:63], v[152:155], v[188:191], 0
	v_mfma_f32_16x16x32_bf16 v[60:63], v[156:159], v[192:195], v[60:63]
	v_mfma_f32_16x16x32_bf16 v[56:59], v[160:163], v[188:191], 0
	v_mfma_f32_16x16x32_bf16 v[56:59], v[164:167], v[192:195], v[56:59]
	v_mfma_f32_16x16x32_bf16 v[52:55], v[152:155], v[196:199], 0
	v_mfma_f32_16x16x32_bf16 v[52:55], v[156:159], v[200:203], v[52:55]
	v_mfma_f32_16x16x32_bf16 v[44:47], v[160:163], v[196:199], 0
	v_mfma_f32_16x16x32_bf16 v[44:47], v[164:167], v[200:203], v[44:47]
	v_mfma_f32_16x16x32_bf16 v[36:39], v[152:155], v[204:207], 0
	v_mfma_f32_16x16x32_bf16 v[36:39], v[156:159], v[208:211], v[36:39]
	v_mfma_f32_16x16x32_bf16 v[28:31], v[160:163], v[204:207], 0
	v_mfma_f32_16x16x32_bf16 v[28:31], v[164:167], v[208:211], v[28:31]
	v_mfma_f32_16x16x32_bf16 v[20:23], v[152:155], v[212:215], 0
	v_mfma_f32_16x16x32_bf16 v[20:23], v[156:159], v[216:219], v[20:23]
	v_mfma_f32_16x16x32_bf16 v[12:15], v[160:163], v[212:215], 0
	v_mfma_f32_16x16x32_bf16 v[12:15], v[164:167], v[216:219], v[12:15]
	v_mfma_f32_16x16x32_bf16 v[48:51], v[168:171], v[188:191], 0
	v_mfma_f32_16x16x32_bf16 v[48:51], v[172:175], v[192:195], v[48:51]
	v_mfma_f32_16x16x32_bf16 v[40:43], v[176:179], v[188:191], 0
	v_mfma_f32_16x16x32_bf16 v[40:43], v[184:187], v[192:195], v[40:43]
	v_mfma_f32_16x16x32_bf16 v[32:35], v[168:171], v[196:199], 0
	v_mfma_f32_16x16x32_bf16 v[32:35], v[172:175], v[200:203], v[32:35]
	v_mfma_f32_16x16x32_bf16 v[24:27], v[176:179], v[196:199], 0
	v_mfma_f32_16x16x32_bf16 v[24:27], v[184:187], v[200:203], v[24:27]
	v_mfma_f32_16x16x32_bf16 v[16:19], v[168:171], v[204:207], 0
	v_mfma_f32_16x16x32_bf16 v[16:19], v[172:175], v[208:211], v[16:19]
	v_mfma_f32_16x16x32_bf16 v[8:11], v[176:179], v[204:207], 0
	v_mfma_f32_16x16x32_bf16 v[8:11], v[184:187], v[208:211], v[8:11]
	v_mfma_f32_16x16x32_bf16 v[4:7], v[168:171], v[212:215], 0
	v_mfma_f32_16x16x32_bf16 v[4:7], v[172:175], v[216:219], v[4:7]
	s_setprio 2
	s_barrier
	v_mfma_f32_16x16x32_bf16 v[0:3], v[176:179], v[212:215], 0
	v_mfma_f32_16x16x32_bf16 v[0:3], v[184:187], v[216:219], v[0:3]
	s_setprio 0
	s_branch .Lmid_gemm10
.LBB0_1311:
	ds_read_b128 v[152:155], v149
	ds_read_b128 v[156:159], v149 offset:1024
	ds_read_b128 v[160:163], v149 offset:2048
	ds_read_b128 v[164:167], v149 offset:3072
	ds_read_b128 v[168:171], v150
	ds_read_b128 v[172:175], v150 offset:1024
	ds_read_b128 v[176:179], v150 offset:2048
	ds_read_b128 v[184:187], v150 offset:3072
	s_add_u32 s58, s56, 0xfffc0080
	s_addc_u32 s59, s57, -1
	s_cmp_eq_u32 s86, 12
	s_cselect_b32 s61, s49, s59
	s_cselect_b32 s60, s82, s58
	s_cselect_b32 s59, s47, s85
	s_cselect_b32 s58, s83, s84
	v_lshl_add_u64 v[144:145], s[56:57], 0, v[136:137]
	s_add_i32 m0, s55, 0xc000
	ds_read_b128 v[188:191], v151
	ds_read_b128 v[192:195], v151 offset:1024
	ds_read_b128 v[196:199], v151 offset:2048
	ds_read_b128 v[200:203], v151 offset:3072
	ds_read_b128 v[204:207], v151 offset:4096
	ds_read_b128 v[208:211], v151 offset:5120
	ds_read_b128 v[212:215], v151 offset:6144
	ds_read_b128 v[216:219], v151 offset:7168
	global_load_lds_dwordx4 v[144:145], off
	v_lshl_add_u64 v[144:145], s[56:57], 0, v[138:139]
	s_add_i32 m0, s55, 0xe000
	s_nop 0
	global_load_lds_dwordx4 v[144:145], off
	s_waitcnt vmcnt(8)
	s_waitcnt lgkmcnt(0)
	s_barrier
	s_setprio 1
	s_waitcnt lgkmcnt(0)
	v_mfma_f32_16x16x32_bf16 v[124:127], v[152:155], v[188:191], v[124:127]
	v_mfma_f32_16x16x32_bf16 v[124:127], v[156:159], v[192:195], v[124:127]
	v_mfma_f32_16x16x32_bf16 v[120:123], v[160:163], v[188:191], v[120:123]
	v_mfma_f32_16x16x32_bf16 v[120:123], v[164:167], v[192:195], v[120:123]
	v_mfma_f32_16x16x32_bf16 v[116:119], v[152:155], v[196:199], v[116:119]
	v_mfma_f32_16x16x32_bf16 v[116:119], v[156:159], v[200:203], v[116:119]
	v_mfma_f32_16x16x32_bf16 v[108:111], v[160:163], v[196:199], v[108:111]
	v_mfma_f32_16x16x32_bf16 v[108:111], v[164:167], v[200:203], v[108:111]
	v_mfma_f32_16x16x32_bf16 v[100:103], v[152:155], v[204:207], v[100:103]
	v_mfma_f32_16x16x32_bf16 v[100:103], v[156:159], v[208:211], v[100:103]
	v_mfma_f32_16x16x32_bf16 v[92:95], v[160:163], v[204:207], v[92:95]
	v_mfma_f32_16x16x32_bf16 v[92:95], v[164:167], v[208:211], v[92:95]
	v_mfma_f32_16x16x32_bf16 v[84:87], v[152:155], v[212:215], v[84:87]
	v_mfma_f32_16x16x32_bf16 v[84:87], v[156:159], v[216:219], v[84:87]
	v_mfma_f32_16x16x32_bf16 v[76:79], v[160:163], v[212:215], v[76:79]
	v_mfma_f32_16x16x32_bf16 v[76:79], v[164:167], v[216:219], v[76:79]
	v_mfma_f32_16x16x32_bf16 v[112:115], v[168:171], v[188:191], v[112:115]
	v_mfma_f32_16x16x32_bf16 v[112:115], v[172:175], v[192:195], v[112:115]
	v_mfma_f32_16x16x32_bf16 v[104:107], v[176:179], v[188:191], v[104:107]
	v_mfma_f32_16x16x32_bf16 v[104:107], v[184:187], v[192:195], v[104:107]
	v_mfma_f32_16x16x32_bf16 v[96:99], v[168:171], v[196:199], v[96:99]
	v_mfma_f32_16x16x32_bf16 v[96:99], v[172:175], v[200:203], v[96:99]
	v_mfma_f32_16x16x32_bf16 v[88:91], v[176:179], v[196:199], v[88:91]
	v_mfma_f32_16x16x32_bf16 v[88:91], v[184:187], v[200:203], v[88:91]
	v_mfma_f32_16x16x32_bf16 v[80:83], v[168:171], v[204:207], v[80:83]
	v_mfma_f32_16x16x32_bf16 v[80:83], v[172:175], v[208:211], v[80:83]
	v_mfma_f32_16x16x32_bf16 v[72:75], v[176:179], v[204:207], v[72:75]
	v_mfma_f32_16x16x32_bf16 v[72:75], v[184:187], v[208:211], v[72:75]
	v_mfma_f32_16x16x32_bf16 v[68:71], v[168:171], v[212:215], v[68:71]
	v_mfma_f32_16x16x32_bf16 v[68:71], v[172:175], v[216:219], v[68:71]
	s_setprio 2
	s_barrier
	v_mfma_f32_16x16x32_bf16 v[64:67], v[176:179], v[212:215], v[64:67]
	v_mfma_f32_16x16x32_bf16 v[64:67], v[184:187], v[216:219], v[64:67]
	s_setprio 0
	s_add_i32 s79, s71, s64
	v_lshl_add_u64 v[144:145], s[58:59], 0, v[130:131]
	s_mov_b32 m0, s79
	ds_read_b128 v[188:191], v151 offset:16384
	ds_read_b128 v[192:195], v151 offset:17408
	ds_read_b128 v[196:199], v151 offset:18432
	ds_read_b128 v[200:203], v151 offset:19456
	ds_read_b128 v[204:207], v151 offset:20480
	ds_read_b128 v[208:211], v151 offset:21504
	ds_read_b128 v[212:215], v151 offset:22528
	ds_read_b128 v[216:219], v151 offset:23552
	global_load_lds_dwordx4 v[144:145], off
	s_add_i32 m0, s79, 0x2000
	s_add_u32 s88, s58, 0x40000
	v_lshl_add_u64 v[220:221], s[58:59], 0, v[134:135]
	s_addc_u32 s89, s59, 0
	s_add_i32 s79, s72, s64
	global_load_lds_dwordx4 v[220:221], off
	v_lshl_add_u64 v[222:223], s[88:89], 0, v[130:131]
	s_mov_b32 m0, s79
	v_lshl_add_u64 v[224:225], s[60:61], 0, v[132:133]
	global_load_lds_dwordx4 v[222:223], off
	v_lshl_add_u64 v[222:223], s[88:89], 0, v[134:135]
	s_add_i32 m0, s79, 0x2000
	s_nop 0
	global_load_lds_dwordx4 v[222:223], off
	v_lshl_add_u64 v[222:223], s[60:61], 0, v[128:129]
	s_mov_b32 m0, s55
	s_nop 0
	global_load_lds_dwordx4 v[222:223], off
	s_mov_b32 m0, s65
	s_nop 0
	global_load_lds_dwordx4 v[224:225], off
	s_waitcnt vmcnt(8)
	s_waitcnt lgkmcnt(0)
	s_barrier
	s_setprio 1
	s_waitcnt lgkmcnt(0)
	v_mfma_f32_16x16x32_bf16 v[60:63], v[152:155], v[188:191], v[60:63]
	v_mfma_f32_16x16x32_bf16 v[60:63], v[156:159], v[192:195], v[60:63]
	v_mfma_f32_16x16x32_bf16 v[56:59], v[160:163], v[188:191], v[56:59]
	v_mfma_f32_16x16x32_bf16 v[56:59], v[164:167], v[192:195], v[56:59]
	v_mfma_f32_16x16x32_bf16 v[52:55], v[152:155], v[196:199], v[52:55]
	v_mfma_f32_16x16x32_bf16 v[52:55], v[156:159], v[200:203], v[52:55]
	v_mfma_f32_16x16x32_bf16 v[44:47], v[160:163], v[196:199], v[44:47]
	v_mfma_f32_16x16x32_bf16 v[44:47], v[164:167], v[200:203], v[44:47]
	v_mfma_f32_16x16x32_bf16 v[36:39], v[152:155], v[204:207], v[36:39]
	v_mfma_f32_16x16x32_bf16 v[36:39], v[156:159], v[208:211], v[36:39]
	v_mfma_f32_16x16x32_bf16 v[28:31], v[160:163], v[204:207], v[28:31]
	v_mfma_f32_16x16x32_bf16 v[28:31], v[164:167], v[208:211], v[28:31]
	v_mfma_f32_16x16x32_bf16 v[20:23], v[152:155], v[212:215], v[20:23]
	v_mfma_f32_16x16x32_bf16 v[20:23], v[156:159], v[216:219], v[20:23]
	v_mfma_f32_16x16x32_bf16 v[12:15], v[160:163], v[212:215], v[12:15]
	v_mfma_f32_16x16x32_bf16 v[12:15], v[164:167], v[216:219], v[12:15]
	v_mfma_f32_16x16x32_bf16 v[48:51], v[168:171], v[188:191], v[48:51]
	v_mfma_f32_16x16x32_bf16 v[48:51], v[172:175], v[192:195], v[48:51]
	v_mfma_f32_16x16x32_bf16 v[40:43], v[176:179], v[188:191], v[40:43]
	v_mfma_f32_16x16x32_bf16 v[40:43], v[184:187], v[192:195], v[40:43]
	v_mfma_f32_16x16x32_bf16 v[32:35], v[168:171], v[196:199], v[32:35]
	v_mfma_f32_16x16x32_bf16 v[32:35], v[172:175], v[200:203], v[32:35]
	v_mfma_f32_16x16x32_bf16 v[24:27], v[176:179], v[196:199], v[24:27]
	v_mfma_f32_16x16x32_bf16 v[24:27], v[184:187], v[200:203], v[24:27]
	v_mfma_f32_16x16x32_bf16 v[16:19], v[168:171], v[204:207], v[16:19]
	v_mfma_f32_16x16x32_bf16 v[16:19], v[172:175], v[208:211], v[16:19]
	v_mfma_f32_16x16x32_bf16 v[8:11], v[176:179], v[204:207], v[8:11]
	v_mfma_f32_16x16x32_bf16 v[8:11], v[184:187], v[208:211], v[8:11]
	v_mfma_f32_16x16x32_bf16 v[4:7], v[168:171], v[212:215], v[4:7]
	v_mfma_f32_16x16x32_bf16 v[4:7], v[172:175], v[216:219], v[4:7]
	s_setprio 2
	s_barrier
	v_mfma_f32_16x16x32_bf16 v[0:3], v[176:179], v[212:215], v[0:3]
	v_mfma_f32_16x16x32_bf16 v[0:3], v[184:187], v[216:219], v[0:3]
	s_setprio 0
.Lmid_gemm10:
	s_add_i32 s79, 0, 0x18000
	s_add_i32 s87, 0, 0x1c000
	v_add_u32_e32 v164, s79, v147
	v_add_u32_e32 v181, s87, v147
	ds_read_b128 v[152:155], v164
	ds_read_b128 v[156:159], v164 offset:1024
	ds_read_b128 v[160:163], v164 offset:2048
	ds_read_b128 v[164:167], v164 offset:3072
	ds_read_b128 v[168:171], v181
	ds_read_b128 v[172:175], v181 offset:1024
	ds_read_b128 v[176:179], v181 offset:2048
	ds_read_b128 v[184:187], v181 offset:3072
	s_add_u32 s60, s60, 0x40000
	s_addc_u32 s61, s61, 0
	s_mov_b32 m0, s66
	v_lshl_add_u64 v[226:227], s[60:61], 0, v[128:129]
	ds_read_b128 v[188:191], v151 offset:32768
	ds_read_b128 v[192:195], v151 offset:33792
	ds_read_b128 v[196:199], v151 offset:34816
	ds_read_b128 v[200:203], v151 offset:35840
	ds_read_b128 v[204:207], v151 offset:36864
	ds_read_b128 v[208:211], v151 offset:37888
	ds_read_b128 v[212:215], v151 offset:38912
	ds_read_b128 v[216:219], v151 offset:39936
	global_load_lds_dwordx4 v[226:227], off
	v_lshl_add_u64 v[226:227], s[60:61], 0, v[132:133]
	s_mov_b32 m0, s67
	s_nop 0
	global_load_lds_dwordx4 v[226:227], off
	s_waitcnt vmcnt(8)
	s_waitcnt lgkmcnt(0)
	s_barrier
	s_setprio 1
	s_waitcnt lgkmcnt(0)
	v_mfma_f32_16x16x32_bf16 v[124:127], v[152:155], v[188:191], v[124:127]
	v_mfma_f32_16x16x32_bf16 v[124:127], v[156:159], v[192:195], v[124:127]
	v_mfma_f32_16x16x32_bf16 v[120:123], v[160:163], v[188:191], v[120:123]
	v_mfma_f32_16x16x32_bf16 v[120:123], v[164:167], v[192:195], v[120:123]
	v_mfma_f32_16x16x32_bf16 v[116:119], v[152:155], v[196:199], v[116:119]
	v_mfma_f32_16x16x32_bf16 v[116:119], v[156:159], v[200:203], v[116:119]
	v_mfma_f32_16x16x32_bf16 v[108:111], v[160:163], v[196:199], v[108:111]
	v_mfma_f32_16x16x32_bf16 v[108:111], v[164:167], v[200:203], v[108:111]
	v_mfma_f32_16x16x32_bf16 v[100:103], v[152:155], v[204:207], v[100:103]
	v_mfma_f32_16x16x32_bf16 v[100:103], v[156:159], v[208:211], v[100:103]
	v_mfma_f32_16x16x32_bf16 v[92:95], v[160:163], v[204:207], v[92:95]
	v_mfma_f32_16x16x32_bf16 v[92:95], v[164:167], v[208:211], v[92:95]
	v_mfma_f32_16x16x32_bf16 v[84:87], v[152:155], v[212:215], v[84:87]
	v_mfma_f32_16x16x32_bf16 v[84:87], v[156:159], v[216:219], v[84:87]
	v_mfma_f32_16x16x32_bf16 v[76:79], v[160:163], v[212:215], v[76:79]
	v_mfma_f32_16x16x32_bf16 v[76:79], v[164:167], v[216:219], v[76:79]
	v_mfma_f32_16x16x32_bf16 v[112:115], v[168:171], v[188:191], v[112:115]
	v_mfma_f32_16x16x32_bf16 v[112:115], v[172:175], v[192:195], v[112:115]
	v_mfma_f32_16x16x32_bf16 v[104:107], v[176:179], v[188:191], v[104:107]
	v_mfma_f32_16x16x32_bf16 v[104:107], v[184:187], v[192:195], v[104:107]
	v_mfma_f32_16x16x32_bf16 v[96:99], v[168:171], v[196:199], v[96:99]
	v_mfma_f32_16x16x32_bf16 v[96:99], v[172:175], v[200:203], v[96:99]
	v_mfma_f32_16x16x32_bf16 v[88:91], v[176:179], v[196:199], v[88:91]
	v_mfma_f32_16x16x32_bf16 v[88:91], v[184:187], v[200:203], v[88:91]
	v_mfma_f32_16x16x32_bf16 v[80:83], v[168:171], v[204:207], v[80:83]
	v_mfma_f32_16x16x32_bf16 v[80:83], v[172:175], v[208:211], v[80:83]
	v_mfma_f32_16x16x32_bf16 v[72:75], v[176:179], v[204:207], v[72:75]
	v_mfma_f32_16x16x32_bf16 v[72:75], v[184:187], v[208:211], v[72:75]
	v_mfma_f32_16x16x32_bf16 v[68:71], v[168:171], v[212:215], v[68:71]
	v_mfma_f32_16x16x32_bf16 v[68:71], v[172:175], v[216:219], v[68:71]
	s_setprio 2
	s_barrier
	v_mfma_f32_16x16x32_bf16 v[64:67], v[176:179], v[212:215], v[64:67]
	v_mfma_f32_16x16x32_bf16 v[64:67], v[184:187], v[216:219], v[64:67]
	s_setprio 0
	s_add_i32 s60, s79, s64
	v_lshl_add_u64 v[144:145], v[144:145], 0, s[16:17]
	s_mov_b32 m0, s60
	ds_read_b128 v[188:191], v151 offset:49152
	ds_read_b128 v[192:195], v151 offset:50176
	ds_read_b128 v[196:199], v151 offset:51200
	ds_read_b128 v[200:203], v151 offset:52224
	ds_read_b128 v[204:207], v151 offset:53248
	ds_read_b128 v[208:211], v151 offset:54272
	ds_read_b128 v[212:215], v151 offset:55296
	ds_read_b128 v[216:219], v151 offset:56320
	global_load_lds_dwordx4 v[144:145], off
	s_add_i32 m0, s60, 0x2000
	s_add_u32 s58, s58, 0x40080
	v_lshl_add_u64 v[144:145], v[220:221], 0, s[16:17]
	s_addc_u32 s59, s59, 0
	s_add_i32 s60, s87, s64
	global_load_lds_dwordx4 v[144:145], off
	v_lshl_add_u64 v[144:145], s[58:59], 0, v[130:131]
	s_mov_b32 m0, s60
	s_nop 0
	global_load_lds_dwordx4 v[144:145], off
	v_lshl_add_u64 v[144:145], s[58:59], 0, v[134:135]
	s_add_i32 m0, s60, 0x2000
	s_nop 0
	global_load_lds_dwordx4 v[144:145], off
	v_lshl_add_u64 v[144:145], v[222:223], 0, s[16:17]
	s_mov_b32 m0, s69
	s_nop 0
	global_load_lds_dwordx4 v[144:145], off
	v_lshl_add_u64 v[144:145], v[224:225], 0, s[16:17]
	s_mov_b32 m0, s70
	s_nop 0
	global_load_lds_dwordx4 v[144:145], off
	s_waitcnt vmcnt(8)
	s_waitcnt lgkmcnt(0)
	s_barrier
	s_setprio 1
	s_waitcnt lgkmcnt(0)
	v_mfma_f32_16x16x32_bf16 v[60:63], v[152:155], v[188:191], v[60:63]
	v_mfma_f32_16x16x32_bf16 v[60:63], v[156:159], v[192:195], v[60:63]
	v_mfma_f32_16x16x32_bf16 v[56:59], v[160:163], v[188:191], v[56:59]
	v_mfma_f32_16x16x32_bf16 v[56:59], v[164:167], v[192:195], v[56:59]
	v_mfma_f32_16x16x32_bf16 v[52:55], v[152:155], v[196:199], v[52:55]
	v_mfma_f32_16x16x32_bf16 v[52:55], v[156:159], v[200:203], v[52:55]
	v_mfma_f32_16x16x32_bf16 v[44:47], v[160:163], v[196:199], v[44:47]
	v_mfma_f32_16x16x32_bf16 v[44:47], v[164:167], v[200:203], v[44:47]
	v_mfma_f32_16x16x32_bf16 v[36:39], v[152:155], v[204:207], v[36:39]
	v_mfma_f32_16x16x32_bf16 v[36:39], v[156:159], v[208:211], v[36:39]
	v_mfma_f32_16x16x32_bf16 v[28:31], v[160:163], v[204:207], v[28:31]
	v_mfma_f32_16x16x32_bf16 v[28:31], v[164:167], v[208:211], v[28:31]
	v_mfma_f32_16x16x32_bf16 v[20:23], v[152:155], v[212:215], v[20:23]
	v_mfma_f32_16x16x32_bf16 v[20:23], v[156:159], v[216:219], v[20:23]
	v_mfma_f32_16x16x32_bf16 v[12:15], v[160:163], v[212:215], v[12:15]
	v_mfma_f32_16x16x32_bf16 v[12:15], v[164:167], v[216:219], v[12:15]
	v_mfma_f32_16x16x32_bf16 v[48:51], v[168:171], v[188:191], v[48:51]
	v_mfma_f32_16x16x32_bf16 v[48:51], v[172:175], v[192:195], v[48:51]
	v_mfma_f32_16x16x32_bf16 v[40:43], v[176:179], v[188:191], v[40:43]
	v_mfma_f32_16x16x32_bf16 v[40:43], v[184:187], v[192:195], v[40:43]
	v_mfma_f32_16x16x32_bf16 v[32:35], v[168:171], v[196:199], v[32:35]
	v_mfma_f32_16x16x32_bf16 v[32:35], v[172:175], v[200:203], v[32:35]
	v_mfma_f32_16x16x32_bf16 v[24:27], v[176:179], v[196:199], v[24:27]
	v_mfma_f32_16x16x32_bf16 v[24:27], v[184:187], v[200:203], v[24:27]
	v_mfma_f32_16x16x32_bf16 v[16:19], v[168:171], v[204:207], v[16:19]
	v_mfma_f32_16x16x32_bf16 v[16:19], v[172:175], v[208:211], v[16:19]
	v_mfma_f32_16x16x32_bf16 v[8:11], v[176:179], v[204:207], v[8:11]
	v_mfma_f32_16x16x32_bf16 v[8:11], v[184:187], v[208:211], v[8:11]
	v_mfma_f32_16x16x32_bf16 v[4:7], v[168:171], v[212:215], v[4:7]
	v_mfma_f32_16x16x32_bf16 v[4:7], v[172:175], v[216:219], v[4:7]
	s_setprio 2
	s_barrier
	v_mfma_f32_16x16x32_bf16 v[0:3], v[176:179], v[212:215], v[0:3]
	v_mfma_f32_16x16x32_bf16 v[0:3], v[184:187], v[216:219], v[0:3]
	s_setprio 0
	s_add_i32 s86, s86, 2
	s_add_u32 s56, s56, 0x100
	s_addc_u32 s57, s57, 0
	s_add_u32 s84, s84, 0x100
	s_addc_u32 s85, s85, 0
	s_cmp_gt_u32 s86, 13
	s_cbranch_scc0 .LBB0_1311
	s_and_b64 vcc, exec, s[18:19]
	s_cbranch_vccz .LBB0_1314
	s_barrier

.LBB0_1433:
	s_ashr_i32 s19, s18, 31
	s_lshl_b64 s[30:31], s[18:19], 19
	s_add_u32 s30, s80, s30
	s_addc_u32 s31, s81, s31
	s_and_b64 s[36:37], s[8:9], exec
	s_cselect_b32 s19, s31, s47
	s_cselect_b32 s66, s30, s46
	s_ashr_i32 s17, s16, 31
	s_lshl_b64 s[36:37], s[16:17], 19
	s_add_u32 s36, s52, s36
	s_addc_u32 s37, s53, s37
	s_and_b64 s[50:51], s[8:9], exec
	s_cselect_b32 s17, s37, s49
	s_cselect_b32 s67, s36, s48
	s_add_u32 s46, s46, 0x40080
	s_addc_u32 s47, s47, 0
	s_add_u32 s68, s48, 0x100
	s_addc_u32 s69, s49, 0
	s_mov_b32 s70, -2
	ds_read_b128 v[140:143], v147
	ds_read_b128 v[150:153], v147 offset:1024
	ds_read_b128 v[154:157], v147 offset:2048
	ds_read_b128 v[158:161], v147 offset:3072
	ds_read_b128 v[162:165], v148
	ds_read_b128 v[166:169], v148 offset:1024
	ds_read_b128 v[170:173], v148 offset:2048
	ds_read_b128 v[174:177], v148 offset:3072
	s_add_u32 s48, s46, 0xfffc0080
	s_addc_u32 s49, s47, -1
	s_cmp_eq_u32 s70, 12
	s_cselect_b32 s51, s19, s49
	s_cselect_b32 s50, s66, s48
	s_cselect_b32 s49, s17, s69
	s_cselect_b32 s48, s67, s68
	v_lshl_add_u64 v[178:179], s[46:47], 0, v[132:133]
	s_add_i32 m0, s45, 0xc000
	ds_read_b128 v[184:187], v149
	ds_read_b128 v[188:191], v149 offset:1024
	ds_read_b128 v[192:195], v149 offset:2048
	ds_read_b128 v[196:199], v149 offset:3072
	ds_read_b128 v[200:203], v149 offset:4096
	ds_read_b128 v[204:207], v149 offset:5120
	ds_read_b128 v[208:211], v149 offset:6144
	ds_read_b128 v[212:215], v149 offset:7168
	global_load_lds_dwordx4 v[178:179], off
	v_lshl_add_u64 v[178:179], s[46:47], 0, v[134:135]
	s_add_i32 m0, s45, 0xe000
	s_nop 0
	global_load_lds_dwordx4 v[178:179], off
	s_waitcnt vmcnt(8)
	s_waitcnt lgkmcnt(0)
	s_barrier
	s_setprio 1
	s_waitcnt lgkmcnt(0)
	v_mfma_f32_16x16x32_bf16 v[124:127], v[140:143], v[184:187], 0
	v_mfma_f32_16x16x32_bf16 v[124:127], v[150:153], v[188:191], v[124:127]
	v_mfma_f32_16x16x32_bf16 v[120:123], v[154:157], v[184:187], 0
	v_mfma_f32_16x16x32_bf16 v[120:123], v[158:161], v[188:191], v[120:123]
	v_mfma_f32_16x16x32_bf16 v[108:111], v[140:143], v[192:195], 0
	v_mfma_f32_16x16x32_bf16 v[108:111], v[150:153], v[196:199], v[108:111]
	v_mfma_f32_16x16x32_bf16 v[104:107], v[154:157], v[192:195], 0
	v_mfma_f32_16x16x32_bf16 v[104:107], v[158:161], v[196:199], v[104:107]
	v_mfma_f32_16x16x32_bf16 v[92:95], v[140:143], v[200:203], 0
	v_mfma_f32_16x16x32_bf16 v[92:95], v[150:153], v[204:207], v[92:95]
	v_mfma_f32_16x16x32_bf16 v[88:91], v[154:157], v[200:203], 0
	v_mfma_f32_16x16x32_bf16 v[88:91], v[158:161], v[204:207], v[88:91]
	v_mfma_f32_16x16x32_bf16 v[76:79], v[140:143], v[208:211], 0
	v_mfma_f32_16x16x32_bf16 v[76:79], v[150:153], v[212:215], v[76:79]
	v_mfma_f32_16x16x32_bf16 v[72:75], v[154:157], v[208:211], 0
	v_mfma_f32_16x16x32_bf16 v[72:75], v[158:161], v[212:215], v[72:75]
	v_mfma_f32_16x16x32_bf16 v[116:119], v[162:165], v[184:187], 0
	v_mfma_f32_16x16x32_bf16 v[116:119], v[166:169], v[188:191], v[116:119]
	v_mfma_f32_16x16x32_bf16 v[112:115], v[170:173], v[184:187], 0
	v_mfma_f32_16x16x32_bf16 v[112:115], v[174:177], v[188:191], v[112:115]
	v_mfma_f32_16x16x32_bf16 v[100:103], v[162:165], v[192:195], 0
	v_mfma_f32_16x16x32_bf16 v[100:103], v[166:169], v[196:199], v[100:103]
	v_mfma_f32_16x16x32_bf16 v[96:99], v[170:173], v[192:195], 0
	v_mfma_f32_16x16x32_bf16 v[96:99], v[174:177], v[196:199], v[96:99]
	v_mfma_f32_16x16x32_bf16 v[84:87], v[162:165], v[200:203], 0
	v_mfma_f32_16x16x32_bf16 v[84:87], v[166:169], v[204:207], v[84:87]
	v_mfma_f32_16x16x32_bf16 v[80:83], v[170:173], v[200:203], 0
	v_mfma_f32_16x16x32_bf16 v[80:83], v[174:177], v[204:207], v[80:83]
	v_mfma_f32_16x16x32_bf16 v[68:71], v[162:165], v[208:211], 0
	v_mfma_f32_16x16x32_bf16 v[68:71], v[166:169], v[212:215], v[68:71]
	s_setprio 2
	s_barrier
	v_mfma_f32_16x16x32_bf16 v[64:67], v[170:173], v[208:211], 0
	v_mfma_f32_16x16x32_bf16 v[64:67], v[174:177], v[212:215], v[64:67]
	s_setprio 0
	s_add_i32 s71, s62, s54
	v_lshl_add_u64 v[178:179], s[48:49], 0, v[130:131]
	s_mov_b32 m0, s71
	ds_read_b128 v[184:187], v149 offset:16384
	ds_read_b128 v[188:191], v149 offset:17408
	ds_read_b128 v[192:195], v149 offset:18432
	ds_read_b128 v[196:199], v149 offset:19456
	ds_read_b128 v[200:203], v149 offset:20480
	ds_read_b128 v[204:207], v149 offset:21504
	ds_read_b128 v[208:211], v149 offset:22528
	ds_read_b128 v[212:215], v149 offset:23552
	global_load_lds_dwordx4 v[178:179], off
	s_add_i32 m0, s71, 0x2000
	s_add_u32 s72, s48, 0x40000
	v_lshl_add_u64 v[216:217], s[48:49], 0, v[128:129]
	s_addc_u32 s73, s49, 0
	s_add_i32 s71, s63, s54
	global_load_lds_dwordx4 v[216:217], off
	v_lshl_add_u64 v[218:219], s[72:73], 0, v[130:131]
	s_mov_b32 m0, s71
	v_lshl_add_u64 v[220:221], s[50:51], 0, v[128:129]
	global_load_lds_dwordx4 v[218:219], off
	v_lshl_add_u64 v[218:219], s[72:73], 0, v[128:129]
	s_add_i32 m0, s71, 0x2000
	s_nop 0
	global_load_lds_dwordx4 v[218:219], off
	v_lshl_add_u64 v[218:219], s[50:51], 0, v[130:131]
	s_mov_b32 m0, s45
	s_nop 0
	global_load_lds_dwordx4 v[218:219], off
	s_mov_b32 m0, s56
	s_nop 0
	global_load_lds_dwordx4 v[220:221], off
	s_waitcnt vmcnt(8)
	s_waitcnt lgkmcnt(0)
	s_barrier
	s_setprio 1
	s_waitcnt lgkmcnt(0)
	v_mfma_f32_16x16x32_bf16 v[60:63], v[140:143], v[184:187], 0
	v_mfma_f32_16x16x32_bf16 v[60:63], v[150:153], v[188:191], v[60:63]
	v_mfma_f32_16x16x32_bf16 v[56:59], v[154:157], v[184:187], 0
	v_mfma_f32_16x16x32_bf16 v[56:59], v[158:161], v[188:191], v[56:59]
	v_mfma_f32_16x16x32_bf16 v[44:47], v[140:143], v[192:195], 0
	v_mfma_f32_16x16x32_bf16 v[44:47], v[150:153], v[196:199], v[44:47]
	v_mfma_f32_16x16x32_bf16 v[40:43], v[154:157], v[192:195], 0
	v_mfma_f32_16x16x32_bf16 v[40:43], v[158:161], v[196:199], v[40:43]
	v_mfma_f32_16x16x32_bf16 v[28:31], v[140:143], v[200:203], 0
	v_mfma_f32_16x16x32_bf16 v[28:31], v[150:153], v[204:207], v[28:31]
	v_mfma_f32_16x16x32_bf16 v[24:27], v[154:157], v[200:203], 0
	v_mfma_f32_16x16x32_bf16 v[24:27], v[158:161], v[204:207], v[24:27]
	v_mfma_f32_16x16x32_bf16 v[12:15], v[140:143], v[208:211], 0
	v_mfma_f32_16x16x32_bf16 v[12:15], v[150:153], v[212:215], v[12:15]
	v_mfma_f32_16x16x32_bf16 v[8:11], v[154:157], v[208:211], 0
	v_mfma_f32_16x16x32_bf16 v[8:11], v[158:161], v[212:215], v[8:11]
	v_mfma_f32_16x16x32_bf16 v[52:55], v[162:165], v[184:187], 0
	v_mfma_f32_16x16x32_bf16 v[52:55], v[166:169], v[188:191], v[52:55]
	v_mfma_f32_16x16x32_bf16 v[48:51], v[170:173], v[184:187], 0
	v_mfma_f32_16x16x32_bf16 v[48:51], v[174:177], v[188:191], v[48:51]
	v_mfma_f32_16x16x32_bf16 v[36:39], v[162:165], v[192:195], 0
	v_mfma_f32_16x16x32_bf16 v[36:39], v[166:169], v[196:199], v[36:39]
	v_mfma_f32_16x16x32_bf16 v[32:35], v[170:173], v[192:195], 0
	v_mfma_f32_16x16x32_bf16 v[32:35], v[174:177], v[196:199], v[32:35]
	v_mfma_f32_16x16x32_bf16 v[20:23], v[162:165], v[200:203], 0
	v_mfma_f32_16x16x32_bf16 v[20:23], v[166:169], v[204:207], v[20:23]
	v_mfma_f32_16x16x32_bf16 v[16:19], v[170:173], v[200:203], 0
	v_mfma_f32_16x16x32_bf16 v[16:19], v[174:177], v[204:207], v[16:19]
	v_mfma_f32_16x16x32_bf16 v[4:7], v[162:165], v[208:211], 0
	v_mfma_f32_16x16x32_bf16 v[4:7], v[166:169], v[212:215], v[4:7]
	s_setprio 2
	s_barrier
	v_mfma_f32_16x16x32_bf16 v[0:3], v[170:173], v[208:211], 0
	v_mfma_f32_16x16x32_bf16 v[0:3], v[174:177], v[212:215], v[0:3]
	s_setprio 0
	s_branch .Lmid_gemm11
.LBB0_1434:
	ds_read_b128 v[140:143], v147
	ds_read_b128 v[150:153], v147 offset:1024
	ds_read_b128 v[154:157], v147 offset:2048
	ds_read_b128 v[158:161], v147 offset:3072
	ds_read_b128 v[162:165], v148
	ds_read_b128 v[166:169], v148 offset:1024
	ds_read_b128 v[170:173], v148 offset:2048
	ds_read_b128 v[174:177], v148 offset:3072
	s_add_u32 s48, s46, 0xfffc0080
	s_addc_u32 s49, s47, -1
	s_cmp_eq_u32 s70, 12
	s_cselect_b32 s51, s19, s49
	s_cselect_b32 s50, s66, s48
	s_cselect_b32 s49, s17, s69
	s_cselect_b32 s48, s67, s68
	v_lshl_add_u64 v[178:179], s[46:47], 0, v[132:133]
	s_add_i32 m0, s45, 0xc000
	ds_read_b128 v[184:187], v149
	ds_read_b128 v[188:191], v149 offset:1024
	ds_read_b128 v[192:195], v149 offset:2048
	ds_read_b128 v[196:199], v149 offset:3072
	ds_read_b128 v[200:203], v149 offset:4096
	ds_read_b128 v[204:207], v149 offset:5120
	ds_read_b128 v[208:211], v149 offset:6144
	ds_read_b128 v[212:215], v149 offset:7168
	global_load_lds_dwordx4 v[178:179], off
	v_lshl_add_u64 v[178:179], s[46:47], 0, v[134:135]
	s_add_i32 m0, s45, 0xe000
	s_nop 0
	global_load_lds_dwordx4 v[178:179], off
	s_waitcnt vmcnt(8)
	s_waitcnt lgkmcnt(0)
	s_barrier
	s_setprio 1
	s_waitcnt lgkmcnt(0)
	v_mfma_f32_16x16x32_bf16 v[124:127], v[140:143], v[184:187], v[124:127]
	v_mfma_f32_16x16x32_bf16 v[124:127], v[150:153], v[188:191], v[124:127]
	v_mfma_f32_16x16x32_bf16 v[120:123], v[154:157], v[184:187], v[120:123]
	v_mfma_f32_16x16x32_bf16 v[120:123], v[158:161], v[188:191], v[120:123]
	v_mfma_f32_16x16x32_bf16 v[108:111], v[140:143], v[192:195], v[108:111]
	v_mfma_f32_16x16x32_bf16 v[108:111], v[150:153], v[196:199], v[108:111]
	v_mfma_f32_16x16x32_bf16 v[104:107], v[154:157], v[192:195], v[104:107]
	v_mfma_f32_16x16x32_bf16 v[104:107], v[158:161], v[196:199], v[104:107]
	v_mfma_f32_16x16x32_bf16 v[92:95], v[140:143], v[200:203], v[92:95]
	v_mfma_f32_16x16x32_bf16 v[92:95], v[150:153], v[204:207], v[92:95]
	v_mfma_f32_16x16x32_bf16 v[88:91], v[154:157], v[200:203], v[88:91]
	v_mfma_f32_16x16x32_bf16 v[88:91], v[158:161], v[204:207], v[88:91]
	v_mfma_f32_16x16x32_bf16 v[76:79], v[140:143], v[208:211], v[76:79]
	v_mfma_f32_16x16x32_bf16 v[76:79], v[150:153], v[212:215], v[76:79]
	v_mfma_f32_16x16x32_bf16 v[72:75], v[154:157], v[208:211], v[72:75]
	v_mfma_f32_16x16x32_bf16 v[72:75], v[158:161], v[212:215], v[72:75]
	v_mfma_f32_16x16x32_bf16 v[116:119], v[162:165], v[184:187], v[116:119]
	v_mfma_f32_16x16x32_bf16 v[116:119], v[166:169], v[188:191], v[116:119]
	v_mfma_f32_16x16x32_bf16 v[112:115], v[170:173], v[184:187], v[112:115]
	v_mfma_f32_16x16x32_bf16 v[112:115], v[174:177], v[188:191], v[112:115]
	v_mfma_f32_16x16x32_bf16 v[100:103], v[162:165], v[192:195], v[100:103]
	v_mfma_f32_16x16x32_bf16 v[100:103], v[166:169], v[196:199], v[100:103]
	v_mfma_f32_16x16x32_bf16 v[96:99], v[170:173], v[192:195], v[96:99]
	v_mfma_f32_16x16x32_bf16 v[96:99], v[174:177], v[196:199], v[96:99]
	v_mfma_f32_16x16x32_bf16 v[84:87], v[162:165], v[200:203], v[84:87]
	v_mfma_f32_16x16x32_bf16 v[84:87], v[166:169], v[204:207], v[84:87]
	v_mfma_f32_16x16x32_bf16 v[80:83], v[170:173], v[200:203], v[80:83]
	v_mfma_f32_16x16x32_bf16 v[80:83], v[174:177], v[204:207], v[80:83]
	v_mfma_f32_16x16x32_bf16 v[68:71], v[162:165], v[208:211], v[68:71]
	v_mfma_f32_16x16x32_bf16 v[68:71], v[166:169], v[212:215], v[68:71]
	s_setprio 2
	s_barrier
	v_mfma_f32_16x16x32_bf16 v[64:67], v[170:173], v[208:211], v[64:67]
	v_mfma_f32_16x16x32_bf16 v[64:67], v[174:177], v[212:215], v[64:67]
	s_setprio 0
	s_add_i32 s71, s62, s54
	v_lshl_add_u64 v[178:179], s[48:49], 0, v[130:131]
	s_mov_b32 m0, s71
	ds_read_b128 v[184:187], v149 offset:16384
	ds_read_b128 v[188:191], v149 offset:17408
	ds_read_b128 v[192:195], v149 offset:18432
	ds_read_b128 v[196:199], v149 offset:19456
	ds_read_b128 v[200:203], v149 offset:20480
	ds_read_b128 v[204:207], v149 offset:21504
	ds_read_b128 v[208:211], v149 offset:22528
	ds_read_b128 v[212:215], v149 offset:23552
	global_load_lds_dwordx4 v[178:179], off
	s_add_i32 m0, s71, 0x2000
	s_add_u32 s72, s48, 0x40000
	v_lshl_add_u64 v[216:217], s[48:49], 0, v[128:129]
	s_addc_u32 s73, s49, 0
	s_add_i32 s71, s63, s54
	global_load_lds_dwordx4 v[216:217], off
	v_lshl_add_u64 v[218:219], s[72:73], 0, v[130:131]
	s_mov_b32 m0, s71
	v_lshl_add_u64 v[220:221], s[50:51], 0, v[128:129]
	global_load_lds_dwordx4 v[218:219], off
	v_lshl_add_u64 v[218:219], s[72:73], 0, v[128:129]
	s_add_i32 m0, s71, 0x2000
	s_nop 0
	global_load_lds_dwordx4 v[218:219], off
	v_lshl_add_u64 v[218:219], s[50:51], 0, v[130:131]
	s_mov_b32 m0, s45
	s_nop 0
	global_load_lds_dwordx4 v[218:219], off
	s_mov_b32 m0, s56
	s_nop 0
	global_load_lds_dwordx4 v[220:221], off
	s_waitcnt vmcnt(8)
	s_waitcnt lgkmcnt(0)
	s_barrier
	s_setprio 1
	s_waitcnt lgkmcnt(0)
	v_mfma_f32_16x16x32_bf16 v[60:63], v[140:143], v[184:187], v[60:63]
	v_mfma_f32_16x16x32_bf16 v[60:63], v[150:153], v[188:191], v[60:63]
	v_mfma_f32_16x16x32_bf16 v[56:59], v[154:157], v[184:187], v[56:59]
	v_mfma_f32_16x16x32_bf16 v[56:59], v[158:161], v[188:191], v[56:59]
	v_mfma_f32_16x16x32_bf16 v[44:47], v[140:143], v[192:195], v[44:47]
	v_mfma_f32_16x16x32_bf16 v[44:47], v[150:153], v[196:199], v[44:47]
	v_mfma_f32_16x16x32_bf16 v[40:43], v[154:157], v[192:195], v[40:43]
	v_mfma_f32_16x16x32_bf16 v[40:43], v[158:161], v[196:199], v[40:43]
	v_mfma_f32_16x16x32_bf16 v[28:31], v[140:143], v[200:203], v[28:31]
	v_mfma_f32_16x16x32_bf16 v[28:31], v[150:153], v[204:207], v[28:31]
	v_mfma_f32_16x16x32_bf16 v[24:27], v[154:157], v[200:203], v[24:27]
	v_mfma_f32_16x16x32_bf16 v[24:27], v[158:161], v[204:207], v[24:27]
	v_mfma_f32_16x16x32_bf16 v[12:15], v[140:143], v[208:211], v[12:15]
	v_mfma_f32_16x16x32_bf16 v[12:15], v[150:153], v[212:215], v[12:15]
	v_mfma_f32_16x16x32_bf16 v[8:11], v[154:157], v[208:211], v[8:11]
	v_mfma_f32_16x16x32_bf16 v[8:11], v[158:161], v[212:215], v[8:11]
	v_mfma_f32_16x16x32_bf16 v[52:55], v[162:165], v[184:187], v[52:55]
	v_mfma_f32_16x16x32_bf16 v[52:55], v[166:169], v[188:191], v[52:55]
	v_mfma_f32_16x16x32_bf16 v[48:51], v[170:173], v[184:187], v[48:51]
	v_mfma_f32_16x16x32_bf16 v[48:51], v[174:177], v[188:191], v[48:51]
	v_mfma_f32_16x16x32_bf16 v[36:39], v[162:165], v[192:195], v[36:39]
	v_mfma_f32_16x16x32_bf16 v[36:39], v[166:169], v[196:199], v[36:39]
	v_mfma_f32_16x16x32_bf16 v[32:35], v[170:173], v[192:195], v[32:35]
	v_mfma_f32_16x16x32_bf16 v[32:35], v[174:177], v[196:199], v[32:35]
	v_mfma_f32_16x16x32_bf16 v[20:23], v[162:165], v[200:203], v[20:23]
	v_mfma_f32_16x16x32_bf16 v[20:23], v[166:169], v[204:207], v[20:23]
	v_mfma_f32_16x16x32_bf16 v[16:19], v[170:173], v[200:203], v[16:19]
	v_mfma_f32_16x16x32_bf16 v[16:19], v[174:177], v[204:207], v[16:19]
	v_mfma_f32_16x16x32_bf16 v[4:7], v[162:165], v[208:211], v[4:7]
	v_mfma_f32_16x16x32_bf16 v[4:7], v[166:169], v[212:215], v[4:7]
	s_setprio 2
	s_barrier
	v_mfma_f32_16x16x32_bf16 v[0:3], v[170:173], v[208:211], v[0:3]
	v_mfma_f32_16x16x32_bf16 v[0:3], v[174:177], v[212:215], v[0:3]
	s_setprio 0
.Lmid_gemm11:
	s_add_i32 s71, 0, 0x18000
	s_add_i32 s72, 0, 0x1c000
	v_add_u32_e32 v158, s71, v145
	v_add_u32_e32 v174, s72, v145
	ds_read_b128 v[140:143], v158
	ds_read_b128 v[150:153], v158 offset:1024
	ds_read_b128 v[154:157], v158 offset:2048
	ds_read_b128 v[158:161], v158 offset:3072
	ds_read_b128 v[162:165], v174
	ds_read_b128 v[166:169], v174 offset:1024
	ds_read_b128 v[170:173], v174 offset:2048
	ds_read_b128 v[174:177], v174 offset:3072
	s_add_u32 s50, s50, 0x40000
	s_addc_u32 s51, s51, 0
	s_mov_b32 m0, s57
	v_lshl_add_u64 v[222:223], s[50:51], 0, v[130:131]
	ds_read_b128 v[184:187], v149 offset:32768
	ds_read_b128 v[188:191], v149 offset:33792
	ds_read_b128 v[192:195], v149 offset:34816
	ds_read_b128 v[196:199], v149 offset:35840
	ds_read_b128 v[200:203], v149 offset:36864
	ds_read_b128 v[204:207], v149 offset:37888
	ds_read_b128 v[208:211], v149 offset:38912
	ds_read_b128 v[212:215], v149 offset:39936
	global_load_lds_dwordx4 v[222:223], off
	v_lshl_add_u64 v[222:223], s[50:51], 0, v[128:129]
	s_mov_b32 m0, s58
	s_nop 0
	global_load_lds_dwordx4 v[222:223], off
	s_waitcnt vmcnt(8)
	s_waitcnt lgkmcnt(0)
	s_barrier
	s_setprio 1
	s_waitcnt lgkmcnt(0)
	v_mfma_f32_16x16x32_bf16 v[124:127], v[140:143], v[184:187], v[124:127]
	v_mfma_f32_16x16x32_bf16 v[124:127], v[150:153], v[188:191], v[124:127]
	v_mfma_f32_16x16x32_bf16 v[120:123], v[154:157], v[184:187], v[120:123]
	v_mfma_f32_16x16x32_bf16 v[120:123], v[158:161], v[188:191], v[120:123]
	v_mfma_f32_16x16x32_bf16 v[108:111], v[140:143], v[192:195], v[108:111]
	v_mfma_f32_16x16x32_bf16 v[108:111], v[150:153], v[196:199], v[108:111]
	v_mfma_f32_16x16x32_bf16 v[104:107], v[154:157], v[192:195], v[104:107]
	v_mfma_f32_16x16x32_bf16 v[104:107], v[158:161], v[196:199], v[104:107]
	v_mfma_f32_16x16x32_bf16 v[92:95], v[140:143], v[200:203], v[92:95]
	v_mfma_f32_16x16x32_bf16 v[92:95], v[150:153], v[204:207], v[92:95]
	v_mfma_f32_16x16x32_bf16 v[88:91], v[154:157], v[200:203], v[88:91]
	v_mfma_f32_16x16x32_bf16 v[88:91], v[158:161], v[204:207], v[88:91]
	v_mfma_f32_16x16x32_bf16 v[76:79], v[140:143], v[208:211], v[76:79]
	v_mfma_f32_16x16x32_bf16 v[76:79], v[150:153], v[212:215], v[76:79]
	v_mfma_f32_16x16x32_bf16 v[72:75], v[154:157], v[208:211], v[72:75]
	v_mfma_f32_16x16x32_bf16 v[72:75], v[158:161], v[212:215], v[72:75]
	v_mfma_f32_16x16x32_bf16 v[116:119], v[162:165], v[184:187], v[116:119]
	v_mfma_f32_16x16x32_bf16 v[116:119], v[166:169], v[188:191], v[116:119]
	v_mfma_f32_16x16x32_bf16 v[112:115], v[170:173], v[184:187], v[112:115]
	v_mfma_f32_16x16x32_bf16 v[112:115], v[174:177], v[188:191], v[112:115]
	v_mfma_f32_16x16x32_bf16 v[100:103], v[162:165], v[192:195], v[100:103]
	v_mfma_f32_16x16x32_bf16 v[100:103], v[166:169], v[196:199], v[100:103]
	v_mfma_f32_16x16x32_bf16 v[96:99], v[170:173], v[192:195], v[96:99]
	v_mfma_f32_16x16x32_bf16 v[96:99], v[174:177], v[196:199], v[96:99]
	v_mfma_f32_16x16x32_bf16 v[84:87], v[162:165], v[200:203], v[84:87]
	v_mfma_f32_16x16x32_bf16 v[84:87], v[166:169], v[204:207], v[84:87]
	v_mfma_f32_16x16x32_bf16 v[80:83], v[170:173], v[200:203], v[80:83]
	v_mfma_f32_16x16x32_bf16 v[80:83], v[174:177], v[204:207], v[80:83]
	v_mfma_f32_16x16x32_bf16 v[68:71], v[162:165], v[208:211], v[68:71]
	v_mfma_f32_16x16x32_bf16 v[68:71], v[166:169], v[212:215], v[68:71]
	s_setprio 2
	s_barrier
	v_mfma_f32_16x16x32_bf16 v[64:67], v[170:173], v[208:211], v[64:67]
	v_mfma_f32_16x16x32_bf16 v[64:67], v[174:177], v[212:215], v[64:67]
	s_setprio 0
	s_add_i32 s50, s71, s54
	v_lshl_add_u64 v[178:179], v[178:179], 0, s[10:11]
	s_mov_b32 m0, s50
	ds_read_b128 v[184:187], v149 offset:49152
	ds_read_b128 v[188:191], v149 offset:50176
	ds_read_b128 v[192:195], v149 offset:51200
	ds_read_b128 v[196:199], v149 offset:52224
	ds_read_b128 v[200:203], v149 offset:53248
	ds_read_b128 v[204:207], v149 offset:54272
	ds_read_b128 v[208:211], v149 offset:55296
	ds_read_b128 v[212:215], v149 offset:56320
	global_load_lds_dwordx4 v[178:179], off
	s_add_i32 m0, s50, 0x2000
	s_add_u32 s48, s48, 0x40080
	v_lshl_add_u64 v[178:179], v[216:217], 0, s[10:11]
	s_addc_u32 s49, s49, 0
	s_add_i32 s50, s72, s54
	global_load_lds_dwordx4 v[178:179], off
	v_lshl_add_u64 v[178:179], s[48:49], 0, v[130:131]
	s_mov_b32 m0, s50
	s_nop 0
	global_load_lds_dwordx4 v[178:179], off
	v_lshl_add_u64 v[178:179], s[48:49], 0, v[128:129]
	s_add_i32 m0, s50, 0x2000
	s_nop 0
	global_load_lds_dwordx4 v[178:179], off
	v_lshl_add_u64 v[178:179], v[218:219], 0, s[10:11]
	s_mov_b32 m0, s60
	s_nop 0
	global_load_lds_dwordx4 v[178:179], off
	v_lshl_add_u64 v[178:179], v[220:221], 0, s[10:11]
	s_mov_b32 m0, s61
	s_nop 0
	global_load_lds_dwordx4 v[178:179], off
	s_waitcnt vmcnt(8)
	s_waitcnt lgkmcnt(0)
	s_barrier
	s_setprio 1
	s_waitcnt lgkmcnt(0)
	v_mfma_f32_16x16x32_bf16 v[60:63], v[140:143], v[184:187], v[60:63]
	v_mfma_f32_16x16x32_bf16 v[60:63], v[150:153], v[188:191], v[60:63]
	v_mfma_f32_16x16x32_bf16 v[56:59], v[154:157], v[184:187], v[56:59]
	v_mfma_f32_16x16x32_bf16 v[56:59], v[158:161], v[188:191], v[56:59]
	v_mfma_f32_16x16x32_bf16 v[44:47], v[140:143], v[192:195], v[44:47]
	v_mfma_f32_16x16x32_bf16 v[44:47], v[150:153], v[196:199], v[44:47]
	v_mfma_f32_16x16x32_bf16 v[40:43], v[154:157], v[192:195], v[40:43]
	v_mfma_f32_16x16x32_bf16 v[40:43], v[158:161], v[196:199], v[40:43]
	v_mfma_f32_16x16x32_bf16 v[28:31], v[140:143], v[200:203], v[28:31]
	v_mfma_f32_16x16x32_bf16 v[28:31], v[150:153], v[204:207], v[28:31]
	v_mfma_f32_16x16x32_bf16 v[24:27], v[154:157], v[200:203], v[24:27]
	v_mfma_f32_16x16x32_bf16 v[24:27], v[158:161], v[204:207], v[24:27]
	v_mfma_f32_16x16x32_bf16 v[12:15], v[140:143], v[208:211], v[12:15]
	v_mfma_f32_16x16x32_bf16 v[12:15], v[150:153], v[212:215], v[12:15]
	v_mfma_f32_16x16x32_bf16 v[8:11], v[154:157], v[208:211], v[8:11]
	v_mfma_f32_16x16x32_bf16 v[8:11], v[158:161], v[212:215], v[8:11]
	v_mfma_f32_16x16x32_bf16 v[52:55], v[162:165], v[184:187], v[52:55]
	v_mfma_f32_16x16x32_bf16 v[52:55], v[166:169], v[188:191], v[52:55]
	v_mfma_f32_16x16x32_bf16 v[48:51], v[170:173], v[184:187], v[48:51]
	v_mfma_f32_16x16x32_bf16 v[48:51], v[174:177], v[188:191], v[48:51]
	v_mfma_f32_16x16x32_bf16 v[36:39], v[162:165], v[192:195], v[36:39]
	v_mfma_f32_16x16x32_bf16 v[36:39], v[166:169], v[196:199], v[36:39]
	v_mfma_f32_16x16x32_bf16 v[32:35], v[170:173], v[192:195], v[32:35]
	v_mfma_f32_16x16x32_bf16 v[32:35], v[174:177], v[196:199], v[32:35]
	v_mfma_f32_16x16x32_bf16 v[20:23], v[162:165], v[200:203], v[20:23]
	v_mfma_f32_16x16x32_bf16 v[20:23], v[166:169], v[204:207], v[20:23]
	v_mfma_f32_16x16x32_bf16 v[16:19], v[170:173], v[200:203], v[16:19]
	v_mfma_f32_16x16x32_bf16 v[16:19], v[174:177], v[204:207], v[16:19]
	v_mfma_f32_16x16x32_bf16 v[4:7], v[162:165], v[208:211], v[4:7]
	v_mfma_f32_16x16x32_bf16 v[4:7], v[166:169], v[212:215], v[4:7]
	s_setprio 2
	s_barrier
	v_mfma_f32_16x16x32_bf16 v[0:3], v[170:173], v[208:211], v[0:3]
	v_mfma_f32_16x16x32_bf16 v[0:3], v[174:177], v[212:215], v[0:3]
	s_setprio 0
	s_add_i32 s70, s70, 2
	s_add_u32 s46, s46, 0x100
	s_addc_u32 s47, s47, 0
	s_add_u32 s68, s68, 0x100
	s_addc_u32 s69, s69, 0
	s_cmp_gt_u32 s70, 13
	s_cbranch_scc0 .LBB0_1434
	s_and_b64 vcc, exec, s[12:13]
	s_cbranch_vccz .LBB0_1437
	s_barrier

.LBB0_1513:
	s_add_u32 s74, s48, 0x100
	s_addc_u32 s75, s49, 0
	s_mov_b32 s76, -2
	ds_read_b128 v[152:155], v149
	ds_read_b128 v[156:159], v149 offset:1024
	ds_read_b128 v[160:163], v149 offset:2048
	ds_read_b128 v[164:167], v149 offset:3072
	ds_read_b128 v[168:171], v150
	ds_read_b128 v[172:175], v150 offset:1024
	ds_read_b128 v[176:179], v150 offset:2048
	ds_read_b128 v[184:187], v150 offset:3072
	s_add_u32 s48, s46, 0x100
	s_addc_u32 s49, s47, 0
	s_cmp_eq_u32 s76, 40
	s_cselect_b32 s53, s9, s49
	s_cselect_b32 s52, s8, s48
	s_cselect_b32 s51, s45, s75
	s_cselect_b32 s50, s44, s74
	v_lshl_add_u64 v[144:145], s[46:47], 0, v[136:137]
	s_add_i32 m0, s57, 0xc000
	ds_read_b128 v[188:191], v151
	ds_read_b128 v[192:195], v151 offset:1024
	ds_read_b128 v[196:199], v151 offset:2048
	ds_read_b128 v[200:203], v151 offset:3072
	ds_read_b128 v[204:207], v151 offset:4096
	ds_read_b128 v[208:211], v151 offset:5120
	ds_read_b128 v[212:215], v151 offset:6144
	ds_read_b128 v[216:219], v151 offset:7168
	global_load_lds_dwordx4 v[144:145], off
	v_lshl_add_u64 v[144:145], s[46:47], 0, v[138:139]
	s_add_i32 m0, s57, 0xe000
	s_nop 0
	global_load_lds_dwordx4 v[144:145], off
	s_waitcnt vmcnt(8)
	s_waitcnt lgkmcnt(0)
	s_barrier
	s_setprio 1
	s_waitcnt lgkmcnt(0)
	v_mfma_f32_16x16x32_bf16 v[124:127], v[152:155], v[188:191], 0
	v_mfma_f32_16x16x32_bf16 v[124:127], v[156:159], v[192:195], v[124:127]
	v_mfma_f32_16x16x32_bf16 v[120:123], v[160:163], v[188:191], 0
	v_mfma_f32_16x16x32_bf16 v[120:123], v[164:167], v[192:195], v[120:123]
	v_mfma_f32_16x16x32_bf16 v[116:119], v[152:155], v[196:199], 0
	v_mfma_f32_16x16x32_bf16 v[116:119], v[156:159], v[200:203], v[116:119]
	v_mfma_f32_16x16x32_bf16 v[108:111], v[160:163], v[196:199], 0
	v_mfma_f32_16x16x32_bf16 v[108:111], v[164:167], v[200:203], v[108:111]
	v_mfma_f32_16x16x32_bf16 v[100:103], v[152:155], v[204:207], 0
	v_mfma_f32_16x16x32_bf16 v[100:103], v[156:159], v[208:211], v[100:103]
	v_mfma_f32_16x16x32_bf16 v[92:95], v[160:163], v[204:207], 0
	v_mfma_f32_16x16x32_bf16 v[92:95], v[164:167], v[208:211], v[92:95]
	v_mfma_f32_16x16x32_bf16 v[84:87], v[152:155], v[212:215], 0
	v_mfma_f32_16x16x32_bf16 v[84:87], v[156:159], v[216:219], v[84:87]
	v_mfma_f32_16x16x32_bf16 v[76:79], v[160:163], v[212:215], 0
	v_mfma_f32_16x16x32_bf16 v[76:79], v[164:167], v[216:219], v[76:79]
	v_mfma_f32_16x16x32_bf16 v[112:115], v[168:171], v[188:191], 0
	v_mfma_f32_16x16x32_bf16 v[112:115], v[172:175], v[192:195], v[112:115]
	v_mfma_f32_16x16x32_bf16 v[104:107], v[176:179], v[188:191], 0
	v_mfma_f32_16x16x32_bf16 v[104:107], v[184:187], v[192:195], v[104:107]
	v_mfma_f32_16x16x32_bf16 v[96:99], v[168:171], v[196:199], 0
	v_mfma_f32_16x16x32_bf16 v[96:99], v[172:175], v[200:203], v[96:99]
	v_mfma_f32_16x16x32_bf16 v[88:91], v[176:179], v[196:199], 0
	v_mfma_f32_16x16x32_bf16 v[88:91], v[184:187], v[200:203], v[88:91]
	v_mfma_f32_16x16x32_bf16 v[80:83], v[168:171], v[204:207], 0
	v_mfma_f32_16x16x32_bf16 v[80:83], v[172:175], v[208:211], v[80:83]
	v_mfma_f32_16x16x32_bf16 v[72:75], v[176:179], v[204:207], 0
	v_mfma_f32_16x16x32_bf16 v[72:75], v[184:187], v[208:211], v[72:75]
	v_mfma_f32_16x16x32_bf16 v[68:71], v[168:171], v[212:215], 0
	v_mfma_f32_16x16x32_bf16 v[68:71], v[172:175], v[216:219], v[68:71]
	s_setprio 2
	s_barrier
	v_mfma_f32_16x16x32_bf16 v[64:67], v[176:179], v[212:215], 0
	v_mfma_f32_16x16x32_bf16 v[64:67], v[184:187], v[216:219], v[64:67]
	s_setprio 0
	s_add_i32 s46, s64, s56
	v_lshl_add_u64 v[144:145], s[50:51], 0, v[130:131]
	s_mov_b32 m0, s46
	ds_read_b128 v[188:191], v151 offset:16384
	ds_read_b128 v[192:195], v151 offset:17408
	ds_read_b128 v[196:199], v151 offset:18432
	ds_read_b128 v[200:203], v151 offset:19456
	ds_read_b128 v[204:207], v151 offset:20480
	ds_read_b128 v[208:211], v151 offset:21504
	ds_read_b128 v[212:215], v151 offset:22528
	ds_read_b128 v[216:219], v151 offset:23552
	global_load_lds_dwordx4 v[144:145], off
	s_add_i32 m0, s46, 0x2000
	s_add_u32 s46, s50, 0xb0000
	v_lshl_add_u64 v[220:221], s[50:51], 0, v[134:135]
	s_addc_u32 s47, s51, 0
	s_add_i32 s77, s65, s56
	global_load_lds_dwordx4 v[220:221], off
	v_lshl_add_u64 v[222:223], s[46:47], 0, v[130:131]
	s_mov_b32 m0, s77
	v_lshl_add_u64 v[224:225], s[52:53], 0, v[132:133]
	global_load_lds_dwordx4 v[222:223], off
	v_lshl_add_u64 v[222:223], s[46:47], 0, v[134:135]
	s_add_i32 m0, s77, 0x2000
	s_nop 0
	global_load_lds_dwordx4 v[222:223], off
	v_lshl_add_u64 v[222:223], s[52:53], 0, v[128:129]
	s_mov_b32 m0, s57
	s_nop 0
	global_load_lds_dwordx4 v[222:223], off
	s_mov_b32 m0, s58
	s_nop 0
	global_load_lds_dwordx4 v[224:225], off
	s_waitcnt vmcnt(8)
	s_waitcnt lgkmcnt(0)
	s_barrier
	s_setprio 1
	s_waitcnt lgkmcnt(0)
	v_mfma_f32_16x16x32_bf16 v[60:63], v[152:155], v[188:191], 0
	v_mfma_f32_16x16x32_bf16 v[60:63], v[156:159], v[192:195], v[60:63]
	v_mfma_f32_16x16x32_bf16 v[56:59], v[160:163], v[188:191], 0
	v_mfma_f32_16x16x32_bf16 v[56:59], v[164:167], v[192:195], v[56:59]
	v_mfma_f32_16x16x32_bf16 v[52:55], v[152:155], v[196:199], 0
	v_mfma_f32_16x16x32_bf16 v[52:55], v[156:159], v[200:203], v[52:55]
	v_mfma_f32_16x16x32_bf16 v[44:47], v[160:163], v[196:199], 0
	v_mfma_f32_16x16x32_bf16 v[44:47], v[164:167], v[200:203], v[44:47]
	v_mfma_f32_16x16x32_bf16 v[36:39], v[152:155], v[204:207], 0
	v_mfma_f32_16x16x32_bf16 v[36:39], v[156:159], v[208:211], v[36:39]
	v_mfma_f32_16x16x32_bf16 v[28:31], v[160:163], v[204:207], 0
	v_mfma_f32_16x16x32_bf16 v[28:31], v[164:167], v[208:211], v[28:31]
	v_mfma_f32_16x16x32_bf16 v[20:23], v[152:155], v[212:215], 0
	v_mfma_f32_16x16x32_bf16 v[20:23], v[156:159], v[216:219], v[20:23]
	v_mfma_f32_16x16x32_bf16 v[12:15], v[160:163], v[212:215], 0
	v_mfma_f32_16x16x32_bf16 v[12:15], v[164:167], v[216:219], v[12:15]
	v_mfma_f32_16x16x32_bf16 v[48:51], v[168:171], v[188:191], 0
	v_mfma_f32_16x16x32_bf16 v[48:51], v[172:175], v[192:195], v[48:51]
	v_mfma_f32_16x16x32_bf16 v[40:43], v[176:179], v[188:191], 0
	v_mfma_f32_16x16x32_bf16 v[40:43], v[184:187], v[192:195], v[40:43]
	v_mfma_f32_16x16x32_bf16 v[32:35], v[168:171], v[196:199], 0
	v_mfma_f32_16x16x32_bf16 v[32:35], v[172:175], v[200:203], v[32:35]
	v_mfma_f32_16x16x32_bf16 v[24:27], v[176:179], v[196:199], 0
	v_mfma_f32_16x16x32_bf16 v[24:27], v[184:187], v[200:203], v[24:27]
	v_mfma_f32_16x16x32_bf16 v[16:19], v[168:171], v[204:207], 0
	v_mfma_f32_16x16x32_bf16 v[16:19], v[172:175], v[208:211], v[16:19]
	v_mfma_f32_16x16x32_bf16 v[8:11], v[176:179], v[204:207], 0
	v_mfma_f32_16x16x32_bf16 v[8:11], v[184:187], v[208:211], v[8:11]
	v_mfma_f32_16x16x32_bf16 v[4:7], v[168:171], v[212:215], 0
	v_mfma_f32_16x16x32_bf16 v[4:7], v[172:175], v[216:219], v[4:7]
	s_setprio 2
	s_barrier
	v_mfma_f32_16x16x32_bf16 v[0:3], v[176:179], v[212:215], 0
	v_mfma_f32_16x16x32_bf16 v[0:3], v[184:187], v[216:219], v[0:3]
	s_setprio 0
	s_branch .Lmid_gemm12
.LBB0_1514:
	ds_read_b128 v[152:155], v149
	ds_read_b128 v[156:159], v149 offset:1024
	ds_read_b128 v[160:163], v149 offset:2048
	ds_read_b128 v[164:167], v149 offset:3072
	ds_read_b128 v[168:171], v150
	ds_read_b128 v[172:175], v150 offset:1024
	ds_read_b128 v[176:179], v150 offset:2048
	ds_read_b128 v[184:187], v150 offset:3072
	s_add_u32 s48, s46, 0x100
	s_addc_u32 s49, s47, 0
	s_cmp_eq_u32 s76, 40
	s_cselect_b32 s53, s9, s49
	s_cselect_b32 s52, s8, s48
	s_cselect_b32 s51, s45, s75
	s_cselect_b32 s50, s44, s74
	v_lshl_add_u64 v[144:145], s[46:47], 0, v[136:137]
	s_add_i32 m0, s57, 0xc000
	ds_read_b128 v[188:191], v151
	ds_read_b128 v[192:195], v151 offset:1024
	ds_read_b128 v[196:199], v151 offset:2048
	ds_read_b128 v[200:203], v151 offset:3072
	ds_read_b128 v[204:207], v151 offset:4096
	ds_read_b128 v[208:211], v151 offset:5120
	ds_read_b128 v[212:215], v151 offset:6144
	ds_read_b128 v[216:219], v151 offset:7168
	global_load_lds_dwordx4 v[144:145], off
	v_lshl_add_u64 v[144:145], s[46:47], 0, v[138:139]
	s_add_i32 m0, s57, 0xe000
	s_nop 0
	global_load_lds_dwordx4 v[144:145], off
	s_waitcnt vmcnt(8)
	s_waitcnt lgkmcnt(0)
	s_barrier
	s_setprio 1
	s_waitcnt lgkmcnt(0)
	v_mfma_f32_16x16x32_bf16 v[124:127], v[152:155], v[188:191], v[124:127]
	v_mfma_f32_16x16x32_bf16 v[124:127], v[156:159], v[192:195], v[124:127]
	v_mfma_f32_16x16x32_bf16 v[120:123], v[160:163], v[188:191], v[120:123]
	v_mfma_f32_16x16x32_bf16 v[120:123], v[164:167], v[192:195], v[120:123]
	v_mfma_f32_16x16x32_bf16 v[116:119], v[152:155], v[196:199], v[116:119]
	v_mfma_f32_16x16x32_bf16 v[116:119], v[156:159], v[200:203], v[116:119]
	v_mfma_f32_16x16x32_bf16 v[108:111], v[160:163], v[196:199], v[108:111]
	v_mfma_f32_16x16x32_bf16 v[108:111], v[164:167], v[200:203], v[108:111]
	v_mfma_f32_16x16x32_bf16 v[100:103], v[152:155], v[204:207], v[100:103]
	v_mfma_f32_16x16x32_bf16 v[100:103], v[156:159], v[208:211], v[100:103]
	v_mfma_f32_16x16x32_bf16 v[92:95], v[160:163], v[204:207], v[92:95]
	v_mfma_f32_16x16x32_bf16 v[92:95], v[164:167], v[208:211], v[92:95]
	v_mfma_f32_16x16x32_bf16 v[84:87], v[152:155], v[212:215], v[84:87]
	v_mfma_f32_16x16x32_bf16 v[84:87], v[156:159], v[216:219], v[84:87]
	v_mfma_f32_16x16x32_bf16 v[76:79], v[160:163], v[212:215], v[76:79]
	v_mfma_f32_16x16x32_bf16 v[76:79], v[164:167], v[216:219], v[76:79]
	v_mfma_f32_16x16x32_bf16 v[112:115], v[168:171], v[188:191], v[112:115]
	v_mfma_f32_16x16x32_bf16 v[112:115], v[172:175], v[192:195], v[112:115]
	v_mfma_f32_16x16x32_bf16 v[104:107], v[176:179], v[188:191], v[104:107]
	v_mfma_f32_16x16x32_bf16 v[104:107], v[184:187], v[192:195], v[104:107]
	v_mfma_f32_16x16x32_bf16 v[96:99], v[168:171], v[196:199], v[96:99]
	v_mfma_f32_16x16x32_bf16 v[96:99], v[172:175], v[200:203], v[96:99]
	v_mfma_f32_16x16x32_bf16 v[88:91], v[176:179], v[196:199], v[88:91]
	v_mfma_f32_16x16x32_bf16 v[88:91], v[184:187], v[200:203], v[88:91]
	v_mfma_f32_16x16x32_bf16 v[80:83], v[168:171], v[204:207], v[80:83]
	v_mfma_f32_16x16x32_bf16 v[80:83], v[172:175], v[208:211], v[80:83]
	v_mfma_f32_16x16x32_bf16 v[72:75], v[176:179], v[204:207], v[72:75]
	v_mfma_f32_16x16x32_bf16 v[72:75], v[184:187], v[208:211], v[72:75]
	v_mfma_f32_16x16x32_bf16 v[68:71], v[168:171], v[212:215], v[68:71]
	v_mfma_f32_16x16x32_bf16 v[68:71], v[172:175], v[216:219], v[68:71]
	s_setprio 2
	s_barrier
	v_mfma_f32_16x16x32_bf16 v[64:67], v[176:179], v[212:215], v[64:67]
	v_mfma_f32_16x16x32_bf16 v[64:67], v[184:187], v[216:219], v[64:67]
	s_setprio 0
	s_add_i32 s46, s64, s56
	v_lshl_add_u64 v[144:145], s[50:51], 0, v[130:131]
	s_mov_b32 m0, s46
	ds_read_b128 v[188:191], v151 offset:16384
	ds_read_b128 v[192:195], v151 offset:17408
	ds_read_b128 v[196:199], v151 offset:18432
	ds_read_b128 v[200:203], v151 offset:19456
	ds_read_b128 v[204:207], v151 offset:20480
	ds_read_b128 v[208:211], v151 offset:21504
	ds_read_b128 v[212:215], v151 offset:22528
	ds_read_b128 v[216:219], v151 offset:23552
	global_load_lds_dwordx4 v[144:145], off
	s_add_i32 m0, s46, 0x2000
	s_add_u32 s46, s50, 0xb0000
	v_lshl_add_u64 v[220:221], s[50:51], 0, v[134:135]
	s_addc_u32 s47, s51, 0
	s_add_i32 s77, s65, s56
	global_load_lds_dwordx4 v[220:221], off
	v_lshl_add_u64 v[222:223], s[46:47], 0, v[130:131]
	s_mov_b32 m0, s77
	v_lshl_add_u64 v[224:225], s[52:53], 0, v[132:133]
	global_load_lds_dwordx4 v[222:223], off
	v_lshl_add_u64 v[222:223], s[46:47], 0, v[134:135]
	s_add_i32 m0, s77, 0x2000
	s_nop 0
	global_load_lds_dwordx4 v[222:223], off
	v_lshl_add_u64 v[222:223], s[52:53], 0, v[128:129]
	s_mov_b32 m0, s57
	s_nop 0
	global_load_lds_dwordx4 v[222:223], off
	s_mov_b32 m0, s58
	s_nop 0
	global_load_lds_dwordx4 v[224:225], off
	s_waitcnt vmcnt(8)
	s_waitcnt lgkmcnt(0)
	s_barrier
	s_setprio 1
	s_waitcnt lgkmcnt(0)
	v_mfma_f32_16x16x32_bf16 v[60:63], v[152:155], v[188:191], v[60:63]
	v_mfma_f32_16x16x32_bf16 v[60:63], v[156:159], v[192:195], v[60:63]
	v_mfma_f32_16x16x32_bf16 v[56:59], v[160:163], v[188:191], v[56:59]
	v_mfma_f32_16x16x32_bf16 v[56:59], v[164:167], v[192:195], v[56:59]
	v_mfma_f32_16x16x32_bf16 v[52:55], v[152:155], v[196:199], v[52:55]
	v_mfma_f32_16x16x32_bf16 v[52:55], v[156:159], v[200:203], v[52:55]
	v_mfma_f32_16x16x32_bf16 v[44:47], v[160:163], v[196:199], v[44:47]
	v_mfma_f32_16x16x32_bf16 v[44:47], v[164:167], v[200:203], v[44:47]
	v_mfma_f32_16x16x32_bf16 v[36:39], v[152:155], v[204:207], v[36:39]
	v_mfma_f32_16x16x32_bf16 v[36:39], v[156:159], v[208:211], v[36:39]
	v_mfma_f32_16x16x32_bf16 v[28:31], v[160:163], v[204:207], v[28:31]
	v_mfma_f32_16x16x32_bf16 v[28:31], v[164:167], v[208:211], v[28:31]
	v_mfma_f32_16x16x32_bf16 v[20:23], v[152:155], v[212:215], v[20:23]
	v_mfma_f32_16x16x32_bf16 v[20:23], v[156:159], v[216:219], v[20:23]
	v_mfma_f32_16x16x32_bf16 v[12:15], v[160:163], v[212:215], v[12:15]
	v_mfma_f32_16x16x32_bf16 v[12:15], v[164:167], v[216:219], v[12:15]
	v_mfma_f32_16x16x32_bf16 v[48:51], v[168:171], v[188:191], v[48:51]
	v_mfma_f32_16x16x32_bf16 v[48:51], v[172:175], v[192:195], v[48:51]
	v_mfma_f32_16x16x32_bf16 v[40:43], v[176:179], v[188:191], v[40:43]
	v_mfma_f32_16x16x32_bf16 v[40:43], v[184:187], v[192:195], v[40:43]
	v_mfma_f32_16x16x32_bf16 v[32:35], v[168:171], v[196:199], v[32:35]
	v_mfma_f32_16x16x32_bf16 v[32:35], v[172:175], v[200:203], v[32:35]
	v_mfma_f32_16x16x32_bf16 v[24:27], v[176:179], v[196:199], v[24:27]
	v_mfma_f32_16x16x32_bf16 v[24:27], v[184:187], v[200:203], v[24:27]
	v_mfma_f32_16x16x32_bf16 v[16:19], v[168:171], v[204:207], v[16:19]
	v_mfma_f32_16x16x32_bf16 v[16:19], v[172:175], v[208:211], v[16:19]
	v_mfma_f32_16x16x32_bf16 v[8:11], v[176:179], v[204:207], v[8:11]
	v_mfma_f32_16x16x32_bf16 v[8:11], v[184:187], v[208:211], v[8:11]
	v_mfma_f32_16x16x32_bf16 v[4:7], v[168:171], v[212:215], v[4:7]
	v_mfma_f32_16x16x32_bf16 v[4:7], v[172:175], v[216:219], v[4:7]
	s_setprio 2
	s_barrier
	v_mfma_f32_16x16x32_bf16 v[0:3], v[176:179], v[212:215], v[0:3]
	v_mfma_f32_16x16x32_bf16 v[0:3], v[184:187], v[216:219], v[0:3]
	s_setprio 0
.Lmid_gemm12:
	s_add_i32 s77, 0, 0x18000
	s_add_i32 s79, 0, 0x1c000
	v_add_u32_e32 v164, s77, v147
	v_add_u32_e32 v181, s79, v147
	ds_read_b128 v[152:155], v164
	ds_read_b128 v[156:159], v164 offset:1024
	ds_read_b128 v[160:163], v164 offset:2048
	ds_read_b128 v[164:167], v164 offset:3072
	ds_read_b128 v[168:171], v181
	ds_read_b128 v[172:175], v181 offset:1024
	ds_read_b128 v[176:179], v181 offset:2048
	ds_read_b128 v[184:187], v181 offset:3072
	s_add_u32 s46, s52, 0xb0000
	s_addc_u32 s47, s53, 0
	s_mov_b32 m0, s59
	v_lshl_add_u64 v[226:227], s[46:47], 0, v[128:129]
	ds_read_b128 v[188:191], v151 offset:32768
	ds_read_b128 v[192:195], v151 offset:33792
	ds_read_b128 v[196:199], v151 offset:34816
	ds_read_b128 v[200:203], v151 offset:35840
	ds_read_b128 v[204:207], v151 offset:36864
	ds_read_b128 v[208:211], v151 offset:37888
	ds_read_b128 v[212:215], v151 offset:38912
	ds_read_b128 v[216:219], v151 offset:39936
	global_load_lds_dwordx4 v[226:227], off
	v_lshl_add_u64 v[226:227], s[46:47], 0, v[132:133]
	s_mov_b32 m0, s60
	s_nop 0
	global_load_lds_dwordx4 v[226:227], off
	s_waitcnt vmcnt(8)
	s_waitcnt lgkmcnt(0)
	s_barrier
	s_setprio 1
	s_waitcnt lgkmcnt(0)
	v_mfma_f32_16x16x32_bf16 v[124:127], v[152:155], v[188:191], v[124:127]
	v_mfma_f32_16x16x32_bf16 v[124:127], v[156:159], v[192:195], v[124:127]
	v_mfma_f32_16x16x32_bf16 v[120:123], v[160:163], v[188:191], v[120:123]
	v_mfma_f32_16x16x32_bf16 v[120:123], v[164:167], v[192:195], v[120:123]
	v_mfma_f32_16x16x32_bf16 v[116:119], v[152:155], v[196:199], v[116:119]
	v_mfma_f32_16x16x32_bf16 v[116:119], v[156:159], v[200:203], v[116:119]
	v_mfma_f32_16x16x32_bf16 v[108:111], v[160:163], v[196:199], v[108:111]
	v_mfma_f32_16x16x32_bf16 v[108:111], v[164:167], v[200:203], v[108:111]
	v_mfma_f32_16x16x32_bf16 v[100:103], v[152:155], v[204:207], v[100:103]
	v_mfma_f32_16x16x32_bf16 v[100:103], v[156:159], v[208:211], v[100:103]
	v_mfma_f32_16x16x32_bf16 v[92:95], v[160:163], v[204:207], v[92:95]
	v_mfma_f32_16x16x32_bf16 v[92:95], v[164:167], v[208:211], v[92:95]
	v_mfma_f32_16x16x32_bf16 v[84:87], v[152:155], v[212:215], v[84:87]
	v_mfma_f32_16x16x32_bf16 v[84:87], v[156:159], v[216:219], v[84:87]
	v_mfma_f32_16x16x32_bf16 v[76:79], v[160:163], v[212:215], v[76:79]
	v_mfma_f32_16x16x32_bf16 v[76:79], v[164:167], v[216:219], v[76:79]
	v_mfma_f32_16x16x32_bf16 v[112:115], v[168:171], v[188:191], v[112:115]
	v_mfma_f32_16x16x32_bf16 v[112:115], v[172:175], v[192:195], v[112:115]
	v_mfma_f32_16x16x32_bf16 v[104:107], v[176:179], v[188:191], v[104:107]
	v_mfma_f32_16x16x32_bf16 v[104:107], v[184:187], v[192:195], v[104:107]
	v_mfma_f32_16x16x32_bf16 v[96:99], v[168:171], v[196:199], v[96:99]
	v_mfma_f32_16x16x32_bf16 v[96:99], v[172:175], v[200:203], v[96:99]
	v_mfma_f32_16x16x32_bf16 v[88:91], v[176:179], v[196:199], v[88:91]
	v_mfma_f32_16x16x32_bf16 v[88:91], v[184:187], v[200:203], v[88:91]
	v_mfma_f32_16x16x32_bf16 v[80:83], v[168:171], v[204:207], v[80:83]
	v_mfma_f32_16x16x32_bf16 v[80:83], v[172:175], v[208:211], v[80:83]
	v_mfma_f32_16x16x32_bf16 v[72:75], v[176:179], v[204:207], v[72:75]
	v_mfma_f32_16x16x32_bf16 v[72:75], v[184:187], v[208:211], v[72:75]
	v_mfma_f32_16x16x32_bf16 v[68:71], v[168:171], v[212:215], v[68:71]
	v_mfma_f32_16x16x32_bf16 v[68:71], v[172:175], v[216:219], v[68:71]
	s_setprio 2
	s_barrier
	v_mfma_f32_16x16x32_bf16 v[64:67], v[176:179], v[212:215], v[64:67]
	v_mfma_f32_16x16x32_bf16 v[64:67], v[184:187], v[216:219], v[64:67]
	s_setprio 0
	s_add_i32 s46, s77, s56
	v_lshl_add_u64 v[144:145], v[144:145], 0, s[10:11]
	s_mov_b32 m0, s46
	ds_read_b128 v[188:191], v151 offset:49152
	ds_read_b128 v[192:195], v151 offset:50176
	ds_read_b128 v[196:199], v151 offset:51200
	ds_read_b128 v[200:203], v151 offset:52224
	ds_read_b128 v[204:207], v151 offset:53248
	ds_read_b128 v[208:211], v151 offset:54272
	ds_read_b128 v[212:215], v151 offset:55296
	ds_read_b128 v[216:219], v151 offset:56320
	global_load_lds_dwordx4 v[144:145], off
	s_add_i32 m0, s46, 0x2000
	s_add_u32 s46, s50, 0xb0080
	v_lshl_add_u64 v[144:145], v[220:221], 0, s[10:11]
	s_addc_u32 s47, s51, 0
	s_add_i32 s50, s79, s56
	global_load_lds_dwordx4 v[144:145], off
	v_lshl_add_u64 v[144:145], s[46:47], 0, v[130:131]
	s_mov_b32 m0, s50
	s_nop 0
	global_load_lds_dwordx4 v[144:145], off
	v_lshl_add_u64 v[144:145], s[46:47], 0, v[134:135]
	s_add_i32 m0, s50, 0x2000
	s_nop 0
	global_load_lds_dwordx4 v[144:145], off
	v_lshl_add_u64 v[144:145], v[222:223], 0, s[10:11]
	s_mov_b32 m0, s62
	s_nop 0
	global_load_lds_dwordx4 v[144:145], off
	v_lshl_add_u64 v[144:145], v[224:225], 0, s[10:11]
	s_mov_b32 m0, s63
	s_nop 0
	global_load_lds_dwordx4 v[144:145], off
	s_waitcnt vmcnt(8)
	s_waitcnt lgkmcnt(0)
	s_barrier
	s_setprio 1
	s_waitcnt lgkmcnt(0)
	v_mfma_f32_16x16x32_bf16 v[60:63], v[152:155], v[188:191], v[60:63]
	v_mfma_f32_16x16x32_bf16 v[60:63], v[156:159], v[192:195], v[60:63]
	v_mfma_f32_16x16x32_bf16 v[56:59], v[160:163], v[188:191], v[56:59]
	v_mfma_f32_16x16x32_bf16 v[56:59], v[164:167], v[192:195], v[56:59]
	v_mfma_f32_16x16x32_bf16 v[52:55], v[152:155], v[196:199], v[52:55]
	v_mfma_f32_16x16x32_bf16 v[52:55], v[156:159], v[200:203], v[52:55]
	v_mfma_f32_16x16x32_bf16 v[44:47], v[160:163], v[196:199], v[44:47]
	v_mfma_f32_16x16x32_bf16 v[44:47], v[164:167], v[200:203], v[44:47]
	v_mfma_f32_16x16x32_bf16 v[36:39], v[152:155], v[204:207], v[36:39]
	v_mfma_f32_16x16x32_bf16 v[36:39], v[156:159], v[208:211], v[36:39]
	v_mfma_f32_16x16x32_bf16 v[28:31], v[160:163], v[204:207], v[28:31]
	v_mfma_f32_16x16x32_bf16 v[28:31], v[164:167], v[208:211], v[28:31]
	v_mfma_f32_16x16x32_bf16 v[20:23], v[152:155], v[212:215], v[20:23]
	v_mfma_f32_16x16x32_bf16 v[20:23], v[156:159], v[216:219], v[20:23]
	v_mfma_f32_16x16x32_bf16 v[12:15], v[160:163], v[212:215], v[12:15]
	v_mfma_f32_16x16x32_bf16 v[12:15], v[164:167], v[216:219], v[12:15]
	v_mfma_f32_16x16x32_bf16 v[48:51], v[168:171], v[188:191], v[48:51]
	v_mfma_f32_16x16x32_bf16 v[48:51], v[172:175], v[192:195], v[48:51]
	v_mfma_f32_16x16x32_bf16 v[40:43], v[176:179], v[188:191], v[40:43]
	v_mfma_f32_16x16x32_bf16 v[40:43], v[184:187], v[192:195], v[40:43]
	v_mfma_f32_16x16x32_bf16 v[32:35], v[168:171], v[196:199], v[32:35]
	v_mfma_f32_16x16x32_bf16 v[32:35], v[172:175], v[200:203], v[32:35]
	v_mfma_f32_16x16x32_bf16 v[24:27], v[176:179], v[196:199], v[24:27]
	v_mfma_f32_16x16x32_bf16 v[24:27], v[184:187], v[200:203], v[24:27]
	v_mfma_f32_16x16x32_bf16 v[16:19], v[168:171], v[204:207], v[16:19]
	v_mfma_f32_16x16x32_bf16 v[16:19], v[172:175], v[208:211], v[16:19]
	v_mfma_f32_16x16x32_bf16 v[8:11], v[176:179], v[204:207], v[8:11]
	v_mfma_f32_16x16x32_bf16 v[8:11], v[184:187], v[208:211], v[8:11]
	v_mfma_f32_16x16x32_bf16 v[4:7], v[168:171], v[212:215], v[4:7]
	v_mfma_f32_16x16x32_bf16 v[4:7], v[172:175], v[216:219], v[4:7]
	s_setprio 2
	s_barrier
	v_mfma_f32_16x16x32_bf16 v[0:3], v[176:179], v[212:215], v[0:3]
	v_mfma_f32_16x16x32_bf16 v[0:3], v[184:187], v[216:219], v[0:3]
	s_setprio 0
	s_add_i32 s76, s76, 2
	s_add_u32 s74, s74, 0x100
	s_addc_u32 s75, s75, 0
	s_cmp_gt_u32 s76, 41
	s_mov_b64 s[46:47], s[48:49]
	s_cbranch_scc0 .LBB0_1514
	s_and_b64 vcc, exec, s[12:13]
	s_cbranch_vccz .LBB0_1517
	s_barrier
